# out-projection epilogue: 4 base loads per row issued together with counted waits; phase-0 sinf large-argument blocks moved out of line; 3 redundant v_max canonicalisations removed in attention loop
# speedup vs baseline: 1.0100x; 1.0039x over previous
; __device__ __forceinline__ void filter_item32(const Args& a, int L, bf16* KR, int t0, int np0, int npn, int lane) {
;     ...
;     const int n = lane & 31, hi = lane >> 5, t = t0 + n;
;     const float tt = (float)t * (1.0f / (float)(L - 1)), w = 6.283185307179586f * (float)t / (float)L;
;     f32x16 h0 = {}, h1 = {};
;     {
;         float cv[8], sv[8];
; #pragma unroll
;         for (int k = 0; k < 8; ++k) { const float f = 1e-4f + (float)(k + 8 * hi) * ((15.0f - 1e-4f) / 15.0f); float s, c; sincosf(f * w, &s, &c); cv[k] = c; sv[k] = -s; }
; __global__ void __launch_bounds__(512, 2) hymba_fwd(Args a) {
;     ...
;         for (int it = NGW - 1 - gw; it < 3 * (I_FP + I_FS); it += NGW) { const int q = it / 3, part = it - 3 * q, np0 = part == 0 ? 0 : (part == 1 ? 6 : 11), npn = part == 0 ? 6 : 5;
;             if (q < I_FP) filter_item32(a, L_P, KRP, 32 * q, np0, npn, lane); else filter_item32(a, L_S, KRS, 32 * (q - I_FP), np0, npn, lane); }
.LBB0_22:
	s_mul_hi_i32 s2, s52, 0x55555556
	s_lshr_b32 s3, s2, 31
	s_add_i32 s2, s2, s3
	s_mul_i32 s3, s2, -3
	s_add_i32 s3, s3, s52
	s_cmp_eq_u32 s3, 1
	s_cselect_b32 s4, 6, 11
	s_cmp_eq_u32 s3, 0
	s_cselect_b32 s66, 6, 5
	s_cselect_b32 s84, 0, s4
	s_lshl_b32 s85, s2, 5
	s_cmpk_gt_i32 s52, 0x5ff
	s_mov_b64 s[2:3], -1
	s_cbranch_scc0 .LBB0_380
	v_add_u32_e32 v64, s85, v109
	v_cvt_f32_i32_e32 v2, v64
	v_mul_f32_e32 v1, 0x40c90fdb, v2
	v_mul_f32_e32 v1, 0x3a000000, v1
	v_mul_f32_e32 v3, v129, v1
	v_and_b32_e32 v4, 0x7fffffff, v3
	v_cmp_nlt_f32_e64 s[2:3], |v3|, s60
	s_and_saveexec_b64 s[4:5], s[2:3]
	s_xor_b64 s[8:9], exec, s[4:5]
	s_cbranch_execnz .Lsl_25
.LBB0_25:
	s_andn2_saveexec_b64 s[2:3], s[8:9]
	v_mul_f32_e64 v5, |v3|, s1
	v_rndne_f32_e32 v7, v5
	v_cvt_i32_f32_e32 v6, v7
	v_fma_f32 v5, v7, s92, |v3|
	v_fmac_f32_e32 v5, 0xb3a22168, v7
	v_fmac_f32_e32 v5, 0xa7c234c4, v7
	s_or_b64 exec, exec, s[2:3]
	v_mul_f32_e32 v7, v130, v1
	v_and_b32_e32 v8, 0x7fffffff, v7
	v_cmp_nlt_f32_e64 s[2:3], |v7|, s60
	s_and_saveexec_b64 s[4:5], s[2:3]
	s_xor_b64 s[8:9], exec, s[4:5]
	s_cbranch_execnz .Lsl_29
.LBB0_29:
	s_andn2_saveexec_b64 s[2:3], s[8:9]
	v_mul_f32_e64 v9, |v7|, s1
	v_rndne_f32_e32 v11, v9
	v_cvt_i32_f32_e32 v10, v11
	v_fma_f32 v9, v11, s92, |v7|
	v_fmac_f32_e32 v9, 0xb3a22168, v11
	v_fmac_f32_e32 v9, 0xa7c234c4, v11
	s_or_b64 exec, exec, s[2:3]
	v_mul_f32_e32 v11, v131, v1
	v_and_b32_e32 v12, 0x7fffffff, v11
	v_cmp_nlt_f32_e64 s[2:3], |v11|, s60
	s_and_saveexec_b64 s[4:5], s[2:3]
	s_xor_b64 s[8:9], exec, s[4:5]
	s_cbranch_execnz .Lsl_33
.LBB0_33:
	s_andn2_saveexec_b64 s[2:3], s[8:9]
	v_mul_f32_e64 v13, |v11|, s1
	v_rndne_f32_e32 v15, v13
	v_cvt_i32_f32_e32 v14, v15
	v_fma_f32 v13, v15, s92, |v11|
	v_fmac_f32_e32 v13, 0xb3a22168, v15
	v_fmac_f32_e32 v13, 0xa7c234c4, v15
	s_or_b64 exec, exec, s[2:3]
	v_mul_f32_e32 v15, v132, v1
	v_and_b32_e32 v16, 0x7fffffff, v15
	v_cmp_nlt_f32_e64 s[2:3], |v15|, s60
	s_and_saveexec_b64 s[4:5], s[2:3]
	s_xor_b64 s[8:9], exec, s[4:5]
	s_cbranch_execnz .Lsl_37
.LBB0_37:
	s_andn2_saveexec_b64 s[2:3], s[8:9]
	v_mul_f32_e64 v17, |v15|, s1
	v_rndne_f32_e32 v19, v17
	v_cvt_i32_f32_e32 v18, v19
	v_fma_f32 v17, v19, s92, |v15|
	v_fmac_f32_e32 v17, 0xb3a22168, v19
	v_fmac_f32_e32 v17, 0xa7c234c4, v19
	s_or_b64 exec, exec, s[2:3]
	v_mul_f32_e32 v19, v133, v1
	v_and_b32_e32 v20, 0x7fffffff, v19
	v_cmp_nlt_f32_e64 s[2:3], |v19|, s60
	s_and_saveexec_b64 s[4:5], s[2:3]
	s_xor_b64 s[8:9], exec, s[4:5]
	s_cbranch_execnz .Lsl_41
.LBB0_41:
	s_andn2_saveexec_b64 s[2:3], s[8:9]
	v_mul_f32_e64 v21, |v19|, s1
	v_rndne_f32_e32 v23, v21
	v_cvt_i32_f32_e32 v22, v23
	v_fma_f32 v21, v23, s92, |v19|
	v_fmac_f32_e32 v21, 0xb3a22168, v23
	v_fmac_f32_e32 v21, 0xa7c234c4, v23
	s_or_b64 exec, exec, s[2:3]
	v_mul_f32_e32 v23, v134, v1
	v_and_b32_e32 v24, 0x7fffffff, v23
	v_cmp_nlt_f32_e64 s[2:3], |v23|, s60
	s_and_saveexec_b64 s[4:5], s[2:3]
	s_xor_b64 s[8:9], exec, s[4:5]
	s_cbranch_execnz .Lsl_45
.LBB0_45:
	s_andn2_saveexec_b64 s[2:3], s[8:9]
	v_mul_f32_e64 v25, |v23|, s1
	v_rndne_f32_e32 v27, v25
	v_cvt_i32_f32_e32 v26, v27
	v_fma_f32 v25, v27, s92, |v23|
	v_fmac_f32_e32 v25, 0xb3a22168, v27
	v_fmac_f32_e32 v25, 0xa7c234c4, v27
	s_or_b64 exec, exec, s[2:3]
	v_mul_f32_e32 v28, v135, v1
	v_and_b32_e32 v30, 0x7fffffff, v28
	v_cmp_nlt_f32_e64 s[2:3], |v28|, s60
	s_and_saveexec_b64 s[4:5], s[2:3]
	s_xor_b64 s[8:9], exec, s[4:5]
	s_cbranch_execnz .Lsl_49
.LBB0_49:
	s_andn2_saveexec_b64 s[2:3], s[8:9]
	v_mul_f32_e64 v27, |v28|, s1
	v_rndne_f32_e32 v27, v27
	v_cvt_i32_f32_e32 v34, v27
	v_fma_f32 v33, v27, s92, |v28|
	v_fmac_f32_e32 v33, 0xb3a22168, v27
	v_fmac_f32_e32 v33, 0xa7c234c4, v27
	s_or_b64 exec, exec, s[2:3]
	v_mul_f32_e32 v27, v128, v1
	v_and_b32_e32 v29, 0x7fffffff, v27
	v_cmp_nlt_f32_e64 s[2:3], |v27|, s60
	s_and_saveexec_b64 s[4:5], s[2:3]
	s_xor_b64 s[8:9], exec, s[4:5]
	s_cbranch_execnz .Lsl_53
.LBB0_53:
	s_andn2_saveexec_b64 s[2:3], s[8:9]
	v_mul_f32_e64 v1, |v27|, s1
	v_rndne_f32_e32 v1, v1
	v_cvt_i32_f32_e32 v32, v1
	v_fma_f32 v31, v1, s92, |v27|
	v_fmac_f32_e32 v31, 0xb3a22168, v1
	v_fmac_f32_e32 v31, 0xa7c234c4, v1
	s_or_b64 exec, exec, s[2:3]
	v_mul_f32_e32 v1, v33, v33
	v_fmamk_f32 v35, v1, 0xb94c1982, v142
	v_fmaak_f32 v35, v1, v35, 0xbe2aaa9d
	v_mul_f32_e32 v35, v1, v35
	v_fmac_f32_e32 v33, v33, v35
	v_fmamk_f32 v35, v1, 0x37d75334, v143
	v_fmaak_f32 v35, v1, v35, 0x3d2aabf7
	v_fmaak_f32 v35, v1, v35, 0xbf000004
	v_fma_f32 v1, v1, v35, 1.0
	v_lshlrev_b32_e32 v35, 30, v34
	v_and_b32_e32 v34, 1, v34
	v_cmp_eq_u32_e32 vcc, 0, v34
	v_xor_b32_e32 v30, v30, v28
	v_and_b32_e32 v36, 0x80000000, v35
	v_cndmask_b32_e32 v34, v1, v33, vcc
	v_xor_b32_e32 v33, 0x80000000, v33
	v_xor_b32_e32 v30, v30, v34
	v_cndmask_b32_e32 v1, v33, v1, vcc
	v_xor_b32_e32 v30, v30, v36
	v_bitop3_b32 v1, v1, v35, s53 bitop3:0x78
	v_cmp_class_f32_e64 vcc, v28, s96
	v_mul_f32_e32 v28, v25, v25
	v_xor_b32_e32 v24, v24, v23
	v_cndmask_b32_e32 v42, v147, v1, vcc
	v_cndmask_b32_e64 v1, v148, -v30, vcc
	v_fmamk_f32 v30, v28, 0xb94c1982, v142
	v_fmaak_f32 v30, v28, v30, 0xbe2aaa9d
	v_mul_f32_e32 v30, v28, v30
	v_fmac_f32_e32 v25, v25, v30
	v_fmamk_f32 v30, v28, 0x37d75334, v143
	v_fmaak_f32 v30, v28, v30, 0x3d2aabf7
	v_fmaak_f32 v30, v28, v30, 0xbf000004
	v_fma_f32 v28, v28, v30, 1.0
	v_lshlrev_b32_e32 v30, 30, v26
	v_and_b32_e32 v26, 1, v26
	v_cmp_eq_u32_e32 vcc, 0, v26
	v_and_b32_e32 v33, 0x80000000, v30
	v_xor_b32_e32 v20, v20, v19
	v_cndmask_b32_e32 v26, v28, v25, vcc
	v_xor_b32_e32 v24, v24, v26
	v_xor_b32_e32 v25, 0x80000000, v25
	v_xor_b32_e32 v24, v24, v33
	v_cndmask_b32_e32 v25, v25, v28, vcc
	v_cmp_class_f32_e64 vcc, v23, s96
	v_mul_f32_e32 v23, v21, v21
; __device__ __forceinline__ void filter_item32(const Args& a, int L, bf16* KR, int t0, int np0, int npn, int lane) {
;     ...
;         for (int k = 0; k < 8; ++k) { const float f = 1e-4f + (float)(k + 8 * hi) * ((15.0f - 1e-4f) / 15.0f); float s, c; sincosf(f * w, &s, &c); cv[k] = c; sv[k] = -s; }
; #pragma unroll
;         for (int kk = 0; kk < 17; ++kk) {
;             const int urow = kk < 8 ? 1 + kk : (kk < 16 ? 17 + (kk - 8) : 0);
;             const float zb = kk < 8 ? cv[kk & 7] : (kk < 16 ? sv[kk & 7] : (hi == 0 ? tt : 0.f));
;             const float* ub = w1 + urow * 64; const int lo1 = kk < 16 ? 8 * hi * 64 + n : n;
;             const float a0 = ub[lo1], a1 = ub[lo1 + 32];
;             h0 = __builtin_amdgcn_mfma_f32_32x32x2f32(a0, zb, h0, 0, 0, 0); h1 = __builtin_amdgcn_mfma_f32_32x32x2f32(a1, zb, h1, 0, 0, 0);
	v_bitop3_b32 v25, v25, v30, s53 bitop3:0x78
	v_cndmask_b32_e64 v34, v148, -v24, vcc
	v_fmamk_f32 v24, v23, 0xb94c1982, v142
	v_fmaak_f32 v24, v23, v24, 0xbe2aaa9d
	v_mul_f32_e32 v24, v23, v24
	v_fmac_f32_e32 v21, v21, v24
	v_fmamk_f32 v24, v23, 0x37d75334, v143
	v_fmaak_f32 v24, v23, v24, 0x3d2aabf7
	v_fmaak_f32 v24, v23, v24, 0xbf000004
	v_fma_f32 v23, v23, v24, 1.0
	v_lshlrev_b32_e32 v24, 30, v22
	v_and_b32_e32 v22, 1, v22
	v_cndmask_b32_e32 v43, v147, v25, vcc
	v_cmp_eq_u32_e32 vcc, 0, v22
	v_and_b32_e32 v25, 0x80000000, v24
	v_xor_b32_e32 v16, v16, v15
	v_cndmask_b32_e32 v22, v23, v21, vcc
	v_xor_b32_e32 v20, v20, v22
	v_xor_b32_e32 v21, 0x80000000, v21
	v_xor_b32_e32 v20, v20, v25
	v_cndmask_b32_e32 v21, v21, v23, vcc
	v_cmp_class_f32_e64 vcc, v19, s96
	v_mul_f32_e32 v19, v17, v17
	v_bitop3_b32 v21, v21, v24, s53 bitop3:0x78
	v_cndmask_b32_e64 v37, v148, -v20, vcc
	v_fmamk_f32 v20, v19, 0xb94c1982, v142
	v_fmaak_f32 v20, v19, v20, 0xbe2aaa9d
	v_mul_f32_e32 v20, v19, v20
	v_fmac_f32_e32 v17, v17, v20
	v_fmamk_f32 v20, v19, 0x37d75334, v143
	v_fmaak_f32 v20, v19, v20, 0x3d2aabf7
	v_fmaak_f32 v20, v19, v20, 0xbf000004
	v_fma_f32 v19, v19, v20, 1.0
	v_lshlrev_b32_e32 v20, 30, v18
	v_and_b32_e32 v18, 1, v18
	v_cndmask_b32_e32 v45, v147, v21, vcc
	v_cmp_eq_u32_e32 vcc, 0, v18
	v_and_b32_e32 v21, 0x80000000, v20
	v_xor_b32_e32 v12, v12, v11
	v_cndmask_b32_e32 v18, v19, v17, vcc
	v_xor_b32_e32 v16, v16, v18
	v_xor_b32_e32 v17, 0x80000000, v17
	v_xor_b32_e32 v16, v16, v21
	v_cndmask_b32_e32 v17, v17, v19, vcc
	v_cmp_class_f32_e64 vcc, v15, s96
	v_mul_f32_e32 v15, v13, v13
	v_bitop3_b32 v17, v17, v20, s53 bitop3:0x78
	v_cndmask_b32_e64 v38, v148, -v16, vcc
	v_fmamk_f32 v16, v15, 0xb94c1982, v142
	v_fmaak_f32 v16, v15, v16, 0xbe2aaa9d
	v_mul_f32_e32 v16, v15, v16
	v_fmac_f32_e32 v13, v13, v16
	v_fmamk_f32 v16, v15, 0x37d75334, v143
	v_fmaak_f32 v16, v15, v16, 0x3d2aabf7
	v_fmaak_f32 v16, v15, v16, 0xbf000004
	v_fma_f32 v15, v15, v16, 1.0
	v_lshlrev_b32_e32 v16, 30, v14
	v_and_b32_e32 v14, 1, v14
	v_cndmask_b32_e32 v46, v147, v17, vcc
	v_cmp_eq_u32_e32 vcc, 0, v14
	v_and_b32_e32 v17, 0x80000000, v16
	v_xor_b32_e32 v8, v8, v7
	v_cndmask_b32_e32 v14, v15, v13, vcc
	v_xor_b32_e32 v12, v12, v14
	v_xor_b32_e32 v13, 0x80000000, v13
	v_xor_b32_e32 v12, v12, v17
	v_cndmask_b32_e32 v13, v13, v15, vcc
	v_cmp_class_f32_e64 vcc, v11, s96
	v_mul_f32_e32 v11, v9, v9
	v_bitop3_b32 v13, v13, v16, s53 bitop3:0x78
	v_cndmask_b32_e64 v39, v148, -v12, vcc
	v_fmamk_f32 v12, v11, 0xb94c1982, v142
	v_fmaak_f32 v12, v11, v12, 0xbe2aaa9d
	v_mul_f32_e32 v12, v11, v12
	v_fmac_f32_e32 v9, v9, v12
	v_fmamk_f32 v12, v11, 0x37d75334, v143
	v_fmaak_f32 v12, v11, v12, 0x3d2aabf7
	v_fmaak_f32 v12, v11, v12, 0xbf000004
	v_fma_f32 v11, v11, v12, 1.0
	v_lshlrev_b32_e32 v12, 30, v10
	v_and_b32_e32 v10, 1, v10
	v_cndmask_b32_e32 v47, v147, v13, vcc
	v_cmp_eq_u32_e32 vcc, 0, v10
	v_and_b32_e32 v13, 0x80000000, v12
	v_xor_b32_e32 v4, v4, v3
	v_cndmask_b32_e32 v10, v11, v9, vcc
	v_xor_b32_e32 v8, v8, v10
	v_xor_b32_e32 v9, 0x80000000, v9
	v_xor_b32_e32 v8, v8, v13
	v_cndmask_b32_e32 v9, v9, v11, vcc
	v_cmp_class_f32_e64 vcc, v7, s96
	v_mul_f32_e32 v7, v5, v5
	v_bitop3_b32 v9, v9, v12, s53 bitop3:0x78
	v_cndmask_b32_e64 v40, v148, -v8, vcc
	v_fmamk_f32 v8, v7, 0xb94c1982, v142
	v_fmaak_f32 v8, v7, v8, 0xbe2aaa9d
	v_mul_f32_e32 v8, v7, v8
	v_fmac_f32_e32 v5, v5, v8
	v_fmamk_f32 v8, v7, 0x37d75334, v143
	v_fmaak_f32 v8, v7, v8, 0x3d2aabf7
	v_fmaak_f32 v8, v7, v8, 0xbf000004
	v_fma_f32 v7, v7, v8, 1.0
	v_lshlrev_b32_e32 v8, 30, v6
	v_and_b32_e32 v6, 1, v6
	v_cndmask_b32_e32 v48, v147, v9, vcc
	v_cmp_eq_u32_e32 vcc, 0, v6
	v_and_b32_e32 v9, 0x80000000, v8
	v_mul_f32_e32 v150, 0x3a001002, v2
	v_cndmask_b32_e32 v6, v7, v5, vcc
	v_xor_b32_e32 v4, v4, v6
	v_xor_b32_e32 v5, 0x80000000, v5
	v_xor_b32_e32 v4, v4, v9
	v_cndmask_b32_e32 v5, v5, v7, vcc
	v_cmp_class_f32_e64 vcc, v3, s96
	v_bitop3_b32 v5, v5, v8, s53 bitop3:0x78
	v_and_b32_e32 v7, 1, v32
	v_cndmask_b32_e64 v41, v148, -v4, vcc
	v_mul_f32_e32 v4, v31, v31
	v_cndmask_b32_e32 v3, v147, v5, vcc
	v_fmamk_f32 v5, v4, 0xb94c1982, v142
	v_fmaak_f32 v5, v4, v5, 0xbe2aaa9d
	v_mul_f32_e32 v5, v4, v5
	v_fmac_f32_e32 v31, v31, v5
	v_fmamk_f32 v5, v4, 0x37d75334, v143
	v_fmaak_f32 v5, v4, v5, 0x3d2aabf7
	v_fmaak_f32 v5, v4, v5, 0xbf000004
	v_fma_f32 v4, v4, v5, 1.0
	v_cmp_eq_u32_e32 vcc, 0, v7
	v_lshlrev_b32_e32 v5, 30, v32
	v_xor_b32_e32 v8, v29, v27
	v_cndmask_b32_e32 v7, v4, v31, vcc
	v_and_b32_e32 v6, 0x80000000, v5
	v_xor_b32_e32 v7, v8, v7
	v_xor_b32_e32 v6, v7, v6
	v_xor_b32_e32 v7, 0x80000000, v31
	v_cndmask_b32_e32 v4, v7, v4, vcc
	v_bitop3_b32 v4, v4, v5, s53 bitop3:0x78
	v_cmp_class_f32_e64 vcc, v27, s96
	v_cndmask_b32_e64 v35, 0, v150, s[54:55]
	s_nop 0
	v_cndmask_b32_e32 v44, v147, v4, vcc
	global_load_dword v2, v[82:83], off offset:256
	global_load_dword v4, v[82:83], off offset:384
	global_load_dword v49, v[82:83], off offset:512
	global_load_dword v50, v[82:83], off offset:640
	v_cndmask_b32_e64 v36, v148, -v6, vcc
	s_waitcnt vmcnt(3)
	v_mfma_f32_32x32x2_f32 v[18:33], v2, v3, 0
	s_waitcnt vmcnt(2)
	v_mfma_f32_32x32x2_f32 v[2:17], v4, v3, 0
	s_waitcnt vmcnt(1)
	v_mfma_f32_32x32x2_f32 v[18:33], v49, v48, v[18:33]
	s_waitcnt vmcnt(0)
	v_mfma_f32_32x32x2_f32 v[2:17], v50, v48, v[2:17]
	global_load_dword v48, v[82:83], off offset:768
	global_load_dword v49, v[82:83], off offset:896
	s_waitcnt vmcnt(1)
	v_mfma_f32_32x32x2_f32 v[18:33], v48, v47, v[18:33]
	s_waitcnt vmcnt(0)
	v_mfma_f32_32x32x2_f32 v[2:17], v49, v47, v[2:17]
	global_load_dword v47, v[82:83], off offset:1024
	global_load_dword v48, v[82:83], off offset:1152
	s_waitcnt vmcnt(1)
; __device__ __forceinline__ int crow16(int r, int hi) { return (r & 3) + 8 * (r >> 2) + 4 * hi; }
; __device__ __forceinline__ void filter_item32(const Args& a, int L, bf16* KR, int t0, int np0, int npn, int lane) {
;     ...
;         for (int kk = 0; kk < 17; ++kk) {
;             const int urow = kk < 8 ? 1 + kk : (kk < 16 ? 17 + (kk - 8) : 0);
;             const float zb = kk < 8 ? cv[kk & 7] : (kk < 16 ? sv[kk & 7] : (hi == 0 ? tt : 0.f));
;             const float* ub = w1 + urow * 64; const int lo1 = kk < 16 ? 8 * hi * 64 + n : n;
;             const float a0 = ub[lo1], a1 = ub[lo1 + 32];
;             h0 = __builtin_amdgcn_mfma_f32_32x32x2f32(a0, zb, h0, 0, 0, 0); h1 = __builtin_amdgcn_mfma_f32_32x32x2f32(a1, zb, h1, 0, 0, 0);
;         }
; #pragma unroll
;         for (int r = 0; r < 16; ++r) { const int j = crow16(r, hi); h0[r] = sinf(fq[j] * (h0[r] + b1[j])); h1[r] = sinf(fq[32 + j] * (h1[r] + b1[32 + j])); }
	v_mfma_f32_32x32x2_f32 v[18:33], v47, v46, v[18:33]
	s_waitcnt vmcnt(0)
	v_mfma_f32_32x32x2_f32 v[2:17], v48, v46, v[2:17]
	global_load_dword v46, v[82:83], off offset:1280
	global_load_dword v47, v[82:83], off offset:1408
	s_waitcnt vmcnt(1)
	v_mfma_f32_32x32x2_f32 v[18:33], v46, v45, v[18:33]
	s_waitcnt vmcnt(0)
	v_mfma_f32_32x32x2_f32 v[2:17], v47, v45, v[2:17]
	global_load_dword v45, v[82:83], off offset:1536
	global_load_dword v46, v[82:83], off offset:1664
	s_waitcnt vmcnt(1)
	v_mfma_f32_32x32x2_f32 v[18:33], v45, v43, v[18:33]
	s_waitcnt vmcnt(0)
	v_mfma_f32_32x32x2_f32 v[2:17], v46, v43, v[2:17]
	global_load_dword v43, v[82:83], off offset:1792
	global_load_dword v45, v[82:83], off offset:1920
	s_waitcnt vmcnt(1)
	v_mfma_f32_32x32x2_f32 v[18:33], v43, v42, v[18:33]
	s_waitcnt vmcnt(0)
	v_mfma_f32_32x32x2_f32 v[2:17], v45, v42, v[2:17]
	global_load_dword v42, v[82:83], off offset:2048
	global_load_dword v43, v[82:83], off offset:2176
	s_waitcnt vmcnt(1)
	v_mfma_f32_32x32x2_f32 v[18:33], v42, v44, v[18:33]
	s_waitcnt vmcnt(0)
	v_mfma_f32_32x32x2_f32 v[2:17], v43, v44, v[2:17]
	global_load_dword v42, v[84:85], off
	global_load_dword v43, v[84:85], off offset:128
	s_waitcnt vmcnt(1)
	v_mfma_f32_32x32x2_f32 v[18:33], v42, v41, v[18:33]
	s_waitcnt vmcnt(0)
	v_mfma_f32_32x32x2_f32 v[2:17], v43, v41, v[2:17]
	global_load_dword v41, v[86:87], off
	global_load_dword v42, v[86:87], off offset:128
	s_waitcnt vmcnt(1)
	v_mfma_f32_32x32x2_f32 v[18:33], v41, v40, v[18:33]
	s_waitcnt vmcnt(0)
	v_mfma_f32_32x32x2_f32 v[2:17], v42, v40, v[2:17]
	global_load_dword v40, v[88:89], off
	global_load_dword v41, v[88:89], off offset:128
	s_waitcnt vmcnt(1)
	v_mfma_f32_32x32x2_f32 v[18:33], v40, v39, v[18:33]
	s_waitcnt vmcnt(0)
	v_mfma_f32_32x32x2_f32 v[2:17], v41, v39, v[2:17]
	global_load_dword v39, v[90:91], off
	global_load_dword v40, v[90:91], off offset:128
	s_waitcnt vmcnt(1)
	v_mfma_f32_32x32x2_f32 v[18:33], v39, v38, v[18:33]
	s_waitcnt vmcnt(0)
	v_mfma_f32_32x32x2_f32 v[2:17], v40, v38, v[2:17]
	global_load_dword v38, v[92:93], off
	global_load_dword v39, v[92:93], off offset:128
	s_waitcnt vmcnt(1)
	v_mfma_f32_32x32x2_f32 v[18:33], v38, v37, v[18:33]
	s_waitcnt vmcnt(0)
	v_mfma_f32_32x32x2_f32 v[2:17], v39, v37, v[2:17]
	global_load_dword v37, v[94:95], off
	global_load_dword v38, v[94:95], off offset:128
	s_waitcnt vmcnt(1)
	v_mfma_f32_32x32x2_f32 v[18:33], v37, v34, v[18:33]
	s_waitcnt vmcnt(0)
	v_mfma_f32_32x32x2_f32 v[2:17], v38, v34, v[2:17]
	global_load_dword v34, v[96:97], off
	global_load_dword v37, v[96:97], off offset:128
	s_waitcnt vmcnt(1)
	v_mfma_f32_32x32x2_f32 v[18:33], v34, v1, v[18:33]
	s_waitcnt vmcnt(0)
	v_mfma_f32_32x32x2_f32 v[2:17], v37, v1, v[2:17]
	global_load_dword v1, v[98:99], off
	global_load_dword v34, v[98:99], off offset:128
	s_waitcnt vmcnt(1)
	v_mfma_f32_32x32x2_f32 v[18:33], v1, v36, v[18:33]
	s_waitcnt vmcnt(0)
	v_mfma_f32_32x32x2_f32 v[2:17], v34, v36, v[2:17]
	global_load_dword v1, v[100:101], off
	global_load_dword v34, v[100:101], off offset:128
	s_waitcnt vmcnt(1)
	v_mfma_f32_32x32x2_f32 v[18:33], v1, v35, v[18:33]
	global_load_dword v65, v[104:105], off
	global_load_dword v1, v[106:107], off
	s_waitcnt vmcnt(0)
	s_nop 14
	v_add_f32_e32 v1, v18, v1
	v_mfma_f32_32x32x2_f32 v[2:17], v34, v35, v[2:17]
	v_mul_f32_e32 v1, v65, v1
	v_and_b32_e32 v34, 0x7fffffff, v1
	v_cmp_nlt_f32_e64 s[2:3], |v1|, s60
	s_and_saveexec_b64 s[4:5], s[2:3]
	s_xor_b64 s[8:9], exec, s[4:5]
	s_cbranch_execnz .Lsl_57
.LBB0_57:
	s_andn2_saveexec_b64 s[2:3], s[8:9]
	v_mul_f32_e64 v18, |v1|, s1
	v_rndne_f32_e32 v18, v18
	v_cvt_i32_f32_e32 v35, v18
	v_fma_f32 v36, v18, s92, |v1|
	v_fmac_f32_e32 v36, 0xb3a22168, v18
	v_fmac_f32_e32 v36, 0xa7c234c4, v18
	s_or_b64 exec, exec, s[2:3]
	global_load_dword v18, v[106:107], off offset:128
	global_load_dword v66, v[104:105], off offset:128
	s_waitcnt vmcnt(1)
	s_nop 0
	v_add_f32_e32 v2, v2, v18
	s_waitcnt vmcnt(0)
	v_mul_f32_e32 v18, v66, v2
	v_and_b32_e32 v48, 0x7fffffff, v18
	v_cmp_nlt_f32_e64 s[2:3], |v18|, s60
	s_and_saveexec_b64 s[4:5], s[2:3]
	s_xor_b64 s[8:9], exec, s[4:5]
	s_cbranch_execnz .Lsl_61
.LBB0_61:
	s_andn2_saveexec_b64 s[2:3], s[8:9]
	v_mul_f32_e64 v2, |v18|, s1
	v_rndne_f32_e32 v2, v2
	v_cvt_i32_f32_e32 v49, v2
	v_fma_f32 v50, v2, s92, |v18|
	v_fmac_f32_e32 v50, 0xb3a22168, v2
	v_fmac_f32_e32 v50, 0xa7c234c4, v2
	s_or_b64 exec, exec, s[2:3]
	global_load_dword v2, v[106:107], off offset:4
	global_load_dword v67, v[104:105], off offset:4
	s_waitcnt vmcnt(1)
	v_add_f32_e32 v2, v19, v2
	s_waitcnt vmcnt(0)
	v_mul_f32_e32 v37, v67, v2
	v_and_b32_e32 v38, 0x7fffffff, v37
	v_cmp_nlt_f32_e64 s[2:3], |v37|, s60
	s_and_saveexec_b64 s[4:5], s[2:3]
	s_xor_b64 s[8:9], exec, s[4:5]
	s_cbranch_execnz .Lsl_65
.LBB0_65:
	s_andn2_saveexec_b64 s[2:3], s[8:9]
	v_mul_f32_e64 v2, |v37|, s1
	v_rndne_f32_e32 v2, v2
	v_cvt_i32_f32_e32 v39, v2
	v_fma_f32 v40, v2, s92, |v37|
	v_fmac_f32_e32 v40, 0xb3a22168, v2
	v_fmac_f32_e32 v40, 0xa7c234c4, v2
	s_or_b64 exec, exec, s[2:3]
	global_load_dword v2, v[106:107], off offset:132
	global_load_dword v68, v[104:105], off offset:132
	s_waitcnt vmcnt(1)
	v_add_f32_e32 v2, v3, v2
	s_waitcnt vmcnt(0)
	v_mul_f32_e32 v3, v68, v2
	v_and_b32_e32 v19, 0x7fffffff, v3
	v_cmp_nlt_f32_e64 s[2:3], |v3|, s60
	s_and_saveexec_b64 s[4:5], s[2:3]
	s_xor_b64 s[8:9], exec, s[4:5]
	s_cbranch_execnz .Lsl_69
; __device__ __forceinline__ int crow16(int r, int hi) { return (r & 3) + 8 * (r >> 2) + 4 * hi; }
; __device__ __forceinline__ void filter_item32(const Args& a, int L, bf16* KR, int t0, int np0, int npn, int lane) {
;     ...
;         for (int r = 0; r < 16; ++r) { const int j = crow16(r, hi); h0[r] = sinf(fq[j] * (h0[r] + b1[j])); h1[r] = sinf(fq[32 + j] * (h1[r] + b1[32 + j])); }
.LBB0_69:
	s_andn2_saveexec_b64 s[2:3], s[8:9]
	v_mul_f32_e64 v2, |v3|, s1
	v_rndne_f32_e32 v2, v2
	v_cvt_i32_f32_e32 v51, v2
	v_fma_f32 v52, v2, s92, |v3|
	v_fmac_f32_e32 v52, 0xb3a22168, v2
	v_fmac_f32_e32 v52, 0xa7c234c4, v2
	s_or_b64 exec, exec, s[2:3]
	global_load_dword v2, v[106:107], off offset:8
	global_load_dword v69, v[104:105], off offset:8
	s_waitcnt vmcnt(1)
	v_add_f32_e32 v2, v20, v2
	s_waitcnt vmcnt(0)
	v_mul_f32_e32 v41, v69, v2
	v_and_b32_e32 v42, 0x7fffffff, v41
	v_cmp_nlt_f32_e64 s[2:3], |v41|, s60
	s_and_saveexec_b64 s[4:5], s[2:3]
	s_xor_b64 s[8:9], exec, s[4:5]
	s_cbranch_execnz .Lsl_73
.LBB0_73:
	s_andn2_saveexec_b64 s[2:3], s[8:9]
	v_mul_f32_e64 v2, |v41|, s1
	v_rndne_f32_e32 v2, v2
	v_cvt_i32_f32_e32 v43, v2
	v_fma_f32 v44, v2, s92, |v41|
	v_fmac_f32_e32 v44, 0xb3a22168, v2
	v_fmac_f32_e32 v44, 0xa7c234c4, v2
	s_or_b64 exec, exec, s[2:3]
	global_load_dword v2, v[106:107], off offset:136
	global_load_dword v70, v[104:105], off offset:136
	s_waitcnt vmcnt(1)
	v_add_f32_e32 v2, v4, v2
	s_waitcnt vmcnt(0)
	v_mul_f32_e32 v4, v70, v2
	v_and_b32_e32 v20, 0x7fffffff, v4
	v_cmp_nlt_f32_e64 s[2:3], |v4|, s60
	s_and_saveexec_b64 s[4:5], s[2:3]
	s_xor_b64 s[8:9], exec, s[4:5]
	s_cbranch_execnz .Lsl_77
.LBB0_77:
	s_andn2_saveexec_b64 s[2:3], s[8:9]
	v_mul_f32_e64 v2, |v4|, s1
	v_rndne_f32_e32 v2, v2
	v_cvt_i32_f32_e32 v53, v2
	v_fma_f32 v54, v2, s92, |v4|
	v_fmac_f32_e32 v54, 0xb3a22168, v2
	v_fmac_f32_e32 v54, 0xa7c234c4, v2
	s_or_b64 exec, exec, s[2:3]
	global_load_dword v2, v[106:107], off offset:12
	global_load_dword v71, v[104:105], off offset:12
	s_waitcnt vmcnt(1)
	v_add_f32_e32 v2, v21, v2
	s_waitcnt vmcnt(0)
	v_mul_f32_e32 v45, v71, v2
	v_and_b32_e32 v46, 0x7fffffff, v45
	v_cmp_nlt_f32_e64 s[2:3], |v45|, s60
	s_and_saveexec_b64 s[4:5], s[2:3]
	s_xor_b64 s[8:9], exec, s[4:5]
	s_cbranch_execnz .Lsl_81
.LBB0_81:
	s_andn2_saveexec_b64 s[2:3], s[8:9]
	v_mul_f32_e64 v2, |v45|, s1
	v_rndne_f32_e32 v2, v2
	v_cvt_i32_f32_e32 v47, v2
	v_fma_f32 v57, v2, s92, |v45|
	v_fmac_f32_e32 v57, 0xb3a22168, v2
	v_fmac_f32_e32 v57, 0xa7c234c4, v2
	s_or_b64 exec, exec, s[2:3]
	global_load_dword v2, v[106:107], off offset:140
	global_load_dword v72, v[104:105], off offset:140
	s_waitcnt vmcnt(1)
	v_add_f32_e32 v2, v5, v2
	s_waitcnt vmcnt(0)
	v_mul_f32_e32 v5, v72, v2
	v_and_b32_e32 v21, 0x7fffffff, v5
	v_cmp_nlt_f32_e64 s[2:3], |v5|, s60
	s_and_saveexec_b64 s[4:5], s[2:3]
	s_xor_b64 s[8:9], exec, s[4:5]
	s_cbranch_execnz .Lsl_85
.LBB0_85:
	s_andn2_saveexec_b64 s[2:3], s[8:9]
	v_mul_f32_e64 v2, |v5|, s1
	v_rndne_f32_e32 v2, v2
	v_cvt_i32_f32_e32 v55, v2
	v_fma_f32 v56, v2, s92, |v5|
	v_fmac_f32_e32 v56, 0xb3a22168, v2
	v_fmac_f32_e32 v56, 0xa7c234c4, v2
	s_or_b64 exec, exec, s[2:3]
	global_load_dword v2, v[106:107], off offset:32
	global_load_dword v73, v[104:105], off offset:32
	s_waitcnt vmcnt(1)
	v_add_f32_e32 v2, v22, v2
	s_waitcnt vmcnt(0)
	v_mul_f32_e32 v60, v73, v2
	v_and_b32_e32 v61, 0x7fffffff, v60
	v_cmp_nlt_f32_e64 s[2:3], |v60|, s60
	s_and_saveexec_b64 s[4:5], s[2:3]
	s_xor_b64 s[8:9], exec, s[4:5]
	s_cbranch_execnz .Lsl_89
.LBB0_89:
	s_andn2_saveexec_b64 s[2:3], s[8:9]
	v_mul_f32_e64 v2, |v60|, s1
	v_rndne_f32_e32 v2, v2
	v_cvt_i32_f32_e32 v62, v2
	v_fma_f32 v63, v2, s92, |v60|
	v_fmac_f32_e32 v63, 0xb3a22168, v2
	v_fmac_f32_e32 v63, 0xa7c234c4, v2
	s_or_b64 exec, exec, s[2:3]
	global_load_dword v2, v[106:107], off offset:160
	global_load_dword v74, v[104:105], off offset:160
	s_waitcnt vmcnt(1)
	v_add_f32_e32 v2, v6, v2
	s_waitcnt vmcnt(0)
	v_mul_f32_e32 v6, v74, v2
	v_and_b32_e32 v22, 0x7fffffff, v6
	v_cmp_nlt_f32_e64 s[2:3], |v6|, s60
	s_and_saveexec_b64 s[4:5], s[2:3]
	s_xor_b64 s[8:9], exec, s[4:5]
	s_cbranch_execnz .Lsl_93
.LBB0_93:
	s_andn2_saveexec_b64 s[2:3], s[8:9]
	v_mul_f32_e64 v2, |v6|, s1
	v_rndne_f32_e32 v2, v2
	v_cvt_i32_f32_e32 v58, v2
	v_fma_f32 v59, v2, s92, |v6|
	v_fmac_f32_e32 v59, 0xb3a22168, v2
	v_fmac_f32_e32 v59, 0xa7c234c4, v2
	s_or_b64 exec, exec, s[2:3]
	global_load_dword v2, v[106:107], off offset:36
	global_load_dword v75, v[104:105], off offset:36
	s_waitcnt vmcnt(1)
	v_add_f32_e32 v2, v23, v2
	s_waitcnt vmcnt(0)
	v_mul_f32_e32 v154, v75, v2
	v_and_b32_e32 v155, 0x7fffffff, v154
	v_cmp_nlt_f32_e64 s[2:3], |v154|, s60
	s_and_saveexec_b64 s[4:5], s[2:3]
	s_xor_b64 s[8:9], exec, s[4:5]
	s_cbranch_execnz .Lsl_97
.LBB0_97:
	s_andn2_saveexec_b64 s[2:3], s[8:9]
	v_mul_f32_e64 v2, |v154|, s1
	v_rndne_f32_e32 v2, v2
	v_cvt_i32_f32_e32 v156, v2
	v_fma_f32 v157, v2, s92, |v154|
	v_fmac_f32_e32 v157, 0xb3a22168, v2
	v_fmac_f32_e32 v157, 0xa7c234c4, v2
	s_or_b64 exec, exec, s[2:3]
	global_load_dword v2, v[106:107], off offset:164
	global_load_dword v76, v[104:105], off offset:164
	s_waitcnt vmcnt(1)
	v_add_f32_e32 v2, v7, v2
	s_waitcnt vmcnt(0)
	v_mul_f32_e32 v7, v76, v2
	v_and_b32_e32 v23, 0x7fffffff, v7
	v_cmp_nlt_f32_e64 s[2:3], |v7|, s60
	s_and_saveexec_b64 s[4:5], s[2:3]
	s_xor_b64 s[8:9], exec, s[4:5]
	s_cbranch_execnz .Lsl_101
.LBB0_101:
	s_andn2_saveexec_b64 s[2:3], s[8:9]
	v_mul_f32_e64 v2, |v7|, s1
	v_rndne_f32_e32 v2, v2
	v_cvt_i32_f32_e32 v152, v2
	v_fma_f32 v153, v2, s92, |v7|
	v_fmac_f32_e32 v153, 0xb3a22168, v2
	v_fmac_f32_e32 v153, 0xa7c234c4, v2
	s_or_b64 exec, exec, s[2:3]
	global_load_dword v2, v[106:107], off offset:40
	global_load_dword v77, v[104:105], off offset:40
	s_waitcnt vmcnt(1)
	v_add_f32_e32 v2, v24, v2
	s_waitcnt vmcnt(0)
	v_mul_f32_e32 v161, v77, v2
	v_and_b32_e32 v163, 0x7fffffff, v161
	v_cmp_nlt_f32_e64 s[2:3], |v161|, s60
	s_and_saveexec_b64 s[4:5], s[2:3]
	s_xor_b64 s[8:9], exec, s[4:5]
	s_cbranch_execnz .Lsl_105
; __device__ __forceinline__ int crow16(int r, int hi) { return (r & 3) + 8 * (r >> 2) + 4 * hi; }
; __device__ __forceinline__ void filter_item32(const Args& a, int L, bf16* KR, int t0, int np0, int npn, int lane) {
;     ...
;         for (int r = 0; r < 16; ++r) { const int j = crow16(r, hi); h0[r] = sinf(fq[j] * (h0[r] + b1[j])); h1[r] = sinf(fq[32 + j] * (h1[r] + b1[32 + j])); }
.LBB0_105:
	s_andn2_saveexec_b64 s[2:3], s[8:9]
	v_mul_f32_e64 v2, |v161|, s1
	v_rndne_f32_e32 v2, v2
	v_cvt_i32_f32_e32 v164, v2
	v_fma_f32 v165, v2, s92, |v161|
	v_fmac_f32_e32 v165, 0xb3a22168, v2
	v_fmac_f32_e32 v165, 0xa7c234c4, v2
	s_or_b64 exec, exec, s[2:3]
	global_load_dword v2, v[106:107], off offset:168
	global_load_dword v78, v[104:105], off offset:168
	s_waitcnt vmcnt(1)
	v_add_f32_e32 v2, v8, v2
	s_waitcnt vmcnt(0)
	v_mul_f32_e32 v8, v78, v2
	v_and_b32_e32 v24, 0x7fffffff, v8
	v_cmp_nlt_f32_e64 s[2:3], |v8|, s60
	s_and_saveexec_b64 s[4:5], s[2:3]
	s_xor_b64 s[8:9], exec, s[4:5]
	s_cbranch_execnz .Lsl_109
.LBB0_109:
	s_andn2_saveexec_b64 s[2:3], s[8:9]
	v_mul_f32_e64 v2, |v8|, s1
	v_rndne_f32_e32 v2, v2
	v_cvt_i32_f32_e32 v158, v2
	v_fma_f32 v159, v2, s92, |v8|
	v_fmac_f32_e32 v159, 0xb3a22168, v2
	v_fmac_f32_e32 v159, 0xa7c234c4, v2
	s_or_b64 exec, exec, s[2:3]
	global_load_dword v2, v[106:107], off offset:44
	global_load_dword v79, v[104:105], off offset:44
	s_waitcnt vmcnt(1)
	v_add_f32_e32 v2, v25, v2
	s_waitcnt vmcnt(0)
	v_mul_f32_e32 v168, v79, v2
	v_and_b32_e32 v169, 0x7fffffff, v168
	v_cmp_nlt_f32_e64 s[2:3], |v168|, s60
	s_and_saveexec_b64 s[4:5], s[2:3]
	s_xor_b64 s[8:9], exec, s[4:5]
	s_cbranch_execnz .Lsl_113
.LBB0_113:
	s_andn2_saveexec_b64 s[2:3], s[8:9]
	v_mul_f32_e64 v2, |v168|, s1
	v_rndne_f32_e32 v2, v2
	v_cvt_i32_f32_e32 v170, v2
	v_fma_f32 v171, v2, s92, |v168|
	v_fmac_f32_e32 v171, 0xb3a22168, v2
	v_fmac_f32_e32 v171, 0xa7c234c4, v2
	s_or_b64 exec, exec, s[2:3]
	global_load_dword v2, v[106:107], off offset:172
	global_load_dword v112, v[104:105], off offset:172
	s_waitcnt vmcnt(1)
	v_add_f32_e32 v2, v9, v2
	s_waitcnt vmcnt(0)
	v_mul_f32_e32 v9, v112, v2
	v_and_b32_e32 v25, 0x7fffffff, v9
	v_cmp_nlt_f32_e64 s[2:3], |v9|, s60
	s_and_saveexec_b64 s[4:5], s[2:3]
	s_xor_b64 s[8:9], exec, s[4:5]
	s_cbranch_execnz .Lsl_117
.LBB0_117:
	s_andn2_saveexec_b64 s[2:3], s[8:9]
	v_mul_f32_e64 v2, |v9|, s1
	v_rndne_f32_e32 v2, v2
	v_cvt_i32_f32_e32 v166, v2
	v_fma_f32 v167, v2, s92, |v9|
	v_fmac_f32_e32 v167, 0xb3a22168, v2
	v_fmac_f32_e32 v167, 0xa7c234c4, v2
	s_or_b64 exec, exec, s[2:3]
	global_load_dword v2, v[106:107], off offset:64
	global_load_dword v113, v[104:105], off offset:64
	s_waitcnt vmcnt(1)
	v_add_f32_e32 v2, v26, v2
	s_waitcnt vmcnt(0)
	v_mul_f32_e32 v174, v113, v2
	v_and_b32_e32 v175, 0x7fffffff, v174
	v_cmp_nlt_f32_e64 s[2:3], |v174|, s60
	s_and_saveexec_b64 s[4:5], s[2:3]
	s_xor_b64 s[8:9], exec, s[4:5]
	s_cbranch_execnz .Lsl_121
.LBB0_121:
	s_andn2_saveexec_b64 s[2:3], s[8:9]
	v_mul_f32_e64 v2, |v174|, s1
	v_rndne_f32_e32 v2, v2
	v_cvt_i32_f32_e32 v176, v2
	v_fma_f32 v177, v2, s92, |v174|
	v_fmac_f32_e32 v177, 0xb3a22168, v2
	v_fmac_f32_e32 v177, 0xa7c234c4, v2
	s_or_b64 exec, exec, s[2:3]
	global_load_dword v2, v[106:107], off offset:192
	global_load_dword v114, v[104:105], off offset:192
	s_waitcnt vmcnt(1)
	v_add_f32_e32 v2, v10, v2
	s_waitcnt vmcnt(0)
	v_mul_f32_e32 v10, v114, v2
	v_and_b32_e32 v26, 0x7fffffff, v10
	v_cmp_nlt_f32_e64 s[2:3], |v10|, s60
	s_and_saveexec_b64 s[4:5], s[2:3]
	s_xor_b64 s[8:9], exec, s[4:5]
	s_cbranch_execnz .Lsl_125
.LBB0_125:
	s_andn2_saveexec_b64 s[2:3], s[8:9]
	v_mul_f32_e64 v2, |v10|, s1
	v_rndne_f32_e32 v2, v2
	v_cvt_i32_f32_e32 v172, v2
	v_fma_f32 v173, v2, s92, |v10|
	v_fmac_f32_e32 v173, 0xb3a22168, v2
	v_fmac_f32_e32 v173, 0xa7c234c4, v2
	s_or_b64 exec, exec, s[2:3]
	global_load_dword v2, v[106:107], off offset:68
	global_load_dword v115, v[104:105], off offset:68
	s_waitcnt vmcnt(1)
	v_add_f32_e32 v2, v27, v2
	s_waitcnt vmcnt(0)
	v_mul_f32_e32 v180, v115, v2
	v_and_b32_e32 v181, 0x7fffffff, v180
	v_cmp_nlt_f32_e64 s[2:3], |v180|, s60
	s_and_saveexec_b64 s[4:5], s[2:3]
	s_xor_b64 s[8:9], exec, s[4:5]
	s_cbranch_execnz .Lsl_129
.LBB0_129:
	s_andn2_saveexec_b64 s[2:3], s[8:9]
	v_mul_f32_e64 v2, |v180|, s1
	v_rndne_f32_e32 v2, v2
	v_cvt_i32_f32_e32 v182, v2
	v_fma_f32 v183, v2, s92, |v180|
	v_fmac_f32_e32 v183, 0xb3a22168, v2
	v_fmac_f32_e32 v183, 0xa7c234c4, v2
	s_or_b64 exec, exec, s[2:3]
	global_load_dword v2, v[106:107], off offset:196
	global_load_dword v116, v[104:105], off offset:196
	s_waitcnt vmcnt(1)
	v_add_f32_e32 v2, v11, v2
	s_waitcnt vmcnt(0)
	v_mul_f32_e32 v11, v116, v2
	v_and_b32_e32 v27, 0x7fffffff, v11
	v_cmp_nlt_f32_e64 s[2:3], |v11|, s60
	s_and_saveexec_b64 s[4:5], s[2:3]
	s_xor_b64 s[8:9], exec, s[4:5]
	s_cbranch_execnz .Lsl_133
.LBB0_133:
	s_andn2_saveexec_b64 s[2:3], s[8:9]
	v_mul_f32_e64 v2, |v11|, s1
	v_rndne_f32_e32 v2, v2
	v_cvt_i32_f32_e32 v178, v2
	v_fma_f32 v179, v2, s92, |v11|
	v_fmac_f32_e32 v179, 0xb3a22168, v2
	v_fmac_f32_e32 v179, 0xa7c234c4, v2
	s_or_b64 exec, exec, s[2:3]
	global_load_dword v2, v[106:107], off offset:72
	global_load_dword v117, v[104:105], off offset:72
	s_waitcnt vmcnt(1)
	v_add_f32_e32 v2, v28, v2
	s_waitcnt vmcnt(0)
	v_mul_f32_e32 v186, v117, v2
	v_and_b32_e32 v187, 0x7fffffff, v186
	v_cmp_nlt_f32_e64 s[2:3], |v186|, s60
	s_and_saveexec_b64 s[4:5], s[2:3]
	s_xor_b64 s[8:9], exec, s[4:5]
	s_cbranch_execnz .Lsl_137
.LBB0_137:
	s_andn2_saveexec_b64 s[2:3], s[8:9]
	v_mul_f32_e64 v2, |v186|, s1
	v_rndne_f32_e32 v2, v2
	v_cvt_i32_f32_e32 v188, v2
	v_fma_f32 v189, v2, s92, |v186|
	v_fmac_f32_e32 v189, 0xb3a22168, v2
	v_fmac_f32_e32 v189, 0xa7c234c4, v2
	s_or_b64 exec, exec, s[2:3]
	global_load_dword v2, v[106:107], off offset:200
	global_load_dword v118, v[104:105], off offset:200
	s_waitcnt vmcnt(1)
	v_add_f32_e32 v2, v12, v2
	s_waitcnt vmcnt(0)
	v_mul_f32_e32 v12, v118, v2
	v_and_b32_e32 v28, 0x7fffffff, v12
	v_cmp_nlt_f32_e64 s[2:3], |v12|, s60
	s_and_saveexec_b64 s[4:5], s[2:3]
	s_xor_b64 s[8:9], exec, s[4:5]
	s_cbranch_execnz .Lsl_141
; __device__ __forceinline__ int crow16(int r, int hi) { return (r & 3) + 8 * (r >> 2) + 4 * hi; }
; __device__ __forceinline__ void filter_item32(const Args& a, int L, bf16* KR, int t0, int np0, int npn, int lane) {
;     ...
;         for (int r = 0; r < 16; ++r) { const int j = crow16(r, hi); h0[r] = sinf(fq[j] * (h0[r] + b1[j])); h1[r] = sinf(fq[32 + j] * (h1[r] + b1[32 + j])); }
.LBB0_141:
	s_andn2_saveexec_b64 s[2:3], s[8:9]
	v_mul_f32_e64 v2, |v12|, s1
	v_rndne_f32_e32 v2, v2
	v_cvt_i32_f32_e32 v184, v2
	v_fma_f32 v185, v2, s92, |v12|
	v_fmac_f32_e32 v185, 0xb3a22168, v2
	v_fmac_f32_e32 v185, 0xa7c234c4, v2
	s_or_b64 exec, exec, s[2:3]
	global_load_dword v2, v[106:107], off offset:76
	global_load_dword v119, v[104:105], off offset:76
	s_waitcnt vmcnt(1)
	v_add_f32_e32 v2, v29, v2
	s_waitcnt vmcnt(0)
	v_mul_f32_e32 v192, v119, v2
	v_and_b32_e32 v193, 0x7fffffff, v192
	v_cmp_nlt_f32_e64 s[2:3], |v192|, s60
	s_and_saveexec_b64 s[4:5], s[2:3]
	s_xor_b64 s[8:9], exec, s[4:5]
	s_cbranch_execnz .Lsl_145
.LBB0_145:
	s_andn2_saveexec_b64 s[2:3], s[8:9]
	v_mul_f32_e64 v2, |v192|, s1
	v_rndne_f32_e32 v2, v2
	v_cvt_i32_f32_e32 v194, v2
	v_fma_f32 v195, v2, s92, |v192|
	v_fmac_f32_e32 v195, 0xb3a22168, v2
	v_fmac_f32_e32 v195, 0xa7c234c4, v2
	s_or_b64 exec, exec, s[2:3]
	global_load_dword v2, v[106:107], off offset:204
	global_load_dword v120, v[104:105], off offset:204
	s_waitcnt vmcnt(1)
	v_add_f32_e32 v2, v13, v2
	s_waitcnt vmcnt(0)
	v_mul_f32_e32 v13, v120, v2
	v_and_b32_e32 v29, 0x7fffffff, v13
	v_cmp_nlt_f32_e64 s[2:3], |v13|, s60
	s_and_saveexec_b64 s[4:5], s[2:3]
	s_xor_b64 s[8:9], exec, s[4:5]
	s_cbranch_execnz .Lsl_149
.LBB0_149:
	s_andn2_saveexec_b64 s[2:3], s[8:9]
	v_mul_f32_e64 v2, |v13|, s1
	v_rndne_f32_e32 v2, v2
	v_cvt_i32_f32_e32 v190, v2
	v_fma_f32 v191, v2, s92, |v13|
	v_fmac_f32_e32 v191, 0xb3a22168, v2
	v_fmac_f32_e32 v191, 0xa7c234c4, v2
	s_or_b64 exec, exec, s[2:3]
	global_load_dword v2, v[106:107], off offset:96
	global_load_dword v121, v[104:105], off offset:96
	s_waitcnt vmcnt(1)
	v_add_f32_e32 v2, v30, v2
	s_waitcnt vmcnt(0)
	v_mul_f32_e32 v198, v121, v2
	v_and_b32_e32 v199, 0x7fffffff, v198
	v_cmp_nlt_f32_e64 s[2:3], |v198|, s60
	s_and_saveexec_b64 s[4:5], s[2:3]
	s_xor_b64 s[8:9], exec, s[4:5]
	s_cbranch_execnz .Lsl_153
.LBB0_153:
	s_andn2_saveexec_b64 s[2:3], s[8:9]
	v_mul_f32_e64 v2, |v198|, s1
	v_rndne_f32_e32 v2, v2
	v_cvt_i32_f32_e32 v200, v2
	v_fma_f32 v201, v2, s92, |v198|
	v_fmac_f32_e32 v201, 0xb3a22168, v2
	v_fmac_f32_e32 v201, 0xa7c234c4, v2
	s_or_b64 exec, exec, s[2:3]
	global_load_dword v2, v[106:107], off offset:224
	global_load_dword v122, v[104:105], off offset:224
	s_waitcnt vmcnt(1)
	v_add_f32_e32 v2, v14, v2
	s_waitcnt vmcnt(0)
	v_mul_f32_e32 v14, v122, v2
	v_and_b32_e32 v30, 0x7fffffff, v14
	v_cmp_nlt_f32_e64 s[2:3], |v14|, s60
	s_and_saveexec_b64 s[4:5], s[2:3]
	s_xor_b64 s[8:9], exec, s[4:5]
	s_cbranch_execnz .Lsl_157
.LBB0_157:
	s_andn2_saveexec_b64 s[2:3], s[8:9]
	v_mul_f32_e64 v2, |v14|, s1
	v_rndne_f32_e32 v2, v2
	v_cvt_i32_f32_e32 v196, v2
	v_fma_f32 v197, v2, s92, |v14|
	v_fmac_f32_e32 v197, 0xb3a22168, v2
	v_fmac_f32_e32 v197, 0xa7c234c4, v2
	s_or_b64 exec, exec, s[2:3]
	global_load_dword v2, v[106:107], off offset:100
	global_load_dword v123, v[104:105], off offset:100
	s_waitcnt vmcnt(1)
	v_add_f32_e32 v2, v31, v2
	s_waitcnt vmcnt(0)
	v_mul_f32_e32 v204, v123, v2
	v_and_b32_e32 v205, 0x7fffffff, v204
	v_cmp_nlt_f32_e64 s[2:3], |v204|, s60
	s_and_saveexec_b64 s[4:5], s[2:3]
	s_xor_b64 s[8:9], exec, s[4:5]
	s_cbranch_execnz .Lsl_161
.LBB0_161:
	s_andn2_saveexec_b64 s[2:3], s[8:9]
	v_mul_f32_e64 v2, |v204|, s1
	v_rndne_f32_e32 v2, v2
	v_cvt_i32_f32_e32 v206, v2
	v_fma_f32 v207, v2, s92, |v204|
	v_fmac_f32_e32 v207, 0xb3a22168, v2
	v_fmac_f32_e32 v207, 0xa7c234c4, v2
	s_or_b64 exec, exec, s[2:3]
	global_load_dword v2, v[106:107], off offset:228
	global_load_dword v124, v[104:105], off offset:228
	s_waitcnt vmcnt(1)
	v_add_f32_e32 v2, v15, v2
	s_waitcnt vmcnt(0)
	v_mul_f32_e32 v15, v124, v2
	v_and_b32_e32 v31, 0x7fffffff, v15
	v_cmp_nlt_f32_e64 s[2:3], |v15|, s60
	s_and_saveexec_b64 s[4:5], s[2:3]
	s_xor_b64 s[8:9], exec, s[4:5]
	s_cbranch_execnz .Lsl_165
.LBB0_165:
	s_andn2_saveexec_b64 s[2:3], s[8:9]
	v_mul_f32_e64 v2, |v15|, s1
	v_rndne_f32_e32 v2, v2
	v_cvt_i32_f32_e32 v202, v2
	v_fma_f32 v203, v2, s92, |v15|
	v_fmac_f32_e32 v203, 0xb3a22168, v2
	v_fmac_f32_e32 v203, 0xa7c234c4, v2
	s_or_b64 exec, exec, s[2:3]
	global_load_dword v2, v[106:107], off offset:104
	global_load_dword v125, v[104:105], off offset:104
	s_waitcnt vmcnt(1)
	v_add_f32_e32 v2, v32, v2
	s_waitcnt vmcnt(0)
	v_mul_f32_e32 v210, v125, v2
	v_and_b32_e32 v211, 0x7fffffff, v210
	v_cmp_nlt_f32_e64 s[2:3], |v210|, s60
	s_and_saveexec_b64 s[4:5], s[2:3]
	s_xor_b64 s[8:9], exec, s[4:5]
	s_cbranch_execnz .Lsl_169
.LBB0_169:
	s_andn2_saveexec_b64 s[2:3], s[8:9]
	v_mul_f32_e64 v2, |v210|, s1
	v_rndne_f32_e32 v2, v2
	v_cvt_i32_f32_e32 v212, v2
	v_fma_f32 v213, v2, s92, |v210|
	v_fmac_f32_e32 v213, 0xb3a22168, v2
	v_fmac_f32_e32 v213, 0xa7c234c4, v2
	s_or_b64 exec, exec, s[2:3]
	global_load_dword v2, v[106:107], off offset:232
	global_load_dword v126, v[104:105], off offset:232
	s_waitcnt vmcnt(1)
	v_add_f32_e32 v2, v16, v2
	s_waitcnt vmcnt(0)
	v_mul_f32_e32 v16, v126, v2
	v_and_b32_e32 v32, 0x7fffffff, v16
	v_cmp_nlt_f32_e64 s[2:3], |v16|, s60
	s_and_saveexec_b64 s[4:5], s[2:3]
	s_xor_b64 s[8:9], exec, s[4:5]
	s_cbranch_execnz .Lsl_173
.LBB0_173:
	s_andn2_saveexec_b64 s[2:3], s[8:9]
	v_mul_f32_e64 v2, |v16|, s1
	v_rndne_f32_e32 v2, v2
	v_cvt_i32_f32_e32 v208, v2
	v_fma_f32 v209, v2, s92, |v16|
	v_fmac_f32_e32 v209, 0xb3a22168, v2
	v_fmac_f32_e32 v209, 0xa7c234c4, v2
	s_or_b64 exec, exec, s[2:3]
	global_load_dword v2, v[106:107], off offset:108
	global_load_dword v127, v[104:105], off offset:108
	s_waitcnt vmcnt(1)
	v_add_f32_e32 v2, v33, v2
	s_waitcnt vmcnt(0)
	v_mul_f32_e32 v215, v127, v2
	v_and_b32_e32 v216, 0x7fffffff, v215
	v_cmp_nlt_f32_e64 s[2:3], |v215|, s60
	s_and_saveexec_b64 s[4:5], s[2:3]
	s_xor_b64 s[8:9], exec, s[4:5]
	s_cbranch_execnz .Lsl_177
.LBB0_177:
	s_andn2_saveexec_b64 s[2:3], s[8:9]
	v_mul_f32_e64 v2, |v215|, s1
	v_rndne_f32_e32 v2, v2
	v_cvt_i32_f32_e32 v217, v2
	v_fma_f32 v218, v2, s92, |v215|
	v_fmac_f32_e32 v218, 0xb3a22168, v2
	v_fmac_f32_e32 v218, 0xa7c234c4, v2
	s_or_b64 exec, exec, s[2:3]
	global_load_dword v2, v[106:107], off offset:236
	global_load_dword v151, v[104:105], off offset:236
	s_waitcnt vmcnt(1)
	v_add_f32_e32 v2, v17, v2
	s_waitcnt vmcnt(0)
	v_mul_f32_e32 v17, v151, v2
	v_and_b32_e32 v33, 0x7fffffff, v17
	v_cmp_nlt_f32_e64 s[2:3], |v17|, s60
	s_and_saveexec_b64 s[4:5], s[2:3]
	s_xor_b64 s[8:9], exec, s[4:5]
	s_cbranch_execnz .Lsl_181

; __device__ __forceinline__ int crow16(int r, int hi) { return (r & 3) + 8 * (r >> 2) + 4 * hi; }
; __device__ __forceinline__ void filter_item32(const Args& a, int L, bf16* KR, int t0, int np0, int npn, int lane) {
;     ...
;     for (int layer = 0; layer < 2; ++layer) {
;         const float* W = layer ? w3 : w2; const float* bb = layer ? b3 : b2;
;         f32x16 g0 = {}, g1 = {}; const int lo2 = 4 * hi * 64 + n;
; #pragma unroll
;         for (int kk = 0; kk < 32; ++kk) {
;             const float* ub = W + (32 * (kk >> 4) + crow16(kk & 15, 0)) * 64;
;             const float zb = kk < 16 ? h0[kk & 15] : h1[kk & 15];
;             const float a0 = ub[lo2], a1 = ub[lo2 + 32];
;             g0 = __builtin_amdgcn_mfma_f32_32x32x2f32(a0, zb, g0, 0, 0, 0); g1 = __builtin_amdgcn_mfma_f32_32x32x2f32(a1, zb, g1, 0, 0, 0);
.LBB0_185:
	s_and_b64 s[2:3], s[8:9], exec
	s_cselect_b32 s3, s77, s81
	s_cselect_b32 s2, s76, s80
	v_lshlrev_b32_e32 v80, 2, v108
	s_cselect_b32 s11, s79, s83
	s_cselect_b32 s10, s78, s82
	v_mov_b32_e32 v252, v80
	v_add_u32_e32 v253, 0x1000, v80
	v_add_u32_e32 v254, 0x2000, v80
	v_add_u32_e32 v255, 0x3000, v80
	global_load_dword v234, v252, s[2:3]
	global_load_dword v235, v252, s[2:3] offset:256
	global_load_dword v236, v252, s[2:3] offset:128
	global_load_dword v237, v252, s[2:3] offset:384
	global_load_dword v238, v252, s[2:3] offset:512
	global_load_dword v239, v252, s[2:3] offset:640
	global_load_dword v240, v252, s[2:3] offset:768
	global_load_dword v241, v252, s[2:3] offset:896
	global_load_dword v244, v252, s[2:3] offset:2048
	global_load_dword v245, v252, s[2:3] offset:2176
	global_load_dword v246, v252, s[2:3] offset:2304
	global_load_dword v247, v252, s[2:3] offset:2432
	global_load_dword v248, v252, s[2:3] offset:2560
	global_load_dword v249, v252, s[2:3] offset:2688
	global_load_dword v250, v252, s[2:3] offset:2816
	global_load_dword v251, v252, s[2:3] offset:2944
	s_waitcnt vmcnt(15)
	v_mfma_f32_32x32x2_f32 v[18:33], v234, v2, 0
	global_load_dword v234, v253, s[2:3]
	s_waitcnt vmcnt(15)
	v_mfma_f32_32x32x2_f32 v[18:33], v235, v1, v[18:33]
	global_load_dword v235, v253, s[2:3] offset:128
	s_waitcnt vmcnt(15)
	v_mfma_f32_32x32x2_f32 v[2:17], v236, v2, 0
	global_load_dword v236, v253, s[2:3] offset:256
	s_waitcnt vmcnt(15)
	v_mfma_f32_32x32x2_f32 v[2:17], v237, v1, v[2:17]
	global_load_dword v237, v253, s[2:3] offset:384
	s_waitcnt vmcnt(15)
	v_mfma_f32_32x32x2_f32 v[18:33], v238, v34, v[18:33]
	global_load_dword v238, v253, s[2:3] offset:512
	s_waitcnt vmcnt(15)
	v_mfma_f32_32x32x2_f32 v[2:17], v239, v34, v[2:17]
	global_load_dword v239, v253, s[2:3] offset:640
	s_waitcnt vmcnt(15)
	v_mfma_f32_32x32x2_f32 v[18:33], v240, v35, v[18:33]
	global_load_dword v240, v253, s[2:3] offset:768
	s_waitcnt vmcnt(15)
	v_mfma_f32_32x32x2_f32 v[2:17], v241, v35, v[2:17]
	global_load_dword v241, v253, s[2:3] offset:896
	s_waitcnt vmcnt(15)
	v_mfma_f32_32x32x2_f32 v[18:33], v244, v36, v[18:33]
	global_load_dword v244, v253, s[2:3] offset:2048
	s_waitcnt vmcnt(15)
	v_mfma_f32_32x32x2_f32 v[2:17], v245, v36, v[2:17]
	global_load_dword v245, v253, s[2:3] offset:2176
	s_waitcnt vmcnt(15)
	v_mfma_f32_32x32x2_f32 v[18:33], v246, v37, v[18:33]
	global_load_dword v246, v253, s[2:3] offset:2304
	s_waitcnt vmcnt(15)
	v_mfma_f32_32x32x2_f32 v[2:17], v247, v37, v[2:17]
	global_load_dword v247, v253, s[2:3] offset:2432
	s_waitcnt vmcnt(15)
	v_mfma_f32_32x32x2_f32 v[18:33], v248, v38, v[18:33]
	global_load_dword v248, v253, s[2:3] offset:2560
	s_waitcnt vmcnt(15)
	v_mfma_f32_32x32x2_f32 v[2:17], v249, v38, v[2:17]
	global_load_dword v249, v253, s[2:3] offset:2688
	s_waitcnt vmcnt(15)
	v_mfma_f32_32x32x2_f32 v[18:33], v250, v39, v[18:33]
	global_load_dword v250, v253, s[2:3] offset:2816
	s_waitcnt vmcnt(15)
	v_mfma_f32_32x32x2_f32 v[2:17], v251, v39, v[2:17]
	global_load_dword v251, v253, s[2:3] offset:2944
	s_waitcnt vmcnt(15)
	v_mfma_f32_32x32x2_f32 v[18:33], v234, v40, v[18:33]
	global_load_dword v234, v254, s[2:3]
	s_waitcnt vmcnt(15)
	v_mfma_f32_32x32x2_f32 v[2:17], v235, v40, v[2:17]
	global_load_dword v235, v254, s[2:3] offset:128
	s_waitcnt vmcnt(15)
	v_mfma_f32_32x32x2_f32 v[18:33], v236, v41, v[18:33]
	global_load_dword v236, v254, s[2:3] offset:256
	s_waitcnt vmcnt(15)
	v_mfma_f32_32x32x2_f32 v[2:17], v237, v41, v[2:17]
	global_load_dword v237, v254, s[2:3] offset:384
	s_waitcnt vmcnt(15)
	v_mfma_f32_32x32x2_f32 v[18:33], v238, v42, v[18:33]
	global_load_dword v238, v254, s[2:3] offset:512
	s_waitcnt vmcnt(15)
	v_mfma_f32_32x32x2_f32 v[2:17], v239, v42, v[2:17]
	global_load_dword v239, v254, s[2:3] offset:640
	s_waitcnt vmcnt(15)
	v_mfma_f32_32x32x2_f32 v[18:33], v240, v43, v[18:33]
	global_load_dword v240, v254, s[2:3] offset:768
	s_waitcnt vmcnt(15)
	v_mfma_f32_32x32x2_f32 v[2:17], v241, v43, v[2:17]
	global_load_dword v241, v254, s[2:3] offset:896
	s_waitcnt vmcnt(15)
	v_mfma_f32_32x32x2_f32 v[18:33], v244, v44, v[18:33]
	global_load_dword v244, v254, s[2:3] offset:2048
	s_waitcnt vmcnt(15)
	v_mfma_f32_32x32x2_f32 v[2:17], v245, v44, v[2:17]
	global_load_dword v245, v254, s[2:3] offset:2176
	s_waitcnt vmcnt(15)
	v_mfma_f32_32x32x2_f32 v[18:33], v246, v45, v[18:33]
	global_load_dword v246, v254, s[2:3] offset:2304
	s_waitcnt vmcnt(15)
	v_mfma_f32_32x32x2_f32 v[2:17], v247, v45, v[2:17]
	global_load_dword v247, v254, s[2:3] offset:2432
	s_waitcnt vmcnt(15)
	v_mfma_f32_32x32x2_f32 v[18:33], v248, v46, v[18:33]
	global_load_dword v248, v254, s[2:3] offset:2560
	s_waitcnt vmcnt(15)
	v_mfma_f32_32x32x2_f32 v[2:17], v249, v46, v[2:17]
	global_load_dword v249, v254, s[2:3] offset:2688
	s_waitcnt vmcnt(15)
	v_mfma_f32_32x32x2_f32 v[18:33], v250, v47, v[18:33]
	global_load_dword v250, v254, s[2:3] offset:2816
	s_waitcnt vmcnt(15)
	v_mfma_f32_32x32x2_f32 v[2:17], v251, v47, v[2:17]
	global_load_dword v251, v254, s[2:3] offset:2944
	s_waitcnt vmcnt(15)
	v_mfma_f32_32x32x2_f32 v[18:33], v234, v48, v[18:33]
	global_load_dword v234, v255, s[2:3]
	s_waitcnt vmcnt(15)
	v_mfma_f32_32x32x2_f32 v[2:17], v235, v48, v[2:17]
	global_load_dword v235, v255, s[2:3] offset:128
	s_waitcnt vmcnt(15)
	v_mfma_f32_32x32x2_f32 v[18:33], v236, v49, v[18:33]
	global_load_dword v236, v255, s[2:3] offset:256
	s_waitcnt vmcnt(15)
	v_mfma_f32_32x32x2_f32 v[2:17], v237, v49, v[2:17]
	global_load_dword v237, v255, s[2:3] offset:384
	s_waitcnt vmcnt(15)
	v_mfma_f32_32x32x2_f32 v[18:33], v238, v50, v[18:33]
	global_load_dword v238, v255, s[2:3] offset:512
	s_waitcnt vmcnt(15)
; __device__ __forceinline__ int crow16(int r, int hi) { return (r & 3) + 8 * (r >> 2) + 4 * hi; }
; __device__ __forceinline__ void filter_item32(const Args& a, int L, bf16* KR, int t0, int np0, int npn, int lane) {
;     ...
;         for (int kk = 0; kk < 32; ++kk) {
;             const float* ub = W + (32 * (kk >> 4) + crow16(kk & 15, 0)) * 64;
;             const float zb = kk < 16 ? h0[kk & 15] : h1[kk & 15];
;             const float a0 = ub[lo2], a1 = ub[lo2 + 32];
;             g0 = __builtin_amdgcn_mfma_f32_32x32x2f32(a0, zb, g0, 0, 0, 0); g1 = __builtin_amdgcn_mfma_f32_32x32x2f32(a1, zb, g1, 0, 0, 0);
;         }
; #pragma unroll
;         for (int r = 0; r < 16; ++r) { const int j = crow16(r, hi); h0[r] = sinf(fq[j] * (g0[r] + bb[j])); h1[r] = sinf(fq[32 + j] * (g1[r] + bb[32 + j])); }
	v_mfma_f32_32x32x2_f32 v[2:17], v239, v50, v[2:17]
	global_load_dword v239, v255, s[2:3] offset:640
	s_waitcnt vmcnt(15)
	v_mfma_f32_32x32x2_f32 v[18:33], v240, v53, v[18:33]
	global_load_dword v240, v255, s[2:3] offset:768
	s_waitcnt vmcnt(15)
	v_mfma_f32_32x32x2_f32 v[2:17], v241, v53, v[2:17]
	global_load_dword v241, v255, s[2:3] offset:896
	s_waitcnt vmcnt(15)
	v_mfma_f32_32x32x2_f32 v[18:33], v244, v54, v[18:33]
	global_load_dword v244, v255, s[2:3] offset:2048
	s_waitcnt vmcnt(15)
	v_mfma_f32_32x32x2_f32 v[2:17], v245, v54, v[2:17]
	global_load_dword v245, v255, s[2:3] offset:2176
	s_waitcnt vmcnt(15)
	v_mfma_f32_32x32x2_f32 v[18:33], v246, v57, v[18:33]
	global_load_dword v246, v255, s[2:3] offset:2304
	s_waitcnt vmcnt(15)
	v_mfma_f32_32x32x2_f32 v[2:17], v247, v57, v[2:17]
	global_load_dword v247, v255, s[2:3] offset:2432
	s_waitcnt vmcnt(15)
	v_mfma_f32_32x32x2_f32 v[18:33], v248, v58, v[18:33]
	global_load_dword v248, v255, s[2:3] offset:2560
	s_waitcnt vmcnt(15)
	v_mfma_f32_32x32x2_f32 v[2:17], v249, v58, v[2:17]
	global_load_dword v249, v255, s[2:3] offset:2688
	s_waitcnt vmcnt(15)
	v_mfma_f32_32x32x2_f32 v[18:33], v250, v61, v[18:33]
	global_load_dword v250, v255, s[2:3] offset:2816
	s_waitcnt vmcnt(15)
	v_mfma_f32_32x32x2_f32 v[2:17], v251, v61, v[2:17]
	global_load_dword v251, v255, s[2:3] offset:2944
	s_waitcnt vmcnt(15)
	v_mfma_f32_32x32x2_f32 v[18:33], v234, v52, v[18:33]
	s_waitcnt vmcnt(14)
	v_mfma_f32_32x32x2_f32 v[2:17], v235, v52, v[2:17]
	s_waitcnt vmcnt(13)
	v_mfma_f32_32x32x2_f32 v[18:33], v236, v55, v[18:33]
	s_waitcnt vmcnt(12)
	v_mfma_f32_32x32x2_f32 v[2:17], v237, v55, v[2:17]
	s_waitcnt vmcnt(11)
	v_mfma_f32_32x32x2_f32 v[18:33], v238, v56, v[18:33]
	s_waitcnt vmcnt(10)
	v_mfma_f32_32x32x2_f32 v[2:17], v239, v56, v[2:17]
	s_waitcnt vmcnt(9)
	v_mfma_f32_32x32x2_f32 v[18:33], v240, v59, v[18:33]
	s_waitcnt vmcnt(8)
	v_mfma_f32_32x32x2_f32 v[2:17], v241, v59, v[2:17]
	s_waitcnt vmcnt(7)
	v_mfma_f32_32x32x2_f32 v[18:33], v244, v60, v[18:33]
	s_waitcnt vmcnt(6)
	v_mfma_f32_32x32x2_f32 v[2:17], v245, v60, v[2:17]
	s_waitcnt vmcnt(5)
	v_mfma_f32_32x32x2_f32 v[18:33], v246, v63, v[18:33]
	s_waitcnt vmcnt(4)
	v_mfma_f32_32x32x2_f32 v[2:17], v247, v63, v[2:17]
	s_waitcnt vmcnt(3)
	v_mfma_f32_32x32x2_f32 v[18:33], v248, v62, v[18:33]
	s_waitcnt vmcnt(2)
	v_mfma_f32_32x32x2_f32 v[2:17], v249, v62, v[2:17]
	s_waitcnt vmcnt(1)
	v_mfma_f32_32x32x2_f32 v[18:33], v250, v51, v[18:33]
	v_lshl_add_u64 v[34:35], s[2:3], 0, v[80:81]
	v_add_co_u32_e32 v36, vcc, s56, v34
	v_addc_co_u32_e32 v37, vcc, 0, v35, vcc
	v_add_co_u32_e32 v38, vcc, s97, v34
	v_lshlrev_b32_e32 v80, 2, v102
	v_addc_co_u32_e32 v39, vcc, 0, v35, vcc
	v_add_co_u32_e32 v34, vcc, s57, v34
	v_addc_co_u32_e32 v35, vcc, 0, v35, vcc
	global_load_dword v1, v80, s[10:11]
	s_waitcnt vmcnt(0)
	s_nop 15
	v_add_f32_e32 v1, v18, v1
	v_mfma_f32_32x32x2_f32 v[2:17], v251, v51, v[2:17]
	v_mul_f32_e32 v1, v65, v1
	v_and_b32_e32 v36, 0x7fffffff, v1
	v_cmp_nlt_f32_e64 s[2:3], |v1|, s60
	s_and_saveexec_b64 s[4:5], s[2:3]
	s_xor_b64 s[12:13], exec, s[4:5]
	s_cbranch_execnz .Lsl_187
.LBB0_187:
	s_andn2_saveexec_b64 s[2:3], s[12:13]
	v_mul_f32_e64 v18, |v1|, s1
	v_rndne_f32_e32 v18, v18
	v_cvt_i32_f32_e32 v37, v18
	v_fma_f32 v38, v18, s92, |v1|
	v_fmac_f32_e32 v38, 0xb3a22168, v18
	v_fmac_f32_e32 v38, 0xa7c234c4, v18
	s_or_b64 exec, exec, s[2:3]
	v_lshl_add_u64 v[34:35], s[10:11], 0, v[80:81]
	global_load_dword v18, v[34:35], off offset:128
	s_waitcnt vmcnt(0)
	s_nop 0
	v_add_f32_e32 v2, v2, v18
	v_mul_f32_e32 v18, v66, v2
	v_and_b32_e32 v48, 0x7fffffff, v18
	v_cmp_nlt_f32_e64 s[2:3], |v18|, s60
	s_and_saveexec_b64 s[4:5], s[2:3]
	s_xor_b64 s[10:11], exec, s[4:5]
	s_cbranch_execnz .Lsl_191
.LBB0_191:
	s_andn2_saveexec_b64 s[2:3], s[10:11]
	v_mul_f32_e64 v2, |v18|, s1
	v_rndne_f32_e32 v2, v2
	v_cvt_i32_f32_e32 v49, v2
	v_fma_f32 v50, v2, s92, |v18|
	v_fmac_f32_e32 v50, 0xb3a22168, v2
	v_fmac_f32_e32 v50, 0xa7c234c4, v2
	s_or_b64 exec, exec, s[2:3]
	global_load_dword v2, v[34:35], off offset:4
	s_waitcnt vmcnt(0)
	v_add_f32_e32 v2, v19, v2
	v_mul_f32_e32 v39, v67, v2
	v_and_b32_e32 v40, 0x7fffffff, v39
	v_cmp_nlt_f32_e64 s[2:3], |v39|, s60
	s_and_saveexec_b64 s[4:5], s[2:3]
	s_xor_b64 s[10:11], exec, s[4:5]
	s_cbranch_execnz .Lsl_195
.LBB0_195:
	s_andn2_saveexec_b64 s[2:3], s[10:11]
	v_mul_f32_e64 v2, |v39|, s1
	v_rndne_f32_e32 v2, v2
	v_cvt_i32_f32_e32 v41, v2
	v_fma_f32 v42, v2, s92, |v39|
	v_fmac_f32_e32 v42, 0xb3a22168, v2
	v_fmac_f32_e32 v42, 0xa7c234c4, v2
	s_or_b64 exec, exec, s[2:3]
	global_load_dword v2, v[34:35], off offset:132
	s_waitcnt vmcnt(0)
	v_add_f32_e32 v2, v3, v2
	v_mul_f32_e32 v3, v68, v2
	v_and_b32_e32 v19, 0x7fffffff, v3
	v_cmp_nlt_f32_e64 s[2:3], |v3|, s60
	s_and_saveexec_b64 s[4:5], s[2:3]
	s_xor_b64 s[10:11], exec, s[4:5]
	s_cbranch_execnz .Lsl_199
.LBB0_199:
	s_andn2_saveexec_b64 s[2:3], s[10:11]
	v_mul_f32_e64 v2, |v3|, s1
	v_rndne_f32_e32 v2, v2
	v_cvt_i32_f32_e32 v51, v2
	v_fma_f32 v52, v2, s92, |v3|
	v_fmac_f32_e32 v52, 0xb3a22168, v2
	v_fmac_f32_e32 v52, 0xa7c234c4, v2
	s_or_b64 exec, exec, s[2:3]
	global_load_dword v2, v[34:35], off offset:8
	s_waitcnt vmcnt(0)
	v_add_f32_e32 v2, v20, v2
	v_mul_f32_e32 v43, v69, v2
	v_and_b32_e32 v44, 0x7fffffff, v43
	v_cmp_nlt_f32_e64 s[2:3], |v43|, s60
	s_and_saveexec_b64 s[4:5], s[2:3]
	s_xor_b64 s[10:11], exec, s[4:5]
	s_cbranch_execnz .Lsl_203
; __device__ __forceinline__ int crow16(int r, int hi) { return (r & 3) + 8 * (r >> 2) + 4 * hi; }
; __device__ __forceinline__ void filter_item32(const Args& a, int L, bf16* KR, int t0, int np0, int npn, int lane) {
;     ...
;         for (int r = 0; r < 16; ++r) { const int j = crow16(r, hi); h0[r] = sinf(fq[j] * (g0[r] + bb[j])); h1[r] = sinf(fq[32 + j] * (g1[r] + bb[32 + j])); }
.LBB0_203:
	s_andn2_saveexec_b64 s[2:3], s[10:11]
	v_mul_f32_e64 v2, |v43|, s1
	v_rndne_f32_e32 v2, v2
	v_cvt_i32_f32_e32 v45, v2
	v_fma_f32 v46, v2, s92, |v43|
	v_fmac_f32_e32 v46, 0xb3a22168, v2
	v_fmac_f32_e32 v46, 0xa7c234c4, v2
	s_or_b64 exec, exec, s[2:3]
	global_load_dword v2, v[34:35], off offset:136
	s_waitcnt vmcnt(0)
	v_add_f32_e32 v2, v4, v2
	v_mul_f32_e32 v4, v70, v2
	v_and_b32_e32 v20, 0x7fffffff, v4
	v_cmp_nlt_f32_e64 s[2:3], |v4|, s60
	s_and_saveexec_b64 s[4:5], s[2:3]
	s_xor_b64 s[10:11], exec, s[4:5]
	s_cbranch_execnz .Lsl_207
.LBB0_207:
	s_andn2_saveexec_b64 s[2:3], s[10:11]
	v_mul_f32_e64 v2, |v4|, s1
	v_rndne_f32_e32 v2, v2
	v_cvt_i32_f32_e32 v53, v2
	v_fma_f32 v54, v2, s92, |v4|
	v_fmac_f32_e32 v54, 0xb3a22168, v2
	v_fmac_f32_e32 v54, 0xa7c234c4, v2
	s_or_b64 exec, exec, s[2:3]
	global_load_dword v2, v[34:35], off offset:12
	s_waitcnt vmcnt(0)
	v_add_f32_e32 v2, v21, v2
	v_mul_f32_e32 v47, v71, v2
	v_and_b32_e32 v57, 0x7fffffff, v47
	v_cmp_nlt_f32_e64 s[2:3], |v47|, s60
	s_and_saveexec_b64 s[4:5], s[2:3]
	s_xor_b64 s[10:11], exec, s[4:5]
	s_cbranch_execnz .Lsl_211
.LBB0_211:
	s_andn2_saveexec_b64 s[2:3], s[10:11]
	v_mul_f32_e64 v2, |v47|, s1
	v_rndne_f32_e32 v2, v2
	v_cvt_i32_f32_e32 v58, v2
	v_fma_f32 v59, v2, s92, |v47|
	v_fmac_f32_e32 v59, 0xb3a22168, v2
	v_fmac_f32_e32 v59, 0xa7c234c4, v2
	s_or_b64 exec, exec, s[2:3]
	global_load_dword v2, v[34:35], off offset:140
	s_waitcnt vmcnt(0)
	v_add_f32_e32 v2, v5, v2
	v_mul_f32_e32 v5, v72, v2
	v_and_b32_e32 v21, 0x7fffffff, v5
	v_cmp_nlt_f32_e64 s[2:3], |v5|, s60
	s_and_saveexec_b64 s[4:5], s[2:3]
	s_xor_b64 s[10:11], exec, s[4:5]
	s_cbranch_execnz .Lsl_215
.LBB0_215:
	s_andn2_saveexec_b64 s[2:3], s[10:11]
	v_mul_f32_e64 v2, |v5|, s1
	v_rndne_f32_e32 v2, v2
	v_cvt_i32_f32_e32 v55, v2
	v_fma_f32 v56, v2, s92, |v5|
	v_fmac_f32_e32 v56, 0xb3a22168, v2
	v_fmac_f32_e32 v56, 0xa7c234c4, v2
	s_or_b64 exec, exec, s[2:3]
	global_load_dword v2, v[34:35], off offset:32
	s_waitcnt vmcnt(0)
	v_add_f32_e32 v2, v22, v2
	v_mul_f32_e32 v62, v73, v2
	v_and_b32_e32 v63, 0x7fffffff, v62
	v_cmp_nlt_f32_e64 s[2:3], |v62|, s60
	s_and_saveexec_b64 s[4:5], s[2:3]
	s_xor_b64 s[10:11], exec, s[4:5]
	s_cbranch_execnz .Lsl_219
.LBB0_219:
	s_andn2_saveexec_b64 s[2:3], s[10:11]
	v_mul_f32_e64 v2, |v62|, s1
	v_rndne_f32_e32 v2, v2
	v_cvt_i32_f32_e32 v152, v2
	v_fma_f32 v153, v2, s92, |v62|
	v_fmac_f32_e32 v153, 0xb3a22168, v2
	v_fmac_f32_e32 v153, 0xa7c234c4, v2
	s_or_b64 exec, exec, s[2:3]
	global_load_dword v2, v[34:35], off offset:160
	s_waitcnt vmcnt(0)
	v_add_f32_e32 v2, v6, v2
	v_mul_f32_e32 v6, v74, v2
	v_and_b32_e32 v22, 0x7fffffff, v6
	v_cmp_nlt_f32_e64 s[2:3], |v6|, s60
	s_and_saveexec_b64 s[4:5], s[2:3]
	s_xor_b64 s[10:11], exec, s[4:5]
	s_cbranch_execnz .Lsl_223
.LBB0_223:
	s_andn2_saveexec_b64 s[2:3], s[10:11]
	v_mul_f32_e64 v2, |v6|, s1
	v_rndne_f32_e32 v2, v2
	v_cvt_i32_f32_e32 v60, v2
	v_fma_f32 v61, v2, s92, |v6|
	v_fmac_f32_e32 v61, 0xb3a22168, v2
	v_fmac_f32_e32 v61, 0xa7c234c4, v2
	s_or_b64 exec, exec, s[2:3]
	global_load_dword v2, v[34:35], off offset:36
	s_waitcnt vmcnt(0)
	v_add_f32_e32 v2, v23, v2
	v_mul_f32_e32 v156, v75, v2
	v_and_b32_e32 v157, 0x7fffffff, v156
	v_cmp_nlt_f32_e64 s[2:3], |v156|, s60
	s_and_saveexec_b64 s[4:5], s[2:3]
	s_xor_b64 s[10:11], exec, s[4:5]
	s_cbranch_execnz .Lsl_227
.LBB0_227:
	s_andn2_saveexec_b64 s[2:3], s[10:11]
	v_mul_f32_e64 v2, |v156|, s1
	v_rndne_f32_e32 v2, v2
	v_cvt_i32_f32_e32 v158, v2
	v_fma_f32 v159, v2, s92, |v156|
	v_fmac_f32_e32 v159, 0xb3a22168, v2
	v_fmac_f32_e32 v159, 0xa7c234c4, v2
	s_or_b64 exec, exec, s[2:3]
	global_load_dword v2, v[34:35], off offset:164
	s_waitcnt vmcnt(0)
	v_add_f32_e32 v2, v7, v2
	v_mul_f32_e32 v7, v76, v2
	v_and_b32_e32 v23, 0x7fffffff, v7
	v_cmp_nlt_f32_e64 s[2:3], |v7|, s60
	s_and_saveexec_b64 s[4:5], s[2:3]
	s_xor_b64 s[10:11], exec, s[4:5]
	s_cbranch_execnz .Lsl_231
.LBB0_231:
	s_andn2_saveexec_b64 s[2:3], s[10:11]
	v_mul_f32_e64 v2, |v7|, s1
	v_rndne_f32_e32 v2, v2
	v_cvt_i32_f32_e32 v154, v2
	v_fma_f32 v155, v2, s92, |v7|
	v_fmac_f32_e32 v155, 0xb3a22168, v2
	v_fmac_f32_e32 v155, 0xa7c234c4, v2
	s_or_b64 exec, exec, s[2:3]
	global_load_dword v2, v[34:35], off offset:40
	s_waitcnt vmcnt(0)
	v_add_f32_e32 v2, v24, v2
	v_mul_f32_e32 v164, v77, v2
	v_and_b32_e32 v165, 0x7fffffff, v164
	v_cmp_nlt_f32_e64 s[2:3], |v164|, s60
	s_and_saveexec_b64 s[4:5], s[2:3]
	s_xor_b64 s[10:11], exec, s[4:5]
	s_cbranch_execnz .Lsl_235
.LBB0_235:
	s_andn2_saveexec_b64 s[2:3], s[10:11]
	v_mul_f32_e64 v2, |v164|, s1
	v_rndne_f32_e32 v2, v2
	v_cvt_i32_f32_e32 v166, v2
	v_fma_f32 v167, v2, s92, |v164|
	v_fmac_f32_e32 v167, 0xb3a22168, v2
	v_fmac_f32_e32 v167, 0xa7c234c4, v2
	s_or_b64 exec, exec, s[2:3]
	global_load_dword v2, v[34:35], off offset:168
	s_waitcnt vmcnt(0)
	v_add_f32_e32 v2, v8, v2
	v_mul_f32_e32 v8, v78, v2
	v_and_b32_e32 v24, 0x7fffffff, v8
	v_cmp_nlt_f32_e64 s[2:3], |v8|, s60
	s_and_saveexec_b64 s[4:5], s[2:3]
	s_xor_b64 s[10:11], exec, s[4:5]
	s_cbranch_execnz .Lsl_239
.LBB0_239:
	s_andn2_saveexec_b64 s[2:3], s[10:11]
	v_mul_f32_e64 v2, |v8|, s1
	v_rndne_f32_e32 v2, v2
	v_cvt_i32_f32_e32 v161, v2
	v_fma_f32 v163, v2, s92, |v8|
	v_fmac_f32_e32 v163, 0xb3a22168, v2
	v_fmac_f32_e32 v163, 0xa7c234c4, v2
	s_or_b64 exec, exec, s[2:3]
	global_load_dword v2, v[34:35], off offset:44
	s_waitcnt vmcnt(0)
	v_add_f32_e32 v2, v25, v2
	v_mul_f32_e32 v170, v79, v2
	v_and_b32_e32 v171, 0x7fffffff, v170
	v_cmp_nlt_f32_e64 s[2:3], |v170|, s60
	s_and_saveexec_b64 s[4:5], s[2:3]
	s_xor_b64 s[10:11], exec, s[4:5]
	s_cbranch_execnz .Lsl_243
; __device__ __forceinline__ int crow16(int r, int hi) { return (r & 3) + 8 * (r >> 2) + 4 * hi; }
; __device__ __forceinline__ void filter_item32(const Args& a, int L, bf16* KR, int t0, int np0, int npn, int lane) {
;     ...
;         for (int r = 0; r < 16; ++r) { const int j = crow16(r, hi); h0[r] = sinf(fq[j] * (g0[r] + bb[j])); h1[r] = sinf(fq[32 + j] * (g1[r] + bb[32 + j])); }
.LBB0_243:
	s_andn2_saveexec_b64 s[2:3], s[10:11]
	v_mul_f32_e64 v2, |v170|, s1
	v_rndne_f32_e32 v2, v2
	v_cvt_i32_f32_e32 v172, v2
	v_fma_f32 v173, v2, s92, |v170|
	v_fmac_f32_e32 v173, 0xb3a22168, v2
	v_fmac_f32_e32 v173, 0xa7c234c4, v2
	s_or_b64 exec, exec, s[2:3]
	global_load_dword v2, v[34:35], off offset:172
	s_waitcnt vmcnt(0)
	v_add_f32_e32 v2, v9, v2
	v_mul_f32_e32 v9, v112, v2
	v_and_b32_e32 v25, 0x7fffffff, v9
	v_cmp_nlt_f32_e64 s[2:3], |v9|, s60
	s_and_saveexec_b64 s[4:5], s[2:3]
	s_xor_b64 s[10:11], exec, s[4:5]
	s_cbranch_execnz .Lsl_247
.LBB0_247:
	s_andn2_saveexec_b64 s[2:3], s[10:11]
	v_mul_f32_e64 v2, |v9|, s1
	v_rndne_f32_e32 v2, v2
	v_cvt_i32_f32_e32 v168, v2
	v_fma_f32 v169, v2, s92, |v9|
	v_fmac_f32_e32 v169, 0xb3a22168, v2
	v_fmac_f32_e32 v169, 0xa7c234c4, v2
	s_or_b64 exec, exec, s[2:3]
	global_load_dword v2, v[34:35], off offset:64
	s_waitcnt vmcnt(0)
	v_add_f32_e32 v2, v26, v2
	v_mul_f32_e32 v176, v113, v2
	v_and_b32_e32 v177, 0x7fffffff, v176
	v_cmp_nlt_f32_e64 s[2:3], |v176|, s60
	s_and_saveexec_b64 s[4:5], s[2:3]
	s_xor_b64 s[10:11], exec, s[4:5]
	s_cbranch_execnz .Lsl_251
.LBB0_251:
	s_andn2_saveexec_b64 s[2:3], s[10:11]
	v_mul_f32_e64 v2, |v176|, s1
	v_rndne_f32_e32 v2, v2
	v_cvt_i32_f32_e32 v178, v2
	v_fma_f32 v179, v2, s92, |v176|
	v_fmac_f32_e32 v179, 0xb3a22168, v2
	v_fmac_f32_e32 v179, 0xa7c234c4, v2
	s_or_b64 exec, exec, s[2:3]
	global_load_dword v2, v[34:35], off offset:192
	s_waitcnt vmcnt(0)
	v_add_f32_e32 v2, v10, v2
	v_mul_f32_e32 v10, v114, v2
	v_and_b32_e32 v26, 0x7fffffff, v10
	v_cmp_nlt_f32_e64 s[2:3], |v10|, s60
	s_and_saveexec_b64 s[4:5], s[2:3]
	s_xor_b64 s[10:11], exec, s[4:5]
	s_cbranch_execnz .Lsl_255
.LBB0_255:
	s_andn2_saveexec_b64 s[2:3], s[10:11]
	v_mul_f32_e64 v2, |v10|, s1
	v_rndne_f32_e32 v2, v2
	v_cvt_i32_f32_e32 v174, v2
	v_fma_f32 v175, v2, s92, |v10|
	v_fmac_f32_e32 v175, 0xb3a22168, v2
	v_fmac_f32_e32 v175, 0xa7c234c4, v2
	s_or_b64 exec, exec, s[2:3]
	global_load_dword v2, v[34:35], off offset:68
	s_waitcnt vmcnt(0)
	v_add_f32_e32 v2, v27, v2
	v_mul_f32_e32 v182, v115, v2
	v_and_b32_e32 v183, 0x7fffffff, v182
	v_cmp_nlt_f32_e64 s[2:3], |v182|, s60
	s_and_saveexec_b64 s[4:5], s[2:3]
	s_xor_b64 s[10:11], exec, s[4:5]
	s_cbranch_execnz .Lsl_259
.LBB0_259:
	s_andn2_saveexec_b64 s[2:3], s[10:11]
	v_mul_f32_e64 v2, |v182|, s1
	v_rndne_f32_e32 v2, v2
	v_cvt_i32_f32_e32 v184, v2
	v_fma_f32 v185, v2, s92, |v182|
	v_fmac_f32_e32 v185, 0xb3a22168, v2
	v_fmac_f32_e32 v185, 0xa7c234c4, v2
	s_or_b64 exec, exec, s[2:3]
	global_load_dword v2, v[34:35], off offset:196
	s_waitcnt vmcnt(0)
	v_add_f32_e32 v2, v11, v2
	v_mul_f32_e32 v11, v116, v2
	v_and_b32_e32 v27, 0x7fffffff, v11
	v_cmp_nlt_f32_e64 s[2:3], |v11|, s60
	s_and_saveexec_b64 s[4:5], s[2:3]
	s_xor_b64 s[10:11], exec, s[4:5]
	s_cbranch_execnz .Lsl_263
.LBB0_263:
	s_andn2_saveexec_b64 s[2:3], s[10:11]
	v_mul_f32_e64 v2, |v11|, s1
	v_rndne_f32_e32 v2, v2
	v_cvt_i32_f32_e32 v180, v2
	v_fma_f32 v181, v2, s92, |v11|
	v_fmac_f32_e32 v181, 0xb3a22168, v2
	v_fmac_f32_e32 v181, 0xa7c234c4, v2
	s_or_b64 exec, exec, s[2:3]
	global_load_dword v2, v[34:35], off offset:72
	s_waitcnt vmcnt(0)
	v_add_f32_e32 v2, v28, v2
	v_mul_f32_e32 v188, v117, v2
	v_and_b32_e32 v189, 0x7fffffff, v188
	v_cmp_nlt_f32_e64 s[2:3], |v188|, s60
	s_and_saveexec_b64 s[4:5], s[2:3]
	s_xor_b64 s[10:11], exec, s[4:5]
	s_cbranch_execnz .Lsl_267
.LBB0_267:
	s_andn2_saveexec_b64 s[2:3], s[10:11]
	v_mul_f32_e64 v2, |v188|, s1
	v_rndne_f32_e32 v2, v2
	v_cvt_i32_f32_e32 v190, v2
	v_fma_f32 v191, v2, s92, |v188|
	v_fmac_f32_e32 v191, 0xb3a22168, v2
	v_fmac_f32_e32 v191, 0xa7c234c4, v2
	s_or_b64 exec, exec, s[2:3]
	global_load_dword v2, v[34:35], off offset:200
	s_waitcnt vmcnt(0)
	v_add_f32_e32 v2, v12, v2
	v_mul_f32_e32 v12, v118, v2
	v_and_b32_e32 v28, 0x7fffffff, v12
	v_cmp_nlt_f32_e64 s[2:3], |v12|, s60
	s_and_saveexec_b64 s[4:5], s[2:3]
	s_xor_b64 s[10:11], exec, s[4:5]
	s_cbranch_execnz .Lsl_271
.LBB0_271:
	s_andn2_saveexec_b64 s[2:3], s[10:11]
	v_mul_f32_e64 v2, |v12|, s1
	v_rndne_f32_e32 v2, v2
	v_cvt_i32_f32_e32 v186, v2
	v_fma_f32 v187, v2, s92, |v12|
	v_fmac_f32_e32 v187, 0xb3a22168, v2
	v_fmac_f32_e32 v187, 0xa7c234c4, v2
	s_or_b64 exec, exec, s[2:3]
	global_load_dword v2, v[34:35], off offset:76
	s_waitcnt vmcnt(0)
	v_add_f32_e32 v2, v29, v2
	v_mul_f32_e32 v194, v119, v2
	v_and_b32_e32 v195, 0x7fffffff, v194
	v_cmp_nlt_f32_e64 s[2:3], |v194|, s60
	s_and_saveexec_b64 s[4:5], s[2:3]
	s_xor_b64 s[10:11], exec, s[4:5]
	s_cbranch_execnz .Lsl_275
.LBB0_275:
	s_andn2_saveexec_b64 s[2:3], s[10:11]
	v_mul_f32_e64 v2, |v194|, s1
	v_rndne_f32_e32 v2, v2
	v_cvt_i32_f32_e32 v196, v2
	v_fma_f32 v197, v2, s92, |v194|
	v_fmac_f32_e32 v197, 0xb3a22168, v2
	v_fmac_f32_e32 v197, 0xa7c234c4, v2
	s_or_b64 exec, exec, s[2:3]
	global_load_dword v2, v[34:35], off offset:204
	s_waitcnt vmcnt(0)
	v_add_f32_e32 v2, v13, v2
	v_mul_f32_e32 v13, v120, v2
	v_and_b32_e32 v29, 0x7fffffff, v13
	v_cmp_nlt_f32_e64 s[2:3], |v13|, s60
	s_and_saveexec_b64 s[4:5], s[2:3]
	s_xor_b64 s[10:11], exec, s[4:5]
	s_cbranch_execnz .Lsl_279
; __device__ __forceinline__ int crow16(int r, int hi) { return (r & 3) + 8 * (r >> 2) + 4 * hi; }
; __device__ __forceinline__ void filter_item32(const Args& a, int L, bf16* KR, int t0, int np0, int npn, int lane) {
;     ...
;         for (int r = 0; r < 16; ++r) { const int j = crow16(r, hi); h0[r] = sinf(fq[j] * (g0[r] + bb[j])); h1[r] = sinf(fq[32 + j] * (g1[r] + bb[32 + j])); }
.LBB0_279:
	s_andn2_saveexec_b64 s[2:3], s[10:11]
	v_mul_f32_e64 v2, |v13|, s1
	v_rndne_f32_e32 v2, v2
	v_cvt_i32_f32_e32 v192, v2
	v_fma_f32 v193, v2, s92, |v13|
	v_fmac_f32_e32 v193, 0xb3a22168, v2
	v_fmac_f32_e32 v193, 0xa7c234c4, v2
	s_or_b64 exec, exec, s[2:3]
	global_load_dword v2, v[34:35], off offset:96
	s_waitcnt vmcnt(0)
	v_add_f32_e32 v2, v30, v2
	v_mul_f32_e32 v200, v121, v2
	v_and_b32_e32 v201, 0x7fffffff, v200
	v_cmp_nlt_f32_e64 s[2:3], |v200|, s60
	s_and_saveexec_b64 s[4:5], s[2:3]
	s_xor_b64 s[10:11], exec, s[4:5]
	s_cbranch_execnz .Lsl_283
.LBB0_283:
	s_andn2_saveexec_b64 s[2:3], s[10:11]
	v_mul_f32_e64 v2, |v200|, s1
	v_rndne_f32_e32 v2, v2
	v_cvt_i32_f32_e32 v202, v2
	v_fma_f32 v203, v2, s92, |v200|
	v_fmac_f32_e32 v203, 0xb3a22168, v2
	v_fmac_f32_e32 v203, 0xa7c234c4, v2
	s_or_b64 exec, exec, s[2:3]
	global_load_dword v2, v[34:35], off offset:224
	s_waitcnt vmcnt(0)
	v_add_f32_e32 v2, v14, v2
	v_mul_f32_e32 v14, v122, v2
	v_and_b32_e32 v30, 0x7fffffff, v14
	v_cmp_nlt_f32_e64 s[2:3], |v14|, s60
	s_and_saveexec_b64 s[4:5], s[2:3]
	s_xor_b64 s[10:11], exec, s[4:5]
	s_cbranch_execnz .Lsl_287
.LBB0_287:
	s_andn2_saveexec_b64 s[2:3], s[10:11]
	v_mul_f32_e64 v2, |v14|, s1
	v_rndne_f32_e32 v2, v2
	v_cvt_i32_f32_e32 v198, v2
	v_fma_f32 v199, v2, s92, |v14|
	v_fmac_f32_e32 v199, 0xb3a22168, v2
	v_fmac_f32_e32 v199, 0xa7c234c4, v2
	s_or_b64 exec, exec, s[2:3]
	global_load_dword v2, v[34:35], off offset:100
	s_waitcnt vmcnt(0)
	v_add_f32_e32 v2, v31, v2
	v_mul_f32_e32 v206, v123, v2
	v_and_b32_e32 v207, 0x7fffffff, v206
	v_cmp_nlt_f32_e64 s[2:3], |v206|, s60
	s_and_saveexec_b64 s[4:5], s[2:3]
	s_xor_b64 s[10:11], exec, s[4:5]
	s_cbranch_execnz .Lsl_291
.LBB0_291:
	s_andn2_saveexec_b64 s[2:3], s[10:11]
	v_mul_f32_e64 v2, |v206|, s1
	v_rndne_f32_e32 v2, v2
	v_cvt_i32_f32_e32 v208, v2
	v_fma_f32 v209, v2, s92, |v206|
	v_fmac_f32_e32 v209, 0xb3a22168, v2
	v_fmac_f32_e32 v209, 0xa7c234c4, v2
	s_or_b64 exec, exec, s[2:3]
	global_load_dword v2, v[34:35], off offset:228
	s_waitcnt vmcnt(0)
	v_add_f32_e32 v2, v15, v2
	v_mul_f32_e32 v15, v124, v2
	v_and_b32_e32 v31, 0x7fffffff, v15
	v_cmp_nlt_f32_e64 s[2:3], |v15|, s60
	s_and_saveexec_b64 s[4:5], s[2:3]
	s_xor_b64 s[10:11], exec, s[4:5]
	s_cbranch_execnz .Lsl_295
.LBB0_295:
	s_andn2_saveexec_b64 s[2:3], s[10:11]
	v_mul_f32_e64 v2, |v15|, s1
	v_rndne_f32_e32 v2, v2
	v_cvt_i32_f32_e32 v204, v2
	v_fma_f32 v205, v2, s92, |v15|
	v_fmac_f32_e32 v205, 0xb3a22168, v2
	v_fmac_f32_e32 v205, 0xa7c234c4, v2
	s_or_b64 exec, exec, s[2:3]
	global_load_dword v2, v[34:35], off offset:104
	s_waitcnt vmcnt(0)
	v_add_f32_e32 v2, v32, v2
	v_mul_f32_e32 v212, v125, v2
	v_and_b32_e32 v213, 0x7fffffff, v212
	v_cmp_nlt_f32_e64 s[2:3], |v212|, s60
	s_and_saveexec_b64 s[4:5], s[2:3]
	s_xor_b64 s[10:11], exec, s[4:5]
	s_cbranch_execnz .Lsl_299
.LBB0_299:
	s_andn2_saveexec_b64 s[2:3], s[10:11]
	v_mul_f32_e64 v2, |v212|, s1
	v_rndne_f32_e32 v2, v2
	v_cvt_i32_f32_e32 v214, v2
	v_fma_f32 v215, v2, s92, |v212|
	v_fmac_f32_e32 v215, 0xb3a22168, v2
	v_fmac_f32_e32 v215, 0xa7c234c4, v2
	s_or_b64 exec, exec, s[2:3]
	global_load_dword v2, v[34:35], off offset:232
	s_waitcnt vmcnt(0)
	v_add_f32_e32 v2, v16, v2
	v_mul_f32_e32 v16, v126, v2
	v_and_b32_e32 v32, 0x7fffffff, v16
	v_cmp_nlt_f32_e64 s[2:3], |v16|, s60
	s_and_saveexec_b64 s[4:5], s[2:3]
	s_xor_b64 s[10:11], exec, s[4:5]
	s_cbranch_execnz .Lsl_303
.LBB0_303:
	s_andn2_saveexec_b64 s[2:3], s[10:11]
	v_mul_f32_e64 v2, |v16|, s1
	v_rndne_f32_e32 v2, v2
	v_cvt_i32_f32_e32 v210, v2
	v_fma_f32 v211, v2, s92, |v16|
	v_fmac_f32_e32 v211, 0xb3a22168, v2
	v_fmac_f32_e32 v211, 0xa7c234c4, v2
	s_or_b64 exec, exec, s[2:3]
	global_load_dword v2, v[34:35], off offset:108
	s_waitcnt vmcnt(0)
	v_add_f32_e32 v2, v33, v2
	v_mul_f32_e32 v217, v127, v2
	v_and_b32_e32 v218, 0x7fffffff, v217
	v_cmp_nlt_f32_e64 s[2:3], |v217|, s60
	s_and_saveexec_b64 s[4:5], s[2:3]
	s_xor_b64 s[10:11], exec, s[4:5]
	s_cbranch_execnz .Lsl_307
.LBB0_307:
	s_andn2_saveexec_b64 s[2:3], s[10:11]
	v_mul_f32_e64 v2, |v217|, s1
	v_rndne_f32_e32 v2, v2
	v_cvt_i32_f32_e32 v219, v2
	v_fma_f32 v220, v2, s92, |v217|
	v_fmac_f32_e32 v220, 0xb3a22168, v2
	v_fmac_f32_e32 v220, 0xa7c234c4, v2
	s_or_b64 exec, exec, s[2:3]
	global_load_dword v2, v[34:35], off offset:236
	s_waitcnt vmcnt(0)
	v_add_f32_e32 v2, v17, v2
	v_mul_f32_e32 v17, v151, v2
	v_and_b32_e32 v33, 0x7fffffff, v17
	v_cmp_nlt_f32_e64 s[2:3], |v17|, s60
	s_and_saveexec_b64 s[4:5], s[2:3]
	s_xor_b64 s[10:11], exec, s[4:5]
	s_cbranch_execnz .Lsl_311

; __device__ __forceinline__ int crow16(int r, int hi) { return (r & 3) + 8 * (r >> 2) + 4 * hi; }
; __device__ __forceinline__ void filter_item32(const Args& a, int L, bf16* KR, int t0, int np0, int npn, int lane) {
;     ...
;         for (int r = 0; r < 16; ++r) { const int j = crow16(r, hi); h0[r] = sinf(fq[j] * (h0[r] + b1[j])); h1[r] = sinf(fq[32 + j] * (h1[r] + b1[32 + j])); }
.Lsl_25:
	v_lshrrev_b32_e32 v5, 23, v4
	v_add_u32_e32 v5, 0xffffff88, v5
	v_cmp_lt_u32_e32 vcc, 63, v5
	s_nop 1
	v_cndmask_b32_e32 v6, 0, v145, vcc
	v_add_u32_e32 v5, v6, v5
	v_cmp_lt_u32_e64 s[2:3], 31, v5
	s_nop 1
	v_cndmask_b32_e64 v6, 0, v146, s[2:3]
	v_add_u32_e32 v5, v6, v5
	v_cmp_lt_u32_e64 s[4:5], 31, v5
	s_nop 1
	v_cndmask_b32_e64 v6, 0, v146, s[4:5]
	v_add_u32_e32 v5, v6, v5
	v_and_b32_e32 v6, 0x7fffff, v4
	v_or_b32_e32 v18, 0x800000, v6
	v_mad_u64_u32 v[6:7], s[6:7], v18, s61, 0
	v_mov_b32_e32 v80, v7
	v_mad_u64_u32 v[8:9], s[6:7], v18, s62, v[80:81]
	v_mov_b32_e32 v80, v9
	v_mad_u64_u32 v[10:11], s[6:7], v18, s63, v[80:81]
	v_mov_b32_e32 v80, v11
	v_mad_u64_u32 v[12:13], s[6:7], v18, s72, v[80:81]
	v_mov_b32_e32 v80, v13
	v_mad_u64_u32 v[14:15], s[6:7], v18, s73, v[80:81]
	v_mov_b32_e32 v80, v15
	v_mad_u64_u32 v[16:17], s[6:7], v18, s74, v[80:81]
	v_mov_b32_e32 v80, v17
	v_mad_u64_u32 v[18:19], s[6:7], v18, s75, v[80:81]
	v_cndmask_b32_e32 v7, v16, v12, vcc
	v_cndmask_b32_e32 v9, v18, v14, vcc
	v_cndmask_b32_e32 v13, v19, v16, vcc
	v_cndmask_b32_e64 v11, v9, v7, s[2:3]
	v_cndmask_b32_e64 v9, v13, v9, s[2:3]
	v_cndmask_b32_e32 v13, v14, v10, vcc
	v_cndmask_b32_e64 v7, v7, v13, s[2:3]
	v_sub_u32_e32 v14, 32, v5
	v_cmp_eq_u32_e64 s[6:7], 0, v5
	v_cndmask_b32_e32 v5, v12, v8, vcc
	v_cndmask_b32_e64 v9, v9, v11, s[4:5]
	v_cndmask_b32_e64 v11, v11, v7, s[4:5]
	v_cndmask_b32_e64 v8, v13, v5, s[2:3]
	v_alignbit_b32 v15, v9, v11, v14
	v_cndmask_b32_e64 v7, v7, v8, s[4:5]
	v_cndmask_b32_e64 v9, v15, v9, s[6:7]
	v_alignbit_b32 v12, v11, v7, v14
	v_cndmask_b32_e32 v6, v10, v6, vcc
	v_cndmask_b32_e64 v11, v12, v11, s[6:7]
	v_bfe_u32 v15, v9, 29, 1
	v_cndmask_b32_e64 v5, v5, v6, s[2:3]
	v_alignbit_b32 v12, v9, v11, 30
	v_sub_u32_e32 v16, 0, v15
	v_cndmask_b32_e64 v5, v8, v5, s[4:5]
	v_xor_b32_e32 v12, v12, v16
	v_alignbit_b32 v6, v7, v5, v14
	v_cndmask_b32_e64 v6, v6, v7, s[6:7]
	v_ffbh_u32_e32 v8, v12
	v_alignbit_b32 v7, v11, v6, 30
	v_min_u32_e32 v8, 32, v8
	v_alignbit_b32 v5, v6, v5, 30
	v_xor_b32_e32 v7, v7, v16
	v_sub_u32_e32 v10, 31, v8
	v_xor_b32_e32 v5, v5, v16
	v_alignbit_b32 v11, v12, v7, v10
	v_alignbit_b32 v5, v7, v5, v10
	v_alignbit_b32 v6, v11, v5, 9
	v_ffbh_u32_e32 v7, v6
	v_min_u32_e32 v7, 32, v7
	v_lshrrev_b32_e32 v13, 29, v9
	v_not_b32_e32 v10, v7
	v_alignbit_b32 v5, v6, v5, v10
	v_lshlrev_b32_e32 v6, 31, v13
	v_or_b32_e32 v10, 0x33000000, v6
	v_add_lshl_u32 v7, v7, v8, 23
	v_lshrrev_b32_e32 v5, 9, v5
	v_sub_u32_e32 v7, v10, v7
	v_or_b32_e32 v6, 0.5, v6
	v_lshlrev_b32_e32 v8, 23, v8
	v_or_b32_e32 v5, v7, v5
	v_lshrrev_b32_e32 v7, 9, v11
	v_sub_u32_e32 v6, v6, v8
	v_or_b32_e32 v6, v7, v6
	v_mul_f32_e32 v7, 0x3fc90fda, v6
	v_fma_f32 v8, v6, s0, -v7
	v_fmac_f32_e32 v8, 0x33a22168, v6
	v_fmac_f32_e32 v8, 0x3fc90fda, v5
	v_lshrrev_b32_e32 v6, 30, v9
	v_add_f32_e32 v5, v7, v8
	v_add_u32_e32 v6, v15, v6
	s_branch .LBB0_25
.Lsl_29:
	v_lshrrev_b32_e32 v9, 23, v8
	v_add_u32_e32 v9, 0xffffff88, v9
	v_cmp_lt_u32_e32 vcc, 63, v9
	s_nop 1
	v_cndmask_b32_e32 v10, 0, v145, vcc
	v_add_u32_e32 v9, v10, v9
	v_cmp_lt_u32_e64 s[2:3], 31, v9
	s_nop 1
	v_cndmask_b32_e64 v10, 0, v146, s[2:3]
	v_add_u32_e32 v9, v10, v9
	v_cmp_lt_u32_e64 s[4:5], 31, v9
	s_nop 1
	v_cndmask_b32_e64 v10, 0, v146, s[4:5]
	v_add_u32_e32 v9, v10, v9
	v_and_b32_e32 v10, 0x7fffff, v8
	v_or_b32_e32 v22, 0x800000, v10
	v_mad_u64_u32 v[10:11], s[6:7], v22, s61, 0
	v_mov_b32_e32 v80, v11
	v_mad_u64_u32 v[12:13], s[6:7], v22, s62, v[80:81]
	v_mov_b32_e32 v80, v13
	v_mad_u64_u32 v[14:15], s[6:7], v22, s63, v[80:81]
	v_mov_b32_e32 v80, v15
	v_mad_u64_u32 v[16:17], s[6:7], v22, s72, v[80:81]
	v_mov_b32_e32 v80, v17
	v_mad_u64_u32 v[18:19], s[6:7], v22, s73, v[80:81]
	v_mov_b32_e32 v80, v19
	v_mad_u64_u32 v[20:21], s[6:7], v22, s74, v[80:81]
	v_mov_b32_e32 v80, v21
	v_mad_u64_u32 v[22:23], s[6:7], v22, s75, v[80:81]
	v_cndmask_b32_e32 v11, v20, v16, vcc
	v_cndmask_b32_e32 v13, v22, v18, vcc
	v_cndmask_b32_e32 v17, v23, v20, vcc
	v_cndmask_b32_e64 v15, v13, v11, s[2:3]
	v_cndmask_b32_e64 v13, v17, v13, s[2:3]
	v_cndmask_b32_e32 v17, v18, v14, vcc
	v_cndmask_b32_e64 v11, v11, v17, s[2:3]
	v_sub_u32_e32 v18, 32, v9
	v_cmp_eq_u32_e64 s[6:7], 0, v9
	v_cndmask_b32_e32 v9, v16, v12, vcc
	v_cndmask_b32_e64 v13, v13, v15, s[4:5]
	v_cndmask_b32_e64 v15, v15, v11, s[4:5]
	v_cndmask_b32_e64 v12, v17, v9, s[2:3]
	v_alignbit_b32 v19, v13, v15, v18
	v_cndmask_b32_e64 v11, v11, v12, s[4:5]
	v_cndmask_b32_e64 v13, v19, v13, s[6:7]
	v_alignbit_b32 v16, v15, v11, v18
	v_cndmask_b32_e32 v10, v14, v10, vcc
	v_cndmask_b32_e64 v15, v16, v15, s[6:7]
	v_bfe_u32 v19, v13, 29, 1
	v_cndmask_b32_e64 v9, v9, v10, s[2:3]
	v_alignbit_b32 v16, v13, v15, 30
	v_sub_u32_e32 v20, 0, v19
	v_cndmask_b32_e64 v9, v12, v9, s[4:5]
	v_xor_b32_e32 v16, v16, v20
	v_alignbit_b32 v10, v11, v9, v18
	v_cndmask_b32_e64 v10, v10, v11, s[6:7]
	v_ffbh_u32_e32 v12, v16
	v_alignbit_b32 v11, v15, v10, 30
	v_min_u32_e32 v12, 32, v12
	v_alignbit_b32 v9, v10, v9, 30
	v_xor_b32_e32 v11, v11, v20
	v_sub_u32_e32 v14, 31, v12
	v_xor_b32_e32 v9, v9, v20
	v_alignbit_b32 v15, v16, v11, v14
	v_alignbit_b32 v9, v11, v9, v14
	v_alignbit_b32 v10, v15, v9, 9
	v_ffbh_u32_e32 v11, v10
	v_min_u32_e32 v11, 32, v11
	v_lshrrev_b32_e32 v17, 29, v13
	v_not_b32_e32 v14, v11
	v_alignbit_b32 v9, v10, v9, v14
	v_lshlrev_b32_e32 v10, 31, v17
	v_or_b32_e32 v14, 0x33000000, v10
	v_add_lshl_u32 v11, v11, v12, 23
	v_lshrrev_b32_e32 v9, 9, v9
	v_sub_u32_e32 v11, v14, v11
	v_or_b32_e32 v10, 0.5, v10
	v_lshlrev_b32_e32 v12, 23, v12
	v_or_b32_e32 v9, v11, v9
	v_lshrrev_b32_e32 v11, 9, v15
	v_sub_u32_e32 v10, v10, v12
	v_or_b32_e32 v10, v11, v10
	v_mul_f32_e32 v11, 0x3fc90fda, v10
	v_fma_f32 v12, v10, s0, -v11
	v_fmac_f32_e32 v12, 0x33a22168, v10
	v_fmac_f32_e32 v12, 0x3fc90fda, v9
	v_lshrrev_b32_e32 v10, 30, v13
	v_add_f32_e32 v9, v11, v12
	v_add_u32_e32 v10, v19, v10
	s_branch .LBB0_29
; __device__ __forceinline__ int crow16(int r, int hi) { return (r & 3) + 8 * (r >> 2) + 4 * hi; }
; __device__ __forceinline__ void filter_item32(const Args& a, int L, bf16* KR, int t0, int np0, int npn, int lane) {
;     ...
;         for (int r = 0; r < 16; ++r) { const int j = crow16(r, hi); h0[r] = sinf(fq[j] * (h0[r] + b1[j])); h1[r] = sinf(fq[32 + j] * (h1[r] + b1[32 + j])); }
.Lsl_33:
	v_lshrrev_b32_e32 v13, 23, v12
	v_add_u32_e32 v13, 0xffffff88, v13
	v_cmp_lt_u32_e32 vcc, 63, v13
	s_nop 1
	v_cndmask_b32_e32 v14, 0, v145, vcc
	v_add_u32_e32 v13, v14, v13
	v_cmp_lt_u32_e64 s[2:3], 31, v13
	s_nop 1
	v_cndmask_b32_e64 v14, 0, v146, s[2:3]
	v_add_u32_e32 v13, v14, v13
	v_cmp_lt_u32_e64 s[4:5], 31, v13
	s_nop 1
	v_cndmask_b32_e64 v14, 0, v146, s[4:5]
	v_add_u32_e32 v13, v14, v13
	v_and_b32_e32 v14, 0x7fffff, v12
	v_or_b32_e32 v26, 0x800000, v14
	v_mad_u64_u32 v[14:15], s[6:7], v26, s61, 0
	v_mov_b32_e32 v80, v15
	v_mad_u64_u32 v[16:17], s[6:7], v26, s62, v[80:81]
	v_mov_b32_e32 v80, v17
	v_mad_u64_u32 v[18:19], s[6:7], v26, s63, v[80:81]
	v_mov_b32_e32 v80, v19
	v_mad_u64_u32 v[20:21], s[6:7], v26, s72, v[80:81]
	v_mov_b32_e32 v80, v21
	v_mad_u64_u32 v[22:23], s[6:7], v26, s73, v[80:81]
	v_mov_b32_e32 v80, v23
	v_mad_u64_u32 v[24:25], s[6:7], v26, s74, v[80:81]
	v_mov_b32_e32 v80, v25
	v_mad_u64_u32 v[26:27], s[6:7], v26, s75, v[80:81]
	v_cndmask_b32_e32 v15, v24, v20, vcc
	v_cndmask_b32_e32 v17, v26, v22, vcc
	v_cndmask_b32_e32 v21, v27, v24, vcc
	v_cndmask_b32_e64 v19, v17, v15, s[2:3]
	v_cndmask_b32_e64 v17, v21, v17, s[2:3]
	v_cndmask_b32_e32 v21, v22, v18, vcc
	v_cndmask_b32_e64 v15, v15, v21, s[2:3]
	v_sub_u32_e32 v22, 32, v13
	v_cmp_eq_u32_e64 s[6:7], 0, v13
	v_cndmask_b32_e32 v13, v20, v16, vcc
	v_cndmask_b32_e64 v17, v17, v19, s[4:5]
	v_cndmask_b32_e64 v19, v19, v15, s[4:5]
	v_cndmask_b32_e64 v16, v21, v13, s[2:3]
	v_alignbit_b32 v23, v17, v19, v22
	v_cndmask_b32_e64 v15, v15, v16, s[4:5]
	v_cndmask_b32_e64 v17, v23, v17, s[6:7]
	v_alignbit_b32 v20, v19, v15, v22
	v_cndmask_b32_e32 v14, v18, v14, vcc
	v_cndmask_b32_e64 v19, v20, v19, s[6:7]
	v_bfe_u32 v23, v17, 29, 1
	v_cndmask_b32_e64 v13, v13, v14, s[2:3]
	v_alignbit_b32 v20, v17, v19, 30
	v_sub_u32_e32 v24, 0, v23
	v_cndmask_b32_e64 v13, v16, v13, s[4:5]
	v_xor_b32_e32 v20, v20, v24
	v_alignbit_b32 v14, v15, v13, v22
	v_cndmask_b32_e64 v14, v14, v15, s[6:7]
	v_ffbh_u32_e32 v16, v20
	v_alignbit_b32 v15, v19, v14, 30
	v_min_u32_e32 v16, 32, v16
	v_alignbit_b32 v13, v14, v13, 30
	v_xor_b32_e32 v15, v15, v24
	v_sub_u32_e32 v18, 31, v16
	v_xor_b32_e32 v13, v13, v24
	v_alignbit_b32 v19, v20, v15, v18
	v_alignbit_b32 v13, v15, v13, v18
	v_alignbit_b32 v14, v19, v13, 9
	v_ffbh_u32_e32 v15, v14
	v_min_u32_e32 v15, 32, v15
	v_lshrrev_b32_e32 v21, 29, v17
	v_not_b32_e32 v18, v15
	v_alignbit_b32 v13, v14, v13, v18
	v_lshlrev_b32_e32 v14, 31, v21
	v_or_b32_e32 v18, 0x33000000, v14
	v_add_lshl_u32 v15, v15, v16, 23
	v_lshrrev_b32_e32 v13, 9, v13
	v_sub_u32_e32 v15, v18, v15
	v_or_b32_e32 v14, 0.5, v14
	v_lshlrev_b32_e32 v16, 23, v16
	v_or_b32_e32 v13, v15, v13
	v_lshrrev_b32_e32 v15, 9, v19
	v_sub_u32_e32 v14, v14, v16
	v_or_b32_e32 v14, v15, v14
	v_mul_f32_e32 v15, 0x3fc90fda, v14
	v_fma_f32 v16, v14, s0, -v15
	v_fmac_f32_e32 v16, 0x33a22168, v14
	v_fmac_f32_e32 v16, 0x3fc90fda, v13
	v_lshrrev_b32_e32 v14, 30, v17
	v_add_f32_e32 v13, v15, v16
	v_add_u32_e32 v14, v23, v14
	s_branch .LBB0_33
.Lsl_37:
	v_lshrrev_b32_e32 v17, 23, v16
	v_add_u32_e32 v17, 0xffffff88, v17
	v_cmp_lt_u32_e32 vcc, 63, v17
	s_nop 1
	v_cndmask_b32_e32 v18, 0, v145, vcc
	v_add_u32_e32 v17, v18, v17
	v_cmp_lt_u32_e64 s[2:3], 31, v17
	s_nop 1
	v_cndmask_b32_e64 v18, 0, v146, s[2:3]
	v_add_u32_e32 v17, v18, v17
	v_cmp_lt_u32_e64 s[4:5], 31, v17
	s_nop 1
	v_cndmask_b32_e64 v18, 0, v146, s[4:5]
	v_add_u32_e32 v17, v18, v17
	v_and_b32_e32 v18, 0x7fffff, v16
	v_or_b32_e32 v30, 0x800000, v18
	v_mad_u64_u32 v[18:19], s[6:7], v30, s61, 0
	v_mov_b32_e32 v80, v19
	v_mad_u64_u32 v[20:21], s[6:7], v30, s62, v[80:81]
	v_mov_b32_e32 v80, v21
	v_mad_u64_u32 v[22:23], s[6:7], v30, s63, v[80:81]
	v_mov_b32_e32 v80, v23
	v_mad_u64_u32 v[24:25], s[6:7], v30, s72, v[80:81]
	v_mov_b32_e32 v80, v25
	v_mad_u64_u32 v[26:27], s[6:7], v30, s73, v[80:81]
	v_mov_b32_e32 v80, v27
	v_mad_u64_u32 v[28:29], s[6:7], v30, s74, v[80:81]
	v_mov_b32_e32 v80, v29
	v_mad_u64_u32 v[30:31], s[6:7], v30, s75, v[80:81]
	v_cndmask_b32_e32 v19, v28, v24, vcc
	v_cndmask_b32_e32 v21, v30, v26, vcc
	v_cndmask_b32_e32 v25, v31, v28, vcc
	v_cndmask_b32_e64 v23, v21, v19, s[2:3]
	v_cndmask_b32_e64 v21, v25, v21, s[2:3]
	v_cndmask_b32_e32 v25, v26, v22, vcc
	v_cndmask_b32_e64 v19, v19, v25, s[2:3]
	v_sub_u32_e32 v26, 32, v17
	v_cmp_eq_u32_e64 s[6:7], 0, v17
	v_cndmask_b32_e32 v17, v24, v20, vcc
	v_cndmask_b32_e64 v21, v21, v23, s[4:5]
	v_cndmask_b32_e64 v23, v23, v19, s[4:5]
	v_cndmask_b32_e64 v20, v25, v17, s[2:3]
	v_alignbit_b32 v27, v21, v23, v26
	v_cndmask_b32_e64 v19, v19, v20, s[4:5]
	v_cndmask_b32_e64 v21, v27, v21, s[6:7]
	v_alignbit_b32 v24, v23, v19, v26
	v_cndmask_b32_e32 v18, v22, v18, vcc
	v_cndmask_b32_e64 v23, v24, v23, s[6:7]
	v_bfe_u32 v27, v21, 29, 1
	v_cndmask_b32_e64 v17, v17, v18, s[2:3]
	v_alignbit_b32 v24, v21, v23, 30
	v_sub_u32_e32 v28, 0, v27
	v_cndmask_b32_e64 v17, v20, v17, s[4:5]
	v_xor_b32_e32 v24, v24, v28
	v_alignbit_b32 v18, v19, v17, v26
	v_cndmask_b32_e64 v18, v18, v19, s[6:7]
	v_ffbh_u32_e32 v20, v24
	v_alignbit_b32 v19, v23, v18, 30
	v_min_u32_e32 v20, 32, v20
	v_alignbit_b32 v17, v18, v17, 30
	v_xor_b32_e32 v19, v19, v28
	v_sub_u32_e32 v22, 31, v20
	v_xor_b32_e32 v17, v17, v28
	v_alignbit_b32 v23, v24, v19, v22
	v_alignbit_b32 v17, v19, v17, v22
	v_alignbit_b32 v18, v23, v17, 9
	v_ffbh_u32_e32 v19, v18
	v_min_u32_e32 v19, 32, v19
	v_lshrrev_b32_e32 v25, 29, v21
	v_not_b32_e32 v22, v19
	v_alignbit_b32 v17, v18, v17, v22
	v_lshlrev_b32_e32 v18, 31, v25
	v_or_b32_e32 v22, 0x33000000, v18
	v_add_lshl_u32 v19, v19, v20, 23
	v_lshrrev_b32_e32 v17, 9, v17
	v_sub_u32_e32 v19, v22, v19
	v_or_b32_e32 v18, 0.5, v18
	v_lshlrev_b32_e32 v20, 23, v20
	v_or_b32_e32 v17, v19, v17
	v_lshrrev_b32_e32 v19, 9, v23
	v_sub_u32_e32 v18, v18, v20
	v_or_b32_e32 v18, v19, v18
	v_mul_f32_e32 v19, 0x3fc90fda, v18
	v_fma_f32 v20, v18, s0, -v19
	v_fmac_f32_e32 v20, 0x33a22168, v18
	v_fmac_f32_e32 v20, 0x3fc90fda, v17
	v_lshrrev_b32_e32 v18, 30, v21
	v_add_f32_e32 v17, v19, v20
	v_add_u32_e32 v18, v27, v18
	s_branch .LBB0_37
; __device__ __forceinline__ int crow16(int r, int hi) { return (r & 3) + 8 * (r >> 2) + 4 * hi; }
; __device__ __forceinline__ void filter_item32(const Args& a, int L, bf16* KR, int t0, int np0, int npn, int lane) {
;     ...
;         for (int r = 0; r < 16; ++r) { const int j = crow16(r, hi); h0[r] = sinf(fq[j] * (h0[r] + b1[j])); h1[r] = sinf(fq[32 + j] * (h1[r] + b1[32 + j])); }
.Lsl_41:
	v_lshrrev_b32_e32 v21, 23, v20
	v_add_u32_e32 v21, 0xffffff88, v21
	v_cmp_lt_u32_e32 vcc, 63, v21
	s_nop 1
	v_cndmask_b32_e32 v22, 0, v145, vcc
	v_add_u32_e32 v21, v22, v21
	v_cmp_lt_u32_e64 s[2:3], 31, v21
	s_nop 1
	v_cndmask_b32_e64 v22, 0, v146, s[2:3]
	v_add_u32_e32 v21, v22, v21
	v_cmp_lt_u32_e64 s[4:5], 31, v21
	s_nop 1
	v_cndmask_b32_e64 v22, 0, v146, s[4:5]
	v_add_u32_e32 v21, v22, v21
	v_and_b32_e32 v22, 0x7fffff, v20
	v_or_b32_e32 v34, 0x800000, v22
	v_mad_u64_u32 v[22:23], s[6:7], v34, s61, 0
	v_mov_b32_e32 v80, v23
	v_mad_u64_u32 v[24:25], s[6:7], v34, s62, v[80:81]
	v_mov_b32_e32 v80, v25
	v_mad_u64_u32 v[26:27], s[6:7], v34, s63, v[80:81]
	v_mov_b32_e32 v80, v27
	v_mad_u64_u32 v[28:29], s[6:7], v34, s72, v[80:81]
	v_mov_b32_e32 v80, v29
	v_mad_u64_u32 v[30:31], s[6:7], v34, s73, v[80:81]
	v_mov_b32_e32 v80, v31
	v_mad_u64_u32 v[32:33], s[6:7], v34, s74, v[80:81]
	v_mov_b32_e32 v80, v33
	v_mad_u64_u32 v[34:35], s[6:7], v34, s75, v[80:81]
	v_cndmask_b32_e32 v23, v32, v28, vcc
	v_cndmask_b32_e32 v25, v34, v30, vcc
	v_cndmask_b32_e32 v29, v35, v32, vcc
	v_cndmask_b32_e64 v27, v25, v23, s[2:3]
	v_cndmask_b32_e64 v25, v29, v25, s[2:3]
	v_cndmask_b32_e32 v29, v30, v26, vcc
	v_cndmask_b32_e64 v23, v23, v29, s[2:3]
	v_sub_u32_e32 v30, 32, v21
	v_cmp_eq_u32_e64 s[6:7], 0, v21
	v_cndmask_b32_e32 v21, v28, v24, vcc
	v_cndmask_b32_e64 v25, v25, v27, s[4:5]
	v_cndmask_b32_e64 v27, v27, v23, s[4:5]
	v_cndmask_b32_e64 v24, v29, v21, s[2:3]
	v_alignbit_b32 v31, v25, v27, v30
	v_cndmask_b32_e64 v23, v23, v24, s[4:5]
	v_cndmask_b32_e64 v25, v31, v25, s[6:7]
	v_alignbit_b32 v28, v27, v23, v30
	v_cndmask_b32_e32 v22, v26, v22, vcc
	v_cndmask_b32_e64 v27, v28, v27, s[6:7]
	v_bfe_u32 v31, v25, 29, 1
	v_cndmask_b32_e64 v21, v21, v22, s[2:3]
	v_alignbit_b32 v28, v25, v27, 30
	v_sub_u32_e32 v32, 0, v31
	v_cndmask_b32_e64 v21, v24, v21, s[4:5]
	v_xor_b32_e32 v28, v28, v32
	v_alignbit_b32 v22, v23, v21, v30
	v_cndmask_b32_e64 v22, v22, v23, s[6:7]
	v_ffbh_u32_e32 v24, v28
	v_alignbit_b32 v23, v27, v22, 30
	v_min_u32_e32 v24, 32, v24
	v_alignbit_b32 v21, v22, v21, 30
	v_xor_b32_e32 v23, v23, v32
	v_sub_u32_e32 v26, 31, v24
	v_xor_b32_e32 v21, v21, v32
	v_alignbit_b32 v27, v28, v23, v26
	v_alignbit_b32 v21, v23, v21, v26
	v_alignbit_b32 v22, v27, v21, 9
	v_ffbh_u32_e32 v23, v22
	v_min_u32_e32 v23, 32, v23
	v_lshrrev_b32_e32 v29, 29, v25
	v_not_b32_e32 v26, v23
	v_alignbit_b32 v21, v22, v21, v26
	v_lshlrev_b32_e32 v22, 31, v29
	v_or_b32_e32 v26, 0x33000000, v22
	v_add_lshl_u32 v23, v23, v24, 23
	v_lshrrev_b32_e32 v21, 9, v21
	v_sub_u32_e32 v23, v26, v23
	v_or_b32_e32 v22, 0.5, v22
	v_lshlrev_b32_e32 v24, 23, v24
	v_or_b32_e32 v21, v23, v21
	v_lshrrev_b32_e32 v23, 9, v27
	v_sub_u32_e32 v22, v22, v24
	v_or_b32_e32 v22, v23, v22
	v_mul_f32_e32 v23, 0x3fc90fda, v22
	v_fma_f32 v24, v22, s0, -v23
	v_fmac_f32_e32 v24, 0x33a22168, v22
	v_fmac_f32_e32 v24, 0x3fc90fda, v21
	v_lshrrev_b32_e32 v22, 30, v25
	v_add_f32_e32 v21, v23, v24
	v_add_u32_e32 v22, v31, v22
	s_branch .LBB0_41
.Lsl_45:
	v_lshrrev_b32_e32 v25, 23, v24
	v_add_u32_e32 v25, 0xffffff88, v25
	v_cmp_lt_u32_e32 vcc, 63, v25
	s_nop 1
	v_cndmask_b32_e32 v26, 0, v145, vcc
	v_add_u32_e32 v25, v26, v25
	v_cmp_lt_u32_e64 s[2:3], 31, v25
	s_nop 1
	v_cndmask_b32_e64 v26, 0, v146, s[2:3]
	v_add_u32_e32 v25, v26, v25
	v_cmp_lt_u32_e64 s[4:5], 31, v25
	s_nop 1
	v_cndmask_b32_e64 v26, 0, v146, s[4:5]
	v_add_u32_e32 v25, v26, v25
	v_and_b32_e32 v26, 0x7fffff, v24
	v_or_b32_e32 v38, 0x800000, v26
	v_mad_u64_u32 v[26:27], s[6:7], v38, s61, 0
	v_mov_b32_e32 v80, v27
	v_mad_u64_u32 v[28:29], s[6:7], v38, s62, v[80:81]
	v_mov_b32_e32 v80, v29
	v_mad_u64_u32 v[30:31], s[6:7], v38, s63, v[80:81]
	v_mov_b32_e32 v80, v31
	v_mad_u64_u32 v[32:33], s[6:7], v38, s72, v[80:81]
	v_mov_b32_e32 v80, v33
	v_mad_u64_u32 v[34:35], s[6:7], v38, s73, v[80:81]
	v_mov_b32_e32 v80, v35
	v_mad_u64_u32 v[36:37], s[6:7], v38, s74, v[80:81]
	v_mov_b32_e32 v80, v37
	v_mad_u64_u32 v[38:39], s[6:7], v38, s75, v[80:81]
	v_cndmask_b32_e32 v27, v36, v32, vcc
	v_cndmask_b32_e32 v29, v38, v34, vcc
	v_cndmask_b32_e32 v33, v39, v36, vcc
	v_cndmask_b32_e64 v31, v29, v27, s[2:3]
	v_cndmask_b32_e64 v29, v33, v29, s[2:3]
	v_cndmask_b32_e32 v33, v34, v30, vcc
	v_cndmask_b32_e64 v27, v27, v33, s[2:3]
	v_sub_u32_e32 v34, 32, v25
	v_cmp_eq_u32_e64 s[6:7], 0, v25
	v_cndmask_b32_e32 v25, v32, v28, vcc
	v_cndmask_b32_e64 v29, v29, v31, s[4:5]
	v_cndmask_b32_e64 v31, v31, v27, s[4:5]
	v_cndmask_b32_e64 v28, v33, v25, s[2:3]
	v_alignbit_b32 v35, v29, v31, v34
	v_cndmask_b32_e64 v27, v27, v28, s[4:5]
	v_cndmask_b32_e64 v29, v35, v29, s[6:7]
	v_alignbit_b32 v32, v31, v27, v34
	v_cndmask_b32_e32 v26, v30, v26, vcc
	v_cndmask_b32_e64 v31, v32, v31, s[6:7]
	v_bfe_u32 v35, v29, 29, 1
	v_cndmask_b32_e64 v25, v25, v26, s[2:3]
	v_alignbit_b32 v32, v29, v31, 30
	v_sub_u32_e32 v36, 0, v35
	v_cndmask_b32_e64 v25, v28, v25, s[4:5]
	v_xor_b32_e32 v32, v32, v36
	v_alignbit_b32 v26, v27, v25, v34
	v_cndmask_b32_e64 v26, v26, v27, s[6:7]
	v_ffbh_u32_e32 v28, v32
	v_alignbit_b32 v27, v31, v26, 30
	v_min_u32_e32 v28, 32, v28
	v_alignbit_b32 v25, v26, v25, 30
	v_xor_b32_e32 v27, v27, v36
	v_sub_u32_e32 v30, 31, v28
	v_xor_b32_e32 v25, v25, v36
	v_alignbit_b32 v31, v32, v27, v30
	v_alignbit_b32 v25, v27, v25, v30
	v_alignbit_b32 v26, v31, v25, 9
	v_ffbh_u32_e32 v27, v26
	v_min_u32_e32 v27, 32, v27
	v_lshrrev_b32_e32 v33, 29, v29
	v_not_b32_e32 v30, v27
	v_alignbit_b32 v25, v26, v25, v30
	v_lshlrev_b32_e32 v26, 31, v33
	v_or_b32_e32 v30, 0x33000000, v26
	v_add_lshl_u32 v27, v27, v28, 23
	v_lshrrev_b32_e32 v25, 9, v25
	v_sub_u32_e32 v27, v30, v27
	v_or_b32_e32 v26, 0.5, v26
	v_lshlrev_b32_e32 v28, 23, v28
	v_or_b32_e32 v25, v27, v25
	v_lshrrev_b32_e32 v27, 9, v31
	v_sub_u32_e32 v26, v26, v28
	v_or_b32_e32 v26, v27, v26
	v_mul_f32_e32 v27, 0x3fc90fda, v26
	v_fma_f32 v28, v26, s0, -v27
	v_fmac_f32_e32 v28, 0x33a22168, v26
	v_fmac_f32_e32 v28, 0x3fc90fda, v25
	v_lshrrev_b32_e32 v26, 30, v29
	v_add_f32_e32 v25, v27, v28
	v_add_u32_e32 v26, v35, v26
	s_branch .LBB0_45
; __device__ __forceinline__ int crow16(int r, int hi) { return (r & 3) + 8 * (r >> 2) + 4 * hi; }
; __device__ __forceinline__ void filter_item32(const Args& a, int L, bf16* KR, int t0, int np0, int npn, int lane) {
;     ...
;         for (int r = 0; r < 16; ++r) { const int j = crow16(r, hi); h0[r] = sinf(fq[j] * (h0[r] + b1[j])); h1[r] = sinf(fq[32 + j] * (h1[r] + b1[32 + j])); }
.Lsl_49:
	v_lshrrev_b32_e32 v27, 23, v30
	v_add_u32_e32 v27, 0xffffff88, v27
	v_cmp_lt_u32_e32 vcc, 63, v27
	s_nop 1
	v_cndmask_b32_e32 v29, 0, v145, vcc
	v_add_u32_e32 v27, v29, v27
	v_cmp_lt_u32_e64 s[2:3], 31, v27
	s_nop 1
	v_cndmask_b32_e64 v29, 0, v146, s[2:3]
	v_add_u32_e32 v27, v29, v27
	v_cmp_lt_u32_e64 s[4:5], 31, v27
	s_nop 1
	v_cndmask_b32_e64 v29, 0, v146, s[4:5]
	v_add_u32_e32 v27, v29, v27
	v_and_b32_e32 v29, 0x7fffff, v30
	v_or_b32_e32 v29, 0x800000, v29
	v_mad_u64_u32 v[32:33], s[6:7], v29, s61, 0
	v_mov_b32_e32 v80, v33
	v_mad_u64_u32 v[34:35], s[6:7], v29, s62, v[80:81]
	v_mov_b32_e32 v80, v35
	v_mad_u64_u32 v[36:37], s[6:7], v29, s63, v[80:81]
	v_mov_b32_e32 v80, v37
	v_mad_u64_u32 v[38:39], s[6:7], v29, s72, v[80:81]
	v_mov_b32_e32 v80, v39
	v_mad_u64_u32 v[40:41], s[6:7], v29, s73, v[80:81]
	v_mov_b32_e32 v80, v41
	v_mad_u64_u32 v[42:43], s[6:7], v29, s74, v[80:81]
	v_mov_b32_e32 v80, v43
	v_mad_u64_u32 v[44:45], s[6:7], v29, s75, v[80:81]
	v_cndmask_b32_e32 v31, v42, v38, vcc
	v_cndmask_b32_e32 v29, v44, v40, vcc
	v_cndmask_b32_e32 v35, v45, v42, vcc
	v_cndmask_b32_e64 v33, v29, v31, s[2:3]
	v_cndmask_b32_e64 v29, v35, v29, s[2:3]
	v_cndmask_b32_e32 v35, v40, v36, vcc
	v_cndmask_b32_e64 v31, v31, v35, s[2:3]
	v_cndmask_b32_e64 v29, v29, v33, s[4:5]
	v_cndmask_b32_e64 v33, v33, v31, s[4:5]
	v_sub_u32_e32 v37, 32, v27
	v_alignbit_b32 v39, v29, v33, v37
	v_cmp_eq_u32_e64 s[6:7], 0, v27
	v_cndmask_b32_e32 v32, v36, v32, vcc
	s_nop 0
	v_cndmask_b32_e64 v27, v39, v29, s[6:7]
	v_cndmask_b32_e32 v29, v38, v34, vcc
	v_cndmask_b32_e64 v34, v35, v29, s[2:3]
	v_cndmask_b32_e64 v31, v31, v34, s[4:5]
	v_alignbit_b32 v35, v33, v31, v37
	v_cndmask_b32_e64 v29, v29, v32, s[2:3]
	v_cndmask_b32_e64 v33, v35, v33, s[6:7]
	v_bfe_u32 v39, v27, 29, 1
	v_cndmask_b32_e64 v29, v34, v29, s[4:5]
	v_alignbit_b32 v35, v27, v33, 30
	v_sub_u32_e32 v40, 0, v39
	v_alignbit_b32 v32, v31, v29, v37
	v_xor_b32_e32 v35, v35, v40
	v_cndmask_b32_e64 v31, v32, v31, s[6:7]
	v_alignbit_b32 v32, v33, v31, 30
	v_ffbh_u32_e32 v33, v35
	v_min_u32_e32 v33, 32, v33
	v_alignbit_b32 v29, v31, v29, 30
	v_xor_b32_e32 v32, v32, v40
	v_sub_u32_e32 v34, 31, v33
	v_xor_b32_e32 v29, v29, v40
	v_alignbit_b32 v35, v35, v32, v34
	v_alignbit_b32 v29, v32, v29, v34
	v_alignbit_b32 v31, v35, v29, 9
	v_ffbh_u32_e32 v32, v31
	v_min_u32_e32 v32, 32, v32
	v_lshrrev_b32_e32 v38, 29, v27
	v_not_b32_e32 v34, v32
	v_alignbit_b32 v29, v31, v29, v34
	v_lshlrev_b32_e32 v31, 31, v38
	v_or_b32_e32 v34, 0x33000000, v31
	v_add_lshl_u32 v32, v32, v33, 23
	v_lshrrev_b32_e32 v29, 9, v29
	v_sub_u32_e32 v32, v34, v32
	v_or_b32_e32 v31, 0.5, v31
	v_lshlrev_b32_e32 v33, 23, v33
	v_or_b32_e32 v29, v32, v29
	v_lshrrev_b32_e32 v32, 9, v35
	v_sub_u32_e32 v31, v31, v33
	v_or_b32_e32 v31, v32, v31
	v_mul_f32_e32 v32, 0x3fc90fda, v31
	v_fma_f32 v33, v31, s0, -v32
	v_fmac_f32_e32 v33, 0x33a22168, v31
	v_fmac_f32_e32 v33, 0x3fc90fda, v29
	v_lshrrev_b32_e32 v27, 30, v27
	v_add_f32_e32 v33, v32, v33
	v_add_u32_e32 v34, v39, v27
	s_branch .LBB0_49
.Lsl_53:
	v_lshrrev_b32_e32 v1, 23, v29
	v_add_u32_e32 v1, 0xffffff88, v1
	v_cmp_lt_u32_e32 vcc, 63, v1
	s_nop 1
	v_cndmask_b32_e32 v31, 0, v145, vcc
	v_add_u32_e32 v1, v31, v1
	v_cmp_lt_u32_e64 s[2:3], 31, v1
	s_nop 1
	v_cndmask_b32_e64 v31, 0, v146, s[2:3]
	v_add_u32_e32 v1, v31, v1
	v_cmp_lt_u32_e64 s[4:5], 31, v1
	s_nop 1
	v_cndmask_b32_e64 v31, 0, v146, s[4:5]
	v_add_u32_e32 v1, v31, v1
	v_and_b32_e32 v31, 0x7fffff, v29
	v_or_b32_e32 v31, 0x800000, v31
	v_mad_u64_u32 v[36:37], s[6:7], v31, s61, 0
	v_mov_b32_e32 v80, v37
	v_mad_u64_u32 v[38:39], s[6:7], v31, s62, v[80:81]
	v_mov_b32_e32 v80, v39
	v_mad_u64_u32 v[40:41], s[6:7], v31, s63, v[80:81]
	v_mov_b32_e32 v80, v41
	v_mad_u64_u32 v[42:43], s[6:7], v31, s72, v[80:81]
	v_mov_b32_e32 v80, v43
	v_mad_u64_u32 v[44:45], s[6:7], v31, s73, v[80:81]
	v_mov_b32_e32 v80, v45
	v_mad_u64_u32 v[46:47], s[6:7], v31, s74, v[80:81]
	v_mov_b32_e32 v80, v47
	v_mad_u64_u32 v[48:49], s[6:7], v31, s75, v[80:81]
	v_cndmask_b32_e32 v32, v46, v42, vcc
	v_cndmask_b32_e32 v31, v48, v44, vcc
	v_cndmask_b32_e32 v37, v49, v46, vcc
	v_cndmask_b32_e64 v35, v31, v32, s[2:3]
	v_cndmask_b32_e64 v31, v37, v31, s[2:3]
	v_cndmask_b32_e32 v37, v44, v40, vcc
	v_cndmask_b32_e64 v32, v32, v37, s[2:3]
	v_cndmask_b32_e64 v31, v31, v35, s[4:5]
	v_cndmask_b32_e64 v35, v35, v32, s[4:5]
	v_sub_u32_e32 v39, 32, v1
	v_alignbit_b32 v41, v31, v35, v39
	v_cmp_eq_u32_e64 s[6:7], 0, v1
	v_cndmask_b32_e32 v36, v40, v36, vcc
	s_nop 0
	v_cndmask_b32_e64 v1, v41, v31, s[6:7]
	v_cndmask_b32_e32 v31, v42, v38, vcc
	v_cndmask_b32_e64 v37, v37, v31, s[2:3]
	v_cndmask_b32_e64 v32, v32, v37, s[4:5]
	v_alignbit_b32 v38, v35, v32, v39
	v_cndmask_b32_e64 v35, v38, v35, s[6:7]
	v_bfe_u32 v42, v1, 29, 1
	v_cndmask_b32_e64 v31, v31, v36, s[2:3]
	v_alignbit_b32 v38, v1, v35, 30
	v_sub_u32_e32 v43, 0, v42
	v_cndmask_b32_e64 v31, v37, v31, s[4:5]
	v_xor_b32_e32 v38, v38, v43
	v_alignbit_b32 v36, v32, v31, v39
	v_cndmask_b32_e64 v32, v36, v32, s[6:7]
	v_ffbh_u32_e32 v36, v38
	v_alignbit_b32 v35, v35, v32, 30
	v_min_u32_e32 v36, 32, v36
	v_alignbit_b32 v31, v32, v31, 30
	v_xor_b32_e32 v35, v35, v43
	v_sub_u32_e32 v37, 31, v36
	v_xor_b32_e32 v31, v31, v43
	v_alignbit_b32 v38, v38, v35, v37
	v_alignbit_b32 v31, v35, v31, v37
	v_alignbit_b32 v32, v38, v31, 9
	v_ffbh_u32_e32 v35, v32
	v_min_u32_e32 v35, 32, v35
	v_lshrrev_b32_e32 v41, 29, v1
	v_not_b32_e32 v37, v35
	v_alignbit_b32 v31, v32, v31, v37
	v_lshlrev_b32_e32 v32, 31, v41
	v_or_b32_e32 v37, 0x33000000, v32
	v_add_lshl_u32 v35, v35, v36, 23
	v_lshrrev_b32_e32 v31, 9, v31
	v_sub_u32_e32 v35, v37, v35
	v_or_b32_e32 v32, 0.5, v32
	v_lshlrev_b32_e32 v36, 23, v36
	v_or_b32_e32 v31, v35, v31
	v_lshrrev_b32_e32 v35, 9, v38
	v_sub_u32_e32 v32, v32, v36
	v_or_b32_e32 v32, v35, v32
	v_mul_f32_e32 v35, 0x3fc90fda, v32
	v_fma_f32 v36, v32, s0, -v35
	v_fmac_f32_e32 v36, 0x33a22168, v32
	v_fmac_f32_e32 v36, 0x3fc90fda, v31
	v_lshrrev_b32_e32 v1, 30, v1
	v_add_f32_e32 v31, v35, v36
	v_add_u32_e32 v32, v42, v1
	s_branch .LBB0_53
; __device__ __forceinline__ int crow16(int r, int hi) { return (r & 3) + 8 * (r >> 2) + 4 * hi; }
; __device__ __forceinline__ void filter_item32(const Args& a, int L, bf16* KR, int t0, int np0, int npn, int lane) {
;     ...
;         for (int r = 0; r < 16; ++r) { const int j = crow16(r, hi); h0[r] = sinf(fq[j] * (h0[r] + b1[j])); h1[r] = sinf(fq[32 + j] * (h1[r] + b1[32 + j])); }
.Lsl_57:
	v_lshrrev_b32_e32 v18, 23, v34
	v_add_u32_e32 v18, 0xffffff88, v18
	v_cmp_lt_u32_e32 vcc, 63, v18
	s_nop 1
	v_cndmask_b32_e32 v35, 0, v145, vcc
	v_add_u32_e32 v18, v35, v18
	v_cmp_lt_u32_e64 s[2:3], 31, v18
	s_nop 1
	v_cndmask_b32_e64 v35, 0, v146, s[2:3]
	v_add_u32_e32 v18, v35, v18
	v_cmp_lt_u32_e64 s[4:5], 31, v18
	s_nop 1
	v_cndmask_b32_e64 v35, 0, v146, s[4:5]
	v_add_u32_e32 v18, v35, v18
	v_and_b32_e32 v35, 0x7fffff, v34
	v_or_b32_e32 v35, 0x800000, v35
	v_mad_u64_u32 v[36:37], s[6:7], v35, s61, 0
	v_mov_b32_e32 v80, v37
	v_mad_u64_u32 v[38:39], s[6:7], v35, s62, v[80:81]
	v_mov_b32_e32 v80, v39
	v_mad_u64_u32 v[40:41], s[6:7], v35, s63, v[80:81]
	v_mov_b32_e32 v80, v41
	v_mad_u64_u32 v[42:43], s[6:7], v35, s72, v[80:81]
	v_mov_b32_e32 v80, v43
	v_mad_u64_u32 v[44:45], s[6:7], v35, s73, v[80:81]
	v_mov_b32_e32 v80, v45
	v_mad_u64_u32 v[46:47], s[6:7], v35, s74, v[80:81]
	v_mov_b32_e32 v80, v47
	v_mad_u64_u32 v[48:49], s[6:7], v35, s75, v[80:81]
	v_cndmask_b32_e32 v37, v46, v42, vcc
	v_cndmask_b32_e32 v35, v48, v44, vcc
	v_cndmask_b32_e32 v41, v49, v46, vcc
	v_cndmask_b32_e64 v39, v35, v37, s[2:3]
	v_cndmask_b32_e64 v35, v41, v35, s[2:3]
	v_cndmask_b32_e32 v41, v44, v40, vcc
	v_cndmask_b32_e64 v37, v37, v41, s[2:3]
	v_cndmask_b32_e64 v35, v35, v39, s[4:5]
	v_cndmask_b32_e64 v39, v39, v37, s[4:5]
	v_sub_u32_e32 v43, 32, v18
	v_alignbit_b32 v44, v35, v39, v43
	v_cmp_eq_u32_e64 s[6:7], 0, v18
	v_cndmask_b32_e32 v36, v40, v36, vcc
	s_nop 0
	v_cndmask_b32_e64 v18, v44, v35, s[6:7]
	v_cndmask_b32_e32 v35, v42, v38, vcc
	v_cndmask_b32_e64 v38, v41, v35, s[2:3]
	v_cndmask_b32_e64 v37, v37, v38, s[4:5]
	v_alignbit_b32 v41, v39, v37, v43
	v_cndmask_b32_e64 v39, v41, v39, s[6:7]
	v_bfe_u32 v44, v18, 29, 1
	v_cndmask_b32_e64 v35, v35, v36, s[2:3]
	v_alignbit_b32 v41, v18, v39, 30
	v_sub_u32_e32 v45, 0, v44
	v_cndmask_b32_e64 v35, v38, v35, s[4:5]
	v_xor_b32_e32 v41, v41, v45
	v_alignbit_b32 v36, v37, v35, v43
	v_cndmask_b32_e64 v36, v36, v37, s[6:7]
	v_ffbh_u32_e32 v38, v41
	v_alignbit_b32 v37, v39, v36, 30
	v_min_u32_e32 v38, 32, v38
	v_alignbit_b32 v35, v36, v35, 30
	v_xor_b32_e32 v37, v37, v45
	v_sub_u32_e32 v39, 31, v38
	v_xor_b32_e32 v35, v35, v45
	v_alignbit_b32 v40, v41, v37, v39
	v_alignbit_b32 v35, v37, v35, v39
	v_alignbit_b32 v36, v40, v35, 9
	v_ffbh_u32_e32 v37, v36
	v_min_u32_e32 v37, 32, v37
	v_lshrrev_b32_e32 v42, 29, v18
	v_not_b32_e32 v39, v37
	v_alignbit_b32 v35, v36, v35, v39
	v_lshlrev_b32_e32 v36, 31, v42
	v_or_b32_e32 v39, 0x33000000, v36
	v_add_lshl_u32 v37, v37, v38, 23
	v_lshrrev_b32_e32 v35, 9, v35
	v_sub_u32_e32 v37, v39, v37
	v_or_b32_e32 v36, 0.5, v36
	v_lshlrev_b32_e32 v38, 23, v38
	v_or_b32_e32 v35, v37, v35
	v_lshrrev_b32_e32 v37, 9, v40
	v_sub_u32_e32 v36, v36, v38
	v_or_b32_e32 v36, v37, v36
	v_mul_f32_e32 v37, 0x3fc90fda, v36
	v_fma_f32 v38, v36, s0, -v37
	v_fmac_f32_e32 v38, 0x33a22168, v36
	v_fmac_f32_e32 v38, 0x3fc90fda, v35
	v_lshrrev_b32_e32 v18, 30, v18
	v_add_f32_e32 v36, v37, v38
	v_add_u32_e32 v35, v44, v18
	s_branch .LBB0_57
.Lsl_61:
	v_lshrrev_b32_e32 v2, 23, v48
	v_add_u32_e32 v2, 0xffffff88, v2
	v_cmp_lt_u32_e32 vcc, 63, v2
	s_nop 1
	v_cndmask_b32_e32 v37, 0, v145, vcc
	v_add_u32_e32 v2, v37, v2
	v_cmp_lt_u32_e64 s[2:3], 31, v2
	s_nop 1
	v_cndmask_b32_e64 v37, 0, v146, s[2:3]
	v_add_u32_e32 v2, v37, v2
	v_cmp_lt_u32_e64 s[4:5], 31, v2
	s_nop 1
	v_cndmask_b32_e64 v37, 0, v146, s[4:5]
	v_add_u32_e32 v2, v37, v2
	v_and_b32_e32 v37, 0x7fffff, v48
	v_or_b32_e32 v37, 0x800000, v37
	v_mad_u64_u32 v[38:39], s[6:7], v37, s61, 0
	v_mov_b32_e32 v80, v39
	v_mad_u64_u32 v[40:41], s[6:7], v37, s62, v[80:81]
	v_mov_b32_e32 v80, v41
	v_mad_u64_u32 v[42:43], s[6:7], v37, s63, v[80:81]
	v_mov_b32_e32 v80, v43
	v_mad_u64_u32 v[44:45], s[6:7], v37, s72, v[80:81]
	v_mov_b32_e32 v80, v45
	v_mad_u64_u32 v[46:47], s[6:7], v37, s73, v[80:81]
	v_mov_b32_e32 v80, v47
	v_mad_u64_u32 v[50:51], s[6:7], v37, s74, v[80:81]
	v_mov_b32_e32 v80, v51
	v_mad_u64_u32 v[52:53], s[6:7], v37, s75, v[80:81]
	v_cndmask_b32_e32 v39, v50, v44, vcc
	v_cndmask_b32_e32 v37, v52, v46, vcc
	v_cndmask_b32_e32 v43, v53, v50, vcc
	v_cndmask_b32_e64 v41, v37, v39, s[2:3]
	v_cndmask_b32_e64 v37, v43, v37, s[2:3]
	v_cndmask_b32_e32 v43, v46, v42, vcc
	v_cndmask_b32_e64 v39, v39, v43, s[2:3]
	v_cndmask_b32_e64 v37, v37, v41, s[4:5]
	v_cndmask_b32_e64 v41, v41, v39, s[4:5]
	v_sub_u32_e32 v45, 32, v2
	v_alignbit_b32 v46, v37, v41, v45
	v_cmp_eq_u32_e64 s[6:7], 0, v2
	v_cndmask_b32_e32 v38, v42, v38, vcc
	s_nop 0
	v_cndmask_b32_e64 v2, v46, v37, s[6:7]
	v_cndmask_b32_e32 v37, v44, v40, vcc
	v_cndmask_b32_e64 v40, v43, v37, s[2:3]
	v_cndmask_b32_e64 v39, v39, v40, s[4:5]
	v_alignbit_b32 v43, v41, v39, v45
	v_cndmask_b32_e64 v41, v43, v41, s[6:7]
	v_bfe_u32 v46, v2, 29, 1
	v_cndmask_b32_e64 v37, v37, v38, s[2:3]
	v_alignbit_b32 v43, v2, v41, 30
	v_sub_u32_e32 v47, 0, v46
	v_cndmask_b32_e64 v37, v40, v37, s[4:5]
	v_xor_b32_e32 v43, v43, v47
	v_alignbit_b32 v38, v39, v37, v45
	v_cndmask_b32_e64 v38, v38, v39, s[6:7]
	v_ffbh_u32_e32 v40, v43
	v_alignbit_b32 v39, v41, v38, 30
	v_min_u32_e32 v40, 32, v40
	v_alignbit_b32 v37, v38, v37, 30
	v_xor_b32_e32 v39, v39, v47
	v_sub_u32_e32 v41, 31, v40
	v_xor_b32_e32 v37, v37, v47
	v_alignbit_b32 v42, v43, v39, v41
	v_alignbit_b32 v37, v39, v37, v41
	v_alignbit_b32 v38, v42, v37, 9
	v_ffbh_u32_e32 v39, v38
	v_min_u32_e32 v39, 32, v39
	v_lshrrev_b32_e32 v44, 29, v2
	v_not_b32_e32 v41, v39
	v_alignbit_b32 v37, v38, v37, v41
	v_lshlrev_b32_e32 v38, 31, v44
	v_or_b32_e32 v41, 0x33000000, v38
	v_add_lshl_u32 v39, v39, v40, 23
	v_lshrrev_b32_e32 v37, 9, v37
	v_sub_u32_e32 v39, v41, v39
	v_or_b32_e32 v38, 0.5, v38
	v_lshlrev_b32_e32 v40, 23, v40
	v_or_b32_e32 v37, v39, v37
	v_lshrrev_b32_e32 v39, 9, v42
	v_sub_u32_e32 v38, v38, v40
	v_or_b32_e32 v38, v39, v38
	v_mul_f32_e32 v39, 0x3fc90fda, v38
	v_fma_f32 v40, v38, s0, -v39
	v_fmac_f32_e32 v40, 0x33a22168, v38
	v_fmac_f32_e32 v40, 0x3fc90fda, v37
	v_lshrrev_b32_e32 v2, 30, v2
	v_add_f32_e32 v50, v39, v40
	v_add_u32_e32 v49, v46, v2
	s_branch .LBB0_61
; __device__ __forceinline__ int crow16(int r, int hi) { return (r & 3) + 8 * (r >> 2) + 4 * hi; }
; __device__ __forceinline__ void filter_item32(const Args& a, int L, bf16* KR, int t0, int np0, int npn, int lane) {
;     ...
;         for (int r = 0; r < 16; ++r) { const int j = crow16(r, hi); h0[r] = sinf(fq[j] * (h0[r] + b1[j])); h1[r] = sinf(fq[32 + j] * (h1[r] + b1[32 + j])); }
.Lsl_65:
	v_lshrrev_b32_e32 v2, 23, v38
	v_add_u32_e32 v2, 0xffffff88, v2
	v_cmp_lt_u32_e32 vcc, 63, v2
	s_nop 1
	v_cndmask_b32_e32 v19, 0, v145, vcc
	v_add_u32_e32 v2, v19, v2
	v_cmp_lt_u32_e64 s[2:3], 31, v2
	s_nop 1
	v_cndmask_b32_e64 v19, 0, v146, s[2:3]
	v_add_u32_e32 v2, v19, v2
	v_cmp_lt_u32_e64 s[4:5], 31, v2
	s_nop 1
	v_cndmask_b32_e64 v19, 0, v146, s[4:5]
	v_add_u32_e32 v2, v19, v2
	v_and_b32_e32 v19, 0x7fffff, v38
	v_or_b32_e32 v19, 0x800000, v19
	v_mad_u64_u32 v[40:41], s[6:7], v19, s61, 0
	v_mov_b32_e32 v80, v41
	v_mad_u64_u32 v[42:43], s[6:7], v19, s62, v[80:81]
	v_mov_b32_e32 v80, v43
	v_mad_u64_u32 v[44:45], s[6:7], v19, s63, v[80:81]
	v_mov_b32_e32 v80, v45
	v_mad_u64_u32 v[46:47], s[6:7], v19, s72, v[80:81]
	v_mov_b32_e32 v80, v47
	v_mad_u64_u32 v[52:53], s[6:7], v19, s73, v[80:81]
	v_mov_b32_e32 v80, v53
	v_mad_u64_u32 v[54:55], s[6:7], v19, s74, v[80:81]
	v_mov_b32_e32 v80, v55
	v_mad_u64_u32 v[56:57], s[6:7], v19, s75, v[80:81]
	v_cndmask_b32_e32 v39, v54, v46, vcc
	v_cndmask_b32_e32 v19, v56, v52, vcc
	v_cndmask_b32_e32 v43, v57, v54, vcc
	v_cndmask_b32_e64 v41, v19, v39, s[2:3]
	v_cndmask_b32_e64 v19, v43, v19, s[2:3]
	v_cndmask_b32_e32 v43, v52, v44, vcc
	v_cndmask_b32_e64 v39, v39, v43, s[2:3]
	v_cndmask_b32_e64 v19, v19, v41, s[4:5]
	v_cndmask_b32_e64 v41, v41, v39, s[4:5]
	v_sub_u32_e32 v45, 32, v2
	v_alignbit_b32 v47, v19, v41, v45
	v_cmp_eq_u32_e64 s[6:7], 0, v2
	v_cndmask_b32_e32 v40, v44, v40, vcc
	s_nop 0
	v_cndmask_b32_e64 v2, v47, v19, s[6:7]
	v_cndmask_b32_e32 v19, v46, v42, vcc
	v_cndmask_b32_e64 v42, v43, v19, s[2:3]
	v_cndmask_b32_e64 v39, v39, v42, s[4:5]
	v_alignbit_b32 v43, v41, v39, v45
	v_cndmask_b32_e64 v19, v19, v40, s[2:3]
	v_cndmask_b32_e64 v41, v43, v41, s[6:7]
	v_bfe_u32 v47, v2, 29, 1
	v_cndmask_b32_e64 v19, v42, v19, s[4:5]
	v_alignbit_b32 v43, v2, v41, 30
	v_sub_u32_e32 v51, 0, v47
	v_alignbit_b32 v40, v39, v19, v45
	v_xor_b32_e32 v43, v43, v51
	v_cndmask_b32_e64 v39, v40, v39, s[6:7]
	v_alignbit_b32 v40, v41, v39, 30
	v_ffbh_u32_e32 v41, v43
	v_min_u32_e32 v41, 32, v41
	v_alignbit_b32 v19, v39, v19, 30
	v_xor_b32_e32 v40, v40, v51
	v_sub_u32_e32 v42, 31, v41
	v_xor_b32_e32 v19, v19, v51
	v_alignbit_b32 v43, v43, v40, v42
	v_alignbit_b32 v19, v40, v19, v42
	v_alignbit_b32 v39, v43, v19, 9
	v_ffbh_u32_e32 v40, v39
	v_min_u32_e32 v40, 32, v40
	v_lshrrev_b32_e32 v46, 29, v2
	v_not_b32_e32 v42, v40
	v_alignbit_b32 v19, v39, v19, v42
	v_lshlrev_b32_e32 v39, 31, v46
	v_or_b32_e32 v42, 0x33000000, v39
	v_add_lshl_u32 v40, v40, v41, 23
	v_lshrrev_b32_e32 v19, 9, v19
	v_sub_u32_e32 v40, v42, v40
	v_or_b32_e32 v39, 0.5, v39
	v_lshlrev_b32_e32 v41, 23, v41
	v_or_b32_e32 v19, v40, v19
	v_lshrrev_b32_e32 v40, 9, v43
	v_sub_u32_e32 v39, v39, v41
	v_or_b32_e32 v39, v40, v39
	v_mul_f32_e32 v40, 0x3fc90fda, v39
	v_fma_f32 v41, v39, s0, -v40
	v_fmac_f32_e32 v41, 0x33a22168, v39
	v_fmac_f32_e32 v41, 0x3fc90fda, v19
	v_lshrrev_b32_e32 v2, 30, v2
	v_add_f32_e32 v40, v40, v41
	v_add_u32_e32 v39, v47, v2
	s_branch .LBB0_65
.Lsl_69:
	v_lshrrev_b32_e32 v2, 23, v19
	v_add_u32_e32 v2, 0xffffff88, v2
	v_cmp_lt_u32_e32 vcc, 63, v2
	s_nop 1
	v_cndmask_b32_e32 v41, 0, v145, vcc
	v_add_u32_e32 v2, v41, v2
	v_cmp_lt_u32_e64 s[2:3], 31, v2
	s_nop 1
	v_cndmask_b32_e64 v41, 0, v146, s[2:3]
	v_add_u32_e32 v2, v41, v2
	v_cmp_lt_u32_e64 s[4:5], 31, v2
	s_nop 1
	v_cndmask_b32_e64 v41, 0, v146, s[4:5]
	v_add_u32_e32 v2, v41, v2
	v_and_b32_e32 v41, 0x7fffff, v19
	v_or_b32_e32 v41, 0x800000, v41
	v_mad_u64_u32 v[42:43], s[6:7], v41, s61, 0
	v_mov_b32_e32 v80, v43
	v_mad_u64_u32 v[44:45], s[6:7], v41, s62, v[80:81]
	v_mov_b32_e32 v80, v45
	v_mad_u64_u32 v[46:47], s[6:7], v41, s63, v[80:81]
	v_mov_b32_e32 v80, v47
	v_mad_u64_u32 v[52:53], s[6:7], v41, s72, v[80:81]
	v_mov_b32_e32 v80, v53
	v_mad_u64_u32 v[54:55], s[6:7], v41, s73, v[80:81]
	v_mov_b32_e32 v80, v55
	v_mad_u64_u32 v[56:57], s[6:7], v41, s74, v[80:81]
	v_mov_b32_e32 v80, v57
	v_mad_u64_u32 v[58:59], s[6:7], v41, s75, v[80:81]
	v_cndmask_b32_e32 v43, v56, v52, vcc
	v_cndmask_b32_e32 v41, v58, v54, vcc
	v_cndmask_b32_e32 v47, v59, v56, vcc
	v_cndmask_b32_e64 v45, v41, v43, s[2:3]
	v_cndmask_b32_e64 v41, v47, v41, s[2:3]
	v_cndmask_b32_e32 v47, v54, v46, vcc
	v_cndmask_b32_e64 v43, v43, v47, s[2:3]
	v_cndmask_b32_e64 v41, v41, v45, s[4:5]
	v_cndmask_b32_e64 v45, v45, v43, s[4:5]
	v_sub_u32_e32 v51, 32, v2
	v_alignbit_b32 v53, v41, v45, v51
	v_cmp_eq_u32_e64 s[6:7], 0, v2
	v_cndmask_b32_e32 v42, v46, v42, vcc
	s_nop 0
	v_cndmask_b32_e64 v2, v53, v41, s[6:7]
	v_cndmask_b32_e32 v41, v52, v44, vcc
	v_cndmask_b32_e64 v44, v47, v41, s[2:3]
	v_cndmask_b32_e64 v43, v43, v44, s[4:5]
	v_alignbit_b32 v47, v45, v43, v51
	v_cndmask_b32_e64 v45, v47, v45, s[6:7]
	v_bfe_u32 v53, v2, 29, 1
	v_cndmask_b32_e64 v41, v41, v42, s[2:3]
	v_alignbit_b32 v47, v2, v45, 30
	v_sub_u32_e32 v54, 0, v53
	v_cndmask_b32_e64 v41, v44, v41, s[4:5]
	v_xor_b32_e32 v47, v47, v54
	v_alignbit_b32 v42, v43, v41, v51
	v_cndmask_b32_e64 v42, v42, v43, s[6:7]
	v_ffbh_u32_e32 v44, v47
	v_alignbit_b32 v43, v45, v42, 30
	v_min_u32_e32 v44, 32, v44
	v_alignbit_b32 v41, v42, v41, 30
	v_xor_b32_e32 v43, v43, v54
	v_sub_u32_e32 v45, 31, v44
	v_xor_b32_e32 v41, v41, v54
	v_alignbit_b32 v46, v47, v43, v45
	v_alignbit_b32 v41, v43, v41, v45
	v_alignbit_b32 v42, v46, v41, 9
	v_ffbh_u32_e32 v43, v42
	v_min_u32_e32 v43, 32, v43
	v_lshrrev_b32_e32 v52, 29, v2
	v_not_b32_e32 v45, v43
	v_alignbit_b32 v41, v42, v41, v45
	v_lshlrev_b32_e32 v42, 31, v52
	v_or_b32_e32 v45, 0x33000000, v42
	v_add_lshl_u32 v43, v43, v44, 23
	v_lshrrev_b32_e32 v41, 9, v41
	v_sub_u32_e32 v43, v45, v43
	v_or_b32_e32 v42, 0.5, v42
	v_lshlrev_b32_e32 v44, 23, v44
	v_or_b32_e32 v41, v43, v41
	v_lshrrev_b32_e32 v43, 9, v46
	v_sub_u32_e32 v42, v42, v44
	v_or_b32_e32 v42, v43, v42
	v_mul_f32_e32 v43, 0x3fc90fda, v42
	v_fma_f32 v44, v42, s0, -v43
	v_fmac_f32_e32 v44, 0x33a22168, v42
	v_fmac_f32_e32 v44, 0x3fc90fda, v41
	v_lshrrev_b32_e32 v2, 30, v2
	v_add_f32_e32 v52, v43, v44
	v_add_u32_e32 v51, v53, v2
	s_branch .LBB0_69
; __device__ __forceinline__ int crow16(int r, int hi) { return (r & 3) + 8 * (r >> 2) + 4 * hi; }
; __device__ __forceinline__ void filter_item32(const Args& a, int L, bf16* KR, int t0, int np0, int npn, int lane) {
;     ...
;         for (int r = 0; r < 16; ++r) { const int j = crow16(r, hi); h0[r] = sinf(fq[j] * (h0[r] + b1[j])); h1[r] = sinf(fq[32 + j] * (h1[r] + b1[32 + j])); }
.Lsl_73:
	v_lshrrev_b32_e32 v2, 23, v42
	v_add_u32_e32 v2, 0xffffff88, v2
	v_cmp_lt_u32_e32 vcc, 63, v2
	s_nop 1
	v_cndmask_b32_e32 v20, 0, v145, vcc
	v_add_u32_e32 v2, v20, v2
	v_cmp_lt_u32_e64 s[2:3], 31, v2
	s_nop 1
	v_cndmask_b32_e64 v20, 0, v146, s[2:3]
	v_add_u32_e32 v2, v20, v2
	v_cmp_lt_u32_e64 s[4:5], 31, v2
	s_nop 1
	v_cndmask_b32_e64 v20, 0, v146, s[4:5]
	v_add_u32_e32 v2, v20, v2
	v_and_b32_e32 v20, 0x7fffff, v42
	v_or_b32_e32 v20, 0x800000, v20
	v_mad_u64_u32 v[44:45], s[6:7], v20, s61, 0
	v_mov_b32_e32 v80, v45
	v_mad_u64_u32 v[46:47], s[6:7], v20, s62, v[80:81]
	v_mov_b32_e32 v80, v47
	v_mad_u64_u32 v[54:55], s[6:7], v20, s63, v[80:81]
	v_mov_b32_e32 v80, v55
	v_mad_u64_u32 v[56:57], s[6:7], v20, s72, v[80:81]
	v_mov_b32_e32 v80, v57
	v_mad_u64_u32 v[58:59], s[6:7], v20, s73, v[80:81]
	v_mov_b32_e32 v80, v59
	v_mad_u64_u32 v[60:61], s[6:7], v20, s74, v[80:81]
	v_mov_b32_e32 v80, v61
	v_mad_u64_u32 v[62:63], s[6:7], v20, s75, v[80:81]
	v_cndmask_b32_e32 v43, v60, v56, vcc
	v_cndmask_b32_e32 v20, v62, v58, vcc
	v_cndmask_b32_e32 v47, v63, v60, vcc
	v_cndmask_b32_e64 v45, v20, v43, s[2:3]
	v_cndmask_b32_e64 v20, v47, v20, s[2:3]
	v_cndmask_b32_e32 v47, v58, v54, vcc
	v_cndmask_b32_e64 v43, v43, v47, s[2:3]
	v_cndmask_b32_e64 v20, v20, v45, s[4:5]
	v_cndmask_b32_e64 v45, v45, v43, s[4:5]
	v_sub_u32_e32 v53, 32, v2
	v_alignbit_b32 v55, v20, v45, v53
	v_cmp_eq_u32_e64 s[6:7], 0, v2
	v_cndmask_b32_e32 v44, v54, v44, vcc
	s_nop 0
	v_cndmask_b32_e64 v2, v55, v20, s[6:7]
	v_cndmask_b32_e32 v20, v56, v46, vcc
	v_cndmask_b32_e64 v46, v47, v20, s[2:3]
	v_cndmask_b32_e64 v43, v43, v46, s[4:5]
	v_alignbit_b32 v47, v45, v43, v53
	v_cndmask_b32_e64 v20, v20, v44, s[2:3]
	v_cndmask_b32_e64 v45, v47, v45, s[6:7]
	v_bfe_u32 v56, v2, 29, 1
	v_cndmask_b32_e64 v20, v46, v20, s[4:5]
	v_alignbit_b32 v47, v2, v45, 30
	v_sub_u32_e32 v57, 0, v56
	v_alignbit_b32 v44, v43, v20, v53
	v_xor_b32_e32 v47, v47, v57
	v_cndmask_b32_e64 v43, v44, v43, s[6:7]
	v_alignbit_b32 v44, v45, v43, 30
	v_ffbh_u32_e32 v45, v47
	v_min_u32_e32 v45, 32, v45
	v_alignbit_b32 v20, v43, v20, 30
	v_xor_b32_e32 v44, v44, v57
	v_sub_u32_e32 v46, 31, v45
	v_xor_b32_e32 v20, v20, v57
	v_alignbit_b32 v47, v47, v44, v46
	v_alignbit_b32 v20, v44, v20, v46
	v_alignbit_b32 v43, v47, v20, 9
	v_ffbh_u32_e32 v44, v43
	v_min_u32_e32 v44, 32, v44
	v_lshrrev_b32_e32 v55, 29, v2
	v_not_b32_e32 v46, v44
	v_alignbit_b32 v20, v43, v20, v46
	v_lshlrev_b32_e32 v43, 31, v55
	v_or_b32_e32 v46, 0x33000000, v43
	v_add_lshl_u32 v44, v44, v45, 23
	v_lshrrev_b32_e32 v20, 9, v20
	v_sub_u32_e32 v44, v46, v44
	v_or_b32_e32 v43, 0.5, v43
	v_lshlrev_b32_e32 v45, 23, v45
	v_or_b32_e32 v20, v44, v20
	v_lshrrev_b32_e32 v44, 9, v47
	v_sub_u32_e32 v43, v43, v45
	v_or_b32_e32 v43, v44, v43
	v_mul_f32_e32 v44, 0x3fc90fda, v43
	v_fma_f32 v45, v43, s0, -v44
	v_fmac_f32_e32 v45, 0x33a22168, v43
	v_fmac_f32_e32 v45, 0x3fc90fda, v20
	v_lshrrev_b32_e32 v2, 30, v2
	v_add_f32_e32 v44, v44, v45
	v_add_u32_e32 v43, v56, v2
	s_branch .LBB0_73
.Lsl_77:
	v_lshrrev_b32_e32 v2, 23, v20
	v_add_u32_e32 v2, 0xffffff88, v2
	v_cmp_lt_u32_e32 vcc, 63, v2
	s_nop 1
	v_cndmask_b32_e32 v45, 0, v145, vcc
	v_add_u32_e32 v2, v45, v2
	v_cmp_lt_u32_e64 s[2:3], 31, v2
	s_nop 1
	v_cndmask_b32_e64 v45, 0, v146, s[2:3]
	v_add_u32_e32 v2, v45, v2
	v_cmp_lt_u32_e64 s[4:5], 31, v2
	s_nop 1
	v_cndmask_b32_e64 v45, 0, v146, s[4:5]
	v_add_u32_e32 v2, v45, v2
	v_and_b32_e32 v45, 0x7fffff, v20
	v_or_b32_e32 v45, 0x800000, v45
	v_mad_u64_u32 v[46:47], s[6:7], v45, s61, 0
	v_mov_b32_e32 v80, v47
	v_mad_u64_u32 v[54:55], s[6:7], v45, s62, v[80:81]
	v_mov_b32_e32 v80, v55
	v_mad_u64_u32 v[56:57], s[6:7], v45, s63, v[80:81]
	v_mov_b32_e32 v80, v57
	v_mad_u64_u32 v[58:59], s[6:7], v45, s72, v[80:81]
	v_mov_b32_e32 v80, v59
	v_mad_u64_u32 v[60:61], s[6:7], v45, s73, v[80:81]
	v_mov_b32_e32 v80, v61
	v_mad_u64_u32 v[62:63], s[6:7], v45, s74, v[80:81]
	v_mov_b32_e32 v80, v63
	v_mad_u64_u32 v[72:73], s[6:7], v45, s75, v[80:81]
	v_cndmask_b32_e32 v47, v62, v58, vcc
	v_cndmask_b32_e32 v45, v72, v60, vcc
	v_cndmask_b32_e32 v55, v73, v62, vcc
	v_cndmask_b32_e64 v53, v45, v47, s[2:3]
	v_cndmask_b32_e64 v45, v55, v45, s[2:3]
	v_cndmask_b32_e32 v55, v60, v56, vcc
	v_cndmask_b32_e64 v47, v47, v55, s[2:3]
	v_cndmask_b32_e64 v45, v45, v53, s[4:5]
	v_cndmask_b32_e64 v53, v53, v47, s[4:5]
	v_sub_u32_e32 v57, 32, v2
	v_alignbit_b32 v59, v45, v53, v57
	v_cmp_eq_u32_e64 s[6:7], 0, v2
	v_cndmask_b32_e32 v46, v56, v46, vcc
	s_nop 0
	v_cndmask_b32_e64 v2, v59, v45, s[6:7]
	v_cndmask_b32_e32 v45, v58, v54, vcc
	v_cndmask_b32_e64 v54, v55, v45, s[2:3]
	v_cndmask_b32_e64 v47, v47, v54, s[4:5]
	v_alignbit_b32 v55, v53, v47, v57
	v_cndmask_b32_e64 v45, v45, v46, s[2:3]
	v_cndmask_b32_e64 v53, v55, v53, s[6:7]
	v_bfe_u32 v59, v2, 29, 1
	v_cndmask_b32_e64 v45, v54, v45, s[4:5]
	v_alignbit_b32 v55, v2, v53, 30
	v_sub_u32_e32 v60, 0, v59
	v_alignbit_b32 v46, v47, v45, v57
	v_xor_b32_e32 v55, v55, v60
	v_cndmask_b32_e64 v46, v46, v47, s[6:7]
	v_alignbit_b32 v47, v53, v46, 30
	v_ffbh_u32_e32 v53, v55
	v_min_u32_e32 v53, 32, v53
	v_alignbit_b32 v45, v46, v45, 30
	v_xor_b32_e32 v47, v47, v60
	v_sub_u32_e32 v54, 31, v53
	v_xor_b32_e32 v45, v45, v60
	v_alignbit_b32 v55, v55, v47, v54
	v_alignbit_b32 v45, v47, v45, v54
	v_alignbit_b32 v46, v55, v45, 9
	v_ffbh_u32_e32 v47, v46
	v_min_u32_e32 v47, 32, v47
	v_lshrrev_b32_e32 v58, 29, v2
	v_not_b32_e32 v54, v47
	v_alignbit_b32 v45, v46, v45, v54
	v_lshlrev_b32_e32 v46, 31, v58
	v_or_b32_e32 v54, 0x33000000, v46
	v_add_lshl_u32 v47, v47, v53, 23
	v_lshrrev_b32_e32 v45, 9, v45
	v_sub_u32_e32 v47, v54, v47
	v_or_b32_e32 v46, 0.5, v46
	v_lshlrev_b32_e32 v53, 23, v53
	v_or_b32_e32 v45, v47, v45
	v_lshrrev_b32_e32 v47, 9, v55
	v_sub_u32_e32 v46, v46, v53
	v_or_b32_e32 v46, v47, v46
	v_mul_f32_e32 v47, 0x3fc90fda, v46
	v_fma_f32 v53, v46, s0, -v47
	v_fmac_f32_e32 v53, 0x33a22168, v46
	v_fmac_f32_e32 v53, 0x3fc90fda, v45
	v_lshrrev_b32_e32 v2, 30, v2
	v_add_f32_e32 v54, v47, v53
	v_add_u32_e32 v53, v59, v2
	s_branch .LBB0_77
; __device__ __forceinline__ int crow16(int r, int hi) { return (r & 3) + 8 * (r >> 2) + 4 * hi; }
; __device__ __forceinline__ void filter_item32(const Args& a, int L, bf16* KR, int t0, int np0, int npn, int lane) {
;     ...
;         for (int r = 0; r < 16; ++r) { const int j = crow16(r, hi); h0[r] = sinf(fq[j] * (h0[r] + b1[j])); h1[r] = sinf(fq[32 + j] * (h1[r] + b1[32 + j])); }
.Lsl_81:
	v_lshrrev_b32_e32 v2, 23, v46
	v_add_u32_e32 v2, 0xffffff88, v2
	v_cmp_lt_u32_e32 vcc, 63, v2
	s_nop 1
	v_cndmask_b32_e32 v21, 0, v145, vcc
	v_add_u32_e32 v2, v21, v2
	v_cmp_lt_u32_e64 s[2:3], 31, v2
	s_nop 1
	v_cndmask_b32_e64 v21, 0, v146, s[2:3]
	v_add_u32_e32 v2, v21, v2
	v_cmp_lt_u32_e64 s[4:5], 31, v2
	s_nop 1
	v_cndmask_b32_e64 v21, 0, v146, s[4:5]
	v_add_u32_e32 v2, v21, v2
	v_and_b32_e32 v21, 0x7fffff, v46
	v_or_b32_e32 v21, 0x800000, v21
	v_mad_u64_u32 v[56:57], s[6:7], v21, s61, 0
	v_mov_b32_e32 v80, v57
	v_mad_u64_u32 v[58:59], s[6:7], v21, s62, v[80:81]
	v_mov_b32_e32 v80, v59
	v_mad_u64_u32 v[60:61], s[6:7], v21, s63, v[80:81]
	v_mov_b32_e32 v80, v61
	v_mad_u64_u32 v[62:63], s[6:7], v21, s72, v[80:81]
	v_mov_b32_e32 v80, v63
	v_mad_u64_u32 v[72:73], s[6:7], v21, s73, v[80:81]
	v_mov_b32_e32 v80, v73
	v_mad_u64_u32 v[74:75], s[6:7], v21, s74, v[80:81]
	v_mov_b32_e32 v80, v75
	v_mad_u64_u32 v[76:77], s[6:7], v21, s75, v[80:81]
	v_cndmask_b32_e32 v47, v74, v62, vcc
	v_cndmask_b32_e32 v21, v76, v72, vcc
	v_cndmask_b32_e32 v57, v77, v74, vcc
	v_cndmask_b32_e64 v55, v21, v47, s[2:3]
	v_cndmask_b32_e64 v21, v57, v21, s[2:3]
	v_cndmask_b32_e32 v57, v72, v60, vcc
	v_cndmask_b32_e64 v47, v47, v57, s[2:3]
	v_cndmask_b32_e64 v21, v21, v55, s[4:5]
	v_cndmask_b32_e64 v55, v55, v47, s[4:5]
	v_sub_u32_e32 v59, 32, v2
	v_alignbit_b32 v61, v21, v55, v59
	v_cmp_eq_u32_e64 s[6:7], 0, v2
	v_cndmask_b32_e32 v56, v60, v56, vcc
	s_nop 0
	v_cndmask_b32_e64 v2, v61, v21, s[6:7]
	v_cndmask_b32_e32 v21, v62, v58, vcc
	v_cndmask_b32_e64 v57, v57, v21, s[2:3]
	v_cndmask_b32_e64 v47, v47, v57, s[4:5]
	v_alignbit_b32 v58, v55, v47, v59
	v_cndmask_b32_e64 v55, v58, v55, s[6:7]
	v_bfe_u32 v62, v2, 29, 1
	v_cndmask_b32_e64 v21, v21, v56, s[2:3]
	v_alignbit_b32 v58, v2, v55, 30
	v_sub_u32_e32 v63, 0, v62
	v_cndmask_b32_e64 v21, v57, v21, s[4:5]
	v_xor_b32_e32 v58, v58, v63
	v_alignbit_b32 v56, v47, v21, v59
	v_cndmask_b32_e64 v47, v56, v47, s[6:7]
	v_ffbh_u32_e32 v56, v58
	v_alignbit_b32 v55, v55, v47, 30
	v_min_u32_e32 v56, 32, v56
	v_alignbit_b32 v21, v47, v21, 30
	v_xor_b32_e32 v55, v55, v63
	v_sub_u32_e32 v57, 31, v56
	v_xor_b32_e32 v21, v21, v63
	v_alignbit_b32 v58, v58, v55, v57
	v_alignbit_b32 v21, v55, v21, v57
	v_alignbit_b32 v47, v58, v21, 9
	v_ffbh_u32_e32 v55, v47
	v_min_u32_e32 v55, 32, v55
	v_lshrrev_b32_e32 v61, 29, v2
	v_not_b32_e32 v57, v55
	v_alignbit_b32 v21, v47, v21, v57
	v_lshlrev_b32_e32 v47, 31, v61
	v_or_b32_e32 v57, 0x33000000, v47
	v_add_lshl_u32 v55, v55, v56, 23
	v_lshrrev_b32_e32 v21, 9, v21
	v_sub_u32_e32 v55, v57, v55
	v_or_b32_e32 v47, 0.5, v47
	v_lshlrev_b32_e32 v56, 23, v56
	v_or_b32_e32 v21, v55, v21
	v_lshrrev_b32_e32 v55, 9, v58
	v_sub_u32_e32 v47, v47, v56
	v_or_b32_e32 v47, v55, v47
	v_mul_f32_e32 v55, 0x3fc90fda, v47
	v_fma_f32 v56, v47, s0, -v55
	v_fmac_f32_e32 v56, 0x33a22168, v47
	v_fmac_f32_e32 v56, 0x3fc90fda, v21
	v_lshrrev_b32_e32 v2, 30, v2
	v_add_f32_e32 v57, v55, v56
	v_add_u32_e32 v47, v62, v2
	s_branch .LBB0_81
.Lsl_85:
	v_lshrrev_b32_e32 v2, 23, v21
	v_add_u32_e32 v2, 0xffffff88, v2
	v_cmp_lt_u32_e32 vcc, 63, v2
	s_nop 1
	v_cndmask_b32_e32 v55, 0, v145, vcc
	v_add_u32_e32 v2, v55, v2
	v_cmp_lt_u32_e64 s[2:3], 31, v2
	s_nop 1
	v_cndmask_b32_e64 v55, 0, v146, s[2:3]
	v_add_u32_e32 v2, v55, v2
	v_cmp_lt_u32_e64 s[4:5], 31, v2
	s_nop 1
	v_cndmask_b32_e64 v55, 0, v146, s[4:5]
	v_add_u32_e32 v2, v55, v2
	v_and_b32_e32 v55, 0x7fffff, v21
	v_or_b32_e32 v55, 0x800000, v55
	v_mad_u64_u32 v[58:59], s[6:7], v55, s61, 0
	v_mov_b32_e32 v80, v59
	v_mad_u64_u32 v[60:61], s[6:7], v55, s62, v[80:81]
	v_mov_b32_e32 v80, v61
	v_mad_u64_u32 v[62:63], s[6:7], v55, s63, v[80:81]
	v_mov_b32_e32 v80, v63
	v_mad_u64_u32 v[74:75], s[6:7], v55, s72, v[80:81]
	v_mov_b32_e32 v80, v75
	v_mad_u64_u32 v[76:77], s[6:7], v55, s73, v[80:81]
	v_mov_b32_e32 v80, v77
	v_mad_u64_u32 v[78:79], s[6:7], v55, s74, v[80:81]
	v_mov_b32_e32 v80, v79
	v_mad_u64_u32 v[112:113], s[6:7], v55, s75, v[80:81]
	v_cndmask_b32_e32 v56, v78, v74, vcc
	v_cndmask_b32_e32 v55, v112, v76, vcc
	v_cndmask_b32_e32 v61, v113, v78, vcc
	v_cndmask_b32_e64 v59, v55, v56, s[2:3]
	v_cndmask_b32_e64 v55, v61, v55, s[2:3]
	v_cndmask_b32_e32 v61, v76, v62, vcc
	v_cndmask_b32_e64 v56, v56, v61, s[2:3]
	v_cndmask_b32_e64 v55, v55, v59, s[4:5]
	v_cndmask_b32_e64 v59, v59, v56, s[4:5]
	v_sub_u32_e32 v63, 32, v2
	v_alignbit_b32 v73, v55, v59, v63
	v_cmp_eq_u32_e64 s[6:7], 0, v2
	v_cndmask_b32_e32 v58, v62, v58, vcc
	s_nop 0
	v_cndmask_b32_e64 v2, v73, v55, s[6:7]
	v_cndmask_b32_e32 v55, v74, v60, vcc
	v_cndmask_b32_e64 v60, v61, v55, s[2:3]
	v_cndmask_b32_e64 v56, v56, v60, s[4:5]
	v_alignbit_b32 v61, v59, v56, v63
	v_cndmask_b32_e64 v55, v55, v58, s[2:3]
	v_cndmask_b32_e64 v59, v61, v59, s[6:7]
	v_bfe_u32 v74, v2, 29, 1
	v_cndmask_b32_e64 v55, v60, v55, s[4:5]
	v_alignbit_b32 v61, v2, v59, 30
	v_sub_u32_e32 v75, 0, v74
	v_alignbit_b32 v58, v56, v55, v63
	v_xor_b32_e32 v61, v61, v75
	v_cndmask_b32_e64 v56, v58, v56, s[6:7]
	v_alignbit_b32 v58, v59, v56, 30
	v_ffbh_u32_e32 v59, v61
	v_min_u32_e32 v59, 32, v59
	v_alignbit_b32 v55, v56, v55, 30
	v_xor_b32_e32 v58, v58, v75
	v_sub_u32_e32 v60, 31, v59
	v_xor_b32_e32 v55, v55, v75
	v_alignbit_b32 v61, v61, v58, v60
	v_alignbit_b32 v55, v58, v55, v60
	v_alignbit_b32 v56, v61, v55, 9
	v_ffbh_u32_e32 v58, v56
	v_min_u32_e32 v58, 32, v58
	v_lshrrev_b32_e32 v73, 29, v2
	v_not_b32_e32 v60, v58
	v_alignbit_b32 v55, v56, v55, v60
	v_lshlrev_b32_e32 v56, 31, v73
	v_or_b32_e32 v60, 0x33000000, v56
	v_add_lshl_u32 v58, v58, v59, 23
	v_lshrrev_b32_e32 v55, 9, v55
	v_sub_u32_e32 v58, v60, v58
	v_or_b32_e32 v56, 0.5, v56
	v_lshlrev_b32_e32 v59, 23, v59
	v_or_b32_e32 v55, v58, v55
	v_lshrrev_b32_e32 v58, 9, v61
	v_sub_u32_e32 v56, v56, v59
	v_or_b32_e32 v56, v58, v56
	v_mul_f32_e32 v58, 0x3fc90fda, v56
	v_fma_f32 v59, v56, s0, -v58
	v_fmac_f32_e32 v59, 0x33a22168, v56
	v_fmac_f32_e32 v59, 0x3fc90fda, v55
	v_lshrrev_b32_e32 v2, 30, v2
	v_add_f32_e32 v56, v58, v59
	v_add_u32_e32 v55, v74, v2
	s_branch .LBB0_85
; __device__ __forceinline__ int crow16(int r, int hi) { return (r & 3) + 8 * (r >> 2) + 4 * hi; }
; __device__ __forceinline__ void filter_item32(const Args& a, int L, bf16* KR, int t0, int np0, int npn, int lane) {
;     ...
;         for (int r = 0; r < 16; ++r) { const int j = crow16(r, hi); h0[r] = sinf(fq[j] * (h0[r] + b1[j])); h1[r] = sinf(fq[32 + j] * (h1[r] + b1[32 + j])); }
.Lsl_89:
	v_lshrrev_b32_e32 v2, 23, v61
	v_add_u32_e32 v2, 0xffffff88, v2
	v_cmp_lt_u32_e32 vcc, 63, v2
	s_nop 1
	v_cndmask_b32_e32 v22, 0, v145, vcc
	v_add_u32_e32 v2, v22, v2
	v_cmp_lt_u32_e64 s[2:3], 31, v2
	s_nop 1
	v_cndmask_b32_e64 v22, 0, v146, s[2:3]
	v_add_u32_e32 v2, v22, v2
	v_cmp_lt_u32_e64 s[4:5], 31, v2
	s_nop 1
	v_cndmask_b32_e64 v22, 0, v146, s[4:5]
	v_add_u32_e32 v2, v22, v2
	v_and_b32_e32 v22, 0x7fffff, v61
	v_or_b32_e32 v22, 0x800000, v22
	v_mad_u64_u32 v[58:59], s[6:7], v22, s61, 0
	v_mov_b32_e32 v80, v59
	v_mad_u64_u32 v[62:63], s[6:7], v22, s62, v[80:81]
	v_mov_b32_e32 v80, v63
	v_mad_u64_u32 v[74:75], s[6:7], v22, s63, v[80:81]
	v_mov_b32_e32 v80, v75
	v_mad_u64_u32 v[76:77], s[6:7], v22, s72, v[80:81]
	v_mov_b32_e32 v80, v77
	v_mad_u64_u32 v[78:79], s[6:7], v22, s73, v[80:81]
	v_mov_b32_e32 v80, v79
	v_mad_u64_u32 v[112:113], s[6:7], v22, s74, v[80:81]
	v_mov_b32_e32 v80, v113
	v_mad_u64_u32 v[114:115], s[6:7], v22, s75, v[80:81]
	v_cndmask_b32_e32 v59, v112, v76, vcc
	v_cndmask_b32_e32 v22, v114, v78, vcc
	v_cndmask_b32_e32 v75, v115, v112, vcc
	v_cndmask_b32_e64 v63, v22, v59, s[2:3]
	v_cndmask_b32_e64 v22, v75, v22, s[2:3]
	v_cndmask_b32_e32 v75, v78, v74, vcc
	v_cndmask_b32_e64 v59, v59, v75, s[2:3]
	v_cndmask_b32_e64 v22, v22, v63, s[4:5]
	v_cndmask_b32_e64 v63, v63, v59, s[4:5]
	v_sub_u32_e32 v77, 32, v2
	v_alignbit_b32 v78, v22, v63, v77
	v_cmp_eq_u32_e64 s[6:7], 0, v2
	v_cndmask_b32_e32 v58, v74, v58, vcc
	s_nop 0
	v_cndmask_b32_e64 v2, v78, v22, s[6:7]
	v_cndmask_b32_e32 v22, v76, v62, vcc
	v_cndmask_b32_e64 v62, v75, v22, s[2:3]
	v_cndmask_b32_e64 v59, v59, v62, s[4:5]
	v_alignbit_b32 v75, v63, v59, v77
	v_cndmask_b32_e64 v63, v75, v63, s[6:7]
	v_bfe_u32 v78, v2, 29, 1
	v_cndmask_b32_e64 v22, v22, v58, s[2:3]
	v_alignbit_b32 v75, v2, v63, 30
	v_sub_u32_e32 v79, 0, v78
	v_cndmask_b32_e64 v22, v62, v22, s[4:5]
	v_xor_b32_e32 v75, v75, v79
	v_alignbit_b32 v58, v59, v22, v77
	v_cndmask_b32_e64 v58, v58, v59, s[6:7]
	v_ffbh_u32_e32 v62, v75
	v_alignbit_b32 v59, v63, v58, 30
	v_min_u32_e32 v62, 32, v62
	v_alignbit_b32 v22, v58, v22, 30
	v_xor_b32_e32 v59, v59, v79
	v_sub_u32_e32 v63, 31, v62
	v_xor_b32_e32 v22, v22, v79
	v_alignbit_b32 v74, v75, v59, v63
	v_alignbit_b32 v22, v59, v22, v63
	v_alignbit_b32 v58, v74, v22, 9
	v_ffbh_u32_e32 v59, v58
	v_min_u32_e32 v59, 32, v59
	v_lshrrev_b32_e32 v76, 29, v2
	v_not_b32_e32 v63, v59
	v_alignbit_b32 v22, v58, v22, v63
	v_lshlrev_b32_e32 v58, 31, v76
	v_or_b32_e32 v63, 0x33000000, v58
	v_add_lshl_u32 v59, v59, v62, 23
	v_lshrrev_b32_e32 v22, 9, v22
	v_sub_u32_e32 v59, v63, v59
	v_or_b32_e32 v58, 0.5, v58
	v_lshlrev_b32_e32 v62, 23, v62
	v_or_b32_e32 v22, v59, v22
	v_lshrrev_b32_e32 v59, 9, v74
	v_sub_u32_e32 v58, v58, v62
	v_or_b32_e32 v58, v59, v58
	v_mul_f32_e32 v59, 0x3fc90fda, v58
	v_fma_f32 v62, v58, s0, -v59
	v_fmac_f32_e32 v62, 0x33a22168, v58
	v_fmac_f32_e32 v62, 0x3fc90fda, v22
	v_lshrrev_b32_e32 v2, 30, v2
	v_add_f32_e32 v63, v59, v62
	v_add_u32_e32 v62, v78, v2
	s_branch .LBB0_89
.Lsl_93:
	v_lshrrev_b32_e32 v2, 23, v22
	v_add_u32_e32 v2, 0xffffff88, v2
	v_cmp_lt_u32_e32 vcc, 63, v2
	s_nop 1
	v_cndmask_b32_e32 v58, 0, v145, vcc
	v_add_u32_e32 v2, v58, v2
	v_cmp_lt_u32_e64 s[2:3], 31, v2
	s_nop 1
	v_cndmask_b32_e64 v58, 0, v146, s[2:3]
	v_add_u32_e32 v2, v58, v2
	v_cmp_lt_u32_e64 s[4:5], 31, v2
	s_nop 1
	v_cndmask_b32_e64 v58, 0, v146, s[4:5]
	v_add_u32_e32 v2, v58, v2
	v_and_b32_e32 v58, 0x7fffff, v22
	v_or_b32_e32 v75, 0x800000, v58
	v_mad_u64_u32 v[58:59], s[6:7], v75, s61, 0
	v_mov_b32_e32 v80, v59
	v_mad_u64_u32 v[76:77], s[6:7], v75, s62, v[80:81]
	v_mov_b32_e32 v80, v77
	v_mad_u64_u32 v[78:79], s[6:7], v75, s63, v[80:81]
	v_mov_b32_e32 v80, v79
	v_mad_u64_u32 v[112:113], s[6:7], v75, s72, v[80:81]
	v_mov_b32_e32 v80, v113
	v_mad_u64_u32 v[114:115], s[6:7], v75, s73, v[80:81]
	v_mov_b32_e32 v80, v115
	v_mad_u64_u32 v[116:117], s[6:7], v75, s74, v[80:81]
	v_mov_b32_e32 v80, v117
	v_mad_u64_u32 v[118:119], s[6:7], v75, s75, v[80:81]
	v_cndmask_b32_e32 v59, v116, v112, vcc
	v_cndmask_b32_e32 v75, v118, v114, vcc
	v_cndmask_b32_e32 v79, v119, v116, vcc
	v_cndmask_b32_e64 v77, v75, v59, s[2:3]
	v_cndmask_b32_e64 v75, v79, v75, s[2:3]
	v_cndmask_b32_e32 v79, v114, v78, vcc
	v_cndmask_b32_e64 v59, v59, v79, s[2:3]
	v_cndmask_b32_e64 v75, v75, v77, s[4:5]
	v_cndmask_b32_e64 v77, v77, v59, s[4:5]
	v_sub_u32_e32 v80, 32, v2
	v_alignbit_b32 v113, v75, v77, v80
	v_cmp_eq_u32_e64 s[6:7], 0, v2
	v_cndmask_b32_e32 v58, v78, v58, vcc
	s_nop 0
	v_cndmask_b32_e64 v2, v113, v75, s[6:7]
	v_cndmask_b32_e32 v75, v112, v76, vcc
	v_cndmask_b32_e64 v76, v79, v75, s[2:3]
	v_cndmask_b32_e64 v59, v59, v76, s[4:5]
	v_alignbit_b32 v79, v77, v59, v80
	v_cndmask_b32_e64 v77, v79, v77, s[6:7]
	v_bfe_u32 v113, v2, 29, 1
	v_cndmask_b32_e64 v58, v75, v58, s[2:3]
	v_alignbit_b32 v79, v2, v77, 30
	v_sub_u32_e32 v114, 0, v113
	v_cndmask_b32_e64 v58, v76, v58, s[4:5]
	v_xor_b32_e32 v79, v79, v114
	v_alignbit_b32 v75, v59, v58, v80
	v_cndmask_b32_e64 v59, v75, v59, s[6:7]
	v_ffbh_u32_e32 v76, v79
	v_alignbit_b32 v75, v77, v59, 30
	v_min_u32_e32 v76, 32, v76
	v_alignbit_b32 v58, v59, v58, 30
	v_xor_b32_e32 v75, v75, v114
	v_sub_u32_e32 v77, 31, v76
	v_xor_b32_e32 v58, v58, v114
	v_alignbit_b32 v78, v79, v75, v77
	v_alignbit_b32 v58, v75, v58, v77
	v_alignbit_b32 v59, v78, v58, 9
	v_ffbh_u32_e32 v75, v59
	v_min_u32_e32 v75, 32, v75
	v_lshrrev_b32_e32 v112, 29, v2
	v_not_b32_e32 v77, v75
	v_alignbit_b32 v58, v59, v58, v77
	v_lshlrev_b32_e32 v59, 31, v112
	v_or_b32_e32 v77, 0x33000000, v59
	v_add_lshl_u32 v75, v75, v76, 23
	v_lshrrev_b32_e32 v58, 9, v58
	v_sub_u32_e32 v75, v77, v75
	v_or_b32_e32 v59, 0.5, v59
	v_lshlrev_b32_e32 v76, 23, v76
	v_or_b32_e32 v58, v75, v58
	v_lshrrev_b32_e32 v75, 9, v78
	v_sub_u32_e32 v59, v59, v76
	v_or_b32_e32 v59, v75, v59
	v_mul_f32_e32 v75, 0x3fc90fda, v59
	v_fma_f32 v76, v59, s0, -v75
	v_fmac_f32_e32 v76, 0x33a22168, v59
	v_fmac_f32_e32 v76, 0x3fc90fda, v58
	v_lshrrev_b32_e32 v2, 30, v2
	v_add_f32_e32 v59, v75, v76
	v_add_u32_e32 v58, v113, v2
	s_branch .LBB0_93
; __device__ __forceinline__ int crow16(int r, int hi) { return (r & 3) + 8 * (r >> 2) + 4 * hi; }
; __device__ __forceinline__ void filter_item32(const Args& a, int L, bf16* KR, int t0, int np0, int npn, int lane) {
;     ...
;         for (int r = 0; r < 16; ++r) { const int j = crow16(r, hi); h0[r] = sinf(fq[j] * (h0[r] + b1[j])); h1[r] = sinf(fq[32 + j] * (h1[r] + b1[32 + j])); }
.Lsl_97:
	v_lshrrev_b32_e32 v2, 23, v155
	v_add_u32_e32 v2, 0xffffff88, v2
	v_cmp_lt_u32_e32 vcc, 63, v2
	s_nop 1
	v_cndmask_b32_e32 v23, 0, v145, vcc
	v_add_u32_e32 v2, v23, v2
	v_cmp_lt_u32_e64 s[2:3], 31, v2
	s_nop 1
	v_cndmask_b32_e64 v23, 0, v146, s[2:3]
	v_add_u32_e32 v2, v23, v2
	v_cmp_lt_u32_e64 s[4:5], 31, v2
	s_nop 1
	v_cndmask_b32_e64 v23, 0, v146, s[4:5]
	v_add_u32_e32 v2, v23, v2
	v_and_b32_e32 v23, 0x7fffff, v155
	v_or_b32_e32 v23, 0x800000, v23
	v_mad_u64_u32 v[76:77], s[6:7], v23, s61, 0
	v_mov_b32_e32 v80, v77
	v_mad_u64_u32 v[78:79], s[6:7], v23, s62, v[80:81]
	v_mov_b32_e32 v80, v79
	v_mad_u64_u32 v[112:113], s[6:7], v23, s63, v[80:81]
	v_mov_b32_e32 v80, v113
	v_mad_u64_u32 v[114:115], s[6:7], v23, s72, v[80:81]
	v_mov_b32_e32 v80, v115
	v_mad_u64_u32 v[116:117], s[6:7], v23, s73, v[80:81]
	v_mov_b32_e32 v80, v117
	v_mad_u64_u32 v[118:119], s[6:7], v23, s74, v[80:81]
	v_mov_b32_e32 v80, v119
	v_mad_u64_u32 v[120:121], s[6:7], v23, s75, v[80:81]
	v_cndmask_b32_e32 v77, v118, v114, vcc
	v_cndmask_b32_e32 v23, v120, v116, vcc
	v_cndmask_b32_e32 v80, v121, v118, vcc
	v_cndmask_b32_e64 v79, v23, v77, s[2:3]
	v_cndmask_b32_e64 v23, v80, v23, s[2:3]
	v_cndmask_b32_e32 v80, v116, v112, vcc
	v_cndmask_b32_e64 v77, v77, v80, s[2:3]
	v_cndmask_b32_e64 v23, v23, v79, s[4:5]
	v_cndmask_b32_e64 v79, v79, v77, s[4:5]
	v_sub_u32_e32 v113, 32, v2
	v_alignbit_b32 v115, v23, v79, v113
	v_cmp_eq_u32_e64 s[6:7], 0, v2
	v_cndmask_b32_e32 v76, v112, v76, vcc
	s_nop 0
	v_cndmask_b32_e64 v2, v115, v23, s[6:7]
	v_cndmask_b32_e32 v23, v114, v78, vcc
	v_cndmask_b32_e64 v78, v80, v23, s[2:3]
	v_cndmask_b32_e64 v77, v77, v78, s[4:5]
	v_alignbit_b32 v80, v79, v77, v113
	v_cndmask_b32_e64 v79, v80, v79, s[6:7]
	v_bfe_u32 v115, v2, 29, 1
	v_cndmask_b32_e64 v23, v23, v76, s[2:3]
	v_alignbit_b32 v80, v2, v79, 30
	v_sub_u32_e32 v116, 0, v115
	v_cndmask_b32_e64 v23, v78, v23, s[4:5]
	v_xor_b32_e32 v80, v80, v116
	v_alignbit_b32 v76, v77, v23, v113
	v_cndmask_b32_e64 v76, v76, v77, s[6:7]
	v_ffbh_u32_e32 v78, v80
	v_alignbit_b32 v77, v79, v76, 30
	v_min_u32_e32 v78, 32, v78
	v_alignbit_b32 v23, v76, v23, 30
	v_xor_b32_e32 v77, v77, v116
	v_sub_u32_e32 v79, 31, v78
	v_xor_b32_e32 v23, v23, v116
	v_alignbit_b32 v80, v80, v77, v79
	v_alignbit_b32 v23, v77, v23, v79
	v_alignbit_b32 v76, v80, v23, 9
	v_ffbh_u32_e32 v77, v76
	v_min_u32_e32 v77, 32, v77
	v_lshrrev_b32_e32 v114, 29, v2
	v_not_b32_e32 v79, v77
	v_alignbit_b32 v23, v76, v23, v79
	v_lshlrev_b32_e32 v76, 31, v114
	v_or_b32_e32 v79, 0x33000000, v76
	v_add_lshl_u32 v77, v77, v78, 23
	v_lshrrev_b32_e32 v23, 9, v23
	v_sub_u32_e32 v77, v79, v77
	v_or_b32_e32 v76, 0.5, v76
	v_lshlrev_b32_e32 v78, 23, v78
	v_or_b32_e32 v23, v77, v23
	v_lshrrev_b32_e32 v77, 9, v80
	v_sub_u32_e32 v76, v76, v78
	v_or_b32_e32 v76, v77, v76
	v_mul_f32_e32 v77, 0x3fc90fda, v76
	v_fma_f32 v78, v76, s0, -v77
	v_fmac_f32_e32 v78, 0x33a22168, v76
	v_fmac_f32_e32 v78, 0x3fc90fda, v23
	v_lshrrev_b32_e32 v2, 30, v2
	v_add_f32_e32 v157, v77, v78
	v_add_u32_e32 v156, v115, v2
	s_branch .LBB0_97
.Lsl_101:
	v_lshrrev_b32_e32 v2, 23, v23
	v_add_u32_e32 v2, 0xffffff88, v2
	v_cmp_lt_u32_e32 vcc, 63, v2
	s_nop 1
	v_cndmask_b32_e32 v77, 0, v145, vcc
	v_add_u32_e32 v2, v77, v2
	v_cmp_lt_u32_e64 s[2:3], 31, v2
	s_nop 1
	v_cndmask_b32_e64 v77, 0, v146, s[2:3]
	v_add_u32_e32 v2, v77, v2
	v_cmp_lt_u32_e64 s[4:5], 31, v2
	s_nop 1
	v_cndmask_b32_e64 v77, 0, v146, s[4:5]
	v_add_u32_e32 v2, v77, v2
	v_and_b32_e32 v77, 0x7fffff, v23
	v_or_b32_e32 v77, 0x800000, v77
	v_mad_u64_u32 v[78:79], s[6:7], v77, s61, 0
	v_mov_b32_e32 v80, v79
	v_mad_u64_u32 v[112:113], s[6:7], v77, s62, v[80:81]
	v_mov_b32_e32 v80, v113
	v_mad_u64_u32 v[114:115], s[6:7], v77, s63, v[80:81]
	v_mov_b32_e32 v80, v115
	v_mad_u64_u32 v[116:117], s[6:7], v77, s72, v[80:81]
	v_mov_b32_e32 v80, v117
	v_mad_u64_u32 v[118:119], s[6:7], v77, s73, v[80:81]
	v_mov_b32_e32 v80, v119
	v_mad_u64_u32 v[120:121], s[6:7], v77, s74, v[80:81]
	v_mov_b32_e32 v80, v121
	v_mad_u64_u32 v[122:123], s[6:7], v77, s75, v[80:81]
	v_cndmask_b32_e32 v79, v120, v116, vcc
	v_cndmask_b32_e32 v77, v122, v118, vcc
	v_cndmask_b32_e32 v113, v123, v120, vcc
	v_cndmask_b32_e64 v80, v77, v79, s[2:3]
	v_cndmask_b32_e64 v77, v113, v77, s[2:3]
	v_cndmask_b32_e32 v113, v118, v114, vcc
	v_cndmask_b32_e64 v79, v79, v113, s[2:3]
	v_cndmask_b32_e64 v77, v77, v80, s[4:5]
	v_cndmask_b32_e64 v80, v80, v79, s[4:5]
	v_sub_u32_e32 v115, 32, v2
	v_alignbit_b32 v117, v77, v80, v115
	v_cmp_eq_u32_e64 s[6:7], 0, v2
	v_cndmask_b32_e32 v78, v114, v78, vcc
	s_nop 0
	v_cndmask_b32_e64 v2, v117, v77, s[6:7]
	v_cndmask_b32_e32 v77, v116, v112, vcc
	v_cndmask_b32_e64 v112, v113, v77, s[2:3]
	v_cndmask_b32_e64 v79, v79, v112, s[4:5]
	v_alignbit_b32 v113, v80, v79, v115
	v_cndmask_b32_e64 v77, v77, v78, s[2:3]
	v_cndmask_b32_e64 v80, v113, v80, s[6:7]
	v_bfe_u32 v117, v2, 29, 1
	v_cndmask_b32_e64 v77, v112, v77, s[4:5]
	v_alignbit_b32 v113, v2, v80, 30
	v_sub_u32_e32 v118, 0, v117
	v_alignbit_b32 v78, v79, v77, v115
	v_xor_b32_e32 v113, v113, v118
	v_cndmask_b32_e64 v78, v78, v79, s[6:7]
	v_alignbit_b32 v79, v80, v78, 30
	v_ffbh_u32_e32 v80, v113
	v_min_u32_e32 v80, 32, v80
	v_alignbit_b32 v77, v78, v77, 30
	v_xor_b32_e32 v79, v79, v118
	v_sub_u32_e32 v112, 31, v80
	v_xor_b32_e32 v77, v77, v118
	v_alignbit_b32 v113, v113, v79, v112
	v_alignbit_b32 v77, v79, v77, v112
	v_alignbit_b32 v78, v113, v77, 9
	v_ffbh_u32_e32 v79, v78
	v_min_u32_e32 v79, 32, v79
	v_lshrrev_b32_e32 v116, 29, v2
	v_not_b32_e32 v112, v79
	v_alignbit_b32 v77, v78, v77, v112
	v_lshlrev_b32_e32 v78, 31, v116
	v_or_b32_e32 v112, 0x33000000, v78
	v_add_lshl_u32 v79, v79, v80, 23
	v_lshrrev_b32_e32 v77, 9, v77
	v_sub_u32_e32 v79, v112, v79
	v_or_b32_e32 v78, 0.5, v78
	v_lshlrev_b32_e32 v80, 23, v80
	v_or_b32_e32 v77, v79, v77
	v_lshrrev_b32_e32 v79, 9, v113
	v_sub_u32_e32 v78, v78, v80
	v_or_b32_e32 v78, v79, v78
	v_mul_f32_e32 v79, 0x3fc90fda, v78
	v_fma_f32 v80, v78, s0, -v79
	v_fmac_f32_e32 v80, 0x33a22168, v78
	v_fmac_f32_e32 v80, 0x3fc90fda, v77
	v_lshrrev_b32_e32 v2, 30, v2
	v_add_f32_e32 v153, v79, v80
	v_add_u32_e32 v152, v117, v2
	s_branch .LBB0_101
; __device__ __forceinline__ int crow16(int r, int hi) { return (r & 3) + 8 * (r >> 2) + 4 * hi; }
; __device__ __forceinline__ void filter_item32(const Args& a, int L, bf16* KR, int t0, int np0, int npn, int lane) {
;     ...
;         for (int r = 0; r < 16; ++r) { const int j = crow16(r, hi); h0[r] = sinf(fq[j] * (h0[r] + b1[j])); h1[r] = sinf(fq[32 + j] * (h1[r] + b1[32 + j])); }
.Lsl_105:
	v_lshrrev_b32_e32 v2, 23, v163
	v_add_u32_e32 v2, 0xffffff88, v2
	v_cmp_lt_u32_e32 vcc, 63, v2
	s_nop 1
	v_cndmask_b32_e32 v24, 0, v145, vcc
	v_add_u32_e32 v2, v24, v2
	v_cmp_lt_u32_e64 s[2:3], 31, v2
	s_nop 1
	v_cndmask_b32_e64 v24, 0, v146, s[2:3]
	v_add_u32_e32 v2, v24, v2
	v_cmp_lt_u32_e64 s[4:5], 31, v2
	s_nop 1
	v_cndmask_b32_e64 v24, 0, v146, s[4:5]
	v_add_u32_e32 v2, v24, v2
	v_and_b32_e32 v24, 0x7fffff, v163
	v_or_b32_e32 v24, 0x800000, v24
	v_mad_u64_u32 v[78:79], s[6:7], v24, s61, 0
	v_mov_b32_e32 v80, v79
	v_mad_u64_u32 v[112:113], s[6:7], v24, s62, v[80:81]
	v_mov_b32_e32 v80, v113
	v_mad_u64_u32 v[114:115], s[6:7], v24, s63, v[80:81]
	v_mov_b32_e32 v80, v115
	v_mad_u64_u32 v[116:117], s[6:7], v24, s72, v[80:81]
	v_mov_b32_e32 v80, v117
	v_mad_u64_u32 v[118:119], s[6:7], v24, s73, v[80:81]
	v_mov_b32_e32 v80, v119
	v_mad_u64_u32 v[120:121], s[6:7], v24, s74, v[80:81]
	v_mov_b32_e32 v80, v121
	v_mad_u64_u32 v[122:123], s[6:7], v24, s75, v[80:81]
	v_cndmask_b32_e32 v79, v120, v116, vcc
	v_cndmask_b32_e32 v24, v122, v118, vcc
	v_cndmask_b32_e32 v113, v123, v120, vcc
	v_cndmask_b32_e64 v80, v24, v79, s[2:3]
	v_cndmask_b32_e64 v24, v113, v24, s[2:3]
	v_cndmask_b32_e32 v113, v118, v114, vcc
	v_cndmask_b32_e64 v79, v79, v113, s[2:3]
	v_cndmask_b32_e64 v24, v24, v80, s[4:5]
	v_cndmask_b32_e64 v80, v80, v79, s[4:5]
	v_sub_u32_e32 v115, 32, v2
	v_alignbit_b32 v117, v24, v80, v115
	v_cmp_eq_u32_e64 s[6:7], 0, v2
	v_cndmask_b32_e32 v78, v114, v78, vcc
	s_nop 0
	v_cndmask_b32_e64 v2, v117, v24, s[6:7]
	v_cndmask_b32_e32 v24, v116, v112, vcc
	v_cndmask_b32_e64 v112, v113, v24, s[2:3]
	v_cndmask_b32_e64 v79, v79, v112, s[4:5]
	v_alignbit_b32 v113, v80, v79, v115
	v_cndmask_b32_e64 v24, v24, v78, s[2:3]
	v_cndmask_b32_e64 v80, v113, v80, s[6:7]
	v_bfe_u32 v117, v2, 29, 1
	v_cndmask_b32_e64 v24, v112, v24, s[4:5]
	v_alignbit_b32 v113, v2, v80, 30
	v_sub_u32_e32 v118, 0, v117
	v_alignbit_b32 v78, v79, v24, v115
	v_xor_b32_e32 v113, v113, v118
	v_cndmask_b32_e64 v78, v78, v79, s[6:7]
	v_alignbit_b32 v79, v80, v78, 30
	v_ffbh_u32_e32 v80, v113
	v_min_u32_e32 v80, 32, v80
	v_alignbit_b32 v24, v78, v24, 30
	v_xor_b32_e32 v79, v79, v118
	v_sub_u32_e32 v112, 31, v80
	v_xor_b32_e32 v24, v24, v118
	v_alignbit_b32 v113, v113, v79, v112
	v_alignbit_b32 v24, v79, v24, v112
	v_alignbit_b32 v78, v113, v24, 9
	v_ffbh_u32_e32 v79, v78
	v_min_u32_e32 v79, 32, v79
	v_lshrrev_b32_e32 v116, 29, v2
	v_not_b32_e32 v112, v79
	v_alignbit_b32 v24, v78, v24, v112
	v_lshlrev_b32_e32 v78, 31, v116
	v_or_b32_e32 v112, 0x33000000, v78
	v_add_lshl_u32 v79, v79, v80, 23
	v_lshrrev_b32_e32 v24, 9, v24
	v_sub_u32_e32 v79, v112, v79
	v_or_b32_e32 v78, 0.5, v78
	v_lshlrev_b32_e32 v80, 23, v80
	v_or_b32_e32 v24, v79, v24
	v_lshrrev_b32_e32 v79, 9, v113
	v_sub_u32_e32 v78, v78, v80
	v_or_b32_e32 v78, v79, v78
	v_mul_f32_e32 v79, 0x3fc90fda, v78
	v_fma_f32 v80, v78, s0, -v79
	v_fmac_f32_e32 v80, 0x33a22168, v78
	v_fmac_f32_e32 v80, 0x3fc90fda, v24
	v_lshrrev_b32_e32 v2, 30, v2
	v_add_f32_e32 v165, v79, v80
	v_add_u32_e32 v164, v117, v2
	s_branch .LBB0_105
.Lsl_109:
	v_lshrrev_b32_e32 v2, 23, v24
	v_add_u32_e32 v2, 0xffffff88, v2
	v_cmp_lt_u32_e32 vcc, 63, v2
	s_nop 1
	v_cndmask_b32_e32 v79, 0, v145, vcc
	v_add_u32_e32 v2, v79, v2
	v_cmp_lt_u32_e64 s[2:3], 31, v2
	s_nop 1
	v_cndmask_b32_e64 v79, 0, v146, s[2:3]
	v_add_u32_e32 v2, v79, v2
	v_cmp_lt_u32_e64 s[4:5], 31, v2
	s_nop 1
	v_cndmask_b32_e64 v79, 0, v146, s[4:5]
	v_add_u32_e32 v2, v79, v2
	v_and_b32_e32 v79, 0x7fffff, v24
	v_or_b32_e32 v79, 0x800000, v79
	v_mad_u64_u32 v[112:113], s[6:7], v79, s61, 0
	v_mov_b32_e32 v80, v113
	v_mad_u64_u32 v[114:115], s[6:7], v79, s62, v[80:81]
	v_mov_b32_e32 v80, v115
	v_mad_u64_u32 v[116:117], s[6:7], v79, s63, v[80:81]
	v_mov_b32_e32 v80, v117
	v_mad_u64_u32 v[118:119], s[6:7], v79, s72, v[80:81]
	v_mov_b32_e32 v80, v119
	v_mad_u64_u32 v[120:121], s[6:7], v79, s73, v[80:81]
	v_mov_b32_e32 v80, v121
	v_mad_u64_u32 v[122:123], s[6:7], v79, s74, v[80:81]
	v_mov_b32_e32 v80, v123
	v_mad_u64_u32 v[124:125], s[6:7], v79, s75, v[80:81]
	v_cndmask_b32_e32 v113, v122, v118, vcc
	v_cndmask_b32_e32 v79, v124, v120, vcc
	v_cndmask_b32_e32 v115, v125, v122, vcc
	v_cndmask_b32_e64 v80, v79, v113, s[2:3]
	v_cndmask_b32_e64 v79, v115, v79, s[2:3]
	v_cndmask_b32_e32 v115, v120, v116, vcc
	v_cndmask_b32_e64 v113, v113, v115, s[2:3]
	v_cndmask_b32_e64 v79, v79, v80, s[4:5]
	v_cndmask_b32_e64 v80, v80, v113, s[4:5]
	v_sub_u32_e32 v117, 32, v2
	v_alignbit_b32 v119, v79, v80, v117
	v_cmp_eq_u32_e64 s[6:7], 0, v2
	v_cndmask_b32_e32 v112, v116, v112, vcc
	s_nop 0
	v_cndmask_b32_e64 v2, v119, v79, s[6:7]
	v_cndmask_b32_e32 v79, v118, v114, vcc
	v_cndmask_b32_e64 v114, v115, v79, s[2:3]
	v_cndmask_b32_e64 v113, v113, v114, s[4:5]
	v_alignbit_b32 v115, v80, v113, v117
	v_cndmask_b32_e64 v80, v115, v80, s[6:7]
	v_bfe_u32 v119, v2, 29, 1
	v_cndmask_b32_e64 v79, v79, v112, s[2:3]
	v_alignbit_b32 v115, v2, v80, 30
	v_sub_u32_e32 v120, 0, v119
	v_cndmask_b32_e64 v79, v114, v79, s[4:5]
	v_xor_b32_e32 v115, v115, v120
	v_alignbit_b32 v112, v113, v79, v117
	v_cndmask_b32_e64 v112, v112, v113, s[6:7]
	v_ffbh_u32_e32 v113, v115
	v_alignbit_b32 v80, v80, v112, 30
	v_min_u32_e32 v113, 32, v113
	v_alignbit_b32 v79, v112, v79, 30
	v_xor_b32_e32 v80, v80, v120
	v_sub_u32_e32 v114, 31, v113
	v_xor_b32_e32 v79, v79, v120
	v_alignbit_b32 v115, v115, v80, v114
	v_alignbit_b32 v79, v80, v79, v114
	v_alignbit_b32 v80, v115, v79, 9
	v_ffbh_u32_e32 v112, v80
	v_min_u32_e32 v112, 32, v112
	v_lshrrev_b32_e32 v118, 29, v2
	v_not_b32_e32 v114, v112
	v_alignbit_b32 v79, v80, v79, v114
	v_lshlrev_b32_e32 v80, 31, v118
	v_or_b32_e32 v114, 0x33000000, v80
	v_add_lshl_u32 v112, v112, v113, 23
	v_lshrrev_b32_e32 v79, 9, v79
	v_sub_u32_e32 v112, v114, v112
	v_or_b32_e32 v80, 0.5, v80
	v_lshlrev_b32_e32 v113, 23, v113
	v_or_b32_e32 v79, v112, v79
	v_lshrrev_b32_e32 v112, 9, v115
	v_sub_u32_e32 v80, v80, v113
	v_or_b32_e32 v80, v112, v80
	v_mul_f32_e32 v112, 0x3fc90fda, v80
	v_fma_f32 v113, v80, s0, -v112
	v_fmac_f32_e32 v113, 0x33a22168, v80
	v_fmac_f32_e32 v113, 0x3fc90fda, v79
	v_lshrrev_b32_e32 v2, 30, v2
	v_add_f32_e32 v159, v112, v113
	v_add_u32_e32 v158, v119, v2
	s_branch .LBB0_109
; __device__ __forceinline__ int crow16(int r, int hi) { return (r & 3) + 8 * (r >> 2) + 4 * hi; }
; __device__ __forceinline__ void filter_item32(const Args& a, int L, bf16* KR, int t0, int np0, int npn, int lane) {
;     ...
;         for (int r = 0; r < 16; ++r) { const int j = crow16(r, hi); h0[r] = sinf(fq[j] * (h0[r] + b1[j])); h1[r] = sinf(fq[32 + j] * (h1[r] + b1[32 + j])); }
.Lsl_113:
	v_lshrrev_b32_e32 v2, 23, v169
	v_add_u32_e32 v2, 0xffffff88, v2
	v_cmp_lt_u32_e32 vcc, 63, v2
	s_nop 1
	v_cndmask_b32_e32 v25, 0, v145, vcc
	v_add_u32_e32 v2, v25, v2
	v_cmp_lt_u32_e64 s[2:3], 31, v2
	s_nop 1
	v_cndmask_b32_e64 v25, 0, v146, s[2:3]
	v_add_u32_e32 v2, v25, v2
	v_cmp_lt_u32_e64 s[4:5], 31, v2
	s_nop 1
	v_cndmask_b32_e64 v25, 0, v146, s[4:5]
	v_add_u32_e32 v2, v25, v2
	v_and_b32_e32 v25, 0x7fffff, v169
	v_or_b32_e32 v25, 0x800000, v25
	v_mad_u64_u32 v[112:113], s[6:7], v25, s61, 0
	v_mov_b32_e32 v80, v113
	v_mad_u64_u32 v[114:115], s[6:7], v25, s62, v[80:81]
	v_mov_b32_e32 v80, v115
	v_mad_u64_u32 v[116:117], s[6:7], v25, s63, v[80:81]
	v_mov_b32_e32 v80, v117
	v_mad_u64_u32 v[118:119], s[6:7], v25, s72, v[80:81]
	v_mov_b32_e32 v80, v119
	v_mad_u64_u32 v[120:121], s[6:7], v25, s73, v[80:81]
	v_mov_b32_e32 v80, v121
	v_mad_u64_u32 v[122:123], s[6:7], v25, s74, v[80:81]
	v_mov_b32_e32 v80, v123
	v_mad_u64_u32 v[124:125], s[6:7], v25, s75, v[80:81]
	v_cndmask_b32_e32 v113, v122, v118, vcc
	v_cndmask_b32_e32 v25, v124, v120, vcc
	v_cndmask_b32_e32 v115, v125, v122, vcc
	v_cndmask_b32_e64 v80, v25, v113, s[2:3]
	v_cndmask_b32_e64 v25, v115, v25, s[2:3]
	v_cndmask_b32_e32 v115, v120, v116, vcc
	v_cndmask_b32_e64 v113, v113, v115, s[2:3]
	v_cndmask_b32_e64 v25, v25, v80, s[4:5]
	v_cndmask_b32_e64 v80, v80, v113, s[4:5]
	v_sub_u32_e32 v117, 32, v2
	v_alignbit_b32 v119, v25, v80, v117
	v_cmp_eq_u32_e64 s[6:7], 0, v2
	v_cndmask_b32_e32 v112, v116, v112, vcc
	s_nop 0
	v_cndmask_b32_e64 v2, v119, v25, s[6:7]
	v_cndmask_b32_e32 v25, v118, v114, vcc
	v_cndmask_b32_e64 v114, v115, v25, s[2:3]
	v_cndmask_b32_e64 v113, v113, v114, s[4:5]
	v_alignbit_b32 v115, v80, v113, v117
	v_cndmask_b32_e64 v80, v115, v80, s[6:7]
	v_bfe_u32 v119, v2, 29, 1
	v_cndmask_b32_e64 v25, v25, v112, s[2:3]
	v_alignbit_b32 v115, v2, v80, 30
	v_sub_u32_e32 v120, 0, v119
	v_cndmask_b32_e64 v25, v114, v25, s[4:5]
	v_xor_b32_e32 v115, v115, v120
	v_alignbit_b32 v112, v113, v25, v117
	v_cndmask_b32_e64 v112, v112, v113, s[6:7]
	v_ffbh_u32_e32 v113, v115
	v_alignbit_b32 v80, v80, v112, 30
	v_min_u32_e32 v113, 32, v113
	v_alignbit_b32 v25, v112, v25, 30
	v_xor_b32_e32 v80, v80, v120
	v_sub_u32_e32 v114, 31, v113
	v_xor_b32_e32 v25, v25, v120
	v_alignbit_b32 v115, v115, v80, v114
	v_alignbit_b32 v25, v80, v25, v114
	v_alignbit_b32 v80, v115, v25, 9
	v_ffbh_u32_e32 v112, v80
	v_min_u32_e32 v112, 32, v112
	v_lshrrev_b32_e32 v118, 29, v2
	v_not_b32_e32 v114, v112
	v_alignbit_b32 v25, v80, v25, v114
	v_lshlrev_b32_e32 v80, 31, v118
	v_or_b32_e32 v114, 0x33000000, v80
	v_add_lshl_u32 v112, v112, v113, 23
	v_lshrrev_b32_e32 v25, 9, v25
	v_sub_u32_e32 v112, v114, v112
	v_or_b32_e32 v80, 0.5, v80
	v_lshlrev_b32_e32 v113, 23, v113
	v_or_b32_e32 v25, v112, v25
	v_lshrrev_b32_e32 v112, 9, v115
	v_sub_u32_e32 v80, v80, v113
	v_or_b32_e32 v80, v112, v80
	v_mul_f32_e32 v112, 0x3fc90fda, v80
	v_fma_f32 v113, v80, s0, -v112
	v_fmac_f32_e32 v113, 0x33a22168, v80
	v_fmac_f32_e32 v113, 0x3fc90fda, v25
	v_lshrrev_b32_e32 v2, 30, v2
	v_add_f32_e32 v171, v112, v113
	v_add_u32_e32 v170, v119, v2
	s_branch .LBB0_113
.Lsl_117:
	v_lshrrev_b32_e32 v2, 23, v25
	v_add_u32_e32 v2, 0xffffff88, v2
	v_cmp_lt_u32_e32 vcc, 63, v2
	s_nop 1
	v_cndmask_b32_e32 v80, 0, v145, vcc
	v_add_u32_e32 v2, v80, v2
	v_cmp_lt_u32_e64 s[2:3], 31, v2
	s_nop 1
	v_cndmask_b32_e64 v80, 0, v146, s[2:3]
	v_add_u32_e32 v2, v80, v2
	v_cmp_lt_u32_e64 s[4:5], 31, v2
	s_nop 1
	v_cndmask_b32_e64 v80, 0, v146, s[4:5]
	v_add_u32_e32 v2, v80, v2
	v_and_b32_e32 v80, 0x7fffff, v25
	v_or_b32_e32 v113, 0x800000, v80
	v_mad_u64_u32 v[114:115], s[6:7], v113, s61, 0
	v_mov_b32_e32 v80, v115
	v_mad_u64_u32 v[116:117], s[6:7], v113, s62, v[80:81]
	v_mov_b32_e32 v80, v117
	v_mad_u64_u32 v[118:119], s[6:7], v113, s63, v[80:81]
	v_mov_b32_e32 v80, v119
	v_mad_u64_u32 v[120:121], s[6:7], v113, s72, v[80:81]
	v_mov_b32_e32 v80, v121
	v_mad_u64_u32 v[122:123], s[6:7], v113, s73, v[80:81]
	v_mov_b32_e32 v80, v123
	v_mad_u64_u32 v[124:125], s[6:7], v113, s74, v[80:81]
	v_mov_b32_e32 v80, v125
	v_mad_u64_u32 v[126:127], s[6:7], v113, s75, v[80:81]
	v_cndmask_b32_e32 v115, v124, v120, vcc
	v_cndmask_b32_e32 v80, v126, v122, vcc
	v_cndmask_b32_e32 v117, v127, v124, vcc
	v_cndmask_b32_e64 v113, v80, v115, s[2:3]
	v_cndmask_b32_e64 v80, v117, v80, s[2:3]
	v_cndmask_b32_e32 v117, v122, v118, vcc
	v_cndmask_b32_e64 v115, v115, v117, s[2:3]
	v_cndmask_b32_e64 v80, v80, v113, s[4:5]
	v_cndmask_b32_e64 v113, v113, v115, s[4:5]
	v_sub_u32_e32 v119, 32, v2
	v_alignbit_b32 v121, v80, v113, v119
	v_cmp_eq_u32_e64 s[6:7], 0, v2
	v_cndmask_b32_e32 v114, v118, v114, vcc
	s_nop 0
	v_cndmask_b32_e64 v2, v121, v80, s[6:7]
	v_cndmask_b32_e32 v80, v120, v116, vcc
	v_cndmask_b32_e64 v116, v117, v80, s[2:3]
	v_cndmask_b32_e64 v115, v115, v116, s[4:5]
	v_alignbit_b32 v117, v113, v115, v119
	v_cndmask_b32_e64 v113, v117, v113, s[6:7]
	v_bfe_u32 v121, v2, 29, 1
	v_cndmask_b32_e64 v80, v80, v114, s[2:3]
	v_alignbit_b32 v117, v2, v113, 30
	v_sub_u32_e32 v122, 0, v121
	v_cndmask_b32_e64 v80, v116, v80, s[4:5]
	v_xor_b32_e32 v117, v117, v122
	v_alignbit_b32 v114, v115, v80, v119
	v_cndmask_b32_e64 v114, v114, v115, s[6:7]
	v_ffbh_u32_e32 v115, v117
	v_alignbit_b32 v113, v113, v114, 30
	v_min_u32_e32 v115, 32, v115
	v_alignbit_b32 v80, v114, v80, 30
	v_xor_b32_e32 v113, v113, v122
	v_sub_u32_e32 v116, 31, v115
	v_xor_b32_e32 v80, v80, v122
	v_alignbit_b32 v117, v117, v113, v116
	v_alignbit_b32 v80, v113, v80, v116
	v_alignbit_b32 v113, v117, v80, 9
	v_ffbh_u32_e32 v114, v113
	v_min_u32_e32 v114, 32, v114
	v_lshrrev_b32_e32 v120, 29, v2
	v_not_b32_e32 v116, v114
	v_alignbit_b32 v80, v113, v80, v116
	v_lshlrev_b32_e32 v113, 31, v120
	v_or_b32_e32 v116, 0x33000000, v113
	v_add_lshl_u32 v114, v114, v115, 23
	v_lshrrev_b32_e32 v80, 9, v80
	v_sub_u32_e32 v114, v116, v114
	v_or_b32_e32 v113, 0.5, v113
	v_lshlrev_b32_e32 v115, 23, v115
	v_or_b32_e32 v80, v114, v80
	v_lshrrev_b32_e32 v114, 9, v117
	v_sub_u32_e32 v113, v113, v115
	v_or_b32_e32 v113, v114, v113
	v_mul_f32_e32 v114, 0x3fc90fda, v113
	v_fma_f32 v115, v113, s0, -v114
	v_fmac_f32_e32 v115, 0x33a22168, v113
	v_fmac_f32_e32 v115, 0x3fc90fda, v80
	v_lshrrev_b32_e32 v2, 30, v2
	v_add_f32_e32 v167, v114, v115
	v_add_u32_e32 v166, v121, v2
	s_branch .LBB0_117
; __device__ __forceinline__ int crow16(int r, int hi) { return (r & 3) + 8 * (r >> 2) + 4 * hi; }
; __device__ __forceinline__ void filter_item32(const Args& a, int L, bf16* KR, int t0, int np0, int npn, int lane) {
;     ...
;         for (int r = 0; r < 16; ++r) { const int j = crow16(r, hi); h0[r] = sinf(fq[j] * (h0[r] + b1[j])); h1[r] = sinf(fq[32 + j] * (h1[r] + b1[32 + j])); }
.Lsl_121:
	v_lshrrev_b32_e32 v2, 23, v175
	v_add_u32_e32 v2, 0xffffff88, v2
	v_cmp_lt_u32_e32 vcc, 63, v2
	s_nop 1
	v_cndmask_b32_e32 v26, 0, v145, vcc
	v_add_u32_e32 v2, v26, v2
	v_cmp_lt_u32_e64 s[2:3], 31, v2
	s_nop 1
	v_cndmask_b32_e64 v26, 0, v146, s[2:3]
	v_add_u32_e32 v2, v26, v2
	v_cmp_lt_u32_e64 s[4:5], 31, v2
	s_nop 1
	v_cndmask_b32_e64 v26, 0, v146, s[4:5]
	v_add_u32_e32 v2, v26, v2
	v_and_b32_e32 v26, 0x7fffff, v175
	v_or_b32_e32 v26, 0x800000, v26
	v_mad_u64_u32 v[114:115], s[6:7], v26, s61, 0
	v_mov_b32_e32 v80, v115
	v_mad_u64_u32 v[116:117], s[6:7], v26, s62, v[80:81]
	v_mov_b32_e32 v80, v117
	v_mad_u64_u32 v[118:119], s[6:7], v26, s63, v[80:81]
	v_mov_b32_e32 v80, v119
	v_mad_u64_u32 v[120:121], s[6:7], v26, s72, v[80:81]
	v_mov_b32_e32 v80, v121
	v_mad_u64_u32 v[122:123], s[6:7], v26, s73, v[80:81]
	v_mov_b32_e32 v80, v123
	v_mad_u64_u32 v[124:125], s[6:7], v26, s74, v[80:81]
	v_mov_b32_e32 v80, v125
	v_mad_u64_u32 v[126:127], s[6:7], v26, s75, v[80:81]
	v_cndmask_b32_e32 v115, v124, v120, vcc
	v_cndmask_b32_e32 v26, v126, v122, vcc
	v_cndmask_b32_e32 v117, v127, v124, vcc
	v_cndmask_b32_e64 v80, v26, v115, s[2:3]
	v_cndmask_b32_e64 v26, v117, v26, s[2:3]
	v_cndmask_b32_e32 v117, v122, v118, vcc
	v_cndmask_b32_e64 v115, v115, v117, s[2:3]
	v_cndmask_b32_e64 v26, v26, v80, s[4:5]
	v_cndmask_b32_e64 v80, v80, v115, s[4:5]
	v_sub_u32_e32 v119, 32, v2
	v_alignbit_b32 v121, v26, v80, v119
	v_cmp_eq_u32_e64 s[6:7], 0, v2
	v_cndmask_b32_e32 v114, v118, v114, vcc
	s_nop 0
	v_cndmask_b32_e64 v2, v121, v26, s[6:7]
	v_cndmask_b32_e32 v26, v120, v116, vcc
	v_cndmask_b32_e64 v116, v117, v26, s[2:3]
	v_cndmask_b32_e64 v115, v115, v116, s[4:5]
	v_alignbit_b32 v117, v80, v115, v119
	v_cndmask_b32_e64 v80, v117, v80, s[6:7]
	v_bfe_u32 v121, v2, 29, 1
	v_cndmask_b32_e64 v26, v26, v114, s[2:3]
	v_alignbit_b32 v117, v2, v80, 30
	v_sub_u32_e32 v122, 0, v121
	v_cndmask_b32_e64 v26, v116, v26, s[4:5]
	v_xor_b32_e32 v117, v117, v122
	v_alignbit_b32 v114, v115, v26, v119
	v_cndmask_b32_e64 v114, v114, v115, s[6:7]
	v_ffbh_u32_e32 v115, v117
	v_alignbit_b32 v80, v80, v114, 30
	v_min_u32_e32 v115, 32, v115
	v_alignbit_b32 v26, v114, v26, 30
	v_xor_b32_e32 v80, v80, v122
	v_sub_u32_e32 v116, 31, v115
	v_xor_b32_e32 v26, v26, v122
	v_alignbit_b32 v117, v117, v80, v116
	v_alignbit_b32 v26, v80, v26, v116
	v_alignbit_b32 v80, v117, v26, 9
	v_ffbh_u32_e32 v114, v80
	v_min_u32_e32 v114, 32, v114
	v_lshrrev_b32_e32 v120, 29, v2
	v_not_b32_e32 v116, v114
	v_alignbit_b32 v26, v80, v26, v116
	v_lshlrev_b32_e32 v80, 31, v120
	v_or_b32_e32 v116, 0x33000000, v80
	v_add_lshl_u32 v114, v114, v115, 23
	v_lshrrev_b32_e32 v26, 9, v26
	v_sub_u32_e32 v114, v116, v114
	v_or_b32_e32 v80, 0.5, v80
	v_lshlrev_b32_e32 v115, 23, v115
	v_or_b32_e32 v26, v114, v26
	v_lshrrev_b32_e32 v114, 9, v117
	v_sub_u32_e32 v80, v80, v115
	v_or_b32_e32 v80, v114, v80
	v_mul_f32_e32 v114, 0x3fc90fda, v80
	v_fma_f32 v115, v80, s0, -v114
	v_fmac_f32_e32 v115, 0x33a22168, v80
	v_fmac_f32_e32 v115, 0x3fc90fda, v26
	v_lshrrev_b32_e32 v2, 30, v2
	v_add_f32_e32 v177, v114, v115
	v_add_u32_e32 v176, v121, v2
	s_branch .LBB0_121
.Lsl_125:
	v_lshrrev_b32_e32 v2, 23, v26
	v_add_u32_e32 v2, 0xffffff88, v2
	v_cmp_lt_u32_e32 vcc, 63, v2
	s_nop 1
	v_cndmask_b32_e32 v80, 0, v145, vcc
	v_add_u32_e32 v2, v80, v2
	v_cmp_lt_u32_e64 s[2:3], 31, v2
	s_nop 1
	v_cndmask_b32_e64 v80, 0, v146, s[2:3]
	v_add_u32_e32 v2, v80, v2
	v_cmp_lt_u32_e64 s[4:5], 31, v2
	s_nop 1
	v_cndmask_b32_e64 v80, 0, v146, s[4:5]
	v_add_u32_e32 v2, v80, v2
	v_and_b32_e32 v80, 0x7fffff, v26
	v_or_b32_e32 v115, 0x800000, v80
	v_mad_u64_u32 v[116:117], s[6:7], v115, s61, 0
	v_mov_b32_e32 v80, v117
	v_mad_u64_u32 v[118:119], s[6:7], v115, s62, v[80:81]
	v_mov_b32_e32 v80, v119
	v_mad_u64_u32 v[120:121], s[6:7], v115, s63, v[80:81]
	v_mov_b32_e32 v80, v121
	v_mad_u64_u32 v[122:123], s[6:7], v115, s72, v[80:81]
	v_mov_b32_e32 v80, v123
	v_mad_u64_u32 v[124:125], s[6:7], v115, s73, v[80:81]
	v_mov_b32_e32 v80, v125
	v_mad_u64_u32 v[126:127], s[6:7], v115, s74, v[80:81]
	v_mov_b32_e32 v80, v127
	v_mad_u64_u32 v[172:173], s[6:7], v115, s75, v[80:81]
	v_cndmask_b32_e32 v117, v126, v122, vcc
	v_cndmask_b32_e32 v80, v172, v124, vcc
	v_cndmask_b32_e32 v119, v173, v126, vcc
	v_cndmask_b32_e64 v115, v80, v117, s[2:3]
	v_cndmask_b32_e64 v80, v119, v80, s[2:3]
	v_cndmask_b32_e32 v119, v124, v120, vcc
	v_cndmask_b32_e64 v117, v117, v119, s[2:3]
	v_cndmask_b32_e64 v80, v80, v115, s[4:5]
	v_cndmask_b32_e64 v115, v115, v117, s[4:5]
	v_sub_u32_e32 v121, 32, v2
	v_alignbit_b32 v123, v80, v115, v121
	v_cmp_eq_u32_e64 s[6:7], 0, v2
	v_cndmask_b32_e32 v116, v120, v116, vcc
	s_nop 0
	v_cndmask_b32_e64 v2, v123, v80, s[6:7]
	v_cndmask_b32_e32 v80, v122, v118, vcc
	v_cndmask_b32_e64 v118, v119, v80, s[2:3]
	v_cndmask_b32_e64 v117, v117, v118, s[4:5]
	v_alignbit_b32 v119, v115, v117, v121
	v_cndmask_b32_e64 v115, v119, v115, s[6:7]
	v_bfe_u32 v123, v2, 29, 1
	v_cndmask_b32_e64 v80, v80, v116, s[2:3]
	v_alignbit_b32 v119, v2, v115, 30
	v_sub_u32_e32 v124, 0, v123
	v_cndmask_b32_e64 v80, v118, v80, s[4:5]
	v_xor_b32_e32 v119, v119, v124
	v_alignbit_b32 v116, v117, v80, v121
	v_cndmask_b32_e64 v116, v116, v117, s[6:7]
	v_ffbh_u32_e32 v117, v119
	v_alignbit_b32 v115, v115, v116, 30
	v_min_u32_e32 v117, 32, v117
	v_alignbit_b32 v80, v116, v80, 30
	v_xor_b32_e32 v115, v115, v124
	v_sub_u32_e32 v118, 31, v117
	v_xor_b32_e32 v80, v80, v124
	v_alignbit_b32 v119, v119, v115, v118
	v_alignbit_b32 v80, v115, v80, v118
	v_alignbit_b32 v115, v119, v80, 9
	v_ffbh_u32_e32 v116, v115
	v_min_u32_e32 v116, 32, v116
	v_lshrrev_b32_e32 v122, 29, v2
	v_not_b32_e32 v118, v116
	v_alignbit_b32 v80, v115, v80, v118
	v_lshlrev_b32_e32 v115, 31, v122
	v_or_b32_e32 v118, 0x33000000, v115
	v_add_lshl_u32 v116, v116, v117, 23
	v_lshrrev_b32_e32 v80, 9, v80
	v_sub_u32_e32 v116, v118, v116
	v_or_b32_e32 v115, 0.5, v115
	v_lshlrev_b32_e32 v117, 23, v117
	v_or_b32_e32 v80, v116, v80
	v_lshrrev_b32_e32 v116, 9, v119
	v_sub_u32_e32 v115, v115, v117
	v_or_b32_e32 v115, v116, v115
	v_mul_f32_e32 v116, 0x3fc90fda, v115
	v_fma_f32 v117, v115, s0, -v116
	v_fmac_f32_e32 v117, 0x33a22168, v115
	v_fmac_f32_e32 v117, 0x3fc90fda, v80
	v_lshrrev_b32_e32 v2, 30, v2
	v_add_f32_e32 v173, v116, v117
	v_add_u32_e32 v172, v123, v2
	s_branch .LBB0_125
; __device__ __forceinline__ int crow16(int r, int hi) { return (r & 3) + 8 * (r >> 2) + 4 * hi; }
; __device__ __forceinline__ void filter_item32(const Args& a, int L, bf16* KR, int t0, int np0, int npn, int lane) {
;     ...
;         for (int r = 0; r < 16; ++r) { const int j = crow16(r, hi); h0[r] = sinf(fq[j] * (h0[r] + b1[j])); h1[r] = sinf(fq[32 + j] * (h1[r] + b1[32 + j])); }
.Lsl_129:
	v_lshrrev_b32_e32 v2, 23, v181
	v_add_u32_e32 v2, 0xffffff88, v2
	v_cmp_lt_u32_e32 vcc, 63, v2
	s_nop 1
	v_cndmask_b32_e32 v27, 0, v145, vcc
	v_add_u32_e32 v2, v27, v2
	v_cmp_lt_u32_e64 s[2:3], 31, v2
	s_nop 1
	v_cndmask_b32_e64 v27, 0, v146, s[2:3]
	v_add_u32_e32 v2, v27, v2
	v_cmp_lt_u32_e64 s[4:5], 31, v2
	s_nop 1
	v_cndmask_b32_e64 v27, 0, v146, s[4:5]
	v_add_u32_e32 v2, v27, v2
	v_and_b32_e32 v27, 0x7fffff, v181
	v_or_b32_e32 v27, 0x800000, v27
	v_mad_u64_u32 v[116:117], s[6:7], v27, s61, 0
	v_mov_b32_e32 v80, v117
	v_mad_u64_u32 v[118:119], s[6:7], v27, s62, v[80:81]
	v_mov_b32_e32 v80, v119
	v_mad_u64_u32 v[120:121], s[6:7], v27, s63, v[80:81]
	v_mov_b32_e32 v80, v121
	v_mad_u64_u32 v[122:123], s[6:7], v27, s72, v[80:81]
	v_mov_b32_e32 v80, v123
	v_mad_u64_u32 v[124:125], s[6:7], v27, s73, v[80:81]
	v_mov_b32_e32 v80, v125
	v_mad_u64_u32 v[126:127], s[6:7], v27, s74, v[80:81]
	v_mov_b32_e32 v80, v127
	v_mad_u64_u32 v[178:179], s[6:7], v27, s75, v[80:81]
	v_cndmask_b32_e32 v117, v126, v122, vcc
	v_cndmask_b32_e32 v27, v178, v124, vcc
	v_cndmask_b32_e32 v119, v179, v126, vcc
	v_cndmask_b32_e64 v80, v27, v117, s[2:3]
	v_cndmask_b32_e64 v27, v119, v27, s[2:3]
	v_cndmask_b32_e32 v119, v124, v120, vcc
	v_cndmask_b32_e64 v117, v117, v119, s[2:3]
	v_cndmask_b32_e64 v27, v27, v80, s[4:5]
	v_cndmask_b32_e64 v80, v80, v117, s[4:5]
	v_sub_u32_e32 v121, 32, v2
	v_alignbit_b32 v123, v27, v80, v121
	v_cmp_eq_u32_e64 s[6:7], 0, v2
	v_cndmask_b32_e32 v116, v120, v116, vcc
	s_nop 0
	v_cndmask_b32_e64 v2, v123, v27, s[6:7]
	v_cndmask_b32_e32 v27, v122, v118, vcc
	v_cndmask_b32_e64 v118, v119, v27, s[2:3]
	v_cndmask_b32_e64 v117, v117, v118, s[4:5]
	v_alignbit_b32 v119, v80, v117, v121
	v_cndmask_b32_e64 v80, v119, v80, s[6:7]
	v_bfe_u32 v123, v2, 29, 1
	v_cndmask_b32_e64 v27, v27, v116, s[2:3]
	v_alignbit_b32 v119, v2, v80, 30
	v_sub_u32_e32 v124, 0, v123
	v_cndmask_b32_e64 v27, v118, v27, s[4:5]
	v_xor_b32_e32 v119, v119, v124
	v_alignbit_b32 v116, v117, v27, v121
	v_cndmask_b32_e64 v116, v116, v117, s[6:7]
	v_ffbh_u32_e32 v117, v119
	v_alignbit_b32 v80, v80, v116, 30
	v_min_u32_e32 v117, 32, v117
	v_alignbit_b32 v27, v116, v27, 30
	v_xor_b32_e32 v80, v80, v124
	v_sub_u32_e32 v118, 31, v117
	v_xor_b32_e32 v27, v27, v124
	v_alignbit_b32 v119, v119, v80, v118
	v_alignbit_b32 v27, v80, v27, v118
	v_alignbit_b32 v80, v119, v27, 9
	v_ffbh_u32_e32 v116, v80
	v_min_u32_e32 v116, 32, v116
	v_lshrrev_b32_e32 v122, 29, v2
	v_not_b32_e32 v118, v116
	v_alignbit_b32 v27, v80, v27, v118
	v_lshlrev_b32_e32 v80, 31, v122
	v_or_b32_e32 v118, 0x33000000, v80
	v_add_lshl_u32 v116, v116, v117, 23
	v_lshrrev_b32_e32 v27, 9, v27
	v_sub_u32_e32 v116, v118, v116
	v_or_b32_e32 v80, 0.5, v80
	v_lshlrev_b32_e32 v117, 23, v117
	v_or_b32_e32 v27, v116, v27
	v_lshrrev_b32_e32 v116, 9, v119
	v_sub_u32_e32 v80, v80, v117
	v_or_b32_e32 v80, v116, v80
	v_mul_f32_e32 v116, 0x3fc90fda, v80
	v_fma_f32 v117, v80, s0, -v116
	v_fmac_f32_e32 v117, 0x33a22168, v80
	v_fmac_f32_e32 v117, 0x3fc90fda, v27
	v_lshrrev_b32_e32 v2, 30, v2
	v_add_f32_e32 v183, v116, v117
	v_add_u32_e32 v182, v123, v2
	s_branch .LBB0_129
.Lsl_133:
	v_lshrrev_b32_e32 v2, 23, v27
	v_add_u32_e32 v2, 0xffffff88, v2
	v_cmp_lt_u32_e32 vcc, 63, v2
	s_nop 1
	v_cndmask_b32_e32 v80, 0, v145, vcc
	v_add_u32_e32 v2, v80, v2
	v_cmp_lt_u32_e64 s[2:3], 31, v2
	s_nop 1
	v_cndmask_b32_e64 v80, 0, v146, s[2:3]
	v_add_u32_e32 v2, v80, v2
	v_cmp_lt_u32_e64 s[4:5], 31, v2
	s_nop 1
	v_cndmask_b32_e64 v80, 0, v146, s[4:5]
	v_add_u32_e32 v2, v80, v2
	v_and_b32_e32 v80, 0x7fffff, v27
	v_or_b32_e32 v117, 0x800000, v80
	v_mad_u64_u32 v[118:119], s[6:7], v117, s61, 0
	v_mov_b32_e32 v80, v119
	v_mad_u64_u32 v[120:121], s[6:7], v117, s62, v[80:81]
	v_mov_b32_e32 v80, v121
	v_mad_u64_u32 v[122:123], s[6:7], v117, s63, v[80:81]
	v_mov_b32_e32 v80, v123
	v_mad_u64_u32 v[124:125], s[6:7], v117, s72, v[80:81]
	v_mov_b32_e32 v80, v125
	v_mad_u64_u32 v[126:127], s[6:7], v117, s73, v[80:81]
	v_mov_b32_e32 v80, v127
	v_mad_u64_u32 v[178:179], s[6:7], v117, s74, v[80:81]
	v_mov_b32_e32 v80, v179
	v_mad_u64_u32 v[184:185], s[6:7], v117, s75, v[80:81]
	v_cndmask_b32_e32 v119, v178, v124, vcc
	v_cndmask_b32_e32 v80, v184, v126, vcc
	v_cndmask_b32_e32 v121, v185, v178, vcc
	v_cndmask_b32_e64 v117, v80, v119, s[2:3]
	v_cndmask_b32_e64 v80, v121, v80, s[2:3]
	v_cndmask_b32_e32 v121, v126, v122, vcc
	v_cndmask_b32_e64 v119, v119, v121, s[2:3]
	v_cndmask_b32_e64 v80, v80, v117, s[4:5]
	v_cndmask_b32_e64 v117, v117, v119, s[4:5]
	v_sub_u32_e32 v123, 32, v2
	v_alignbit_b32 v125, v80, v117, v123
	v_cmp_eq_u32_e64 s[6:7], 0, v2
	v_cndmask_b32_e32 v118, v122, v118, vcc
	s_nop 0
	v_cndmask_b32_e64 v2, v125, v80, s[6:7]
	v_cndmask_b32_e32 v80, v124, v120, vcc
	v_cndmask_b32_e64 v120, v121, v80, s[2:3]
	v_cndmask_b32_e64 v119, v119, v120, s[4:5]
	v_alignbit_b32 v121, v117, v119, v123
	v_cndmask_b32_e64 v117, v121, v117, s[6:7]
	v_bfe_u32 v125, v2, 29, 1
	v_cndmask_b32_e64 v80, v80, v118, s[2:3]
	v_alignbit_b32 v121, v2, v117, 30
	v_sub_u32_e32 v126, 0, v125
	v_cndmask_b32_e64 v80, v120, v80, s[4:5]
	v_xor_b32_e32 v121, v121, v126
	v_alignbit_b32 v118, v119, v80, v123
	v_cndmask_b32_e64 v118, v118, v119, s[6:7]
	v_ffbh_u32_e32 v119, v121
	v_alignbit_b32 v117, v117, v118, 30
	v_min_u32_e32 v119, 32, v119
	v_alignbit_b32 v80, v118, v80, 30
	v_xor_b32_e32 v117, v117, v126
	v_sub_u32_e32 v120, 31, v119
	v_xor_b32_e32 v80, v80, v126
	v_alignbit_b32 v121, v121, v117, v120
	v_alignbit_b32 v80, v117, v80, v120
	v_alignbit_b32 v117, v121, v80, 9
	v_ffbh_u32_e32 v118, v117
	v_min_u32_e32 v118, 32, v118
	v_lshrrev_b32_e32 v124, 29, v2
	v_not_b32_e32 v120, v118
	v_alignbit_b32 v80, v117, v80, v120
	v_lshlrev_b32_e32 v117, 31, v124
	v_or_b32_e32 v120, 0x33000000, v117
	v_add_lshl_u32 v118, v118, v119, 23
	v_lshrrev_b32_e32 v80, 9, v80
	v_sub_u32_e32 v118, v120, v118
	v_or_b32_e32 v117, 0.5, v117
	v_lshlrev_b32_e32 v119, 23, v119
	v_or_b32_e32 v80, v118, v80
	v_lshrrev_b32_e32 v118, 9, v121
	v_sub_u32_e32 v117, v117, v119
	v_or_b32_e32 v117, v118, v117
	v_mul_f32_e32 v118, 0x3fc90fda, v117
	v_fma_f32 v119, v117, s0, -v118
	v_fmac_f32_e32 v119, 0x33a22168, v117
	v_fmac_f32_e32 v119, 0x3fc90fda, v80
	v_lshrrev_b32_e32 v2, 30, v2
	v_add_f32_e32 v179, v118, v119
	v_add_u32_e32 v178, v125, v2
	s_branch .LBB0_133
; __device__ __forceinline__ int crow16(int r, int hi) { return (r & 3) + 8 * (r >> 2) + 4 * hi; }
; __device__ __forceinline__ void filter_item32(const Args& a, int L, bf16* KR, int t0, int np0, int npn, int lane) {
;     ...
;         for (int r = 0; r < 16; ++r) { const int j = crow16(r, hi); h0[r] = sinf(fq[j] * (h0[r] + b1[j])); h1[r] = sinf(fq[32 + j] * (h1[r] + b1[32 + j])); }
.Lsl_137:
	v_lshrrev_b32_e32 v2, 23, v187
	v_add_u32_e32 v2, 0xffffff88, v2
	v_cmp_lt_u32_e32 vcc, 63, v2
	s_nop 1
	v_cndmask_b32_e32 v28, 0, v145, vcc
	v_add_u32_e32 v2, v28, v2
	v_cmp_lt_u32_e64 s[2:3], 31, v2
	s_nop 1
	v_cndmask_b32_e64 v28, 0, v146, s[2:3]
	v_add_u32_e32 v2, v28, v2
	v_cmp_lt_u32_e64 s[4:5], 31, v2
	s_nop 1
	v_cndmask_b32_e64 v28, 0, v146, s[4:5]
	v_add_u32_e32 v2, v28, v2
	v_and_b32_e32 v28, 0x7fffff, v187
	v_or_b32_e32 v28, 0x800000, v28
	v_mad_u64_u32 v[118:119], s[6:7], v28, s61, 0
	v_mov_b32_e32 v80, v119
	v_mad_u64_u32 v[120:121], s[6:7], v28, s62, v[80:81]
	v_mov_b32_e32 v80, v121
	v_mad_u64_u32 v[122:123], s[6:7], v28, s63, v[80:81]
	v_mov_b32_e32 v80, v123
	v_mad_u64_u32 v[124:125], s[6:7], v28, s72, v[80:81]
	v_mov_b32_e32 v80, v125
	v_mad_u64_u32 v[126:127], s[6:7], v28, s73, v[80:81]
	v_mov_b32_e32 v80, v127
	v_mad_u64_u32 v[184:185], s[6:7], v28, s74, v[80:81]
	v_mov_b32_e32 v80, v185
	v_mad_u64_u32 v[188:189], s[6:7], v28, s75, v[80:81]
	v_cndmask_b32_e32 v119, v184, v124, vcc
	v_cndmask_b32_e32 v28, v188, v126, vcc
	v_cndmask_b32_e32 v121, v189, v184, vcc
	v_cndmask_b32_e64 v80, v28, v119, s[2:3]
	v_cndmask_b32_e64 v28, v121, v28, s[2:3]
	v_cndmask_b32_e32 v121, v126, v122, vcc
	v_cndmask_b32_e64 v119, v119, v121, s[2:3]
	v_cndmask_b32_e64 v28, v28, v80, s[4:5]
	v_cndmask_b32_e64 v80, v80, v119, s[4:5]
	v_sub_u32_e32 v123, 32, v2
	v_alignbit_b32 v125, v28, v80, v123
	v_cmp_eq_u32_e64 s[6:7], 0, v2
	v_cndmask_b32_e32 v118, v122, v118, vcc
	s_nop 0
	v_cndmask_b32_e64 v2, v125, v28, s[6:7]
	v_cndmask_b32_e32 v28, v124, v120, vcc
	v_cndmask_b32_e64 v120, v121, v28, s[2:3]
	v_cndmask_b32_e64 v119, v119, v120, s[4:5]
	v_alignbit_b32 v121, v80, v119, v123
	v_cndmask_b32_e64 v80, v121, v80, s[6:7]
	v_bfe_u32 v125, v2, 29, 1
	v_cndmask_b32_e64 v28, v28, v118, s[2:3]
	v_alignbit_b32 v121, v2, v80, 30
	v_sub_u32_e32 v126, 0, v125
	v_cndmask_b32_e64 v28, v120, v28, s[4:5]
	v_xor_b32_e32 v121, v121, v126
	v_alignbit_b32 v118, v119, v28, v123
	v_cndmask_b32_e64 v118, v118, v119, s[6:7]
	v_ffbh_u32_e32 v119, v121
	v_alignbit_b32 v80, v80, v118, 30
	v_min_u32_e32 v119, 32, v119
	v_alignbit_b32 v28, v118, v28, 30
	v_xor_b32_e32 v80, v80, v126
	v_sub_u32_e32 v120, 31, v119
	v_xor_b32_e32 v28, v28, v126
	v_alignbit_b32 v121, v121, v80, v120
	v_alignbit_b32 v28, v80, v28, v120
	v_alignbit_b32 v80, v121, v28, 9
	v_ffbh_u32_e32 v118, v80
	v_min_u32_e32 v118, 32, v118
	v_lshrrev_b32_e32 v124, 29, v2
	v_not_b32_e32 v120, v118
	v_alignbit_b32 v28, v80, v28, v120
	v_lshlrev_b32_e32 v80, 31, v124
	v_or_b32_e32 v120, 0x33000000, v80
	v_add_lshl_u32 v118, v118, v119, 23
	v_lshrrev_b32_e32 v28, 9, v28
	v_sub_u32_e32 v118, v120, v118
	v_or_b32_e32 v80, 0.5, v80
	v_lshlrev_b32_e32 v119, 23, v119
	v_or_b32_e32 v28, v118, v28
	v_lshrrev_b32_e32 v118, 9, v121
	v_sub_u32_e32 v80, v80, v119
	v_or_b32_e32 v80, v118, v80
	v_mul_f32_e32 v118, 0x3fc90fda, v80
	v_fma_f32 v119, v80, s0, -v118
	v_fmac_f32_e32 v119, 0x33a22168, v80
	v_fmac_f32_e32 v119, 0x3fc90fda, v28
	v_lshrrev_b32_e32 v2, 30, v2
	v_add_f32_e32 v189, v118, v119
	v_add_u32_e32 v188, v125, v2
	s_branch .LBB0_137
.Lsl_141:
	v_lshrrev_b32_e32 v2, 23, v28
	v_add_u32_e32 v2, 0xffffff88, v2
	v_cmp_lt_u32_e32 vcc, 63, v2
	s_nop 1
	v_cndmask_b32_e32 v80, 0, v145, vcc
	v_add_u32_e32 v2, v80, v2
	v_cmp_lt_u32_e64 s[2:3], 31, v2
	s_nop 1
	v_cndmask_b32_e64 v80, 0, v146, s[2:3]
	v_add_u32_e32 v2, v80, v2
	v_cmp_lt_u32_e64 s[4:5], 31, v2
	s_nop 1
	v_cndmask_b32_e64 v80, 0, v146, s[4:5]
	v_add_u32_e32 v2, v80, v2
	v_and_b32_e32 v80, 0x7fffff, v28
	v_or_b32_e32 v119, 0x800000, v80
	v_mad_u64_u32 v[120:121], s[6:7], v119, s61, 0
	v_mov_b32_e32 v80, v121
	v_mad_u64_u32 v[122:123], s[6:7], v119, s62, v[80:81]
	v_mov_b32_e32 v80, v123
	v_mad_u64_u32 v[124:125], s[6:7], v119, s63, v[80:81]
	v_mov_b32_e32 v80, v125
	v_mad_u64_u32 v[126:127], s[6:7], v119, s72, v[80:81]
	v_mov_b32_e32 v80, v127
	v_mad_u64_u32 v[184:185], s[6:7], v119, s73, v[80:81]
	v_mov_b32_e32 v80, v185
	v_mad_u64_u32 v[190:191], s[6:7], v119, s74, v[80:81]
	v_mov_b32_e32 v80, v191
	v_mad_u64_u32 v[192:193], s[6:7], v119, s75, v[80:81]
	v_cndmask_b32_e32 v121, v190, v126, vcc
	v_cndmask_b32_e32 v80, v192, v184, vcc
	v_cndmask_b32_e32 v123, v193, v190, vcc
	v_cndmask_b32_e64 v119, v80, v121, s[2:3]
	v_cndmask_b32_e64 v80, v123, v80, s[2:3]
	v_cndmask_b32_e32 v123, v184, v124, vcc
	v_cndmask_b32_e64 v121, v121, v123, s[2:3]
	v_cndmask_b32_e64 v80, v80, v119, s[4:5]
	v_cndmask_b32_e64 v119, v119, v121, s[4:5]
	v_sub_u32_e32 v125, 32, v2
	v_alignbit_b32 v127, v80, v119, v125
	v_cmp_eq_u32_e64 s[6:7], 0, v2
	v_cndmask_b32_e32 v120, v124, v120, vcc
	s_nop 0
	v_cndmask_b32_e64 v2, v127, v80, s[6:7]
	v_cndmask_b32_e32 v80, v126, v122, vcc
	v_cndmask_b32_e64 v122, v123, v80, s[2:3]
	v_cndmask_b32_e64 v121, v121, v122, s[4:5]
	v_alignbit_b32 v123, v119, v121, v125
	v_cndmask_b32_e64 v119, v123, v119, s[6:7]
	v_bfe_u32 v127, v2, 29, 1
	v_cndmask_b32_e64 v80, v80, v120, s[2:3]
	v_alignbit_b32 v123, v2, v119, 30
	v_sub_u32_e32 v151, 0, v127
	v_cndmask_b32_e64 v80, v122, v80, s[4:5]
	v_xor_b32_e32 v123, v123, v151
	v_alignbit_b32 v120, v121, v80, v125
	v_cndmask_b32_e64 v120, v120, v121, s[6:7]
	v_ffbh_u32_e32 v121, v123
	v_alignbit_b32 v119, v119, v120, 30
	v_min_u32_e32 v121, 32, v121
	v_alignbit_b32 v80, v120, v80, 30
	v_xor_b32_e32 v119, v119, v151
	v_sub_u32_e32 v122, 31, v121
	v_xor_b32_e32 v80, v80, v151
	v_alignbit_b32 v123, v123, v119, v122
	v_alignbit_b32 v80, v119, v80, v122
	v_alignbit_b32 v119, v123, v80, 9
	v_ffbh_u32_e32 v120, v119
	v_min_u32_e32 v120, 32, v120
	v_lshrrev_b32_e32 v126, 29, v2
	v_not_b32_e32 v122, v120
	v_alignbit_b32 v80, v119, v80, v122
	v_lshlrev_b32_e32 v119, 31, v126
	v_or_b32_e32 v122, 0x33000000, v119
	v_add_lshl_u32 v120, v120, v121, 23
	v_lshrrev_b32_e32 v80, 9, v80
	v_sub_u32_e32 v120, v122, v120
	v_or_b32_e32 v119, 0.5, v119
	v_lshlrev_b32_e32 v121, 23, v121
	v_or_b32_e32 v80, v120, v80
	v_lshrrev_b32_e32 v120, 9, v123
	v_sub_u32_e32 v119, v119, v121
	v_or_b32_e32 v119, v120, v119
	v_mul_f32_e32 v120, 0x3fc90fda, v119
	v_fma_f32 v121, v119, s0, -v120
	v_fmac_f32_e32 v121, 0x33a22168, v119
	v_fmac_f32_e32 v121, 0x3fc90fda, v80
	v_lshrrev_b32_e32 v2, 30, v2
	v_add_f32_e32 v185, v120, v121
	v_add_u32_e32 v184, v127, v2
	s_branch .LBB0_141
; __device__ __forceinline__ int crow16(int r, int hi) { return (r & 3) + 8 * (r >> 2) + 4 * hi; }
; __device__ __forceinline__ void filter_item32(const Args& a, int L, bf16* KR, int t0, int np0, int npn, int lane) {
;     ...
;         for (int r = 0; r < 16; ++r) { const int j = crow16(r, hi); h0[r] = sinf(fq[j] * (h0[r] + b1[j])); h1[r] = sinf(fq[32 + j] * (h1[r] + b1[32 + j])); }
.Lsl_145:
	v_lshrrev_b32_e32 v2, 23, v193
	v_add_u32_e32 v2, 0xffffff88, v2
	v_cmp_lt_u32_e32 vcc, 63, v2
	s_nop 1
	v_cndmask_b32_e32 v29, 0, v145, vcc
	v_add_u32_e32 v2, v29, v2
	v_cmp_lt_u32_e64 s[2:3], 31, v2
	s_nop 1
	v_cndmask_b32_e64 v29, 0, v146, s[2:3]
	v_add_u32_e32 v2, v29, v2
	v_cmp_lt_u32_e64 s[4:5], 31, v2
	s_nop 1
	v_cndmask_b32_e64 v29, 0, v146, s[4:5]
	v_add_u32_e32 v2, v29, v2
	v_and_b32_e32 v29, 0x7fffff, v193
	v_or_b32_e32 v29, 0x800000, v29
	v_mad_u64_u32 v[120:121], s[6:7], v29, s61, 0
	v_mov_b32_e32 v80, v121
	v_mad_u64_u32 v[122:123], s[6:7], v29, s62, v[80:81]
	v_mov_b32_e32 v80, v123
	v_mad_u64_u32 v[124:125], s[6:7], v29, s63, v[80:81]
	v_mov_b32_e32 v80, v125
	v_mad_u64_u32 v[126:127], s[6:7], v29, s72, v[80:81]
	v_mov_b32_e32 v80, v127
	v_mad_u64_u32 v[190:191], s[6:7], v29, s73, v[80:81]
	v_mov_b32_e32 v80, v191
	v_mad_u64_u32 v[194:195], s[6:7], v29, s74, v[80:81]
	v_mov_b32_e32 v80, v195
	v_mad_u64_u32 v[196:197], s[6:7], v29, s75, v[80:81]
	v_cndmask_b32_e32 v121, v194, v126, vcc
	v_cndmask_b32_e32 v29, v196, v190, vcc
	v_cndmask_b32_e32 v123, v197, v194, vcc
	v_cndmask_b32_e64 v80, v29, v121, s[2:3]
	v_cndmask_b32_e64 v29, v123, v29, s[2:3]
	v_cndmask_b32_e32 v123, v190, v124, vcc
	v_cndmask_b32_e64 v121, v121, v123, s[2:3]
	v_cndmask_b32_e64 v29, v29, v80, s[4:5]
	v_cndmask_b32_e64 v80, v80, v121, s[4:5]
	v_sub_u32_e32 v125, 32, v2
	v_alignbit_b32 v127, v29, v80, v125
	v_cmp_eq_u32_e64 s[6:7], 0, v2
	v_cndmask_b32_e32 v120, v124, v120, vcc
	s_nop 0
	v_cndmask_b32_e64 v2, v127, v29, s[6:7]
	v_cndmask_b32_e32 v29, v126, v122, vcc
	v_cndmask_b32_e64 v122, v123, v29, s[2:3]
	v_cndmask_b32_e64 v121, v121, v122, s[4:5]
	v_alignbit_b32 v123, v80, v121, v125
	v_cndmask_b32_e64 v80, v123, v80, s[6:7]
	v_bfe_u32 v127, v2, 29, 1
	v_cndmask_b32_e64 v29, v29, v120, s[2:3]
	v_alignbit_b32 v123, v2, v80, 30
	v_sub_u32_e32 v151, 0, v127
	v_cndmask_b32_e64 v29, v122, v29, s[4:5]
	v_xor_b32_e32 v123, v123, v151
	v_alignbit_b32 v120, v121, v29, v125
	v_cndmask_b32_e64 v120, v120, v121, s[6:7]
	v_ffbh_u32_e32 v121, v123
	v_alignbit_b32 v80, v80, v120, 30
	v_min_u32_e32 v121, 32, v121
	v_alignbit_b32 v29, v120, v29, 30
	v_xor_b32_e32 v80, v80, v151
	v_sub_u32_e32 v122, 31, v121
	v_xor_b32_e32 v29, v29, v151
	v_alignbit_b32 v123, v123, v80, v122
	v_alignbit_b32 v29, v80, v29, v122
	v_alignbit_b32 v80, v123, v29, 9
	v_ffbh_u32_e32 v120, v80
	v_min_u32_e32 v120, 32, v120
	v_lshrrev_b32_e32 v126, 29, v2
	v_not_b32_e32 v122, v120
	v_alignbit_b32 v29, v80, v29, v122
	v_lshlrev_b32_e32 v80, 31, v126
	v_or_b32_e32 v122, 0x33000000, v80
	v_add_lshl_u32 v120, v120, v121, 23
	v_lshrrev_b32_e32 v29, 9, v29
	v_sub_u32_e32 v120, v122, v120
	v_or_b32_e32 v80, 0.5, v80
	v_lshlrev_b32_e32 v121, 23, v121
	v_or_b32_e32 v29, v120, v29
	v_lshrrev_b32_e32 v120, 9, v123
	v_sub_u32_e32 v80, v80, v121
	v_or_b32_e32 v80, v120, v80
	v_mul_f32_e32 v120, 0x3fc90fda, v80
	v_fma_f32 v121, v80, s0, -v120
	v_fmac_f32_e32 v121, 0x33a22168, v80
	v_fmac_f32_e32 v121, 0x3fc90fda, v29
	v_lshrrev_b32_e32 v2, 30, v2
	v_add_f32_e32 v195, v120, v121
	v_add_u32_e32 v194, v127, v2
	s_branch .LBB0_145
.Lsl_149:
	v_lshrrev_b32_e32 v2, 23, v29
	v_add_u32_e32 v2, 0xffffff88, v2
	v_cmp_lt_u32_e32 vcc, 63, v2
	s_nop 1
	v_cndmask_b32_e32 v80, 0, v145, vcc
	v_add_u32_e32 v2, v80, v2
	v_cmp_lt_u32_e64 s[2:3], 31, v2
	s_nop 1
	v_cndmask_b32_e64 v80, 0, v146, s[2:3]
	v_add_u32_e32 v2, v80, v2
	v_cmp_lt_u32_e64 s[4:5], 31, v2
	s_nop 1
	v_cndmask_b32_e64 v80, 0, v146, s[4:5]
	v_add_u32_e32 v2, v80, v2
	v_and_b32_e32 v80, 0x7fffff, v29
	v_or_b32_e32 v121, 0x800000, v80
	v_mad_u64_u32 v[122:123], s[6:7], v121, s61, 0
	v_mov_b32_e32 v80, v123
	v_mad_u64_u32 v[124:125], s[6:7], v121, s62, v[80:81]
	v_mov_b32_e32 v80, v125
	v_mad_u64_u32 v[126:127], s[6:7], v121, s63, v[80:81]
	v_mov_b32_e32 v80, v127
	v_mad_u64_u32 v[190:191], s[6:7], v121, s72, v[80:81]
	v_mov_b32_e32 v80, v191
	v_mad_u64_u32 v[196:197], s[6:7], v121, s73, v[80:81]
	v_mov_b32_e32 v80, v197
	v_mad_u64_u32 v[198:199], s[6:7], v121, s74, v[80:81]
	v_mov_b32_e32 v80, v199
	v_mad_u64_u32 v[200:201], s[6:7], v121, s75, v[80:81]
	v_cndmask_b32_e32 v123, v198, v190, vcc
	v_cndmask_b32_e32 v80, v200, v196, vcc
	v_cndmask_b32_e32 v125, v201, v198, vcc
	v_cndmask_b32_e64 v121, v80, v123, s[2:3]
	v_cndmask_b32_e64 v80, v125, v80, s[2:3]
	v_cndmask_b32_e32 v125, v196, v126, vcc
	v_cndmask_b32_e64 v123, v123, v125, s[2:3]
	v_cndmask_b32_e64 v80, v80, v121, s[4:5]
	v_cndmask_b32_e64 v121, v121, v123, s[4:5]
	v_sub_u32_e32 v127, 32, v2
	v_alignbit_b32 v151, v80, v121, v127
	v_cmp_eq_u32_e64 s[6:7], 0, v2
	v_cndmask_b32_e32 v122, v126, v122, vcc
	s_nop 0
	v_cndmask_b32_e64 v2, v151, v80, s[6:7]
	v_cndmask_b32_e32 v80, v190, v124, vcc
	v_cndmask_b32_e64 v124, v125, v80, s[2:3]
	v_cndmask_b32_e64 v123, v123, v124, s[4:5]
	v_alignbit_b32 v125, v121, v123, v127
	v_cndmask_b32_e64 v121, v125, v121, s[6:7]
	v_bfe_u32 v190, v2, 29, 1
	v_cndmask_b32_e64 v80, v80, v122, s[2:3]
	v_alignbit_b32 v125, v2, v121, 30
	v_sub_u32_e32 v191, 0, v190
	v_cndmask_b32_e64 v80, v124, v80, s[4:5]
	v_xor_b32_e32 v125, v125, v191
	v_alignbit_b32 v122, v123, v80, v127
	v_cndmask_b32_e64 v122, v122, v123, s[6:7]
	v_ffbh_u32_e32 v123, v125
	v_alignbit_b32 v121, v121, v122, 30
	v_min_u32_e32 v123, 32, v123
	v_alignbit_b32 v80, v122, v80, 30
	v_xor_b32_e32 v121, v121, v191
	v_sub_u32_e32 v124, 31, v123
	v_xor_b32_e32 v80, v80, v191
	v_alignbit_b32 v125, v125, v121, v124
	v_alignbit_b32 v80, v121, v80, v124
	v_alignbit_b32 v121, v125, v80, 9
	v_ffbh_u32_e32 v122, v121
	v_min_u32_e32 v122, 32, v122
	v_lshrrev_b32_e32 v151, 29, v2
	v_not_b32_e32 v124, v122
	v_alignbit_b32 v80, v121, v80, v124
	v_lshlrev_b32_e32 v121, 31, v151
	v_or_b32_e32 v124, 0x33000000, v121
	v_add_lshl_u32 v122, v122, v123, 23
	v_lshrrev_b32_e32 v80, 9, v80
	v_sub_u32_e32 v122, v124, v122
	v_or_b32_e32 v121, 0.5, v121
	v_lshlrev_b32_e32 v123, 23, v123
	v_or_b32_e32 v80, v122, v80
	v_lshrrev_b32_e32 v122, 9, v125
	v_sub_u32_e32 v121, v121, v123
	v_or_b32_e32 v121, v122, v121
	v_mul_f32_e32 v122, 0x3fc90fda, v121
	v_fma_f32 v123, v121, s0, -v122
	v_fmac_f32_e32 v123, 0x33a22168, v121
	v_fmac_f32_e32 v123, 0x3fc90fda, v80
	v_lshrrev_b32_e32 v2, 30, v2
	v_add_f32_e32 v191, v122, v123
	v_add_u32_e32 v190, v190, v2
	s_branch .LBB0_149
; __device__ __forceinline__ int crow16(int r, int hi) { return (r & 3) + 8 * (r >> 2) + 4 * hi; }
; __device__ __forceinline__ void filter_item32(const Args& a, int L, bf16* KR, int t0, int np0, int npn, int lane) {
;     ...
;         for (int r = 0; r < 16; ++r) { const int j = crow16(r, hi); h0[r] = sinf(fq[j] * (h0[r] + b1[j])); h1[r] = sinf(fq[32 + j] * (h1[r] + b1[32 + j])); }
.Lsl_153:
	v_lshrrev_b32_e32 v2, 23, v199
	v_add_u32_e32 v2, 0xffffff88, v2
	v_cmp_lt_u32_e32 vcc, 63, v2
	s_nop 1
	v_cndmask_b32_e32 v30, 0, v145, vcc
	v_add_u32_e32 v2, v30, v2
	v_cmp_lt_u32_e64 s[2:3], 31, v2
	s_nop 1
	v_cndmask_b32_e64 v30, 0, v146, s[2:3]
	v_add_u32_e32 v2, v30, v2
	v_cmp_lt_u32_e64 s[4:5], 31, v2
	s_nop 1
	v_cndmask_b32_e64 v30, 0, v146, s[4:5]
	v_add_u32_e32 v2, v30, v2
	v_and_b32_e32 v30, 0x7fffff, v199
	v_or_b32_e32 v30, 0x800000, v30
	v_mad_u64_u32 v[122:123], s[6:7], v30, s61, 0
	v_mov_b32_e32 v80, v123
	v_mad_u64_u32 v[124:125], s[6:7], v30, s62, v[80:81]
	v_mov_b32_e32 v80, v125
	v_mad_u64_u32 v[126:127], s[6:7], v30, s63, v[80:81]
	v_mov_b32_e32 v80, v127
	v_mad_u64_u32 v[196:197], s[6:7], v30, s72, v[80:81]
	v_mov_b32_e32 v80, v197
	v_mad_u64_u32 v[200:201], s[6:7], v30, s73, v[80:81]
	v_mov_b32_e32 v80, v201
	v_mad_u64_u32 v[202:203], s[6:7], v30, s74, v[80:81]
	v_mov_b32_e32 v80, v203
	v_mad_u64_u32 v[204:205], s[6:7], v30, s75, v[80:81]
	v_cndmask_b32_e32 v123, v202, v196, vcc
	v_cndmask_b32_e32 v30, v204, v200, vcc
	v_cndmask_b32_e32 v125, v205, v202, vcc
	v_cndmask_b32_e64 v80, v30, v123, s[2:3]
	v_cndmask_b32_e64 v30, v125, v30, s[2:3]
	v_cndmask_b32_e32 v125, v200, v126, vcc
	v_cndmask_b32_e64 v123, v123, v125, s[2:3]
	v_cndmask_b32_e64 v30, v30, v80, s[4:5]
	v_cndmask_b32_e64 v80, v80, v123, s[4:5]
	v_sub_u32_e32 v127, 32, v2
	v_alignbit_b32 v151, v30, v80, v127
	v_cmp_eq_u32_e64 s[6:7], 0, v2
	v_cndmask_b32_e32 v122, v126, v122, vcc
	s_nop 0
	v_cndmask_b32_e64 v2, v151, v30, s[6:7]
	v_cndmask_b32_e32 v30, v196, v124, vcc
	v_cndmask_b32_e64 v124, v125, v30, s[2:3]
	v_cndmask_b32_e64 v123, v123, v124, s[4:5]
	v_alignbit_b32 v125, v80, v123, v127
	v_cndmask_b32_e64 v80, v125, v80, s[6:7]
	v_bfe_u32 v196, v2, 29, 1
	v_cndmask_b32_e64 v30, v30, v122, s[2:3]
	v_alignbit_b32 v125, v2, v80, 30
	v_sub_u32_e32 v197, 0, v196
	v_cndmask_b32_e64 v30, v124, v30, s[4:5]
	v_xor_b32_e32 v125, v125, v197
	v_alignbit_b32 v122, v123, v30, v127
	v_cndmask_b32_e64 v122, v122, v123, s[6:7]
	v_ffbh_u32_e32 v123, v125
	v_alignbit_b32 v80, v80, v122, 30
	v_min_u32_e32 v123, 32, v123
	v_alignbit_b32 v30, v122, v30, 30
	v_xor_b32_e32 v80, v80, v197
	v_sub_u32_e32 v124, 31, v123
	v_xor_b32_e32 v30, v30, v197
	v_alignbit_b32 v125, v125, v80, v124
	v_alignbit_b32 v30, v80, v30, v124
	v_alignbit_b32 v80, v125, v30, 9
	v_ffbh_u32_e32 v122, v80
	v_min_u32_e32 v122, 32, v122
	v_lshrrev_b32_e32 v151, 29, v2
	v_not_b32_e32 v124, v122
	v_alignbit_b32 v30, v80, v30, v124
	v_lshlrev_b32_e32 v80, 31, v151
	v_or_b32_e32 v124, 0x33000000, v80
	v_add_lshl_u32 v122, v122, v123, 23
	v_lshrrev_b32_e32 v30, 9, v30
	v_sub_u32_e32 v122, v124, v122
	v_or_b32_e32 v80, 0.5, v80
	v_lshlrev_b32_e32 v123, 23, v123
	v_or_b32_e32 v30, v122, v30
	v_lshrrev_b32_e32 v122, 9, v125
	v_sub_u32_e32 v80, v80, v123
	v_or_b32_e32 v80, v122, v80
	v_mul_f32_e32 v122, 0x3fc90fda, v80
	v_fma_f32 v123, v80, s0, -v122
	v_fmac_f32_e32 v123, 0x33a22168, v80
	v_fmac_f32_e32 v123, 0x3fc90fda, v30
	v_lshrrev_b32_e32 v2, 30, v2
	v_add_f32_e32 v201, v122, v123
	v_add_u32_e32 v200, v196, v2
	s_branch .LBB0_153
.Lsl_157:
	v_lshrrev_b32_e32 v2, 23, v30
	v_add_u32_e32 v2, 0xffffff88, v2
	v_cmp_lt_u32_e32 vcc, 63, v2
	s_nop 1
	v_cndmask_b32_e32 v80, 0, v145, vcc
	v_add_u32_e32 v2, v80, v2
	v_cmp_lt_u32_e64 s[2:3], 31, v2
	s_nop 1
	v_cndmask_b32_e64 v80, 0, v146, s[2:3]
	v_add_u32_e32 v2, v80, v2
	v_cmp_lt_u32_e64 s[4:5], 31, v2
	s_nop 1
	v_cndmask_b32_e64 v80, 0, v146, s[4:5]
	v_add_u32_e32 v2, v80, v2
	v_and_b32_e32 v80, 0x7fffff, v30
	v_or_b32_e32 v123, 0x800000, v80
	v_mad_u64_u32 v[124:125], s[6:7], v123, s61, 0
	v_mov_b32_e32 v80, v125
	v_mad_u64_u32 v[126:127], s[6:7], v123, s62, v[80:81]
	v_mov_b32_e32 v80, v127
	v_mad_u64_u32 v[196:197], s[6:7], v123, s63, v[80:81]
	v_mov_b32_e32 v80, v197
	v_mad_u64_u32 v[202:203], s[6:7], v123, s72, v[80:81]
	v_mov_b32_e32 v80, v203
	v_mad_u64_u32 v[204:205], s[6:7], v123, s73, v[80:81]
	v_mov_b32_e32 v80, v205
	v_mad_u64_u32 v[206:207], s[6:7], v123, s74, v[80:81]
	v_mov_b32_e32 v80, v207
	v_mad_u64_u32 v[208:209], s[6:7], v123, s75, v[80:81]
	v_cndmask_b32_e32 v125, v206, v202, vcc
	v_cndmask_b32_e32 v80, v208, v204, vcc
	v_cndmask_b32_e32 v127, v209, v206, vcc
	v_cndmask_b32_e64 v123, v80, v125, s[2:3]
	v_cndmask_b32_e64 v80, v127, v80, s[2:3]
	v_cndmask_b32_e32 v127, v204, v196, vcc
	v_cndmask_b32_e64 v125, v125, v127, s[2:3]
	v_cndmask_b32_e64 v80, v80, v123, s[4:5]
	v_cndmask_b32_e64 v123, v123, v125, s[4:5]
	v_sub_u32_e32 v151, 32, v2
	v_alignbit_b32 v197, v80, v123, v151
	v_cmp_eq_u32_e64 s[6:7], 0, v2
	v_cndmask_b32_e32 v124, v196, v124, vcc
	s_nop 0
	v_cndmask_b32_e64 v2, v197, v80, s[6:7]
	v_cndmask_b32_e32 v80, v202, v126, vcc
	v_cndmask_b32_e64 v126, v127, v80, s[2:3]
	v_cndmask_b32_e64 v125, v125, v126, s[4:5]
	v_alignbit_b32 v127, v123, v125, v151
	v_cndmask_b32_e64 v123, v127, v123, s[6:7]
	v_bfe_u32 v202, v2, 29, 1
	v_cndmask_b32_e64 v80, v80, v124, s[2:3]
	v_alignbit_b32 v127, v2, v123, 30
	v_sub_u32_e32 v203, 0, v202
	v_cndmask_b32_e64 v80, v126, v80, s[4:5]
	v_xor_b32_e32 v127, v127, v203
	v_alignbit_b32 v124, v125, v80, v151
	v_cndmask_b32_e64 v124, v124, v125, s[6:7]
	v_ffbh_u32_e32 v125, v127
	v_alignbit_b32 v123, v123, v124, 30
	v_min_u32_e32 v125, 32, v125
	v_alignbit_b32 v80, v124, v80, 30
	v_xor_b32_e32 v123, v123, v203
	v_sub_u32_e32 v126, 31, v125
	v_xor_b32_e32 v80, v80, v203
	v_alignbit_b32 v127, v127, v123, v126
	v_alignbit_b32 v80, v123, v80, v126
	v_alignbit_b32 v123, v127, v80, 9
	v_ffbh_u32_e32 v124, v123
	v_min_u32_e32 v124, 32, v124
	v_lshrrev_b32_e32 v197, 29, v2
	v_not_b32_e32 v126, v124
	v_alignbit_b32 v80, v123, v80, v126
	v_lshlrev_b32_e32 v123, 31, v197
	v_or_b32_e32 v126, 0x33000000, v123
	v_add_lshl_u32 v124, v124, v125, 23
	v_lshrrev_b32_e32 v80, 9, v80
	v_sub_u32_e32 v124, v126, v124
	v_or_b32_e32 v123, 0.5, v123
	v_lshlrev_b32_e32 v125, 23, v125
	v_or_b32_e32 v80, v124, v80
	v_lshrrev_b32_e32 v124, 9, v127
	v_sub_u32_e32 v123, v123, v125
	v_or_b32_e32 v123, v124, v123
	v_mul_f32_e32 v124, 0x3fc90fda, v123
	v_fma_f32 v125, v123, s0, -v124
	v_fmac_f32_e32 v125, 0x33a22168, v123
	v_fmac_f32_e32 v125, 0x3fc90fda, v80
	v_lshrrev_b32_e32 v2, 30, v2
	v_add_f32_e32 v197, v124, v125
	v_add_u32_e32 v196, v202, v2
	s_branch .LBB0_157
; __device__ __forceinline__ int crow16(int r, int hi) { return (r & 3) + 8 * (r >> 2) + 4 * hi; }
; __device__ __forceinline__ void filter_item32(const Args& a, int L, bf16* KR, int t0, int np0, int npn, int lane) {
;     ...
;         for (int r = 0; r < 16; ++r) { const int j = crow16(r, hi); h0[r] = sinf(fq[j] * (h0[r] + b1[j])); h1[r] = sinf(fq[32 + j] * (h1[r] + b1[32 + j])); }
.Lsl_161:
	v_lshrrev_b32_e32 v2, 23, v205
	v_add_u32_e32 v2, 0xffffff88, v2
	v_cmp_lt_u32_e32 vcc, 63, v2
	s_nop 1
	v_cndmask_b32_e32 v31, 0, v145, vcc
	v_add_u32_e32 v2, v31, v2
	v_cmp_lt_u32_e64 s[2:3], 31, v2
	s_nop 1
	v_cndmask_b32_e64 v31, 0, v146, s[2:3]
	v_add_u32_e32 v2, v31, v2
	v_cmp_lt_u32_e64 s[4:5], 31, v2
	s_nop 1
	v_cndmask_b32_e64 v31, 0, v146, s[4:5]
	v_add_u32_e32 v2, v31, v2
	v_and_b32_e32 v31, 0x7fffff, v205
	v_or_b32_e32 v31, 0x800000, v31
	v_mad_u64_u32 v[124:125], s[6:7], v31, s61, 0
	v_mov_b32_e32 v80, v125
	v_mad_u64_u32 v[126:127], s[6:7], v31, s62, v[80:81]
	v_mov_b32_e32 v80, v127
	v_mad_u64_u32 v[202:203], s[6:7], v31, s63, v[80:81]
	v_mov_b32_e32 v80, v203
	v_mad_u64_u32 v[206:207], s[6:7], v31, s72, v[80:81]
	v_mov_b32_e32 v80, v207
	v_mad_u64_u32 v[208:209], s[6:7], v31, s73, v[80:81]
	v_mov_b32_e32 v80, v209
	v_mad_u64_u32 v[210:211], s[6:7], v31, s74, v[80:81]
	v_mov_b32_e32 v80, v211
	v_mad_u64_u32 v[212:213], s[6:7], v31, s75, v[80:81]
	v_cndmask_b32_e32 v125, v210, v206, vcc
	v_cndmask_b32_e32 v31, v212, v208, vcc
	v_cndmask_b32_e32 v127, v213, v210, vcc
	v_cndmask_b32_e64 v80, v31, v125, s[2:3]
	v_cndmask_b32_e64 v31, v127, v31, s[2:3]
	v_cndmask_b32_e32 v127, v208, v202, vcc
	v_cndmask_b32_e64 v125, v125, v127, s[2:3]
	v_cndmask_b32_e64 v31, v31, v80, s[4:5]
	v_cndmask_b32_e64 v80, v80, v125, s[4:5]
	v_sub_u32_e32 v151, 32, v2
	v_alignbit_b32 v203, v31, v80, v151
	v_cmp_eq_u32_e64 s[6:7], 0, v2
	v_cndmask_b32_e32 v124, v202, v124, vcc
	s_nop 0
	v_cndmask_b32_e64 v2, v203, v31, s[6:7]
	v_cndmask_b32_e32 v31, v206, v126, vcc
	v_cndmask_b32_e64 v126, v127, v31, s[2:3]
	v_cndmask_b32_e64 v125, v125, v126, s[4:5]
	v_alignbit_b32 v127, v80, v125, v151
	v_cndmask_b32_e64 v80, v127, v80, s[6:7]
	v_bfe_u32 v206, v2, 29, 1
	v_cndmask_b32_e64 v31, v31, v124, s[2:3]
	v_alignbit_b32 v127, v2, v80, 30
	v_sub_u32_e32 v207, 0, v206
	v_cndmask_b32_e64 v31, v126, v31, s[4:5]
	v_xor_b32_e32 v127, v127, v207
	v_alignbit_b32 v124, v125, v31, v151
	v_cndmask_b32_e64 v124, v124, v125, s[6:7]
	v_ffbh_u32_e32 v125, v127
	v_alignbit_b32 v80, v80, v124, 30
	v_min_u32_e32 v125, 32, v125
	v_alignbit_b32 v31, v124, v31, 30
	v_xor_b32_e32 v80, v80, v207
	v_sub_u32_e32 v126, 31, v125
	v_xor_b32_e32 v31, v31, v207
	v_alignbit_b32 v127, v127, v80, v126
	v_alignbit_b32 v31, v80, v31, v126
	v_alignbit_b32 v80, v127, v31, 9
	v_ffbh_u32_e32 v124, v80
	v_min_u32_e32 v124, 32, v124
	v_lshrrev_b32_e32 v203, 29, v2
	v_not_b32_e32 v126, v124
	v_alignbit_b32 v31, v80, v31, v126
	v_lshlrev_b32_e32 v80, 31, v203
	v_or_b32_e32 v126, 0x33000000, v80
	v_add_lshl_u32 v124, v124, v125, 23
	v_lshrrev_b32_e32 v31, 9, v31
	v_sub_u32_e32 v124, v126, v124
	v_or_b32_e32 v80, 0.5, v80
	v_lshlrev_b32_e32 v125, 23, v125
	v_or_b32_e32 v31, v124, v31
	v_lshrrev_b32_e32 v124, 9, v127
	v_sub_u32_e32 v80, v80, v125
	v_or_b32_e32 v80, v124, v80
	v_mul_f32_e32 v124, 0x3fc90fda, v80
	v_fma_f32 v125, v80, s0, -v124
	v_fmac_f32_e32 v125, 0x33a22168, v80
	v_fmac_f32_e32 v125, 0x3fc90fda, v31
	v_lshrrev_b32_e32 v2, 30, v2
	v_add_f32_e32 v207, v124, v125
	v_add_u32_e32 v206, v206, v2
	s_branch .LBB0_161
.Lsl_165:
	v_lshrrev_b32_e32 v2, 23, v31
	v_add_u32_e32 v2, 0xffffff88, v2
	v_cmp_lt_u32_e32 vcc, 63, v2
	s_nop 1
	v_cndmask_b32_e32 v80, 0, v145, vcc
	v_add_u32_e32 v2, v80, v2
	v_cmp_lt_u32_e64 s[2:3], 31, v2
	s_nop 1
	v_cndmask_b32_e64 v80, 0, v146, s[2:3]
	v_add_u32_e32 v2, v80, v2
	v_cmp_lt_u32_e64 s[4:5], 31, v2
	s_nop 1
	v_cndmask_b32_e64 v80, 0, v146, s[4:5]
	v_add_u32_e32 v2, v80, v2
	v_and_b32_e32 v80, 0x7fffff, v31
	v_or_b32_e32 v125, 0x800000, v80
	v_mad_u64_u32 v[126:127], s[6:7], v125, s61, 0
	v_mov_b32_e32 v80, v127
	v_mad_u64_u32 v[202:203], s[6:7], v125, s62, v[80:81]
	v_mov_b32_e32 v80, v203
	v_mad_u64_u32 v[208:209], s[6:7], v125, s63, v[80:81]
	v_mov_b32_e32 v80, v209
	v_mad_u64_u32 v[210:211], s[6:7], v125, s72, v[80:81]
	v_mov_b32_e32 v80, v211
	v_mad_u64_u32 v[212:213], s[6:7], v125, s73, v[80:81]
	v_mov_b32_e32 v80, v213
	v_mad_u64_u32 v[214:215], s[6:7], v125, s74, v[80:81]
	v_mov_b32_e32 v80, v215
	v_mad_u64_u32 v[216:217], s[6:7], v125, s75, v[80:81]
	v_cndmask_b32_e32 v127, v214, v210, vcc
	v_cndmask_b32_e32 v80, v216, v212, vcc
	v_cndmask_b32_e32 v151, v217, v214, vcc
	v_cndmask_b32_e64 v125, v80, v127, s[2:3]
	v_cndmask_b32_e64 v80, v151, v80, s[2:3]
	v_cndmask_b32_e32 v151, v212, v208, vcc
	v_cndmask_b32_e64 v127, v127, v151, s[2:3]
	v_cndmask_b32_e64 v80, v80, v125, s[4:5]
	v_cndmask_b32_e64 v125, v125, v127, s[4:5]
	v_sub_u32_e32 v203, 32, v2
	v_alignbit_b32 v209, v80, v125, v203
	v_cmp_eq_u32_e64 s[6:7], 0, v2
	v_cndmask_b32_e32 v126, v208, v126, vcc
	s_nop 0
	v_cndmask_b32_e64 v2, v209, v80, s[6:7]
	v_cndmask_b32_e32 v80, v210, v202, vcc
	v_cndmask_b32_e64 v151, v151, v80, s[2:3]
	v_cndmask_b32_e64 v127, v127, v151, s[4:5]
	v_alignbit_b32 v202, v125, v127, v203
	v_cndmask_b32_e64 v125, v202, v125, s[6:7]
	v_bfe_u32 v210, v2, 29, 1
	v_cndmask_b32_e64 v80, v80, v126, s[2:3]
	v_alignbit_b32 v202, v2, v125, 30
	v_sub_u32_e32 v211, 0, v210
	v_cndmask_b32_e64 v80, v151, v80, s[4:5]
	v_xor_b32_e32 v202, v202, v211
	v_alignbit_b32 v126, v127, v80, v203
	v_cndmask_b32_e64 v126, v126, v127, s[6:7]
	v_ffbh_u32_e32 v127, v202
	v_alignbit_b32 v125, v125, v126, 30
	v_min_u32_e32 v127, 32, v127
	v_alignbit_b32 v80, v126, v80, 30
	v_xor_b32_e32 v125, v125, v211
	v_sub_u32_e32 v151, 31, v127
	v_xor_b32_e32 v80, v80, v211
	v_alignbit_b32 v202, v202, v125, v151
	v_alignbit_b32 v80, v125, v80, v151
	v_alignbit_b32 v125, v202, v80, 9
	v_ffbh_u32_e32 v126, v125
	v_min_u32_e32 v126, 32, v126
	v_lshrrev_b32_e32 v209, 29, v2
	v_not_b32_e32 v151, v126
	v_alignbit_b32 v80, v125, v80, v151
	v_lshlrev_b32_e32 v125, 31, v209
	v_or_b32_e32 v151, 0x33000000, v125
	v_add_lshl_u32 v126, v126, v127, 23
	v_lshrrev_b32_e32 v80, 9, v80
	v_sub_u32_e32 v126, v151, v126
	v_or_b32_e32 v125, 0.5, v125
	v_lshlrev_b32_e32 v127, 23, v127
	v_or_b32_e32 v80, v126, v80
	v_lshrrev_b32_e32 v126, 9, v202
	v_sub_u32_e32 v125, v125, v127
	v_or_b32_e32 v125, v126, v125
	v_mul_f32_e32 v126, 0x3fc90fda, v125
	v_fma_f32 v127, v125, s0, -v126
	v_fmac_f32_e32 v127, 0x33a22168, v125
	v_fmac_f32_e32 v127, 0x3fc90fda, v80
	v_lshrrev_b32_e32 v2, 30, v2
	v_add_f32_e32 v203, v126, v127
	v_add_u32_e32 v202, v210, v2
	s_branch .LBB0_165
; __device__ __forceinline__ int crow16(int r, int hi) { return (r & 3) + 8 * (r >> 2) + 4 * hi; }
; __device__ __forceinline__ void filter_item32(const Args& a, int L, bf16* KR, int t0, int np0, int npn, int lane) {
;     ...
;         for (int r = 0; r < 16; ++r) { const int j = crow16(r, hi); h0[r] = sinf(fq[j] * (h0[r] + b1[j])); h1[r] = sinf(fq[32 + j] * (h1[r] + b1[32 + j])); }
;     ...
;         for (int r = 0; r < 16; ++r) { const int j = crow16(r, hi); h0[r] = sinf(fq[j] * (g0[r] + bb[j])); h1[r] = sinf(fq[32 + j] * (g1[r] + bb[32 + j])); }
.Lsl_169:
	v_lshrrev_b32_e32 v2, 23, v211
	v_add_u32_e32 v2, 0xffffff88, v2
	v_cmp_lt_u32_e32 vcc, 63, v2
	s_nop 1
	v_cndmask_b32_e32 v32, 0, v145, vcc
	v_add_u32_e32 v2, v32, v2
	v_cmp_lt_u32_e64 s[2:3], 31, v2
	s_nop 1
	v_cndmask_b32_e64 v32, 0, v146, s[2:3]
	v_add_u32_e32 v2, v32, v2
	v_cmp_lt_u32_e64 s[4:5], 31, v2
	s_nop 1
	v_cndmask_b32_e64 v32, 0, v146, s[4:5]
	v_add_u32_e32 v2, v32, v2
	v_and_b32_e32 v32, 0x7fffff, v211
	v_or_b32_e32 v32, 0x800000, v32
	v_mad_u64_u32 v[126:127], s[6:7], v32, s61, 0
	v_mov_b32_e32 v80, v127
	v_mad_u64_u32 v[208:209], s[6:7], v32, s62, v[80:81]
	v_mov_b32_e32 v80, v209
	v_mad_u64_u32 v[212:213], s[6:7], v32, s63, v[80:81]
	v_mov_b32_e32 v80, v213
	v_mad_u64_u32 v[214:215], s[6:7], v32, s72, v[80:81]
	v_mov_b32_e32 v80, v215
	v_mad_u64_u32 v[216:217], s[6:7], v32, s73, v[80:81]
	v_mov_b32_e32 v80, v217
	v_mad_u64_u32 v[218:219], s[6:7], v32, s74, v[80:81]
	v_mov_b32_e32 v80, v219
	v_mad_u64_u32 v[220:221], s[6:7], v32, s75, v[80:81]
	v_cndmask_b32_e32 v127, v218, v214, vcc
	v_cndmask_b32_e32 v32, v220, v216, vcc
	v_cndmask_b32_e32 v151, v221, v218, vcc
	v_cndmask_b32_e64 v80, v32, v127, s[2:3]
	v_cndmask_b32_e64 v32, v151, v32, s[2:3]
	v_cndmask_b32_e32 v151, v216, v212, vcc
	v_cndmask_b32_e64 v127, v127, v151, s[2:3]
	v_cndmask_b32_e64 v32, v32, v80, s[4:5]
	v_cndmask_b32_e64 v80, v80, v127, s[4:5]
	v_sub_u32_e32 v209, 32, v2
	v_alignbit_b32 v213, v32, v80, v209
	v_cmp_eq_u32_e64 s[6:7], 0, v2
	v_cndmask_b32_e32 v126, v212, v126, vcc
	s_nop 0
	v_cndmask_b32_e64 v2, v213, v32, s[6:7]
	v_cndmask_b32_e32 v32, v214, v208, vcc
	v_cndmask_b32_e64 v151, v151, v32, s[2:3]
	v_cndmask_b32_e64 v127, v127, v151, s[4:5]
	v_alignbit_b32 v208, v80, v127, v209
	v_cndmask_b32_e64 v80, v208, v80, s[6:7]
	v_bfe_u32 v214, v2, 29, 1
	v_cndmask_b32_e64 v32, v32, v126, s[2:3]
	v_alignbit_b32 v208, v2, v80, 30
	v_sub_u32_e32 v215, 0, v214
	v_cndmask_b32_e64 v32, v151, v32, s[4:5]
	v_xor_b32_e32 v208, v208, v215
	v_alignbit_b32 v126, v127, v32, v209
	v_cndmask_b32_e64 v126, v126, v127, s[6:7]
	v_ffbh_u32_e32 v127, v208
	v_alignbit_b32 v80, v80, v126, 30
	v_min_u32_e32 v127, 32, v127
	v_alignbit_b32 v32, v126, v32, 30
	v_xor_b32_e32 v80, v80, v215
	v_sub_u32_e32 v151, 31, v127
	v_xor_b32_e32 v32, v32, v215
	v_alignbit_b32 v208, v208, v80, v151
	v_alignbit_b32 v32, v80, v32, v151
	v_alignbit_b32 v80, v208, v32, 9
	v_ffbh_u32_e32 v126, v80
	v_min_u32_e32 v126, 32, v126
	v_lshrrev_b32_e32 v213, 29, v2
	v_not_b32_e32 v151, v126
	v_alignbit_b32 v32, v80, v32, v151
	v_lshlrev_b32_e32 v80, 31, v213
	v_or_b32_e32 v151, 0x33000000, v80
	v_add_lshl_u32 v126, v126, v127, 23
	v_lshrrev_b32_e32 v32, 9, v32
	v_sub_u32_e32 v126, v151, v126
	v_or_b32_e32 v80, 0.5, v80
	v_lshlrev_b32_e32 v127, 23, v127
	v_or_b32_e32 v32, v126, v32
	v_lshrrev_b32_e32 v126, 9, v208
	v_sub_u32_e32 v80, v80, v127
	v_or_b32_e32 v80, v126, v80
	v_mul_f32_e32 v126, 0x3fc90fda, v80
	v_fma_f32 v127, v80, s0, -v126
	v_fmac_f32_e32 v127, 0x33a22168, v80
	v_fmac_f32_e32 v127, 0x3fc90fda, v32
	v_lshrrev_b32_e32 v2, 30, v2
	v_add_f32_e32 v213, v126, v127
	v_add_u32_e32 v212, v214, v2
	s_branch .LBB0_169
.Lsl_173:
	v_lshrrev_b32_e32 v2, 23, v32
	v_add_u32_e32 v2, 0xffffff88, v2
	v_cmp_lt_u32_e32 vcc, 63, v2
	s_nop 1
	v_cndmask_b32_e32 v80, 0, v145, vcc
	v_add_u32_e32 v2, v80, v2
	v_cmp_lt_u32_e64 s[2:3], 31, v2
	s_nop 1
	v_cndmask_b32_e64 v80, 0, v146, s[2:3]
	v_add_u32_e32 v2, v80, v2
	v_cmp_lt_u32_e64 s[4:5], 31, v2
	s_nop 1
	v_cndmask_b32_e64 v80, 0, v146, s[4:5]
	v_add_u32_e32 v2, v80, v2
	v_and_b32_e32 v80, 0x7fffff, v32
	v_or_b32_e32 v127, 0x800000, v80
	v_mad_u64_u32 v[208:209], s[6:7], v127, s61, 0
	v_mov_b32_e32 v80, v209
	v_mad_u64_u32 v[214:215], s[6:7], v127, s62, v[80:81]
	v_mov_b32_e32 v80, v215
	v_mad_u64_u32 v[216:217], s[6:7], v127, s63, v[80:81]
	v_mov_b32_e32 v80, v217
	v_mad_u64_u32 v[218:219], s[6:7], v127, s72, v[80:81]
	v_mov_b32_e32 v80, v219
	v_mad_u64_u32 v[220:221], s[6:7], v127, s73, v[80:81]
	v_mov_b32_e32 v80, v221
	v_mad_u64_u32 v[222:223], s[6:7], v127, s74, v[80:81]
	v_mov_b32_e32 v80, v223
	v_mad_u64_u32 v[224:225], s[6:7], v127, s75, v[80:81]
	v_cndmask_b32_e32 v151, v222, v218, vcc
	v_cndmask_b32_e32 v80, v224, v220, vcc
	v_cndmask_b32_e32 v209, v225, v222, vcc
	v_cndmask_b32_e64 v127, v80, v151, s[2:3]
	v_cndmask_b32_e64 v80, v209, v80, s[2:3]
	v_cndmask_b32_e32 v209, v220, v216, vcc
	v_cndmask_b32_e64 v151, v151, v209, s[2:3]
	v_cndmask_b32_e64 v80, v80, v127, s[4:5]
	v_cndmask_b32_e64 v127, v127, v151, s[4:5]
	v_sub_u32_e32 v215, 32, v2
	v_alignbit_b32 v217, v80, v127, v215
	v_cmp_eq_u32_e64 s[6:7], 0, v2
	v_cndmask_b32_e32 v208, v216, v208, vcc
	s_nop 0
	v_cndmask_b32_e64 v2, v217, v80, s[6:7]
	v_cndmask_b32_e32 v80, v218, v214, vcc
	v_cndmask_b32_e64 v209, v209, v80, s[2:3]
	v_cndmask_b32_e64 v151, v151, v209, s[4:5]
	v_alignbit_b32 v214, v127, v151, v215
	v_cndmask_b32_e64 v127, v214, v127, s[6:7]
	v_bfe_u32 v218, v2, 29, 1
	v_cndmask_b32_e64 v80, v80, v208, s[2:3]
	v_alignbit_b32 v214, v2, v127, 30
	v_sub_u32_e32 v219, 0, v218
	v_cndmask_b32_e64 v80, v209, v80, s[4:5]
	v_xor_b32_e32 v214, v214, v219
	v_alignbit_b32 v208, v151, v80, v215
	v_cndmask_b32_e64 v151, v208, v151, s[6:7]
	v_ffbh_u32_e32 v208, v214
	v_alignbit_b32 v127, v127, v151, 30
	v_min_u32_e32 v208, 32, v208
	v_alignbit_b32 v80, v151, v80, 30
	v_xor_b32_e32 v127, v127, v219
	v_sub_u32_e32 v209, 31, v208
	v_xor_b32_e32 v80, v80, v219
	v_alignbit_b32 v214, v214, v127, v209
	v_alignbit_b32 v80, v127, v80, v209
	v_alignbit_b32 v127, v214, v80, 9
	v_ffbh_u32_e32 v151, v127
	v_min_u32_e32 v151, 32, v151
	v_lshrrev_b32_e32 v217, 29, v2
	v_not_b32_e32 v209, v151
	v_alignbit_b32 v80, v127, v80, v209
	v_lshlrev_b32_e32 v127, 31, v217
	v_or_b32_e32 v209, 0x33000000, v127
	v_add_lshl_u32 v151, v151, v208, 23
	v_lshrrev_b32_e32 v80, 9, v80
	v_sub_u32_e32 v151, v209, v151
	v_or_b32_e32 v127, 0.5, v127
	v_lshlrev_b32_e32 v208, 23, v208
	v_or_b32_e32 v80, v151, v80
	v_lshrrev_b32_e32 v151, 9, v214
	v_sub_u32_e32 v127, v127, v208
	v_or_b32_e32 v127, v151, v127
	v_mul_f32_e32 v151, 0x3fc90fda, v127
	v_fma_f32 v208, v127, s0, -v151
	v_fmac_f32_e32 v208, 0x33a22168, v127
	v_fmac_f32_e32 v208, 0x3fc90fda, v80
	v_lshrrev_b32_e32 v2, 30, v2
	v_add_f32_e32 v209, v151, v208
	v_add_u32_e32 v208, v218, v2
	s_branch .LBB0_173
; __device__ __forceinline__ int crow16(int r, int hi) { return (r & 3) + 8 * (r >> 2) + 4 * hi; }
; __device__ __forceinline__ void filter_item32(const Args& a, int L, bf16* KR, int t0, int np0, int npn, int lane) {
;     ...
;         for (int r = 0; r < 16; ++r) { const int j = crow16(r, hi); h0[r] = sinf(fq[j] * (h0[r] + b1[j])); h1[r] = sinf(fq[32 + j] * (h1[r] + b1[32 + j])); }
;     ...
;         for (int r = 0; r < 16; ++r) { const int j = crow16(r, hi); h0[r] = sinf(fq[j] * (g0[r] + bb[j])); h1[r] = sinf(fq[32 + j] * (g1[r] + bb[32 + j])); }
.Lsl_177:
	v_lshrrev_b32_e32 v2, 23, v216
	v_add_u32_e32 v2, 0xffffff88, v2
	v_cmp_lt_u32_e32 vcc, 63, v2
	s_nop 1
	v_cndmask_b32_e32 v33, 0, v145, vcc
	v_add_u32_e32 v2, v33, v2
	v_cmp_lt_u32_e64 s[2:3], 31, v2
	s_nop 1
	v_cndmask_b32_e64 v33, 0, v146, s[2:3]
	v_add_u32_e32 v2, v33, v2
	v_cmp_lt_u32_e64 s[4:5], 31, v2
	s_nop 1
	v_cndmask_b32_e64 v33, 0, v146, s[4:5]
	v_add_u32_e32 v2, v33, v2
	v_and_b32_e32 v33, 0x7fffff, v216
	v_or_b32_e32 v33, 0x800000, v33
	v_mad_u64_u32 v[218:219], s[6:7], v33, s61, 0
	v_mov_b32_e32 v80, v219
	v_mad_u64_u32 v[220:221], s[6:7], v33, s62, v[80:81]
	v_mov_b32_e32 v80, v221
	v_mad_u64_u32 v[222:223], s[6:7], v33, s63, v[80:81]
	v_mov_b32_e32 v80, v223
	v_mad_u64_u32 v[224:225], s[6:7], v33, s72, v[80:81]
	v_mov_b32_e32 v80, v225
	v_mad_u64_u32 v[226:227], s[6:7], v33, s73, v[80:81]
	v_mov_b32_e32 v80, v227
	v_mad_u64_u32 v[228:229], s[6:7], v33, s74, v[80:81]
	v_mov_b32_e32 v80, v229
	v_mad_u64_u32 v[230:231], s[6:7], v33, s75, v[80:81]
	v_cndmask_b32_e32 v151, v228, v224, vcc
	v_cndmask_b32_e32 v33, v230, v226, vcc
	v_cndmask_b32_e32 v214, v231, v228, vcc
	v_cndmask_b32_e64 v80, v33, v151, s[2:3]
	v_cndmask_b32_e64 v33, v214, v33, s[2:3]
	v_cndmask_b32_e32 v214, v226, v222, vcc
	v_cndmask_b32_e64 v151, v151, v214, s[2:3]
	v_cndmask_b32_e64 v33, v33, v80, s[4:5]
	v_cndmask_b32_e64 v80, v80, v151, s[4:5]
	v_sub_u32_e32 v217, 32, v2
	v_alignbit_b32 v219, v33, v80, v217
	v_cmp_eq_u32_e64 s[6:7], 0, v2
	v_cndmask_b32_e32 v218, v222, v218, vcc
	s_nop 0
	v_cndmask_b32_e64 v2, v219, v33, s[6:7]
	v_cndmask_b32_e32 v33, v224, v220, vcc
	v_cndmask_b32_e64 v214, v214, v33, s[2:3]
	v_cndmask_b32_e64 v151, v151, v214, s[4:5]
	v_alignbit_b32 v219, v80, v151, v217
	v_cndmask_b32_e64 v80, v219, v80, s[6:7]
	v_bfe_u32 v221, v2, 29, 1
	v_cndmask_b32_e64 v33, v33, v218, s[2:3]
	v_alignbit_b32 v219, v2, v80, 30
	v_sub_u32_e32 v223, 0, v221
	v_cndmask_b32_e64 v33, v214, v33, s[4:5]
	v_xor_b32_e32 v219, v219, v223
	v_alignbit_b32 v214, v151, v33, v217
	v_cndmask_b32_e64 v151, v214, v151, s[6:7]
	v_ffbh_u32_e32 v214, v219
	v_alignbit_b32 v80, v80, v151, 30
	v_min_u32_e32 v214, 32, v214
	v_alignbit_b32 v33, v151, v33, 30
	v_xor_b32_e32 v80, v80, v223
	v_sub_u32_e32 v217, 31, v214
	v_xor_b32_e32 v33, v33, v223
	v_alignbit_b32 v218, v219, v80, v217
	v_alignbit_b32 v33, v80, v33, v217
	v_alignbit_b32 v80, v218, v33, 9
	v_ffbh_u32_e32 v151, v80
	v_min_u32_e32 v151, 32, v151
	v_lshrrev_b32_e32 v220, 29, v2
	v_not_b32_e32 v217, v151
	v_alignbit_b32 v33, v80, v33, v217
	v_lshlrev_b32_e32 v80, 31, v220
	v_or_b32_e32 v217, 0x33000000, v80
	v_add_lshl_u32 v151, v151, v214, 23
	v_lshrrev_b32_e32 v33, 9, v33
	v_sub_u32_e32 v151, v217, v151
	v_or_b32_e32 v80, 0.5, v80
	v_lshlrev_b32_e32 v214, 23, v214
	v_or_b32_e32 v33, v151, v33
	v_lshrrev_b32_e32 v151, 9, v218
	v_sub_u32_e32 v80, v80, v214
	v_or_b32_e32 v80, v151, v80
	v_mul_f32_e32 v151, 0x3fc90fda, v80
	v_fma_f32 v214, v80, s0, -v151
	v_fmac_f32_e32 v214, 0x33a22168, v80
	v_fmac_f32_e32 v214, 0x3fc90fda, v33
	v_lshrrev_b32_e32 v2, 30, v2
	v_add_f32_e32 v218, v151, v214
	v_add_u32_e32 v217, v221, v2
	s_branch .LBB0_177
.Lsl_181:
	v_lshrrev_b32_e32 v2, 23, v33
	v_add_u32_e32 v2, 0xffffff88, v2
	v_cmp_lt_u32_e32 vcc, 63, v2
	s_nop 1
	v_cndmask_b32_e32 v80, 0, v145, vcc
	v_add_u32_e32 v2, v80, v2
	v_cmp_lt_u32_e64 s[2:3], 31, v2
	s_nop 1
	v_cndmask_b32_e64 v80, 0, v146, s[2:3]
	v_add_u32_e32 v2, v80, v2
	v_cmp_lt_u32_e64 s[4:5], 31, v2
	s_nop 1
	v_cndmask_b32_e64 v80, 0, v146, s[4:5]
	v_add_u32_e32 v2, v80, v2
	v_and_b32_e32 v80, 0x7fffff, v33
	v_or_b32_e32 v214, 0x800000, v80
	v_mad_u64_u32 v[220:221], s[6:7], v214, s61, 0
	v_mov_b32_e32 v80, v221
	v_mad_u64_u32 v[222:223], s[6:7], v214, s62, v[80:81]
	v_mov_b32_e32 v80, v223
	v_mad_u64_u32 v[224:225], s[6:7], v214, s63, v[80:81]
	v_mov_b32_e32 v80, v225
	v_mad_u64_u32 v[226:227], s[6:7], v214, s72, v[80:81]
	v_mov_b32_e32 v80, v227
	v_mad_u64_u32 v[228:229], s[6:7], v214, s73, v[80:81]
	v_mov_b32_e32 v80, v229
	v_mad_u64_u32 v[230:231], s[6:7], v214, s74, v[80:81]
	v_mov_b32_e32 v80, v231
	v_mad_u64_u32 v[232:233], s[6:7], v214, s75, v[80:81]
	v_cndmask_b32_e32 v219, v230, v226, vcc
	v_cndmask_b32_e32 v80, v232, v228, vcc
	v_cndmask_b32_e32 v221, v233, v230, vcc
	v_cndmask_b32_e64 v214, v80, v219, s[2:3]
	v_cndmask_b32_e64 v80, v221, v80, s[2:3]
	v_cndmask_b32_e32 v221, v228, v224, vcc
	v_cndmask_b32_e64 v219, v219, v221, s[2:3]
	v_cndmask_b32_e64 v80, v80, v214, s[4:5]
	v_cndmask_b32_e64 v214, v214, v219, s[4:5]
	v_sub_u32_e32 v223, 32, v2
	v_alignbit_b32 v225, v80, v214, v223
	v_cmp_eq_u32_e64 s[6:7], 0, v2
	v_cndmask_b32_e32 v220, v224, v220, vcc
	s_nop 0
	v_cndmask_b32_e64 v2, v225, v80, s[6:7]
	v_cndmask_b32_e32 v80, v226, v222, vcc
	v_cndmask_b32_e64 v221, v221, v80, s[2:3]
	v_cndmask_b32_e64 v219, v219, v221, s[4:5]
	v_alignbit_b32 v222, v214, v219, v223
	v_cndmask_b32_e64 v214, v222, v214, s[6:7]
	v_bfe_u32 v226, v2, 29, 1
	v_cndmask_b32_e64 v80, v80, v220, s[2:3]
	v_alignbit_b32 v222, v2, v214, 30
	v_sub_u32_e32 v227, 0, v226
	v_cndmask_b32_e64 v80, v221, v80, s[4:5]
	v_xor_b32_e32 v222, v222, v227
	v_alignbit_b32 v220, v219, v80, v223
	v_cndmask_b32_e64 v219, v220, v219, s[6:7]
	v_ffbh_u32_e32 v220, v222
	v_alignbit_b32 v214, v214, v219, 30
	v_min_u32_e32 v220, 32, v220
	v_alignbit_b32 v80, v219, v80, 30
	v_xor_b32_e32 v214, v214, v227
	v_sub_u32_e32 v221, 31, v220
	v_xor_b32_e32 v80, v80, v227
	v_alignbit_b32 v222, v222, v214, v221
	v_alignbit_b32 v80, v214, v80, v221
	v_alignbit_b32 v214, v222, v80, 9
	v_ffbh_u32_e32 v219, v214
	v_min_u32_e32 v219, 32, v219
	v_lshrrev_b32_e32 v225, 29, v2
	v_not_b32_e32 v221, v219
	v_alignbit_b32 v80, v214, v80, v221
	v_lshlrev_b32_e32 v214, 31, v225
	v_or_b32_e32 v221, 0x33000000, v214
	v_add_lshl_u32 v219, v219, v220, 23
	v_lshrrev_b32_e32 v80, 9, v80
	v_sub_u32_e32 v219, v221, v219
	v_or_b32_e32 v214, 0.5, v214
	v_lshlrev_b32_e32 v220, 23, v220
	v_or_b32_e32 v80, v219, v80
	v_lshrrev_b32_e32 v219, 9, v222
	v_sub_u32_e32 v214, v214, v220
	v_or_b32_e32 v214, v219, v214
	v_mul_f32_e32 v219, 0x3fc90fda, v214
	v_fma_f32 v220, v214, s0, -v219
	v_fmac_f32_e32 v220, 0x33a22168, v214
	v_fmac_f32_e32 v220, 0x3fc90fda, v80
	v_lshrrev_b32_e32 v2, 30, v2
	v_add_f32_e32 v214, v219, v220
	v_add_u32_e32 v80, v226, v2
	s_branch .LBB0_181
; __device__ __forceinline__ int crow16(int r, int hi) { return (r & 3) + 8 * (r >> 2) + 4 * hi; }
; __device__ __forceinline__ void filter_item32(const Args& a, int L, bf16* KR, int t0, int np0, int npn, int lane) {
;     ...
;         for (int r = 0; r < 16; ++r) { const int j = crow16(r, hi); h0[r] = sinf(fq[j] * (h0[r] + b1[j])); h1[r] = sinf(fq[32 + j] * (h1[r] + b1[32 + j])); }
;     ...
;         for (int r = 0; r < 16; ++r) { const int j = crow16(r, hi); h0[r] = sinf(fq[j] * (g0[r] + bb[j])); h1[r] = sinf(fq[32 + j] * (g1[r] + bb[32 + j])); }
.Lsl_187:
	v_lshrrev_b32_e32 v18, 23, v36
	v_add_u32_e32 v18, 0xffffff88, v18
	v_cmp_lt_u32_e32 vcc, 63, v18
	v_mov_b32_e32 v39, v81
	v_mov_b32_e32 v41, v81
	v_cndmask_b32_e32 v34, 0, v145, vcc
	v_add_u32_e32 v18, v34, v18
	v_cmp_lt_u32_e64 s[2:3], 31, v18
	v_mov_b32_e32 v43, v81
	v_mov_b32_e32 v45, v81
	v_cndmask_b32_e64 v34, 0, v146, s[2:3]
	v_add_u32_e32 v18, v34, v18
	v_cmp_lt_u32_e64 s[4:5], 31, v18
	v_mov_b32_e32 v47, v81
	v_mov_b32_e32 v49, v81
	v_cndmask_b32_e64 v34, 0, v146, s[4:5]
	v_add_u32_e32 v18, v34, v18
	v_and_b32_e32 v34, 0x7fffff, v36
	v_or_b32_e32 v37, 0x800000, v34
	v_mad_u64_u32 v[34:35], s[6:7], v37, s61, 0
	v_mov_b32_e32 v38, v35
	v_mad_u64_u32 v[38:39], s[6:7], v37, s62, v[38:39]
	v_mov_b32_e32 v40, v39
	v_mad_u64_u32 v[40:41], s[6:7], v37, s63, v[40:41]
	v_mov_b32_e32 v42, v41
	v_mad_u64_u32 v[42:43], s[6:7], v37, s72, v[42:43]
	v_mov_b32_e32 v44, v43
	v_mad_u64_u32 v[44:45], s[6:7], v37, s73, v[44:45]
	v_mov_b32_e32 v46, v45
	v_mad_u64_u32 v[46:47], s[6:7], v37, s74, v[46:47]
	v_mov_b32_e32 v48, v47
	v_mad_u64_u32 v[48:49], s[6:7], v37, s75, v[48:49]
	v_cndmask_b32_e32 v35, v46, v42, vcc
	v_cndmask_b32_e32 v37, v48, v44, vcc
	v_cndmask_b32_e32 v41, v49, v46, vcc
	v_cndmask_b32_e64 v39, v37, v35, s[2:3]
	v_cndmask_b32_e64 v37, v41, v37, s[2:3]
	v_cndmask_b32_e32 v41, v44, v40, vcc
	v_cndmask_b32_e64 v35, v35, v41, s[2:3]
	v_cndmask_b32_e64 v37, v37, v39, s[4:5]
	v_cndmask_b32_e64 v39, v39, v35, s[4:5]
	v_sub_u32_e32 v43, 32, v18
	v_alignbit_b32 v44, v37, v39, v43
	v_cmp_eq_u32_e64 s[6:7], 0, v18
	v_cndmask_b32_e32 v34, v40, v34, vcc
	s_nop 0
	v_cndmask_b32_e64 v18, v44, v37, s[6:7]
	v_cndmask_b32_e32 v37, v42, v38, vcc
	v_cndmask_b32_e64 v38, v41, v37, s[2:3]
	v_cndmask_b32_e64 v35, v35, v38, s[4:5]
	v_alignbit_b32 v41, v39, v35, v43
	v_cndmask_b32_e64 v39, v41, v39, s[6:7]
	v_bfe_u32 v44, v18, 29, 1
	v_cndmask_b32_e64 v34, v37, v34, s[2:3]
	v_alignbit_b32 v41, v18, v39, 30
	v_sub_u32_e32 v45, 0, v44
	v_cndmask_b32_e64 v34, v38, v34, s[4:5]
	v_xor_b32_e32 v41, v41, v45
	v_alignbit_b32 v37, v35, v34, v43
	v_cndmask_b32_e64 v35, v37, v35, s[6:7]
	v_ffbh_u32_e32 v38, v41
	v_alignbit_b32 v37, v39, v35, 30
	v_min_u32_e32 v38, 32, v38
	v_alignbit_b32 v34, v35, v34, 30
	v_xor_b32_e32 v37, v37, v45
	v_sub_u32_e32 v39, 31, v38
	v_xor_b32_e32 v34, v34, v45
	v_alignbit_b32 v40, v41, v37, v39
	v_alignbit_b32 v34, v37, v34, v39
	v_alignbit_b32 v35, v40, v34, 9
	v_ffbh_u32_e32 v37, v35
	v_min_u32_e32 v37, 32, v37
	v_lshrrev_b32_e32 v42, 29, v18
	v_not_b32_e32 v39, v37
	v_alignbit_b32 v34, v35, v34, v39
	v_lshlrev_b32_e32 v35, 31, v42
	v_or_b32_e32 v39, 0x33000000, v35
	v_add_lshl_u32 v37, v37, v38, 23
	v_lshrrev_b32_e32 v34, 9, v34
	v_sub_u32_e32 v37, v39, v37
	v_or_b32_e32 v35, 0.5, v35
	v_lshlrev_b32_e32 v38, 23, v38
	v_or_b32_e32 v34, v37, v34
	v_lshrrev_b32_e32 v37, 9, v40
	v_sub_u32_e32 v35, v35, v38
	v_or_b32_e32 v35, v37, v35
	v_mul_f32_e32 v37, 0x3fc90fda, v35
	v_fma_f32 v38, v35, s0, -v37
	v_fmac_f32_e32 v38, 0x33a22168, v35
	v_fmac_f32_e32 v38, 0x3fc90fda, v34
	v_lshrrev_b32_e32 v18, 30, v18
	v_add_f32_e32 v38, v37, v38
	v_add_u32_e32 v37, v44, v18
	s_branch .LBB0_187
.Lsl_191:
	v_lshrrev_b32_e32 v2, 23, v48
	v_add_u32_e32 v2, 0xffffff88, v2
	v_cmp_lt_u32_e32 vcc, 63, v2
	s_nop 1
	v_cndmask_b32_e32 v39, 0, v145, vcc
	v_add_u32_e32 v2, v39, v2
	v_cmp_lt_u32_e64 s[2:3], 31, v2
	s_nop 1
	v_cndmask_b32_e64 v39, 0, v146, s[2:3]
	v_add_u32_e32 v2, v39, v2
	v_cmp_lt_u32_e64 s[4:5], 31, v2
	s_nop 1
	v_cndmask_b32_e64 v39, 0, v146, s[4:5]
	v_add_u32_e32 v2, v39, v2
	v_and_b32_e32 v39, 0x7fffff, v48
	v_or_b32_e32 v39, 0x800000, v39
	v_mad_u64_u32 v[40:41], s[6:7], v39, s61, 0
	v_mov_b32_e32 v80, v41
	v_mad_u64_u32 v[42:43], s[6:7], v39, s62, v[80:81]
	v_mov_b32_e32 v80, v43
	v_mad_u64_u32 v[44:45], s[6:7], v39, s63, v[80:81]
	v_mov_b32_e32 v80, v45
	v_mad_u64_u32 v[46:47], s[6:7], v39, s72, v[80:81]
	v_mov_b32_e32 v80, v47
	v_mad_u64_u32 v[50:51], s[6:7], v39, s73, v[80:81]
	v_mov_b32_e32 v80, v51
	v_mad_u64_u32 v[52:53], s[6:7], v39, s74, v[80:81]
	v_mov_b32_e32 v80, v53
	v_mad_u64_u32 v[54:55], s[6:7], v39, s75, v[80:81]
	v_cndmask_b32_e32 v41, v52, v46, vcc
	v_cndmask_b32_e32 v39, v54, v50, vcc
	v_cndmask_b32_e32 v45, v55, v52, vcc
	v_cndmask_b32_e64 v43, v39, v41, s[2:3]
	v_cndmask_b32_e64 v39, v45, v39, s[2:3]
	v_cndmask_b32_e32 v45, v50, v44, vcc
	v_cndmask_b32_e64 v41, v41, v45, s[2:3]
	v_cndmask_b32_e64 v39, v39, v43, s[4:5]
	v_cndmask_b32_e64 v43, v43, v41, s[4:5]
	v_sub_u32_e32 v47, 32, v2
	v_alignbit_b32 v49, v39, v43, v47
	v_cmp_eq_u32_e64 s[6:7], 0, v2
	v_cndmask_b32_e32 v40, v44, v40, vcc
	s_nop 0
	v_cndmask_b32_e64 v2, v49, v39, s[6:7]
	v_cndmask_b32_e32 v39, v46, v42, vcc
	v_cndmask_b32_e64 v42, v45, v39, s[2:3]
	v_cndmask_b32_e64 v41, v41, v42, s[4:5]
	v_alignbit_b32 v45, v43, v41, v47
	v_cndmask_b32_e64 v43, v45, v43, s[6:7]
	v_bfe_u32 v49, v2, 29, 1
	v_cndmask_b32_e64 v39, v39, v40, s[2:3]
	v_alignbit_b32 v45, v2, v43, 30
	v_sub_u32_e32 v50, 0, v49
	v_cndmask_b32_e64 v39, v42, v39, s[4:5]
	v_xor_b32_e32 v45, v45, v50
	v_alignbit_b32 v40, v41, v39, v47
	v_cndmask_b32_e64 v40, v40, v41, s[6:7]
	v_ffbh_u32_e32 v42, v45
	v_alignbit_b32 v41, v43, v40, 30
	v_min_u32_e32 v42, 32, v42
	v_alignbit_b32 v39, v40, v39, 30
	v_xor_b32_e32 v41, v41, v50
	v_sub_u32_e32 v43, 31, v42
	v_xor_b32_e32 v39, v39, v50
	v_alignbit_b32 v44, v45, v41, v43
	v_alignbit_b32 v39, v41, v39, v43
	v_alignbit_b32 v40, v44, v39, 9
	v_ffbh_u32_e32 v41, v40
	v_min_u32_e32 v41, 32, v41
	v_lshrrev_b32_e32 v46, 29, v2
	v_not_b32_e32 v43, v41
	v_alignbit_b32 v39, v40, v39, v43
	v_lshlrev_b32_e32 v40, 31, v46
	v_or_b32_e32 v43, 0x33000000, v40
	v_add_lshl_u32 v41, v41, v42, 23
	v_lshrrev_b32_e32 v39, 9, v39
	v_sub_u32_e32 v41, v43, v41
	v_or_b32_e32 v40, 0.5, v40
	v_lshlrev_b32_e32 v42, 23, v42
	v_or_b32_e32 v39, v41, v39
	v_lshrrev_b32_e32 v41, 9, v44
	v_sub_u32_e32 v40, v40, v42
	v_or_b32_e32 v40, v41, v40
	v_mul_f32_e32 v41, 0x3fc90fda, v40
	v_fma_f32 v42, v40, s0, -v41
	v_fmac_f32_e32 v42, 0x33a22168, v40
	v_fmac_f32_e32 v42, 0x3fc90fda, v39
	v_lshrrev_b32_e32 v2, 30, v2
	v_add_f32_e32 v50, v41, v42
	v_add_u32_e32 v49, v49, v2
	s_branch .LBB0_191
; __device__ __forceinline__ int crow16(int r, int hi) { return (r & 3) + 8 * (r >> 2) + 4 * hi; }
; __device__ __forceinline__ void filter_item32(const Args& a, int L, bf16* KR, int t0, int np0, int npn, int lane) {
;     ...
;         for (int r = 0; r < 16; ++r) { const int j = crow16(r, hi); h0[r] = sinf(fq[j] * (h0[r] + b1[j])); h1[r] = sinf(fq[32 + j] * (h1[r] + b1[32 + j])); }
;     ...
;         for (int r = 0; r < 16; ++r) { const int j = crow16(r, hi); h0[r] = sinf(fq[j] * (g0[r] + bb[j])); h1[r] = sinf(fq[32 + j] * (g1[r] + bb[32 + j])); }
.Lsl_195:
	v_lshrrev_b32_e32 v2, 23, v40
	v_add_u32_e32 v2, 0xffffff88, v2
	v_cmp_lt_u32_e32 vcc, 63, v2
	s_nop 1
	v_cndmask_b32_e32 v19, 0, v145, vcc
	v_add_u32_e32 v2, v19, v2
	v_cmp_lt_u32_e64 s[2:3], 31, v2
	s_nop 1
	v_cndmask_b32_e64 v19, 0, v146, s[2:3]
	v_add_u32_e32 v2, v19, v2
	v_cmp_lt_u32_e64 s[4:5], 31, v2
	s_nop 1
	v_cndmask_b32_e64 v19, 0, v146, s[4:5]
	v_add_u32_e32 v2, v19, v2
	v_and_b32_e32 v19, 0x7fffff, v40
	v_or_b32_e32 v19, 0x800000, v19
	v_mad_u64_u32 v[42:43], s[6:7], v19, s61, 0
	v_mov_b32_e32 v80, v43
	v_mad_u64_u32 v[44:45], s[6:7], v19, s62, v[80:81]
	v_mov_b32_e32 v80, v45
	v_mad_u64_u32 v[46:47], s[6:7], v19, s63, v[80:81]
	v_mov_b32_e32 v80, v47
	v_mad_u64_u32 v[52:53], s[6:7], v19, s72, v[80:81]
	v_mov_b32_e32 v80, v53
	v_mad_u64_u32 v[54:55], s[6:7], v19, s73, v[80:81]
	v_mov_b32_e32 v80, v55
	v_mad_u64_u32 v[56:57], s[6:7], v19, s74, v[80:81]
	v_mov_b32_e32 v80, v57
	v_mad_u64_u32 v[58:59], s[6:7], v19, s75, v[80:81]
	v_cndmask_b32_e32 v41, v56, v52, vcc
	v_cndmask_b32_e32 v19, v58, v54, vcc
	v_cndmask_b32_e32 v45, v59, v56, vcc
	v_cndmask_b32_e64 v43, v19, v41, s[2:3]
	v_cndmask_b32_e64 v19, v45, v19, s[2:3]
	v_cndmask_b32_e32 v45, v54, v46, vcc
	v_cndmask_b32_e64 v41, v41, v45, s[2:3]
	v_cndmask_b32_e64 v19, v19, v43, s[4:5]
	v_cndmask_b32_e64 v43, v43, v41, s[4:5]
	v_sub_u32_e32 v47, 32, v2
	v_alignbit_b32 v51, v19, v43, v47
	v_cmp_eq_u32_e64 s[6:7], 0, v2
	v_cndmask_b32_e32 v42, v46, v42, vcc
	s_nop 0
	v_cndmask_b32_e64 v2, v51, v19, s[6:7]
	v_cndmask_b32_e32 v19, v52, v44, vcc
	v_cndmask_b32_e64 v44, v45, v19, s[2:3]
	v_cndmask_b32_e64 v41, v41, v44, s[4:5]
	v_alignbit_b32 v45, v43, v41, v47
	v_cndmask_b32_e64 v19, v19, v42, s[2:3]
	v_cndmask_b32_e64 v43, v45, v43, s[6:7]
	v_bfe_u32 v52, v2, 29, 1
	v_cndmask_b32_e64 v19, v44, v19, s[4:5]
	v_alignbit_b32 v45, v2, v43, 30
	v_sub_u32_e32 v53, 0, v52
	v_alignbit_b32 v42, v41, v19, v47
	v_xor_b32_e32 v45, v45, v53
	v_cndmask_b32_e64 v41, v42, v41, s[6:7]
	v_alignbit_b32 v42, v43, v41, 30
	v_ffbh_u32_e32 v43, v45
	v_min_u32_e32 v43, 32, v43
	v_alignbit_b32 v19, v41, v19, 30
	v_xor_b32_e32 v42, v42, v53
	v_sub_u32_e32 v44, 31, v43
	v_xor_b32_e32 v19, v19, v53
	v_alignbit_b32 v45, v45, v42, v44
	v_alignbit_b32 v19, v42, v19, v44
	v_alignbit_b32 v41, v45, v19, 9
	v_ffbh_u32_e32 v42, v41
	v_min_u32_e32 v42, 32, v42
	v_lshrrev_b32_e32 v51, 29, v2
	v_not_b32_e32 v44, v42
	v_alignbit_b32 v19, v41, v19, v44
	v_lshlrev_b32_e32 v41, 31, v51
	v_or_b32_e32 v44, 0x33000000, v41
	v_add_lshl_u32 v42, v42, v43, 23
	v_lshrrev_b32_e32 v19, 9, v19
	v_sub_u32_e32 v42, v44, v42
	v_or_b32_e32 v41, 0.5, v41
	v_lshlrev_b32_e32 v43, 23, v43
	v_or_b32_e32 v19, v42, v19
	v_lshrrev_b32_e32 v42, 9, v45
	v_sub_u32_e32 v41, v41, v43
	v_or_b32_e32 v41, v42, v41
	v_mul_f32_e32 v42, 0x3fc90fda, v41
	v_fma_f32 v43, v41, s0, -v42
	v_fmac_f32_e32 v43, 0x33a22168, v41
	v_fmac_f32_e32 v43, 0x3fc90fda, v19
	v_lshrrev_b32_e32 v2, 30, v2
	v_add_f32_e32 v42, v42, v43
	v_add_u32_e32 v41, v52, v2
	s_branch .LBB0_195
.Lsl_199:
	v_lshrrev_b32_e32 v2, 23, v19
	v_add_u32_e32 v2, 0xffffff88, v2
	v_cmp_lt_u32_e32 vcc, 63, v2
	s_nop 1
	v_cndmask_b32_e32 v43, 0, v145, vcc
	v_add_u32_e32 v2, v43, v2
	v_cmp_lt_u32_e64 s[2:3], 31, v2
	s_nop 1
	v_cndmask_b32_e64 v43, 0, v146, s[2:3]
	v_add_u32_e32 v2, v43, v2
	v_cmp_lt_u32_e64 s[4:5], 31, v2
	s_nop 1
	v_cndmask_b32_e64 v43, 0, v146, s[4:5]
	v_add_u32_e32 v2, v43, v2
	v_and_b32_e32 v43, 0x7fffff, v19
	v_or_b32_e32 v43, 0x800000, v43
	v_mad_u64_u32 v[44:45], s[6:7], v43, s61, 0
	v_mov_b32_e32 v80, v45
	v_mad_u64_u32 v[46:47], s[6:7], v43, s62, v[80:81]
	v_mov_b32_e32 v80, v47
	v_mad_u64_u32 v[52:53], s[6:7], v43, s63, v[80:81]
	v_mov_b32_e32 v80, v53
	v_mad_u64_u32 v[54:55], s[6:7], v43, s72, v[80:81]
	v_mov_b32_e32 v80, v55
	v_mad_u64_u32 v[56:57], s[6:7], v43, s73, v[80:81]
	v_mov_b32_e32 v80, v57
	v_mad_u64_u32 v[58:59], s[6:7], v43, s74, v[80:81]
	v_mov_b32_e32 v80, v59
	v_mad_u64_u32 v[60:61], s[6:7], v43, s75, v[80:81]
	v_cndmask_b32_e32 v45, v58, v54, vcc
	v_cndmask_b32_e32 v43, v60, v56, vcc
	v_cndmask_b32_e32 v51, v61, v58, vcc
	v_cndmask_b32_e64 v47, v43, v45, s[2:3]
	v_cndmask_b32_e64 v43, v51, v43, s[2:3]
	v_cndmask_b32_e32 v51, v56, v52, vcc
	v_cndmask_b32_e64 v45, v45, v51, s[2:3]
	v_cndmask_b32_e64 v43, v43, v47, s[4:5]
	v_cndmask_b32_e64 v47, v47, v45, s[4:5]
	v_sub_u32_e32 v53, 32, v2
	v_alignbit_b32 v55, v43, v47, v53
	v_cmp_eq_u32_e64 s[6:7], 0, v2
	v_cndmask_b32_e32 v44, v52, v44, vcc
	s_nop 0
	v_cndmask_b32_e64 v2, v55, v43, s[6:7]
	v_cndmask_b32_e32 v43, v54, v46, vcc
	v_cndmask_b32_e64 v46, v51, v43, s[2:3]
	v_cndmask_b32_e64 v45, v45, v46, s[4:5]
	v_alignbit_b32 v51, v47, v45, v53
	v_cndmask_b32_e64 v47, v51, v47, s[6:7]
	v_bfe_u32 v55, v2, 29, 1
	v_cndmask_b32_e64 v43, v43, v44, s[2:3]
	v_alignbit_b32 v51, v2, v47, 30
	v_sub_u32_e32 v56, 0, v55
	v_cndmask_b32_e64 v43, v46, v43, s[4:5]
	v_xor_b32_e32 v51, v51, v56
	v_alignbit_b32 v44, v45, v43, v53
	v_cndmask_b32_e64 v44, v44, v45, s[6:7]
	v_ffbh_u32_e32 v46, v51
	v_alignbit_b32 v45, v47, v44, 30
	v_min_u32_e32 v46, 32, v46
	v_alignbit_b32 v43, v44, v43, 30
	v_xor_b32_e32 v45, v45, v56
	v_sub_u32_e32 v47, 31, v46
	v_xor_b32_e32 v43, v43, v56
	v_alignbit_b32 v51, v51, v45, v47
	v_alignbit_b32 v43, v45, v43, v47
	v_alignbit_b32 v44, v51, v43, 9
	v_ffbh_u32_e32 v45, v44
	v_min_u32_e32 v45, 32, v45
	v_lshrrev_b32_e32 v54, 29, v2
	v_not_b32_e32 v47, v45
	v_alignbit_b32 v43, v44, v43, v47
	v_lshlrev_b32_e32 v44, 31, v54
	v_or_b32_e32 v47, 0x33000000, v44
	v_add_lshl_u32 v45, v45, v46, 23
	v_lshrrev_b32_e32 v43, 9, v43
	v_sub_u32_e32 v45, v47, v45
	v_or_b32_e32 v44, 0.5, v44
	v_lshlrev_b32_e32 v46, 23, v46
	v_or_b32_e32 v43, v45, v43
	v_lshrrev_b32_e32 v45, 9, v51
	v_sub_u32_e32 v44, v44, v46
	v_or_b32_e32 v44, v45, v44
	v_mul_f32_e32 v45, 0x3fc90fda, v44
	v_fma_f32 v46, v44, s0, -v45
	v_fmac_f32_e32 v46, 0x33a22168, v44
	v_fmac_f32_e32 v46, 0x3fc90fda, v43
	v_lshrrev_b32_e32 v2, 30, v2
	v_add_f32_e32 v52, v45, v46
	v_add_u32_e32 v51, v55, v2
	s_branch .LBB0_199
; __device__ __forceinline__ int crow16(int r, int hi) { return (r & 3) + 8 * (r >> 2) + 4 * hi; }
; __device__ __forceinline__ void filter_item32(const Args& a, int L, bf16* KR, int t0, int np0, int npn, int lane) {
;     ...
;         for (int r = 0; r < 16; ++r) { const int j = crow16(r, hi); h0[r] = sinf(fq[j] * (h0[r] + b1[j])); h1[r] = sinf(fq[32 + j] * (h1[r] + b1[32 + j])); }
;     ...
;         for (int r = 0; r < 16; ++r) { const int j = crow16(r, hi); h0[r] = sinf(fq[j] * (g0[r] + bb[j])); h1[r] = sinf(fq[32 + j] * (g1[r] + bb[32 + j])); }
.Lsl_203:
	v_lshrrev_b32_e32 v2, 23, v44
	v_add_u32_e32 v2, 0xffffff88, v2
	v_cmp_lt_u32_e32 vcc, 63, v2
	s_nop 1
	v_cndmask_b32_e32 v20, 0, v145, vcc
	v_add_u32_e32 v2, v20, v2
	v_cmp_lt_u32_e64 s[2:3], 31, v2
	s_nop 1
	v_cndmask_b32_e64 v20, 0, v146, s[2:3]
	v_add_u32_e32 v2, v20, v2
	v_cmp_lt_u32_e64 s[4:5], 31, v2
	s_nop 1
	v_cndmask_b32_e64 v20, 0, v146, s[4:5]
	v_add_u32_e32 v2, v20, v2
	v_and_b32_e32 v20, 0x7fffff, v44
	v_or_b32_e32 v20, 0x800000, v20
	v_mad_u64_u32 v[46:47], s[6:7], v20, s61, 0
	v_mov_b32_e32 v80, v47
	v_mad_u64_u32 v[54:55], s[6:7], v20, s62, v[80:81]
	v_mov_b32_e32 v80, v55
	v_mad_u64_u32 v[56:57], s[6:7], v20, s63, v[80:81]
	v_mov_b32_e32 v80, v57
	v_mad_u64_u32 v[58:59], s[6:7], v20, s72, v[80:81]
	v_mov_b32_e32 v80, v59
	v_mad_u64_u32 v[60:61], s[6:7], v20, s73, v[80:81]
	v_mov_b32_e32 v80, v61
	v_mad_u64_u32 v[62:63], s[6:7], v20, s74, v[80:81]
	v_mov_b32_e32 v80, v63
	v_mad_u64_u32 v[152:153], s[6:7], v20, s75, v[80:81]
	v_cndmask_b32_e32 v45, v62, v58, vcc
	v_cndmask_b32_e32 v20, v152, v60, vcc
	v_cndmask_b32_e32 v53, v153, v62, vcc
	v_cndmask_b32_e64 v47, v20, v45, s[2:3]
	v_cndmask_b32_e64 v20, v53, v20, s[2:3]
	v_cndmask_b32_e32 v53, v60, v56, vcc
	v_cndmask_b32_e64 v45, v45, v53, s[2:3]
	v_cndmask_b32_e64 v20, v20, v47, s[4:5]
	v_cndmask_b32_e64 v47, v47, v45, s[4:5]
	v_sub_u32_e32 v55, 32, v2
	v_alignbit_b32 v57, v20, v47, v55
	v_cmp_eq_u32_e64 s[6:7], 0, v2
	v_cndmask_b32_e32 v46, v56, v46, vcc
	s_nop 0
	v_cndmask_b32_e64 v2, v57, v20, s[6:7]
	v_cndmask_b32_e32 v20, v58, v54, vcc
	v_cndmask_b32_e64 v53, v53, v20, s[2:3]
	v_cndmask_b32_e64 v45, v45, v53, s[4:5]
	v_alignbit_b32 v54, v47, v45, v55
	v_cndmask_b32_e64 v20, v20, v46, s[2:3]
	v_cndmask_b32_e64 v47, v54, v47, s[6:7]
	v_bfe_u32 v58, v2, 29, 1
	v_cndmask_b32_e64 v20, v53, v20, s[4:5]
	v_alignbit_b32 v54, v2, v47, 30
	v_sub_u32_e32 v59, 0, v58
	v_alignbit_b32 v46, v45, v20, v55
	v_xor_b32_e32 v54, v54, v59
	v_cndmask_b32_e64 v45, v46, v45, s[6:7]
	v_alignbit_b32 v46, v47, v45, 30
	v_ffbh_u32_e32 v47, v54
	v_min_u32_e32 v47, 32, v47
	v_alignbit_b32 v20, v45, v20, 30
	v_xor_b32_e32 v46, v46, v59
	v_sub_u32_e32 v53, 31, v47
	v_xor_b32_e32 v20, v20, v59
	v_alignbit_b32 v54, v54, v46, v53
	v_alignbit_b32 v20, v46, v20, v53
	v_alignbit_b32 v45, v54, v20, 9
	v_ffbh_u32_e32 v46, v45
	v_min_u32_e32 v46, 32, v46
	v_lshrrev_b32_e32 v57, 29, v2
	v_not_b32_e32 v53, v46
	v_alignbit_b32 v20, v45, v20, v53
	v_lshlrev_b32_e32 v45, 31, v57
	v_or_b32_e32 v53, 0x33000000, v45
	v_add_lshl_u32 v46, v46, v47, 23
	v_lshrrev_b32_e32 v20, 9, v20
	v_sub_u32_e32 v46, v53, v46
	v_or_b32_e32 v45, 0.5, v45
	v_lshlrev_b32_e32 v47, 23, v47
	v_or_b32_e32 v20, v46, v20
	v_lshrrev_b32_e32 v46, 9, v54
	v_sub_u32_e32 v45, v45, v47
	v_or_b32_e32 v45, v46, v45
	v_mul_f32_e32 v46, 0x3fc90fda, v45
	v_fma_f32 v47, v45, s0, -v46
	v_fmac_f32_e32 v47, 0x33a22168, v45
	v_fmac_f32_e32 v47, 0x3fc90fda, v20
	v_lshrrev_b32_e32 v2, 30, v2
	v_add_f32_e32 v46, v46, v47
	v_add_u32_e32 v45, v58, v2
	s_branch .LBB0_203
.Lsl_207:
	v_lshrrev_b32_e32 v2, 23, v20
	v_add_u32_e32 v2, 0xffffff88, v2
	v_cmp_lt_u32_e32 vcc, 63, v2
	s_nop 1
	v_cndmask_b32_e32 v47, 0, v145, vcc
	v_add_u32_e32 v2, v47, v2
	v_cmp_lt_u32_e64 s[2:3], 31, v2
	s_nop 1
	v_cndmask_b32_e64 v47, 0, v146, s[2:3]
	v_add_u32_e32 v2, v47, v2
	v_cmp_lt_u32_e64 s[4:5], 31, v2
	s_nop 1
	v_cndmask_b32_e64 v47, 0, v146, s[4:5]
	v_add_u32_e32 v2, v47, v2
	v_and_b32_e32 v47, 0x7fffff, v20
	v_or_b32_e32 v47, 0x800000, v47
	v_mad_u64_u32 v[54:55], s[6:7], v47, s61, 0
	v_mov_b32_e32 v80, v55
	v_mad_u64_u32 v[56:57], s[6:7], v47, s62, v[80:81]
	v_mov_b32_e32 v80, v57
	v_mad_u64_u32 v[58:59], s[6:7], v47, s63, v[80:81]
	v_mov_b32_e32 v80, v59
	v_mad_u64_u32 v[60:61], s[6:7], v47, s72, v[80:81]
	v_mov_b32_e32 v80, v61
	v_mad_u64_u32 v[62:63], s[6:7], v47, s73, v[80:81]
	v_mov_b32_e32 v80, v63
	v_mad_u64_u32 v[152:153], s[6:7], v47, s74, v[80:81]
	v_mov_b32_e32 v80, v153
	v_mad_u64_u32 v[154:155], s[6:7], v47, s75, v[80:81]
	v_cndmask_b32_e32 v53, v152, v60, vcc
	v_cndmask_b32_e32 v47, v154, v62, vcc
	v_cndmask_b32_e32 v57, v155, v152, vcc
	v_cndmask_b32_e64 v55, v47, v53, s[2:3]
	v_cndmask_b32_e64 v47, v57, v47, s[2:3]
	v_cndmask_b32_e32 v57, v62, v58, vcc
	v_cndmask_b32_e64 v53, v53, v57, s[2:3]
	v_cndmask_b32_e64 v47, v47, v55, s[4:5]
	v_cndmask_b32_e64 v55, v55, v53, s[4:5]
	v_sub_u32_e32 v59, 32, v2
	v_alignbit_b32 v61, v47, v55, v59
	v_cmp_eq_u32_e64 s[6:7], 0, v2
	v_cndmask_b32_e32 v54, v58, v54, vcc
	s_nop 0
	v_cndmask_b32_e64 v2, v61, v47, s[6:7]
	v_cndmask_b32_e32 v47, v60, v56, vcc
	v_cndmask_b32_e64 v56, v57, v47, s[2:3]
	v_cndmask_b32_e64 v53, v53, v56, s[4:5]
	v_alignbit_b32 v57, v55, v53, v59
	v_cndmask_b32_e64 v47, v47, v54, s[2:3]
	v_cndmask_b32_e64 v55, v57, v55, s[6:7]
	v_bfe_u32 v61, v2, 29, 1
	v_cndmask_b32_e64 v47, v56, v47, s[4:5]
	v_alignbit_b32 v57, v2, v55, 30
	v_sub_u32_e32 v62, 0, v61
	v_alignbit_b32 v54, v53, v47, v59
	v_xor_b32_e32 v57, v57, v62
	v_cndmask_b32_e64 v53, v54, v53, s[6:7]
	v_alignbit_b32 v54, v55, v53, 30
	v_ffbh_u32_e32 v55, v57
	v_min_u32_e32 v55, 32, v55
	v_alignbit_b32 v47, v53, v47, 30
	v_xor_b32_e32 v54, v54, v62
	v_sub_u32_e32 v56, 31, v55
	v_xor_b32_e32 v47, v47, v62
	v_alignbit_b32 v57, v57, v54, v56
	v_alignbit_b32 v47, v54, v47, v56
	v_alignbit_b32 v53, v57, v47, 9
	v_ffbh_u32_e32 v54, v53
	v_min_u32_e32 v54, 32, v54
	v_lshrrev_b32_e32 v60, 29, v2
	v_not_b32_e32 v56, v54
	v_alignbit_b32 v47, v53, v47, v56
	v_lshlrev_b32_e32 v53, 31, v60
	v_or_b32_e32 v56, 0x33000000, v53
	v_add_lshl_u32 v54, v54, v55, 23
	v_lshrrev_b32_e32 v47, 9, v47
	v_sub_u32_e32 v54, v56, v54
	v_or_b32_e32 v53, 0.5, v53
	v_lshlrev_b32_e32 v55, 23, v55
	v_or_b32_e32 v47, v54, v47
	v_lshrrev_b32_e32 v54, 9, v57
	v_sub_u32_e32 v53, v53, v55
	v_or_b32_e32 v53, v54, v53
	v_mul_f32_e32 v54, 0x3fc90fda, v53
	v_fma_f32 v55, v53, s0, -v54
	v_fmac_f32_e32 v55, 0x33a22168, v53
	v_fmac_f32_e32 v55, 0x3fc90fda, v47
	v_lshrrev_b32_e32 v2, 30, v2
	v_add_f32_e32 v54, v54, v55
	v_add_u32_e32 v53, v61, v2
	s_branch .LBB0_207
; __device__ __forceinline__ int crow16(int r, int hi) { return (r & 3) + 8 * (r >> 2) + 4 * hi; }
; __device__ __forceinline__ void filter_item32(const Args& a, int L, bf16* KR, int t0, int np0, int npn, int lane) {
;     ...
;         for (int r = 0; r < 16; ++r) { const int j = crow16(r, hi); h0[r] = sinf(fq[j] * (h0[r] + b1[j])); h1[r] = sinf(fq[32 + j] * (h1[r] + b1[32 + j])); }
;     ...
;         for (int r = 0; r < 16; ++r) { const int j = crow16(r, hi); h0[r] = sinf(fq[j] * (g0[r] + bb[j])); h1[r] = sinf(fq[32 + j] * (g1[r] + bb[32 + j])); }
.Lsl_211:
	v_lshrrev_b32_e32 v2, 23, v57
	v_add_u32_e32 v2, 0xffffff88, v2
	v_cmp_lt_u32_e32 vcc, 63, v2
	s_nop 1
	v_cndmask_b32_e32 v21, 0, v145, vcc
	v_add_u32_e32 v2, v21, v2
	v_cmp_lt_u32_e64 s[2:3], 31, v2
	s_nop 1
	v_cndmask_b32_e64 v21, 0, v146, s[2:3]
	v_add_u32_e32 v2, v21, v2
	v_cmp_lt_u32_e64 s[4:5], 31, v2
	s_nop 1
	v_cndmask_b32_e64 v21, 0, v146, s[4:5]
	v_add_u32_e32 v2, v21, v2
	v_and_b32_e32 v21, 0x7fffff, v57
	v_or_b32_e32 v21, 0x800000, v21
	v_mad_u64_u32 v[58:59], s[6:7], v21, s61, 0
	v_mov_b32_e32 v80, v59
	v_mad_u64_u32 v[60:61], s[6:7], v21, s62, v[80:81]
	v_mov_b32_e32 v80, v61
	v_mad_u64_u32 v[62:63], s[6:7], v21, s63, v[80:81]
	v_mov_b32_e32 v80, v63
	v_mad_u64_u32 v[152:153], s[6:7], v21, s72, v[80:81]
	v_mov_b32_e32 v80, v153
	v_mad_u64_u32 v[154:155], s[6:7], v21, s73, v[80:81]
	v_mov_b32_e32 v80, v155
	v_mad_u64_u32 v[156:157], s[6:7], v21, s74, v[80:81]
	v_mov_b32_e32 v80, v157
	v_mad_u64_u32 v[158:159], s[6:7], v21, s75, v[80:81]
	v_cndmask_b32_e32 v55, v156, v152, vcc
	v_cndmask_b32_e32 v21, v158, v154, vcc
	v_cndmask_b32_e32 v59, v159, v156, vcc
	v_cndmask_b32_e64 v56, v21, v55, s[2:3]
	v_cndmask_b32_e64 v21, v59, v21, s[2:3]
	v_cndmask_b32_e32 v59, v154, v62, vcc
	v_cndmask_b32_e64 v55, v55, v59, s[2:3]
	v_cndmask_b32_e64 v21, v21, v56, s[4:5]
	v_cndmask_b32_e64 v56, v56, v55, s[4:5]
	v_sub_u32_e32 v61, 32, v2
	v_alignbit_b32 v63, v21, v56, v61
	v_cmp_eq_u32_e64 s[6:7], 0, v2
	v_cndmask_b32_e32 v58, v62, v58, vcc
	s_nop 0
	v_cndmask_b32_e64 v2, v63, v21, s[6:7]
	v_cndmask_b32_e32 v21, v152, v60, vcc
	v_cndmask_b32_e64 v59, v59, v21, s[2:3]
	v_cndmask_b32_e64 v55, v55, v59, s[4:5]
	v_alignbit_b32 v60, v56, v55, v61
	v_cndmask_b32_e64 v56, v60, v56, s[6:7]
	v_bfe_u32 v80, v2, 29, 1
	v_cndmask_b32_e64 v21, v21, v58, s[2:3]
	v_alignbit_b32 v60, v2, v56, 30
	v_sub_u32_e32 v152, 0, v80
	v_cndmask_b32_e64 v21, v59, v21, s[4:5]
	v_xor_b32_e32 v60, v60, v152
	v_alignbit_b32 v58, v55, v21, v61
	v_cndmask_b32_e64 v55, v58, v55, s[6:7]
	v_ffbh_u32_e32 v58, v60
	v_alignbit_b32 v56, v56, v55, 30
	v_min_u32_e32 v58, 32, v58
	v_alignbit_b32 v21, v55, v21, 30
	v_xor_b32_e32 v56, v56, v152
	v_sub_u32_e32 v59, 31, v58
	v_xor_b32_e32 v21, v21, v152
	v_alignbit_b32 v60, v60, v56, v59
	v_alignbit_b32 v21, v56, v21, v59
	v_alignbit_b32 v55, v60, v21, 9
	v_ffbh_u32_e32 v56, v55
	v_min_u32_e32 v56, 32, v56
	v_lshrrev_b32_e32 v63, 29, v2
	v_not_b32_e32 v59, v56
	v_alignbit_b32 v21, v55, v21, v59
	v_lshlrev_b32_e32 v55, 31, v63
	v_or_b32_e32 v59, 0x33000000, v55
	v_add_lshl_u32 v56, v56, v58, 23
	v_lshrrev_b32_e32 v21, 9, v21
	v_sub_u32_e32 v56, v59, v56
	v_or_b32_e32 v55, 0.5, v55
	v_lshlrev_b32_e32 v58, 23, v58
	v_or_b32_e32 v21, v56, v21
	v_lshrrev_b32_e32 v56, 9, v60
	v_sub_u32_e32 v55, v55, v58
	v_or_b32_e32 v55, v56, v55
	v_mul_f32_e32 v56, 0x3fc90fda, v55
	v_fma_f32 v58, v55, s0, -v56
	v_fmac_f32_e32 v58, 0x33a22168, v55
	v_fmac_f32_e32 v58, 0x3fc90fda, v21
	v_lshrrev_b32_e32 v2, 30, v2
	v_add_f32_e32 v59, v56, v58
	v_add_u32_e32 v58, v80, v2
	s_branch .LBB0_211
.Lsl_215:
	v_lshrrev_b32_e32 v2, 23, v21
	v_add_u32_e32 v2, 0xffffff88, v2
	v_cmp_lt_u32_e32 vcc, 63, v2
	s_nop 1
	v_cndmask_b32_e32 v55, 0, v145, vcc
	v_add_u32_e32 v2, v55, v2
	v_cmp_lt_u32_e64 s[2:3], 31, v2
	s_nop 1
	v_cndmask_b32_e64 v55, 0, v146, s[2:3]
	v_add_u32_e32 v2, v55, v2
	v_cmp_lt_u32_e64 s[4:5], 31, v2
	s_nop 1
	v_cndmask_b32_e64 v55, 0, v146, s[4:5]
	v_add_u32_e32 v2, v55, v2
	v_and_b32_e32 v55, 0x7fffff, v21
	v_or_b32_e32 v55, 0x800000, v55
	v_mad_u64_u32 v[60:61], s[6:7], v55, s61, 0
	v_mov_b32_e32 v80, v61
	v_mad_u64_u32 v[62:63], s[6:7], v55, s62, v[80:81]
	v_mov_b32_e32 v80, v63
	v_mad_u64_u32 v[152:153], s[6:7], v55, s63, v[80:81]
	v_mov_b32_e32 v80, v153
	v_mad_u64_u32 v[154:155], s[6:7], v55, s72, v[80:81]
	v_mov_b32_e32 v80, v155
	v_mad_u64_u32 v[156:157], s[6:7], v55, s73, v[80:81]
	v_mov_b32_e32 v80, v157
	v_mad_u64_u32 v[158:159], s[6:7], v55, s74, v[80:81]
	v_mov_b32_e32 v80, v159
	v_mad_u64_u32 v[164:165], s[6:7], v55, s75, v[80:81]
	v_cndmask_b32_e32 v56, v158, v154, vcc
	v_cndmask_b32_e32 v55, v164, v156, vcc
	v_cndmask_b32_e32 v63, v165, v158, vcc
	v_cndmask_b32_e64 v61, v55, v56, s[2:3]
	v_cndmask_b32_e64 v55, v63, v55, s[2:3]
	v_cndmask_b32_e32 v63, v156, v152, vcc
	v_cndmask_b32_e64 v56, v56, v63, s[2:3]
	v_cndmask_b32_e64 v55, v55, v61, s[4:5]
	v_cndmask_b32_e64 v61, v61, v56, s[4:5]
	v_sub_u32_e32 v80, 32, v2
	v_alignbit_b32 v153, v55, v61, v80
	v_cmp_eq_u32_e64 s[6:7], 0, v2
	v_cndmask_b32_e32 v60, v152, v60, vcc
	s_nop 0
	v_cndmask_b32_e64 v2, v153, v55, s[6:7]
	v_cndmask_b32_e32 v55, v154, v62, vcc
	v_cndmask_b32_e64 v62, v63, v55, s[2:3]
	v_cndmask_b32_e64 v56, v56, v62, s[4:5]
	v_alignbit_b32 v63, v61, v56, v80
	v_cndmask_b32_e64 v55, v55, v60, s[2:3]
	v_cndmask_b32_e64 v61, v63, v61, s[6:7]
	v_bfe_u32 v154, v2, 29, 1
	v_cndmask_b32_e64 v55, v62, v55, s[4:5]
	v_alignbit_b32 v63, v2, v61, 30
	v_sub_u32_e32 v155, 0, v154
	v_alignbit_b32 v60, v56, v55, v80
	v_xor_b32_e32 v63, v63, v155
	v_cndmask_b32_e64 v56, v60, v56, s[6:7]
	v_alignbit_b32 v60, v61, v56, 30
	v_ffbh_u32_e32 v61, v63
	v_min_u32_e32 v61, 32, v61
	v_alignbit_b32 v55, v56, v55, 30
	v_xor_b32_e32 v60, v60, v155
	v_sub_u32_e32 v62, 31, v61
	v_xor_b32_e32 v55, v55, v155
	v_alignbit_b32 v63, v63, v60, v62
	v_alignbit_b32 v55, v60, v55, v62
	v_alignbit_b32 v56, v63, v55, 9
	v_ffbh_u32_e32 v60, v56
	v_min_u32_e32 v60, 32, v60
	v_lshrrev_b32_e32 v153, 29, v2
	v_not_b32_e32 v62, v60
	v_alignbit_b32 v55, v56, v55, v62
	v_lshlrev_b32_e32 v56, 31, v153
	v_or_b32_e32 v62, 0x33000000, v56
	v_add_lshl_u32 v60, v60, v61, 23
	v_lshrrev_b32_e32 v55, 9, v55
	v_sub_u32_e32 v60, v62, v60
	v_or_b32_e32 v56, 0.5, v56
	v_lshlrev_b32_e32 v61, 23, v61
	v_or_b32_e32 v55, v60, v55
	v_lshrrev_b32_e32 v60, 9, v63
	v_sub_u32_e32 v56, v56, v61
	v_or_b32_e32 v56, v60, v56
	v_mul_f32_e32 v60, 0x3fc90fda, v56
	v_fma_f32 v61, v56, s0, -v60
	v_fmac_f32_e32 v61, 0x33a22168, v56
	v_fmac_f32_e32 v61, 0x3fc90fda, v55
	v_lshrrev_b32_e32 v2, 30, v2
	v_add_f32_e32 v56, v60, v61
	v_add_u32_e32 v55, v154, v2
	s_branch .LBB0_215
; __device__ __forceinline__ int crow16(int r, int hi) { return (r & 3) + 8 * (r >> 2) + 4 * hi; }
; __device__ __forceinline__ void filter_item32(const Args& a, int L, bf16* KR, int t0, int np0, int npn, int lane) {
;     ...
;         for (int r = 0; r < 16; ++r) { const int j = crow16(r, hi); h0[r] = sinf(fq[j] * (h0[r] + b1[j])); h1[r] = sinf(fq[32 + j] * (h1[r] + b1[32 + j])); }
;     ...
;         for (int r = 0; r < 16; ++r) { const int j = crow16(r, hi); h0[r] = sinf(fq[j] * (g0[r] + bb[j])); h1[r] = sinf(fq[32 + j] * (g1[r] + bb[32 + j])); }
.Lsl_219:
	v_lshrrev_b32_e32 v2, 23, v63
	v_add_u32_e32 v2, 0xffffff88, v2
	v_cmp_lt_u32_e32 vcc, 63, v2
	s_nop 1
	v_cndmask_b32_e32 v22, 0, v145, vcc
	v_add_u32_e32 v2, v22, v2
	v_cmp_lt_u32_e64 s[2:3], 31, v2
	s_nop 1
	v_cndmask_b32_e64 v22, 0, v146, s[2:3]
	v_add_u32_e32 v2, v22, v2
	v_cmp_lt_u32_e64 s[4:5], 31, v2
	s_nop 1
	v_cndmask_b32_e64 v22, 0, v146, s[4:5]
	v_add_u32_e32 v2, v22, v2
	v_and_b32_e32 v22, 0x7fffff, v63
	v_or_b32_e32 v22, 0x800000, v22
	v_mad_u64_u32 v[60:61], s[6:7], v22, s61, 0
	v_mov_b32_e32 v80, v61
	v_mad_u64_u32 v[152:153], s[6:7], v22, s62, v[80:81]
	v_mov_b32_e32 v80, v153
	v_mad_u64_u32 v[154:155], s[6:7], v22, s63, v[80:81]
	v_mov_b32_e32 v80, v155
	v_mad_u64_u32 v[156:157], s[6:7], v22, s72, v[80:81]
	v_mov_b32_e32 v80, v157
	v_mad_u64_u32 v[158:159], s[6:7], v22, s73, v[80:81]
	v_mov_b32_e32 v80, v159
	v_mad_u64_u32 v[164:165], s[6:7], v22, s74, v[80:81]
	v_mov_b32_e32 v80, v165
	v_mad_u64_u32 v[166:167], s[6:7], v22, s75, v[80:81]
	v_cndmask_b32_e32 v61, v164, v156, vcc
	v_cndmask_b32_e32 v22, v166, v158, vcc
	v_cndmask_b32_e32 v153, v167, v164, vcc
	v_cndmask_b32_e64 v80, v22, v61, s[2:3]
	v_cndmask_b32_e64 v22, v153, v22, s[2:3]
	v_cndmask_b32_e32 v153, v158, v154, vcc
	v_cndmask_b32_e64 v61, v61, v153, s[2:3]
	v_cndmask_b32_e64 v22, v22, v80, s[4:5]
	v_cndmask_b32_e64 v80, v80, v61, s[4:5]
	v_sub_u32_e32 v155, 32, v2
	v_alignbit_b32 v157, v22, v80, v155
	v_cmp_eq_u32_e64 s[6:7], 0, v2
	v_cndmask_b32_e32 v60, v154, v60, vcc
	s_nop 0
	v_cndmask_b32_e64 v2, v157, v22, s[6:7]
	v_cndmask_b32_e32 v22, v156, v152, vcc
	v_cndmask_b32_e64 v152, v153, v22, s[2:3]
	v_cndmask_b32_e64 v61, v61, v152, s[4:5]
	v_alignbit_b32 v153, v80, v61, v155
	v_cndmask_b32_e64 v22, v22, v60, s[2:3]
	v_cndmask_b32_e64 v80, v153, v80, s[6:7]
	v_bfe_u32 v157, v2, 29, 1
	v_cndmask_b32_e64 v22, v152, v22, s[4:5]
	v_alignbit_b32 v153, v2, v80, 30
	v_sub_u32_e32 v158, 0, v157
	v_alignbit_b32 v60, v61, v22, v155
	v_xor_b32_e32 v153, v153, v158
	v_cndmask_b32_e64 v60, v60, v61, s[6:7]
	v_alignbit_b32 v61, v80, v60, 30
	v_ffbh_u32_e32 v80, v153
	v_min_u32_e32 v80, 32, v80
	v_alignbit_b32 v22, v60, v22, 30
	v_xor_b32_e32 v61, v61, v158
	v_sub_u32_e32 v152, 31, v80
	v_xor_b32_e32 v22, v22, v158
	v_alignbit_b32 v153, v153, v61, v152
	v_alignbit_b32 v22, v61, v22, v152
	v_alignbit_b32 v60, v153, v22, 9
	v_ffbh_u32_e32 v61, v60
	v_min_u32_e32 v61, 32, v61
	v_lshrrev_b32_e32 v156, 29, v2
	v_not_b32_e32 v152, v61
	v_alignbit_b32 v22, v60, v22, v152
	v_lshlrev_b32_e32 v60, 31, v156
	v_or_b32_e32 v152, 0x33000000, v60
	v_add_lshl_u32 v61, v61, v80, 23
	v_lshrrev_b32_e32 v22, 9, v22
	v_sub_u32_e32 v61, v152, v61
	v_or_b32_e32 v60, 0.5, v60
	v_lshlrev_b32_e32 v80, 23, v80
	v_or_b32_e32 v22, v61, v22
	v_lshrrev_b32_e32 v61, 9, v153
	v_sub_u32_e32 v60, v60, v80
	v_or_b32_e32 v60, v61, v60
	v_mul_f32_e32 v61, 0x3fc90fda, v60
	v_fma_f32 v80, v60, s0, -v61
	v_fmac_f32_e32 v80, 0x33a22168, v60
	v_fmac_f32_e32 v80, 0x3fc90fda, v22
	v_lshrrev_b32_e32 v2, 30, v2
	v_add_f32_e32 v153, v61, v80
	v_add_u32_e32 v152, v157, v2
	s_branch .LBB0_219
.Lsl_223:
	v_lshrrev_b32_e32 v2, 23, v22
	v_add_u32_e32 v2, 0xffffff88, v2
	v_cmp_lt_u32_e32 vcc, 63, v2
	s_nop 1
	v_cndmask_b32_e32 v60, 0, v145, vcc
	v_add_u32_e32 v2, v60, v2
	v_cmp_lt_u32_e64 s[2:3], 31, v2
	s_nop 1
	v_cndmask_b32_e64 v60, 0, v146, s[2:3]
	v_add_u32_e32 v2, v60, v2
	v_cmp_lt_u32_e64 s[4:5], 31, v2
	s_nop 1
	v_cndmask_b32_e64 v60, 0, v146, s[4:5]
	v_add_u32_e32 v2, v60, v2
	v_and_b32_e32 v60, 0x7fffff, v22
	v_or_b32_e32 v161, 0x800000, v60
	v_mad_u64_u32 v[60:61], s[6:7], v161, s61, 0
	v_mov_b32_e32 v80, v61
	v_mad_u64_u32 v[154:155], s[6:7], v161, s62, v[80:81]
	v_mov_b32_e32 v80, v155
	v_mad_u64_u32 v[156:157], s[6:7], v161, s63, v[80:81]
	v_mov_b32_e32 v80, v157
	v_mad_u64_u32 v[158:159], s[6:7], v161, s72, v[80:81]
	v_mov_b32_e32 v80, v159
	v_mad_u64_u32 v[164:165], s[6:7], v161, s73, v[80:81]
	v_mov_b32_e32 v80, v165
	v_mad_u64_u32 v[166:167], s[6:7], v161, s74, v[80:81]
	v_mov_b32_e32 v80, v167
	v_mad_u64_u32 v[168:169], s[6:7], v161, s75, v[80:81]
	v_cndmask_b32_e32 v61, v166, v158, vcc
	v_cndmask_b32_e32 v80, v168, v164, vcc
	v_cndmask_b32_e32 v157, v169, v166, vcc
	v_cndmask_b32_e64 v155, v80, v61, s[2:3]
	v_cndmask_b32_e64 v80, v157, v80, s[2:3]
	v_cndmask_b32_e32 v157, v164, v156, vcc
	v_cndmask_b32_e64 v61, v61, v157, s[2:3]
	v_cndmask_b32_e64 v80, v80, v155, s[4:5]
	v_cndmask_b32_e64 v155, v155, v61, s[4:5]
	v_sub_u32_e32 v159, 32, v2
	v_alignbit_b32 v161, v80, v155, v159
	v_cmp_eq_u32_e64 s[6:7], 0, v2
	v_cndmask_b32_e32 v60, v156, v60, vcc
	s_nop 0
	v_cndmask_b32_e64 v2, v161, v80, s[6:7]
	v_cndmask_b32_e32 v80, v158, v154, vcc
	v_cndmask_b32_e64 v154, v157, v80, s[2:3]
	v_cndmask_b32_e64 v61, v61, v154, s[4:5]
	v_alignbit_b32 v157, v155, v61, v159
	v_cndmask_b32_e64 v155, v157, v155, s[6:7]
	v_bfe_u32 v161, v2, 29, 1
	v_cndmask_b32_e64 v60, v80, v60, s[2:3]
	v_alignbit_b32 v157, v2, v155, 30
	v_sub_u32_e32 v163, 0, v161
	v_cndmask_b32_e64 v60, v154, v60, s[4:5]
	v_xor_b32_e32 v157, v157, v163
	v_alignbit_b32 v80, v61, v60, v159
	v_cndmask_b32_e64 v61, v80, v61, s[6:7]
	v_ffbh_u32_e32 v154, v157
	v_alignbit_b32 v80, v155, v61, 30
	v_min_u32_e32 v154, 32, v154
	v_alignbit_b32 v60, v61, v60, 30
	v_xor_b32_e32 v80, v80, v163
	v_sub_u32_e32 v155, 31, v154
	v_xor_b32_e32 v60, v60, v163
	v_alignbit_b32 v156, v157, v80, v155
	v_alignbit_b32 v60, v80, v60, v155
	v_alignbit_b32 v61, v156, v60, 9
	v_ffbh_u32_e32 v80, v61
	v_min_u32_e32 v80, 32, v80
	v_lshrrev_b32_e32 v158, 29, v2
	v_not_b32_e32 v155, v80
	v_alignbit_b32 v60, v61, v60, v155
	v_lshlrev_b32_e32 v61, 31, v158
	v_or_b32_e32 v155, 0x33000000, v61
	v_add_lshl_u32 v80, v80, v154, 23
	v_lshrrev_b32_e32 v60, 9, v60
	v_sub_u32_e32 v80, v155, v80
	v_or_b32_e32 v61, 0.5, v61
	v_lshlrev_b32_e32 v154, 23, v154
	v_or_b32_e32 v60, v80, v60
	v_lshrrev_b32_e32 v80, 9, v156
	v_sub_u32_e32 v61, v61, v154
	v_or_b32_e32 v61, v80, v61
	v_mul_f32_e32 v80, 0x3fc90fda, v61
	v_fma_f32 v154, v61, s0, -v80
	v_fmac_f32_e32 v154, 0x33a22168, v61
	v_fmac_f32_e32 v154, 0x3fc90fda, v60
	v_lshrrev_b32_e32 v2, 30, v2
	v_add_f32_e32 v61, v80, v154
	v_add_u32_e32 v60, v161, v2
	s_branch .LBB0_223
; __device__ __forceinline__ int crow16(int r, int hi) { return (r & 3) + 8 * (r >> 2) + 4 * hi; }
; __device__ __forceinline__ void filter_item32(const Args& a, int L, bf16* KR, int t0, int np0, int npn, int lane) {
;     ...
;         for (int r = 0; r < 16; ++r) { const int j = crow16(r, hi); h0[r] = sinf(fq[j] * (h0[r] + b1[j])); h1[r] = sinf(fq[32 + j] * (h1[r] + b1[32 + j])); }
;     ...
;         for (int r = 0; r < 16; ++r) { const int j = crow16(r, hi); h0[r] = sinf(fq[j] * (g0[r] + bb[j])); h1[r] = sinf(fq[32 + j] * (g1[r] + bb[32 + j])); }
.Lsl_227:
	v_lshrrev_b32_e32 v2, 23, v157
	v_add_u32_e32 v2, 0xffffff88, v2
	v_cmp_lt_u32_e32 vcc, 63, v2
	s_nop 1
	v_cndmask_b32_e32 v23, 0, v145, vcc
	v_add_u32_e32 v2, v23, v2
	v_cmp_lt_u32_e64 s[2:3], 31, v2
	s_nop 1
	v_cndmask_b32_e64 v23, 0, v146, s[2:3]
	v_add_u32_e32 v2, v23, v2
	v_cmp_lt_u32_e64 s[4:5], 31, v2
	s_nop 1
	v_cndmask_b32_e64 v23, 0, v146, s[4:5]
	v_add_u32_e32 v2, v23, v2
	v_and_b32_e32 v23, 0x7fffff, v157
	v_or_b32_e32 v23, 0x800000, v23
	v_mad_u64_u32 v[154:155], s[6:7], v23, s61, 0
	v_mov_b32_e32 v80, v155
	v_mad_u64_u32 v[158:159], s[6:7], v23, s62, v[80:81]
	v_mov_b32_e32 v80, v159
	v_mad_u64_u32 v[164:165], s[6:7], v23, s63, v[80:81]
	v_mov_b32_e32 v80, v165
	v_mad_u64_u32 v[166:167], s[6:7], v23, s72, v[80:81]
	v_mov_b32_e32 v80, v167
	v_mad_u64_u32 v[168:169], s[6:7], v23, s73, v[80:81]
	v_mov_b32_e32 v80, v169
	v_mad_u64_u32 v[170:171], s[6:7], v23, s74, v[80:81]
	v_mov_b32_e32 v80, v171
	v_mad_u64_u32 v[172:173], s[6:7], v23, s75, v[80:81]
	v_cndmask_b32_e32 v155, v170, v166, vcc
	v_cndmask_b32_e32 v23, v172, v168, vcc
	v_cndmask_b32_e32 v159, v173, v170, vcc
	v_cndmask_b32_e64 v80, v23, v155, s[2:3]
	v_cndmask_b32_e64 v23, v159, v23, s[2:3]
	v_cndmask_b32_e32 v159, v168, v164, vcc
	v_cndmask_b32_e64 v155, v155, v159, s[2:3]
	v_cndmask_b32_e64 v23, v23, v80, s[4:5]
	v_cndmask_b32_e64 v80, v80, v155, s[4:5]
	v_sub_u32_e32 v161, 32, v2
	v_alignbit_b32 v163, v23, v80, v161
	v_cmp_eq_u32_e64 s[6:7], 0, v2
	v_cndmask_b32_e32 v154, v164, v154, vcc
	s_nop 0
	v_cndmask_b32_e64 v2, v163, v23, s[6:7]
	v_cndmask_b32_e32 v23, v166, v158, vcc
	v_cndmask_b32_e64 v158, v159, v23, s[2:3]
	v_cndmask_b32_e64 v155, v155, v158, s[4:5]
	v_alignbit_b32 v159, v80, v155, v161
	v_cndmask_b32_e64 v80, v159, v80, s[6:7]
	v_bfe_u32 v165, v2, 29, 1
	v_cndmask_b32_e64 v23, v23, v154, s[2:3]
	v_alignbit_b32 v159, v2, v80, 30
	v_sub_u32_e32 v166, 0, v165
	v_cndmask_b32_e64 v23, v158, v23, s[4:5]
	v_xor_b32_e32 v159, v159, v166
	v_alignbit_b32 v154, v155, v23, v161
	v_cndmask_b32_e64 v154, v154, v155, s[6:7]
	v_ffbh_u32_e32 v155, v159
	v_alignbit_b32 v80, v80, v154, 30
	v_min_u32_e32 v155, 32, v155
	v_alignbit_b32 v23, v154, v23, 30
	v_xor_b32_e32 v80, v80, v166
	v_sub_u32_e32 v158, 31, v155
	v_xor_b32_e32 v23, v23, v166
	v_alignbit_b32 v159, v159, v80, v158
	v_alignbit_b32 v23, v80, v23, v158
	v_alignbit_b32 v80, v159, v23, 9
	v_ffbh_u32_e32 v154, v80
	v_min_u32_e32 v154, 32, v154
	v_lshrrev_b32_e32 v163, 29, v2
	v_not_b32_e32 v158, v154
	v_alignbit_b32 v23, v80, v23, v158
	v_lshlrev_b32_e32 v80, 31, v163
	v_or_b32_e32 v158, 0x33000000, v80
	v_add_lshl_u32 v154, v154, v155, 23
	v_lshrrev_b32_e32 v23, 9, v23
	v_sub_u32_e32 v154, v158, v154
	v_or_b32_e32 v80, 0.5, v80
	v_lshlrev_b32_e32 v155, 23, v155
	v_or_b32_e32 v23, v154, v23
	v_lshrrev_b32_e32 v154, 9, v159
	v_sub_u32_e32 v80, v80, v155
	v_or_b32_e32 v80, v154, v80
	v_mul_f32_e32 v154, 0x3fc90fda, v80
	v_fma_f32 v155, v80, s0, -v154
	v_fmac_f32_e32 v155, 0x33a22168, v80
	v_fmac_f32_e32 v155, 0x3fc90fda, v23
	v_lshrrev_b32_e32 v2, 30, v2
	v_add_f32_e32 v159, v154, v155
	v_add_u32_e32 v158, v165, v2
	s_branch .LBB0_227
.Lsl_231:
	v_lshrrev_b32_e32 v2, 23, v23
	v_add_u32_e32 v2, 0xffffff88, v2
	v_cmp_lt_u32_e32 vcc, 63, v2
	s_nop 1
	v_cndmask_b32_e32 v80, 0, v145, vcc
	v_add_u32_e32 v2, v80, v2
	v_cmp_lt_u32_e64 s[2:3], 31, v2
	s_nop 1
	v_cndmask_b32_e64 v80, 0, v146, s[2:3]
	v_add_u32_e32 v2, v80, v2
	v_cmp_lt_u32_e64 s[4:5], 31, v2
	s_nop 1
	v_cndmask_b32_e64 v80, 0, v146, s[4:5]
	v_add_u32_e32 v2, v80, v2
	v_and_b32_e32 v80, 0x7fffff, v23
	v_or_b32_e32 v161, 0x800000, v80
	v_mad_u64_u32 v[154:155], s[6:7], v161, s61, 0
	v_mov_b32_e32 v80, v155
	v_mad_u64_u32 v[164:165], s[6:7], v161, s62, v[80:81]
	v_mov_b32_e32 v80, v165
	v_mad_u64_u32 v[166:167], s[6:7], v161, s63, v[80:81]
	v_mov_b32_e32 v80, v167
	v_mad_u64_u32 v[168:169], s[6:7], v161, s72, v[80:81]
	v_mov_b32_e32 v80, v169
	v_mad_u64_u32 v[170:171], s[6:7], v161, s73, v[80:81]
	v_mov_b32_e32 v80, v171
	v_mad_u64_u32 v[172:173], s[6:7], v161, s74, v[80:81]
	v_mov_b32_e32 v80, v173
	v_mad_u64_u32 v[174:175], s[6:7], v161, s75, v[80:81]
	v_cndmask_b32_e32 v155, v172, v168, vcc
	v_cndmask_b32_e32 v80, v174, v170, vcc
	v_cndmask_b32_e32 v163, v175, v172, vcc
	v_cndmask_b32_e64 v161, v80, v155, s[2:3]
	v_cndmask_b32_e64 v80, v163, v80, s[2:3]
	v_cndmask_b32_e32 v163, v170, v166, vcc
	v_cndmask_b32_e64 v155, v155, v163, s[2:3]
	v_cndmask_b32_e64 v80, v80, v161, s[4:5]
	v_cndmask_b32_e64 v161, v161, v155, s[4:5]
	v_sub_u32_e32 v165, 32, v2
	v_alignbit_b32 v167, v80, v161, v165
	v_cmp_eq_u32_e64 s[6:7], 0, v2
	v_cndmask_b32_e32 v154, v166, v154, vcc
	s_nop 0
	v_cndmask_b32_e64 v2, v167, v80, s[6:7]
	v_cndmask_b32_e32 v80, v168, v164, vcc
	v_cndmask_b32_e64 v163, v163, v80, s[2:3]
	v_cndmask_b32_e64 v155, v155, v163, s[4:5]
	v_alignbit_b32 v164, v161, v155, v165
	v_cndmask_b32_e64 v80, v80, v154, s[2:3]
	v_cndmask_b32_e64 v161, v164, v161, s[6:7]
	v_bfe_u32 v168, v2, 29, 1
	v_cndmask_b32_e64 v80, v163, v80, s[4:5]
	v_alignbit_b32 v164, v2, v161, 30
	v_sub_u32_e32 v169, 0, v168
	v_alignbit_b32 v154, v155, v80, v165
	v_xor_b32_e32 v164, v164, v169
	v_cndmask_b32_e64 v154, v154, v155, s[6:7]
	v_alignbit_b32 v155, v161, v154, 30
	v_ffbh_u32_e32 v161, v164
	v_min_u32_e32 v161, 32, v161
	v_alignbit_b32 v80, v154, v80, 30
	v_xor_b32_e32 v155, v155, v169
	v_sub_u32_e32 v163, 31, v161
	v_xor_b32_e32 v80, v80, v169
	v_alignbit_b32 v164, v164, v155, v163
	v_alignbit_b32 v80, v155, v80, v163
	v_alignbit_b32 v154, v164, v80, 9
	v_ffbh_u32_e32 v155, v154
	v_min_u32_e32 v155, 32, v155
	v_lshrrev_b32_e32 v167, 29, v2
	v_not_b32_e32 v163, v155
	v_alignbit_b32 v80, v154, v80, v163
	v_lshlrev_b32_e32 v154, 31, v167
	v_or_b32_e32 v163, 0x33000000, v154
	v_add_lshl_u32 v155, v155, v161, 23
	v_lshrrev_b32_e32 v80, 9, v80
	v_sub_u32_e32 v155, v163, v155
	v_or_b32_e32 v154, 0.5, v154
	v_lshlrev_b32_e32 v161, 23, v161
	v_or_b32_e32 v80, v155, v80
	v_lshrrev_b32_e32 v155, 9, v164
	v_sub_u32_e32 v154, v154, v161
	v_or_b32_e32 v154, v155, v154
	v_mul_f32_e32 v155, 0x3fc90fda, v154
	v_fma_f32 v161, v154, s0, -v155
	v_fmac_f32_e32 v161, 0x33a22168, v154
	v_fmac_f32_e32 v161, 0x3fc90fda, v80
	v_lshrrev_b32_e32 v2, 30, v2
	v_add_f32_e32 v155, v155, v161
	v_add_u32_e32 v154, v168, v2
	s_branch .LBB0_231
; __device__ __forceinline__ int crow16(int r, int hi) { return (r & 3) + 8 * (r >> 2) + 4 * hi; }
; __device__ __forceinline__ void filter_item32(const Args& a, int L, bf16* KR, int t0, int np0, int npn, int lane) {
;     ...
;         for (int r = 0; r < 16; ++r) { const int j = crow16(r, hi); h0[r] = sinf(fq[j] * (h0[r] + b1[j])); h1[r] = sinf(fq[32 + j] * (h1[r] + b1[32 + j])); }
;     ...
;         for (int r = 0; r < 16; ++r) { const int j = crow16(r, hi); h0[r] = sinf(fq[j] * (g0[r] + bb[j])); h1[r] = sinf(fq[32 + j] * (g1[r] + bb[32 + j])); }
.Lsl_235:
	v_lshrrev_b32_e32 v2, 23, v165
	v_add_u32_e32 v2, 0xffffff88, v2
	v_cmp_lt_u32_e32 vcc, 63, v2
	s_nop 1
	v_cndmask_b32_e32 v24, 0, v145, vcc
	v_add_u32_e32 v2, v24, v2
	v_cmp_lt_u32_e64 s[2:3], 31, v2
	s_nop 1
	v_cndmask_b32_e64 v24, 0, v146, s[2:3]
	v_add_u32_e32 v2, v24, v2
	v_cmp_lt_u32_e64 s[4:5], 31, v2
	s_nop 1
	v_cndmask_b32_e64 v24, 0, v146, s[4:5]
	v_add_u32_e32 v2, v24, v2
	v_and_b32_e32 v24, 0x7fffff, v165
	v_or_b32_e32 v24, 0x800000, v24
	v_mad_u64_u32 v[166:167], s[6:7], v24, s61, 0
	v_mov_b32_e32 v80, v167
	v_mad_u64_u32 v[168:169], s[6:7], v24, s62, v[80:81]
	v_mov_b32_e32 v80, v169
	v_mad_u64_u32 v[170:171], s[6:7], v24, s63, v[80:81]
	v_mov_b32_e32 v80, v171
	v_mad_u64_u32 v[172:173], s[6:7], v24, s72, v[80:81]
	v_mov_b32_e32 v80, v173
	v_mad_u64_u32 v[174:175], s[6:7], v24, s73, v[80:81]
	v_mov_b32_e32 v80, v175
	v_mad_u64_u32 v[176:177], s[6:7], v24, s74, v[80:81]
	v_mov_b32_e32 v80, v177
	v_mad_u64_u32 v[178:179], s[6:7], v24, s75, v[80:81]
	v_cndmask_b32_e32 v161, v176, v172, vcc
	v_cndmask_b32_e32 v24, v178, v174, vcc
	v_cndmask_b32_e32 v163, v179, v176, vcc
	v_cndmask_b32_e64 v80, v24, v161, s[2:3]
	v_cndmask_b32_e64 v24, v163, v24, s[2:3]
	v_cndmask_b32_e32 v163, v174, v170, vcc
	v_cndmask_b32_e64 v161, v161, v163, s[2:3]
	v_cndmask_b32_e64 v24, v24, v80, s[4:5]
	v_cndmask_b32_e64 v80, v80, v161, s[4:5]
	v_sub_u32_e32 v167, 32, v2
	v_alignbit_b32 v169, v24, v80, v167
	v_cmp_eq_u32_e64 s[6:7], 0, v2
	v_cndmask_b32_e32 v166, v170, v166, vcc
	s_nop 0
	v_cndmask_b32_e64 v2, v169, v24, s[6:7]
	v_cndmask_b32_e32 v24, v172, v168, vcc
	v_cndmask_b32_e64 v163, v163, v24, s[2:3]
	v_cndmask_b32_e64 v161, v161, v163, s[4:5]
	v_alignbit_b32 v168, v80, v161, v167
	v_cndmask_b32_e64 v80, v168, v80, s[6:7]
	v_bfe_u32 v171, v2, 29, 1
	v_cndmask_b32_e64 v24, v24, v166, s[2:3]
	v_alignbit_b32 v168, v2, v80, 30
	v_sub_u32_e32 v172, 0, v171
	v_cndmask_b32_e64 v24, v163, v24, s[4:5]
	v_xor_b32_e32 v168, v168, v172
	v_alignbit_b32 v163, v161, v24, v167
	v_cndmask_b32_e64 v161, v163, v161, s[6:7]
	v_ffbh_u32_e32 v163, v168
	v_alignbit_b32 v80, v80, v161, 30
	v_min_u32_e32 v163, 32, v163
	v_alignbit_b32 v24, v161, v24, 30
	v_xor_b32_e32 v80, v80, v172
	v_sub_u32_e32 v166, 31, v163
	v_xor_b32_e32 v24, v24, v172
	v_alignbit_b32 v167, v168, v80, v166
	v_alignbit_b32 v24, v80, v24, v166
	v_alignbit_b32 v80, v167, v24, 9
	v_ffbh_u32_e32 v161, v80
	v_min_u32_e32 v161, 32, v161
	v_lshrrev_b32_e32 v169, 29, v2
	v_not_b32_e32 v166, v161
	v_alignbit_b32 v24, v80, v24, v166
	v_lshlrev_b32_e32 v80, 31, v169
	v_or_b32_e32 v166, 0x33000000, v80
	v_add_lshl_u32 v161, v161, v163, 23
	v_lshrrev_b32_e32 v24, 9, v24
	v_sub_u32_e32 v161, v166, v161
	v_or_b32_e32 v80, 0.5, v80
	v_lshlrev_b32_e32 v163, 23, v163
	v_or_b32_e32 v24, v161, v24
	v_lshrrev_b32_e32 v161, 9, v167
	v_sub_u32_e32 v80, v80, v163
	v_or_b32_e32 v80, v161, v80
	v_mul_f32_e32 v161, 0x3fc90fda, v80
	v_fma_f32 v163, v80, s0, -v161
	v_fmac_f32_e32 v163, 0x33a22168, v80
	v_fmac_f32_e32 v163, 0x3fc90fda, v24
	v_lshrrev_b32_e32 v2, 30, v2
	v_add_f32_e32 v167, v161, v163
	v_add_u32_e32 v166, v171, v2
	s_branch .LBB0_235
.Lsl_239:
	v_lshrrev_b32_e32 v2, 23, v24
	v_add_u32_e32 v2, 0xffffff88, v2
	v_cmp_lt_u32_e32 vcc, 63, v2
	s_nop 1
	v_cndmask_b32_e32 v80, 0, v145, vcc
	v_add_u32_e32 v2, v80, v2
	v_cmp_lt_u32_e64 s[2:3], 31, v2
	s_nop 1
	v_cndmask_b32_e64 v80, 0, v146, s[2:3]
	v_add_u32_e32 v2, v80, v2
	v_cmp_lt_u32_e64 s[4:5], 31, v2
	s_nop 1
	v_cndmask_b32_e64 v80, 0, v146, s[4:5]
	v_add_u32_e32 v2, v80, v2
	v_and_b32_e32 v80, 0x7fffff, v24
	v_or_b32_e32 v161, 0x800000, v80
	v_mad_u64_u32 v[168:169], s[6:7], v161, s61, 0
	v_mov_b32_e32 v80, v169
	v_mad_u64_u32 v[170:171], s[6:7], v161, s62, v[80:81]
	v_mov_b32_e32 v80, v171
	v_mad_u64_u32 v[172:173], s[6:7], v161, s63, v[80:81]
	v_mov_b32_e32 v80, v173
	v_mad_u64_u32 v[174:175], s[6:7], v161, s72, v[80:81]
	v_mov_b32_e32 v80, v175
	v_mad_u64_u32 v[176:177], s[6:7], v161, s73, v[80:81]
	v_mov_b32_e32 v80, v177
	v_mad_u64_u32 v[178:179], s[6:7], v161, s74, v[80:81]
	v_mov_b32_e32 v80, v179
	v_mad_u64_u32 v[180:181], s[6:7], v161, s75, v[80:81]
	v_cndmask_b32_e32 v163, v178, v174, vcc
	v_cndmask_b32_e32 v80, v180, v176, vcc
	v_cndmask_b32_e32 v169, v181, v178, vcc
	v_cndmask_b32_e64 v161, v80, v163, s[2:3]
	v_cndmask_b32_e64 v80, v169, v80, s[2:3]
	v_cndmask_b32_e32 v169, v176, v172, vcc
	v_cndmask_b32_e64 v163, v163, v169, s[2:3]
	v_cndmask_b32_e64 v80, v80, v161, s[4:5]
	v_cndmask_b32_e64 v161, v161, v163, s[4:5]
	v_sub_u32_e32 v171, 32, v2
	v_alignbit_b32 v173, v80, v161, v171
	v_cmp_eq_u32_e64 s[6:7], 0, v2
	v_cndmask_b32_e32 v168, v172, v168, vcc
	s_nop 0
	v_cndmask_b32_e64 v2, v173, v80, s[6:7]
	v_cndmask_b32_e32 v80, v174, v170, vcc
	v_cndmask_b32_e64 v169, v169, v80, s[2:3]
	v_cndmask_b32_e64 v163, v163, v169, s[4:5]
	v_alignbit_b32 v170, v161, v163, v171
	v_cndmask_b32_e64 v161, v170, v161, s[6:7]
	v_bfe_u32 v174, v2, 29, 1
	v_cndmask_b32_e64 v80, v80, v168, s[2:3]
	v_alignbit_b32 v170, v2, v161, 30
	v_sub_u32_e32 v175, 0, v174
	v_cndmask_b32_e64 v80, v169, v80, s[4:5]
	v_xor_b32_e32 v170, v170, v175
	v_alignbit_b32 v168, v163, v80, v171
	v_cndmask_b32_e64 v163, v168, v163, s[6:7]
	v_ffbh_u32_e32 v168, v170
	v_alignbit_b32 v161, v161, v163, 30
	v_min_u32_e32 v168, 32, v168
	v_alignbit_b32 v80, v163, v80, 30
	v_xor_b32_e32 v161, v161, v175
	v_sub_u32_e32 v169, 31, v168
	v_xor_b32_e32 v80, v80, v175
	v_alignbit_b32 v170, v170, v161, v169
	v_alignbit_b32 v80, v161, v80, v169
	v_alignbit_b32 v161, v170, v80, 9
	v_ffbh_u32_e32 v163, v161
	v_min_u32_e32 v163, 32, v163
	v_lshrrev_b32_e32 v173, 29, v2
	v_not_b32_e32 v169, v163
	v_alignbit_b32 v80, v161, v80, v169
	v_lshlrev_b32_e32 v161, 31, v173
	v_or_b32_e32 v169, 0x33000000, v161
	v_add_lshl_u32 v163, v163, v168, 23
	v_lshrrev_b32_e32 v80, 9, v80
	v_sub_u32_e32 v163, v169, v163
	v_or_b32_e32 v161, 0.5, v161
	v_lshlrev_b32_e32 v168, 23, v168
	v_or_b32_e32 v80, v163, v80
	v_lshrrev_b32_e32 v163, 9, v170
	v_sub_u32_e32 v161, v161, v168
	v_or_b32_e32 v161, v163, v161
	v_mul_f32_e32 v163, 0x3fc90fda, v161
	v_fma_f32 v168, v161, s0, -v163
	v_fmac_f32_e32 v168, 0x33a22168, v161
	v_fmac_f32_e32 v168, 0x3fc90fda, v80
	v_lshrrev_b32_e32 v2, 30, v2
	v_add_f32_e32 v163, v163, v168
	v_add_u32_e32 v161, v174, v2
	s_branch .LBB0_239
; __device__ __forceinline__ int crow16(int r, int hi) { return (r & 3) + 8 * (r >> 2) + 4 * hi; }
; __device__ __forceinline__ void filter_item32(const Args& a, int L, bf16* KR, int t0, int np0, int npn, int lane) {
;     ...
;         for (int r = 0; r < 16; ++r) { const int j = crow16(r, hi); h0[r] = sinf(fq[j] * (h0[r] + b1[j])); h1[r] = sinf(fq[32 + j] * (h1[r] + b1[32 + j])); }
;     ...
;         for (int r = 0; r < 16; ++r) { const int j = crow16(r, hi); h0[r] = sinf(fq[j] * (g0[r] + bb[j])); h1[r] = sinf(fq[32 + j] * (g1[r] + bb[32 + j])); }
.Lsl_243:
	v_lshrrev_b32_e32 v2, 23, v171
	v_add_u32_e32 v2, 0xffffff88, v2
	v_cmp_lt_u32_e32 vcc, 63, v2
	s_nop 1
	v_cndmask_b32_e32 v25, 0, v145, vcc
	v_add_u32_e32 v2, v25, v2
	v_cmp_lt_u32_e64 s[2:3], 31, v2
	s_nop 1
	v_cndmask_b32_e64 v25, 0, v146, s[2:3]
	v_add_u32_e32 v2, v25, v2
	v_cmp_lt_u32_e64 s[4:5], 31, v2
	s_nop 1
	v_cndmask_b32_e64 v25, 0, v146, s[4:5]
	v_add_u32_e32 v2, v25, v2
	v_and_b32_e32 v25, 0x7fffff, v171
	v_or_b32_e32 v25, 0x800000, v25
	v_mad_u64_u32 v[168:169], s[6:7], v25, s61, 0
	v_mov_b32_e32 v80, v169
	v_mad_u64_u32 v[172:173], s[6:7], v25, s62, v[80:81]
	v_mov_b32_e32 v80, v173
	v_mad_u64_u32 v[174:175], s[6:7], v25, s63, v[80:81]
	v_mov_b32_e32 v80, v175
	v_mad_u64_u32 v[176:177], s[6:7], v25, s72, v[80:81]
	v_mov_b32_e32 v80, v177
	v_mad_u64_u32 v[178:179], s[6:7], v25, s73, v[80:81]
	v_mov_b32_e32 v80, v179
	v_mad_u64_u32 v[180:181], s[6:7], v25, s74, v[80:81]
	v_mov_b32_e32 v80, v181
	v_mad_u64_u32 v[182:183], s[6:7], v25, s75, v[80:81]
	v_cndmask_b32_e32 v169, v180, v176, vcc
	v_cndmask_b32_e32 v25, v182, v178, vcc
	v_cndmask_b32_e32 v173, v183, v180, vcc
	v_cndmask_b32_e64 v80, v25, v169, s[2:3]
	v_cndmask_b32_e64 v25, v173, v25, s[2:3]
	v_cndmask_b32_e32 v173, v178, v174, vcc
	v_cndmask_b32_e64 v169, v169, v173, s[2:3]
	v_cndmask_b32_e64 v25, v25, v80, s[4:5]
	v_cndmask_b32_e64 v80, v80, v169, s[4:5]
	v_sub_u32_e32 v175, 32, v2
	v_alignbit_b32 v177, v25, v80, v175
	v_cmp_eq_u32_e64 s[6:7], 0, v2
	v_cndmask_b32_e32 v168, v174, v168, vcc
	s_nop 0
	v_cndmask_b32_e64 v2, v177, v25, s[6:7]
	v_cndmask_b32_e32 v25, v176, v172, vcc
	v_cndmask_b32_e64 v172, v173, v25, s[2:3]
	v_cndmask_b32_e64 v169, v169, v172, s[4:5]
	v_alignbit_b32 v173, v80, v169, v175
	v_cndmask_b32_e64 v80, v173, v80, s[6:7]
	v_bfe_u32 v177, v2, 29, 1
	v_cndmask_b32_e64 v25, v25, v168, s[2:3]
	v_alignbit_b32 v173, v2, v80, 30
	v_sub_u32_e32 v178, 0, v177
	v_cndmask_b32_e64 v25, v172, v25, s[4:5]
	v_xor_b32_e32 v173, v173, v178
	v_alignbit_b32 v168, v169, v25, v175
	v_cndmask_b32_e64 v168, v168, v169, s[6:7]
	v_ffbh_u32_e32 v169, v173
	v_alignbit_b32 v80, v80, v168, 30
	v_min_u32_e32 v169, 32, v169
	v_alignbit_b32 v25, v168, v25, 30
	v_xor_b32_e32 v80, v80, v178
	v_sub_u32_e32 v172, 31, v169
	v_xor_b32_e32 v25, v25, v178
	v_alignbit_b32 v173, v173, v80, v172
	v_alignbit_b32 v25, v80, v25, v172
	v_alignbit_b32 v80, v173, v25, 9
	v_ffbh_u32_e32 v168, v80
	v_min_u32_e32 v168, 32, v168
	v_lshrrev_b32_e32 v176, 29, v2
	v_not_b32_e32 v172, v168
	v_alignbit_b32 v25, v80, v25, v172
	v_lshlrev_b32_e32 v80, 31, v176
	v_or_b32_e32 v172, 0x33000000, v80
	v_add_lshl_u32 v168, v168, v169, 23
	v_lshrrev_b32_e32 v25, 9, v25
	v_sub_u32_e32 v168, v172, v168
	v_or_b32_e32 v80, 0.5, v80
	v_lshlrev_b32_e32 v169, 23, v169
	v_or_b32_e32 v25, v168, v25
	v_lshrrev_b32_e32 v168, 9, v173
	v_sub_u32_e32 v80, v80, v169
	v_or_b32_e32 v80, v168, v80
	v_mul_f32_e32 v168, 0x3fc90fda, v80
	v_fma_f32 v169, v80, s0, -v168
	v_fmac_f32_e32 v169, 0x33a22168, v80
	v_fmac_f32_e32 v169, 0x3fc90fda, v25
	v_lshrrev_b32_e32 v2, 30, v2
	v_add_f32_e32 v173, v168, v169
	v_add_u32_e32 v172, v177, v2
	s_branch .LBB0_243
.Lsl_247:
	v_lshrrev_b32_e32 v2, 23, v25
	v_add_u32_e32 v2, 0xffffff88, v2
	v_cmp_lt_u32_e32 vcc, 63, v2
	s_nop 1
	v_cndmask_b32_e32 v80, 0, v145, vcc
	v_add_u32_e32 v2, v80, v2
	v_cmp_lt_u32_e64 s[2:3], 31, v2
	s_nop 1
	v_cndmask_b32_e64 v80, 0, v146, s[2:3]
	v_add_u32_e32 v2, v80, v2
	v_cmp_lt_u32_e64 s[4:5], 31, v2
	s_nop 1
	v_cndmask_b32_e64 v80, 0, v146, s[4:5]
	v_add_u32_e32 v2, v80, v2
	v_and_b32_e32 v80, 0x7fffff, v25
	v_or_b32_e32 v184, 0x800000, v80
	v_mad_u64_u32 v[168:169], s[6:7], v184, s61, 0
	v_mov_b32_e32 v80, v169
	v_mad_u64_u32 v[174:175], s[6:7], v184, s62, v[80:81]
	v_mov_b32_e32 v80, v175
	v_mad_u64_u32 v[176:177], s[6:7], v184, s63, v[80:81]
	v_mov_b32_e32 v80, v177
	v_mad_u64_u32 v[178:179], s[6:7], v184, s72, v[80:81]
	v_mov_b32_e32 v80, v179
	v_mad_u64_u32 v[180:181], s[6:7], v184, s73, v[80:81]
	v_mov_b32_e32 v80, v181
	v_mad_u64_u32 v[182:183], s[6:7], v184, s74, v[80:81]
	v_mov_b32_e32 v80, v183
	v_mad_u64_u32 v[184:185], s[6:7], v184, s75, v[80:81]
	v_cndmask_b32_e32 v169, v182, v178, vcc
	v_cndmask_b32_e32 v80, v184, v180, vcc
	v_cndmask_b32_e32 v177, v185, v182, vcc
	v_cndmask_b32_e64 v175, v80, v169, s[2:3]
	v_cndmask_b32_e64 v80, v177, v80, s[2:3]
	v_cndmask_b32_e32 v177, v180, v176, vcc
	v_cndmask_b32_e64 v169, v169, v177, s[2:3]
	v_cndmask_b32_e64 v80, v80, v175, s[4:5]
	v_cndmask_b32_e64 v175, v175, v169, s[4:5]
	v_sub_u32_e32 v179, 32, v2
	v_alignbit_b32 v180, v80, v175, v179
	v_cmp_eq_u32_e64 s[6:7], 0, v2
	v_cndmask_b32_e32 v168, v176, v168, vcc
	s_nop 0
	v_cndmask_b32_e64 v2, v180, v80, s[6:7]
	v_cndmask_b32_e32 v80, v178, v174, vcc
	v_cndmask_b32_e64 v174, v177, v80, s[2:3]
	v_cndmask_b32_e64 v169, v169, v174, s[4:5]
	v_alignbit_b32 v177, v175, v169, v179
	v_cndmask_b32_e64 v175, v177, v175, s[6:7]
	v_bfe_u32 v180, v2, 29, 1
	v_cndmask_b32_e64 v80, v80, v168, s[2:3]
	v_alignbit_b32 v177, v2, v175, 30
	v_sub_u32_e32 v181, 0, v180
	v_cndmask_b32_e64 v80, v174, v80, s[4:5]
	v_xor_b32_e32 v177, v177, v181
	v_alignbit_b32 v168, v169, v80, v179
	v_cndmask_b32_e64 v168, v168, v169, s[6:7]
	v_ffbh_u32_e32 v174, v177
	v_alignbit_b32 v169, v175, v168, 30
	v_min_u32_e32 v174, 32, v174
	v_alignbit_b32 v80, v168, v80, 30
	v_xor_b32_e32 v169, v169, v181
	v_sub_u32_e32 v175, 31, v174
	v_xor_b32_e32 v80, v80, v181
	v_alignbit_b32 v176, v177, v169, v175
	v_alignbit_b32 v80, v169, v80, v175
	v_alignbit_b32 v168, v176, v80, 9
	v_ffbh_u32_e32 v169, v168
	v_min_u32_e32 v169, 32, v169
	v_lshrrev_b32_e32 v178, 29, v2
	v_not_b32_e32 v175, v169
	v_alignbit_b32 v80, v168, v80, v175
	v_lshlrev_b32_e32 v168, 31, v178
	v_or_b32_e32 v175, 0x33000000, v168
	v_add_lshl_u32 v169, v169, v174, 23
	v_lshrrev_b32_e32 v80, 9, v80
	v_sub_u32_e32 v169, v175, v169
	v_or_b32_e32 v168, 0.5, v168
	v_lshlrev_b32_e32 v174, 23, v174
	v_or_b32_e32 v80, v169, v80
	v_lshrrev_b32_e32 v169, 9, v176
	v_sub_u32_e32 v168, v168, v174
	v_or_b32_e32 v168, v169, v168
	v_mul_f32_e32 v169, 0x3fc90fda, v168
	v_fma_f32 v174, v168, s0, -v169
	v_fmac_f32_e32 v174, 0x33a22168, v168
	v_fmac_f32_e32 v174, 0x3fc90fda, v80
	v_lshrrev_b32_e32 v2, 30, v2
	v_add_f32_e32 v169, v169, v174
	v_add_u32_e32 v168, v180, v2
	s_branch .LBB0_247
; __device__ __forceinline__ int crow16(int r, int hi) { return (r & 3) + 8 * (r >> 2) + 4 * hi; }
; __device__ __forceinline__ void filter_item32(const Args& a, int L, bf16* KR, int t0, int np0, int npn, int lane) {
;     ...
;         for (int r = 0; r < 16; ++r) { const int j = crow16(r, hi); h0[r] = sinf(fq[j] * (h0[r] + b1[j])); h1[r] = sinf(fq[32 + j] * (h1[r] + b1[32 + j])); }
;     ...
;         for (int r = 0; r < 16; ++r) { const int j = crow16(r, hi); h0[r] = sinf(fq[j] * (g0[r] + bb[j])); h1[r] = sinf(fq[32 + j] * (g1[r] + bb[32 + j])); }
.Lsl_251:
	v_lshrrev_b32_e32 v2, 23, v177
	v_add_u32_e32 v2, 0xffffff88, v2
	v_cmp_lt_u32_e32 vcc, 63, v2
	s_nop 1
	v_cndmask_b32_e32 v26, 0, v145, vcc
	v_add_u32_e32 v2, v26, v2
	v_cmp_lt_u32_e64 s[2:3], 31, v2
	s_nop 1
	v_cndmask_b32_e64 v26, 0, v146, s[2:3]
	v_add_u32_e32 v2, v26, v2
	v_cmp_lt_u32_e64 s[4:5], 31, v2
	s_nop 1
	v_cndmask_b32_e64 v26, 0, v146, s[4:5]
	v_add_u32_e32 v2, v26, v2
	v_and_b32_e32 v26, 0x7fffff, v177
	v_or_b32_e32 v26, 0x800000, v26
	v_mad_u64_u32 v[174:175], s[6:7], v26, s61, 0
	v_mov_b32_e32 v80, v175
	v_mad_u64_u32 v[178:179], s[6:7], v26, s62, v[80:81]
	v_mov_b32_e32 v80, v179
	v_mad_u64_u32 v[180:181], s[6:7], v26, s63, v[80:81]
	v_mov_b32_e32 v80, v181
	v_mad_u64_u32 v[182:183], s[6:7], v26, s72, v[80:81]
	v_mov_b32_e32 v80, v183
	v_mad_u64_u32 v[184:185], s[6:7], v26, s73, v[80:81]
	v_mov_b32_e32 v80, v185
	v_mad_u64_u32 v[186:187], s[6:7], v26, s74, v[80:81]
	v_mov_b32_e32 v80, v187
	v_mad_u64_u32 v[188:189], s[6:7], v26, s75, v[80:81]
	v_cndmask_b32_e32 v175, v186, v182, vcc
	v_cndmask_b32_e32 v26, v188, v184, vcc
	v_cndmask_b32_e32 v179, v189, v186, vcc
	v_cndmask_b32_e64 v80, v26, v175, s[2:3]
	v_cndmask_b32_e64 v26, v179, v26, s[2:3]
	v_cndmask_b32_e32 v179, v184, v180, vcc
	v_cndmask_b32_e64 v175, v175, v179, s[2:3]
	v_cndmask_b32_e64 v26, v26, v80, s[4:5]
	v_cndmask_b32_e64 v80, v80, v175, s[4:5]
	v_sub_u32_e32 v181, 32, v2
	v_alignbit_b32 v183, v26, v80, v181
	v_cmp_eq_u32_e64 s[6:7], 0, v2
	v_cndmask_b32_e32 v174, v180, v174, vcc
	s_nop 0
	v_cndmask_b32_e64 v2, v183, v26, s[6:7]
	v_cndmask_b32_e32 v26, v182, v178, vcc
	v_cndmask_b32_e64 v178, v179, v26, s[2:3]
	v_cndmask_b32_e64 v175, v175, v178, s[4:5]
	v_alignbit_b32 v179, v80, v175, v181
	v_cndmask_b32_e64 v80, v179, v80, s[6:7]
	v_bfe_u32 v183, v2, 29, 1
	v_cndmask_b32_e64 v26, v26, v174, s[2:3]
	v_alignbit_b32 v179, v2, v80, 30
	v_sub_u32_e32 v184, 0, v183
	v_cndmask_b32_e64 v26, v178, v26, s[4:5]
	v_xor_b32_e32 v179, v179, v184
	v_alignbit_b32 v174, v175, v26, v181
	v_cndmask_b32_e64 v174, v174, v175, s[6:7]
	v_ffbh_u32_e32 v175, v179
	v_alignbit_b32 v80, v80, v174, 30
	v_min_u32_e32 v175, 32, v175
	v_alignbit_b32 v26, v174, v26, 30
	v_xor_b32_e32 v80, v80, v184
	v_sub_u32_e32 v178, 31, v175
	v_xor_b32_e32 v26, v26, v184
	v_alignbit_b32 v179, v179, v80, v178
	v_alignbit_b32 v26, v80, v26, v178
	v_alignbit_b32 v80, v179, v26, 9
	v_ffbh_u32_e32 v174, v80
	v_min_u32_e32 v174, 32, v174
	v_lshrrev_b32_e32 v182, 29, v2
	v_not_b32_e32 v178, v174
	v_alignbit_b32 v26, v80, v26, v178
	v_lshlrev_b32_e32 v80, 31, v182
	v_or_b32_e32 v178, 0x33000000, v80
	v_add_lshl_u32 v174, v174, v175, 23
	v_lshrrev_b32_e32 v26, 9, v26
	v_sub_u32_e32 v174, v178, v174
	v_or_b32_e32 v80, 0.5, v80
	v_lshlrev_b32_e32 v175, 23, v175
	v_or_b32_e32 v26, v174, v26
	v_lshrrev_b32_e32 v174, 9, v179
	v_sub_u32_e32 v80, v80, v175
	v_or_b32_e32 v80, v174, v80
	v_mul_f32_e32 v174, 0x3fc90fda, v80
	v_fma_f32 v175, v80, s0, -v174
	v_fmac_f32_e32 v175, 0x33a22168, v80
	v_fmac_f32_e32 v175, 0x3fc90fda, v26
	v_lshrrev_b32_e32 v2, 30, v2
	v_add_f32_e32 v179, v174, v175
	v_add_u32_e32 v178, v183, v2
	s_branch .LBB0_251
.Lsl_255:
	v_lshrrev_b32_e32 v2, 23, v26
	v_add_u32_e32 v2, 0xffffff88, v2
	v_cmp_lt_u32_e32 vcc, 63, v2
	s_nop 1
	v_cndmask_b32_e32 v80, 0, v145, vcc
	v_add_u32_e32 v2, v80, v2
	v_cmp_lt_u32_e64 s[2:3], 31, v2
	s_nop 1
	v_cndmask_b32_e64 v80, 0, v146, s[2:3]
	v_add_u32_e32 v2, v80, v2
	v_cmp_lt_u32_e64 s[4:5], 31, v2
	s_nop 1
	v_cndmask_b32_e64 v80, 0, v146, s[4:5]
	v_add_u32_e32 v2, v80, v2
	v_and_b32_e32 v80, 0x7fffff, v26
	v_or_b32_e32 v190, 0x800000, v80
	v_mad_u64_u32 v[174:175], s[6:7], v190, s61, 0
	v_mov_b32_e32 v80, v175
	v_mad_u64_u32 v[180:181], s[6:7], v190, s62, v[80:81]
	v_mov_b32_e32 v80, v181
	v_mad_u64_u32 v[182:183], s[6:7], v190, s63, v[80:81]
	v_mov_b32_e32 v80, v183
	v_mad_u64_u32 v[184:185], s[6:7], v190, s72, v[80:81]
	v_mov_b32_e32 v80, v185
	v_mad_u64_u32 v[186:187], s[6:7], v190, s73, v[80:81]
	v_mov_b32_e32 v80, v187
	v_mad_u64_u32 v[188:189], s[6:7], v190, s74, v[80:81]
	v_mov_b32_e32 v80, v189
	v_mad_u64_u32 v[190:191], s[6:7], v190, s75, v[80:81]
	v_cndmask_b32_e32 v175, v188, v184, vcc
	v_cndmask_b32_e32 v80, v190, v186, vcc
	v_cndmask_b32_e32 v183, v191, v188, vcc
	v_cndmask_b32_e64 v181, v80, v175, s[2:3]
	v_cndmask_b32_e64 v80, v183, v80, s[2:3]
	v_cndmask_b32_e32 v183, v186, v182, vcc
	v_cndmask_b32_e64 v175, v175, v183, s[2:3]
	v_cndmask_b32_e64 v80, v80, v181, s[4:5]
	v_cndmask_b32_e64 v181, v181, v175, s[4:5]
	v_sub_u32_e32 v185, 32, v2
	v_alignbit_b32 v186, v80, v181, v185
	v_cmp_eq_u32_e64 s[6:7], 0, v2
	v_cndmask_b32_e32 v174, v182, v174, vcc
	s_nop 0
	v_cndmask_b32_e64 v2, v186, v80, s[6:7]
	v_cndmask_b32_e32 v80, v184, v180, vcc
	v_cndmask_b32_e64 v180, v183, v80, s[2:3]
	v_cndmask_b32_e64 v175, v175, v180, s[4:5]
	v_alignbit_b32 v183, v181, v175, v185
	v_cndmask_b32_e64 v181, v183, v181, s[6:7]
	v_bfe_u32 v186, v2, 29, 1
	v_cndmask_b32_e64 v80, v80, v174, s[2:3]
	v_alignbit_b32 v183, v2, v181, 30
	v_sub_u32_e32 v187, 0, v186
	v_cndmask_b32_e64 v80, v180, v80, s[4:5]
	v_xor_b32_e32 v183, v183, v187
	v_alignbit_b32 v174, v175, v80, v185
	v_cndmask_b32_e64 v174, v174, v175, s[6:7]
	v_ffbh_u32_e32 v180, v183
	v_alignbit_b32 v175, v181, v174, 30
	v_min_u32_e32 v180, 32, v180
	v_alignbit_b32 v80, v174, v80, 30
	v_xor_b32_e32 v175, v175, v187
	v_sub_u32_e32 v181, 31, v180
	v_xor_b32_e32 v80, v80, v187
	v_alignbit_b32 v182, v183, v175, v181
	v_alignbit_b32 v80, v175, v80, v181
	v_alignbit_b32 v174, v182, v80, 9
	v_ffbh_u32_e32 v175, v174
	v_min_u32_e32 v175, 32, v175
	v_lshrrev_b32_e32 v184, 29, v2
	v_not_b32_e32 v181, v175
	v_alignbit_b32 v80, v174, v80, v181
	v_lshlrev_b32_e32 v174, 31, v184
	v_or_b32_e32 v181, 0x33000000, v174
	v_add_lshl_u32 v175, v175, v180, 23
	v_lshrrev_b32_e32 v80, 9, v80
	v_sub_u32_e32 v175, v181, v175
	v_or_b32_e32 v174, 0.5, v174
	v_lshlrev_b32_e32 v180, 23, v180
	v_or_b32_e32 v80, v175, v80
	v_lshrrev_b32_e32 v175, 9, v182
	v_sub_u32_e32 v174, v174, v180
	v_or_b32_e32 v174, v175, v174
	v_mul_f32_e32 v175, 0x3fc90fda, v174
	v_fma_f32 v180, v174, s0, -v175
	v_fmac_f32_e32 v180, 0x33a22168, v174
	v_fmac_f32_e32 v180, 0x3fc90fda, v80
	v_lshrrev_b32_e32 v2, 30, v2
	v_add_f32_e32 v175, v175, v180
	v_add_u32_e32 v174, v186, v2
	s_branch .LBB0_255
; __device__ __forceinline__ int crow16(int r, int hi) { return (r & 3) + 8 * (r >> 2) + 4 * hi; }
; __device__ __forceinline__ void filter_item32(const Args& a, int L, bf16* KR, int t0, int np0, int npn, int lane) {
;     ...
;         for (int r = 0; r < 16; ++r) { const int j = crow16(r, hi); h0[r] = sinf(fq[j] * (h0[r] + b1[j])); h1[r] = sinf(fq[32 + j] * (h1[r] + b1[32 + j])); }
;     ...
;         for (int r = 0; r < 16; ++r) { const int j = crow16(r, hi); h0[r] = sinf(fq[j] * (g0[r] + bb[j])); h1[r] = sinf(fq[32 + j] * (g1[r] + bb[32 + j])); }
.Lsl_259:
	v_lshrrev_b32_e32 v2, 23, v183
	v_add_u32_e32 v2, 0xffffff88, v2
	v_cmp_lt_u32_e32 vcc, 63, v2
	s_nop 1
	v_cndmask_b32_e32 v27, 0, v145, vcc
	v_add_u32_e32 v2, v27, v2
	v_cmp_lt_u32_e64 s[2:3], 31, v2
	s_nop 1
	v_cndmask_b32_e64 v27, 0, v146, s[2:3]
	v_add_u32_e32 v2, v27, v2
	v_cmp_lt_u32_e64 s[4:5], 31, v2
	s_nop 1
	v_cndmask_b32_e64 v27, 0, v146, s[4:5]
	v_add_u32_e32 v2, v27, v2
	v_and_b32_e32 v27, 0x7fffff, v183
	v_or_b32_e32 v27, 0x800000, v27
	v_mad_u64_u32 v[180:181], s[6:7], v27, s61, 0
	v_mov_b32_e32 v80, v181
	v_mad_u64_u32 v[184:185], s[6:7], v27, s62, v[80:81]
	v_mov_b32_e32 v80, v185
	v_mad_u64_u32 v[186:187], s[6:7], v27, s63, v[80:81]
	v_mov_b32_e32 v80, v187
	v_mad_u64_u32 v[188:189], s[6:7], v27, s72, v[80:81]
	v_mov_b32_e32 v80, v189
	v_mad_u64_u32 v[190:191], s[6:7], v27, s73, v[80:81]
	v_mov_b32_e32 v80, v191
	v_mad_u64_u32 v[192:193], s[6:7], v27, s74, v[80:81]
	v_mov_b32_e32 v80, v193
	v_mad_u64_u32 v[194:195], s[6:7], v27, s75, v[80:81]
	v_cndmask_b32_e32 v181, v192, v188, vcc
	v_cndmask_b32_e32 v27, v194, v190, vcc
	v_cndmask_b32_e32 v185, v195, v192, vcc
	v_cndmask_b32_e64 v80, v27, v181, s[2:3]
	v_cndmask_b32_e64 v27, v185, v27, s[2:3]
	v_cndmask_b32_e32 v185, v190, v186, vcc
	v_cndmask_b32_e64 v181, v181, v185, s[2:3]
	v_cndmask_b32_e64 v27, v27, v80, s[4:5]
	v_cndmask_b32_e64 v80, v80, v181, s[4:5]
	v_sub_u32_e32 v187, 32, v2
	v_alignbit_b32 v189, v27, v80, v187
	v_cmp_eq_u32_e64 s[6:7], 0, v2
	v_cndmask_b32_e32 v180, v186, v180, vcc
	s_nop 0
	v_cndmask_b32_e64 v2, v189, v27, s[6:7]
	v_cndmask_b32_e32 v27, v188, v184, vcc
	v_cndmask_b32_e64 v184, v185, v27, s[2:3]
	v_cndmask_b32_e64 v181, v181, v184, s[4:5]
	v_alignbit_b32 v185, v80, v181, v187
	v_cndmask_b32_e64 v80, v185, v80, s[6:7]
	v_bfe_u32 v189, v2, 29, 1
	v_cndmask_b32_e64 v27, v27, v180, s[2:3]
	v_alignbit_b32 v185, v2, v80, 30
	v_sub_u32_e32 v190, 0, v189
	v_cndmask_b32_e64 v27, v184, v27, s[4:5]
	v_xor_b32_e32 v185, v185, v190
	v_alignbit_b32 v180, v181, v27, v187
	v_cndmask_b32_e64 v180, v180, v181, s[6:7]
	v_ffbh_u32_e32 v181, v185
	v_alignbit_b32 v80, v80, v180, 30
	v_min_u32_e32 v181, 32, v181
	v_alignbit_b32 v27, v180, v27, 30
	v_xor_b32_e32 v80, v80, v190
	v_sub_u32_e32 v184, 31, v181
	v_xor_b32_e32 v27, v27, v190
	v_alignbit_b32 v185, v185, v80, v184
	v_alignbit_b32 v27, v80, v27, v184
	v_alignbit_b32 v80, v185, v27, 9
	v_ffbh_u32_e32 v180, v80
	v_min_u32_e32 v180, 32, v180
	v_lshrrev_b32_e32 v188, 29, v2
	v_not_b32_e32 v184, v180
	v_alignbit_b32 v27, v80, v27, v184
	v_lshlrev_b32_e32 v80, 31, v188
	v_or_b32_e32 v184, 0x33000000, v80
	v_add_lshl_u32 v180, v180, v181, 23
	v_lshrrev_b32_e32 v27, 9, v27
	v_sub_u32_e32 v180, v184, v180
	v_or_b32_e32 v80, 0.5, v80
	v_lshlrev_b32_e32 v181, 23, v181
	v_or_b32_e32 v27, v180, v27
	v_lshrrev_b32_e32 v180, 9, v185
	v_sub_u32_e32 v80, v80, v181
	v_or_b32_e32 v80, v180, v80
	v_mul_f32_e32 v180, 0x3fc90fda, v80
	v_fma_f32 v181, v80, s0, -v180
	v_fmac_f32_e32 v181, 0x33a22168, v80
	v_fmac_f32_e32 v181, 0x3fc90fda, v27
	v_lshrrev_b32_e32 v2, 30, v2
	v_add_f32_e32 v185, v180, v181
	v_add_u32_e32 v184, v189, v2
	s_branch .LBB0_259
.Lsl_263:
	v_lshrrev_b32_e32 v2, 23, v27
	v_add_u32_e32 v2, 0xffffff88, v2
	v_cmp_lt_u32_e32 vcc, 63, v2
	s_nop 1
	v_cndmask_b32_e32 v80, 0, v145, vcc
	v_add_u32_e32 v2, v80, v2
	v_cmp_lt_u32_e64 s[2:3], 31, v2
	s_nop 1
	v_cndmask_b32_e64 v80, 0, v146, s[2:3]
	v_add_u32_e32 v2, v80, v2
	v_cmp_lt_u32_e64 s[4:5], 31, v2
	s_nop 1
	v_cndmask_b32_e64 v80, 0, v146, s[4:5]
	v_add_u32_e32 v2, v80, v2
	v_and_b32_e32 v80, 0x7fffff, v27
	v_or_b32_e32 v196, 0x800000, v80
	v_mad_u64_u32 v[180:181], s[6:7], v196, s61, 0
	v_mov_b32_e32 v80, v181
	v_mad_u64_u32 v[186:187], s[6:7], v196, s62, v[80:81]
	v_mov_b32_e32 v80, v187
	v_mad_u64_u32 v[188:189], s[6:7], v196, s63, v[80:81]
	v_mov_b32_e32 v80, v189
	v_mad_u64_u32 v[190:191], s[6:7], v196, s72, v[80:81]
	v_mov_b32_e32 v80, v191
	v_mad_u64_u32 v[192:193], s[6:7], v196, s73, v[80:81]
	v_mov_b32_e32 v80, v193
	v_mad_u64_u32 v[194:195], s[6:7], v196, s74, v[80:81]
	v_mov_b32_e32 v80, v195
	v_mad_u64_u32 v[196:197], s[6:7], v196, s75, v[80:81]
	v_cndmask_b32_e32 v181, v194, v190, vcc
	v_cndmask_b32_e32 v80, v196, v192, vcc
	v_cndmask_b32_e32 v189, v197, v194, vcc
	v_cndmask_b32_e64 v187, v80, v181, s[2:3]
	v_cndmask_b32_e64 v80, v189, v80, s[2:3]
	v_cndmask_b32_e32 v189, v192, v188, vcc
	v_cndmask_b32_e64 v181, v181, v189, s[2:3]
	v_cndmask_b32_e64 v80, v80, v187, s[4:5]
	v_cndmask_b32_e64 v187, v187, v181, s[4:5]
	v_sub_u32_e32 v191, 32, v2
	v_alignbit_b32 v192, v80, v187, v191
	v_cmp_eq_u32_e64 s[6:7], 0, v2
	v_cndmask_b32_e32 v180, v188, v180, vcc
	s_nop 0
	v_cndmask_b32_e64 v2, v192, v80, s[6:7]
	v_cndmask_b32_e32 v80, v190, v186, vcc
	v_cndmask_b32_e64 v186, v189, v80, s[2:3]
	v_cndmask_b32_e64 v181, v181, v186, s[4:5]
	v_alignbit_b32 v189, v187, v181, v191
	v_cndmask_b32_e64 v187, v189, v187, s[6:7]
	v_bfe_u32 v192, v2, 29, 1
	v_cndmask_b32_e64 v80, v80, v180, s[2:3]
	v_alignbit_b32 v189, v2, v187, 30
	v_sub_u32_e32 v193, 0, v192
	v_cndmask_b32_e64 v80, v186, v80, s[4:5]
	v_xor_b32_e32 v189, v189, v193
	v_alignbit_b32 v180, v181, v80, v191
	v_cndmask_b32_e64 v180, v180, v181, s[6:7]
	v_ffbh_u32_e32 v186, v189
	v_alignbit_b32 v181, v187, v180, 30
	v_min_u32_e32 v186, 32, v186
	v_alignbit_b32 v80, v180, v80, 30
	v_xor_b32_e32 v181, v181, v193
	v_sub_u32_e32 v187, 31, v186
	v_xor_b32_e32 v80, v80, v193
	v_alignbit_b32 v188, v189, v181, v187
	v_alignbit_b32 v80, v181, v80, v187
	v_alignbit_b32 v180, v188, v80, 9
	v_ffbh_u32_e32 v181, v180
	v_min_u32_e32 v181, 32, v181
	v_lshrrev_b32_e32 v190, 29, v2
	v_not_b32_e32 v187, v181
	v_alignbit_b32 v80, v180, v80, v187
	v_lshlrev_b32_e32 v180, 31, v190
	v_or_b32_e32 v187, 0x33000000, v180
	v_add_lshl_u32 v181, v181, v186, 23
	v_lshrrev_b32_e32 v80, 9, v80
	v_sub_u32_e32 v181, v187, v181
	v_or_b32_e32 v180, 0.5, v180
	v_lshlrev_b32_e32 v186, 23, v186
	v_or_b32_e32 v80, v181, v80
	v_lshrrev_b32_e32 v181, 9, v188
	v_sub_u32_e32 v180, v180, v186
	v_or_b32_e32 v180, v181, v180
	v_mul_f32_e32 v181, 0x3fc90fda, v180
	v_fma_f32 v186, v180, s0, -v181
	v_fmac_f32_e32 v186, 0x33a22168, v180
	v_fmac_f32_e32 v186, 0x3fc90fda, v80
	v_lshrrev_b32_e32 v2, 30, v2
	v_add_f32_e32 v181, v181, v186
	v_add_u32_e32 v180, v192, v2
	s_branch .LBB0_263
; __device__ __forceinline__ int crow16(int r, int hi) { return (r & 3) + 8 * (r >> 2) + 4 * hi; }
; __device__ __forceinline__ void filter_item32(const Args& a, int L, bf16* KR, int t0, int np0, int npn, int lane) {
;     ...
;         for (int r = 0; r < 16; ++r) { const int j = crow16(r, hi); h0[r] = sinf(fq[j] * (h0[r] + b1[j])); h1[r] = sinf(fq[32 + j] * (h1[r] + b1[32 + j])); }
;     ...
;         for (int r = 0; r < 16; ++r) { const int j = crow16(r, hi); h0[r] = sinf(fq[j] * (g0[r] + bb[j])); h1[r] = sinf(fq[32 + j] * (g1[r] + bb[32 + j])); }
.Lsl_267:
	v_lshrrev_b32_e32 v2, 23, v189
	v_add_u32_e32 v2, 0xffffff88, v2
	v_cmp_lt_u32_e32 vcc, 63, v2
	s_nop 1
	v_cndmask_b32_e32 v28, 0, v145, vcc
	v_add_u32_e32 v2, v28, v2
	v_cmp_lt_u32_e64 s[2:3], 31, v2
	s_nop 1
	v_cndmask_b32_e64 v28, 0, v146, s[2:3]
	v_add_u32_e32 v2, v28, v2
	v_cmp_lt_u32_e64 s[4:5], 31, v2
	s_nop 1
	v_cndmask_b32_e64 v28, 0, v146, s[4:5]
	v_add_u32_e32 v2, v28, v2
	v_and_b32_e32 v28, 0x7fffff, v189
	v_or_b32_e32 v28, 0x800000, v28
	v_mad_u64_u32 v[186:187], s[6:7], v28, s61, 0
	v_mov_b32_e32 v80, v187
	v_mad_u64_u32 v[190:191], s[6:7], v28, s62, v[80:81]
	v_mov_b32_e32 v80, v191
	v_mad_u64_u32 v[192:193], s[6:7], v28, s63, v[80:81]
	v_mov_b32_e32 v80, v193
	v_mad_u64_u32 v[194:195], s[6:7], v28, s72, v[80:81]
	v_mov_b32_e32 v80, v195
	v_mad_u64_u32 v[196:197], s[6:7], v28, s73, v[80:81]
	v_mov_b32_e32 v80, v197
	v_mad_u64_u32 v[198:199], s[6:7], v28, s74, v[80:81]
	v_mov_b32_e32 v80, v199
	v_mad_u64_u32 v[200:201], s[6:7], v28, s75, v[80:81]
	v_cndmask_b32_e32 v187, v198, v194, vcc
	v_cndmask_b32_e32 v28, v200, v196, vcc
	v_cndmask_b32_e32 v191, v201, v198, vcc
	v_cndmask_b32_e64 v80, v28, v187, s[2:3]
	v_cndmask_b32_e64 v28, v191, v28, s[2:3]
	v_cndmask_b32_e32 v191, v196, v192, vcc
	v_cndmask_b32_e64 v187, v187, v191, s[2:3]
	v_cndmask_b32_e64 v28, v28, v80, s[4:5]
	v_cndmask_b32_e64 v80, v80, v187, s[4:5]
	v_sub_u32_e32 v193, 32, v2
	v_alignbit_b32 v195, v28, v80, v193
	v_cmp_eq_u32_e64 s[6:7], 0, v2
	v_cndmask_b32_e32 v186, v192, v186, vcc
	s_nop 0
	v_cndmask_b32_e64 v2, v195, v28, s[6:7]
	v_cndmask_b32_e32 v28, v194, v190, vcc
	v_cndmask_b32_e64 v190, v191, v28, s[2:3]
	v_cndmask_b32_e64 v187, v187, v190, s[4:5]
	v_alignbit_b32 v191, v80, v187, v193
	v_cndmask_b32_e64 v80, v191, v80, s[6:7]
	v_bfe_u32 v195, v2, 29, 1
	v_cndmask_b32_e64 v28, v28, v186, s[2:3]
	v_alignbit_b32 v191, v2, v80, 30
	v_sub_u32_e32 v196, 0, v195
	v_cndmask_b32_e64 v28, v190, v28, s[4:5]
	v_xor_b32_e32 v191, v191, v196
	v_alignbit_b32 v186, v187, v28, v193
	v_cndmask_b32_e64 v186, v186, v187, s[6:7]
	v_ffbh_u32_e32 v187, v191
	v_alignbit_b32 v80, v80, v186, 30
	v_min_u32_e32 v187, 32, v187
	v_alignbit_b32 v28, v186, v28, 30
	v_xor_b32_e32 v80, v80, v196
	v_sub_u32_e32 v190, 31, v187
	v_xor_b32_e32 v28, v28, v196
	v_alignbit_b32 v191, v191, v80, v190
	v_alignbit_b32 v28, v80, v28, v190
	v_alignbit_b32 v80, v191, v28, 9
	v_ffbh_u32_e32 v186, v80
	v_min_u32_e32 v186, 32, v186
	v_lshrrev_b32_e32 v194, 29, v2
	v_not_b32_e32 v190, v186
	v_alignbit_b32 v28, v80, v28, v190
	v_lshlrev_b32_e32 v80, 31, v194
	v_or_b32_e32 v190, 0x33000000, v80
	v_add_lshl_u32 v186, v186, v187, 23
	v_lshrrev_b32_e32 v28, 9, v28
	v_sub_u32_e32 v186, v190, v186
	v_or_b32_e32 v80, 0.5, v80
	v_lshlrev_b32_e32 v187, 23, v187
	v_or_b32_e32 v28, v186, v28
	v_lshrrev_b32_e32 v186, 9, v191
	v_sub_u32_e32 v80, v80, v187
	v_or_b32_e32 v80, v186, v80
	v_mul_f32_e32 v186, 0x3fc90fda, v80
	v_fma_f32 v187, v80, s0, -v186
	v_fmac_f32_e32 v187, 0x33a22168, v80
	v_fmac_f32_e32 v187, 0x3fc90fda, v28
	v_lshrrev_b32_e32 v2, 30, v2
	v_add_f32_e32 v191, v186, v187
	v_add_u32_e32 v190, v195, v2
	s_branch .LBB0_267
.Lsl_271:
	v_lshrrev_b32_e32 v2, 23, v28
	v_add_u32_e32 v2, 0xffffff88, v2
	v_cmp_lt_u32_e32 vcc, 63, v2
	s_nop 1
	v_cndmask_b32_e32 v80, 0, v145, vcc
	v_add_u32_e32 v2, v80, v2
	v_cmp_lt_u32_e64 s[2:3], 31, v2
	s_nop 1
	v_cndmask_b32_e64 v80, 0, v146, s[2:3]
	v_add_u32_e32 v2, v80, v2
	v_cmp_lt_u32_e64 s[4:5], 31, v2
	s_nop 1
	v_cndmask_b32_e64 v80, 0, v146, s[4:5]
	v_add_u32_e32 v2, v80, v2
	v_and_b32_e32 v80, 0x7fffff, v28
	v_or_b32_e32 v202, 0x800000, v80
	v_mad_u64_u32 v[186:187], s[6:7], v202, s61, 0
	v_mov_b32_e32 v80, v187
	v_mad_u64_u32 v[192:193], s[6:7], v202, s62, v[80:81]
	v_mov_b32_e32 v80, v193
	v_mad_u64_u32 v[194:195], s[6:7], v202, s63, v[80:81]
	v_mov_b32_e32 v80, v195
	v_mad_u64_u32 v[196:197], s[6:7], v202, s72, v[80:81]
	v_mov_b32_e32 v80, v197
	v_mad_u64_u32 v[198:199], s[6:7], v202, s73, v[80:81]
	v_mov_b32_e32 v80, v199
	v_mad_u64_u32 v[200:201], s[6:7], v202, s74, v[80:81]
	v_mov_b32_e32 v80, v201
	v_mad_u64_u32 v[202:203], s[6:7], v202, s75, v[80:81]
	v_cndmask_b32_e32 v187, v200, v196, vcc
	v_cndmask_b32_e32 v80, v202, v198, vcc
	v_cndmask_b32_e32 v195, v203, v200, vcc
	v_cndmask_b32_e64 v193, v80, v187, s[2:3]
	v_cndmask_b32_e64 v80, v195, v80, s[2:3]
	v_cndmask_b32_e32 v195, v198, v194, vcc
	v_cndmask_b32_e64 v187, v187, v195, s[2:3]
	v_cndmask_b32_e64 v80, v80, v193, s[4:5]
	v_cndmask_b32_e64 v193, v193, v187, s[4:5]
	v_sub_u32_e32 v197, 32, v2
	v_alignbit_b32 v198, v80, v193, v197
	v_cmp_eq_u32_e64 s[6:7], 0, v2
	v_cndmask_b32_e32 v186, v194, v186, vcc
	s_nop 0
	v_cndmask_b32_e64 v2, v198, v80, s[6:7]
	v_cndmask_b32_e32 v80, v196, v192, vcc
	v_cndmask_b32_e64 v192, v195, v80, s[2:3]
	v_cndmask_b32_e64 v187, v187, v192, s[4:5]
	v_alignbit_b32 v195, v193, v187, v197
	v_cndmask_b32_e64 v193, v195, v193, s[6:7]
	v_bfe_u32 v198, v2, 29, 1
	v_cndmask_b32_e64 v80, v80, v186, s[2:3]
	v_alignbit_b32 v195, v2, v193, 30
	v_sub_u32_e32 v199, 0, v198
	v_cndmask_b32_e64 v80, v192, v80, s[4:5]
	v_xor_b32_e32 v195, v195, v199
	v_alignbit_b32 v186, v187, v80, v197
	v_cndmask_b32_e64 v186, v186, v187, s[6:7]
	v_ffbh_u32_e32 v192, v195
	v_alignbit_b32 v187, v193, v186, 30
	v_min_u32_e32 v192, 32, v192
	v_alignbit_b32 v80, v186, v80, 30
	v_xor_b32_e32 v187, v187, v199
	v_sub_u32_e32 v193, 31, v192
	v_xor_b32_e32 v80, v80, v199
	v_alignbit_b32 v194, v195, v187, v193
	v_alignbit_b32 v80, v187, v80, v193
	v_alignbit_b32 v186, v194, v80, 9
	v_ffbh_u32_e32 v187, v186
	v_min_u32_e32 v187, 32, v187
	v_lshrrev_b32_e32 v196, 29, v2
	v_not_b32_e32 v193, v187
	v_alignbit_b32 v80, v186, v80, v193
	v_lshlrev_b32_e32 v186, 31, v196
	v_or_b32_e32 v193, 0x33000000, v186
	v_add_lshl_u32 v187, v187, v192, 23
	v_lshrrev_b32_e32 v80, 9, v80
	v_sub_u32_e32 v187, v193, v187
	v_or_b32_e32 v186, 0.5, v186
	v_lshlrev_b32_e32 v192, 23, v192
	v_or_b32_e32 v80, v187, v80
	v_lshrrev_b32_e32 v187, 9, v194
	v_sub_u32_e32 v186, v186, v192
	v_or_b32_e32 v186, v187, v186
	v_mul_f32_e32 v187, 0x3fc90fda, v186
	v_fma_f32 v192, v186, s0, -v187
	v_fmac_f32_e32 v192, 0x33a22168, v186
	v_fmac_f32_e32 v192, 0x3fc90fda, v80
	v_lshrrev_b32_e32 v2, 30, v2
	v_add_f32_e32 v187, v187, v192
	v_add_u32_e32 v186, v198, v2
	s_branch .LBB0_271
; __device__ __forceinline__ int crow16(int r, int hi) { return (r & 3) + 8 * (r >> 2) + 4 * hi; }
; __device__ __forceinline__ void filter_item32(const Args& a, int L, bf16* KR, int t0, int np0, int npn, int lane) {
;     ...
;         for (int r = 0; r < 16; ++r) { const int j = crow16(r, hi); h0[r] = sinf(fq[j] * (h0[r] + b1[j])); h1[r] = sinf(fq[32 + j] * (h1[r] + b1[32 + j])); }
;     ...
;         for (int r = 0; r < 16; ++r) { const int j = crow16(r, hi); h0[r] = sinf(fq[j] * (g0[r] + bb[j])); h1[r] = sinf(fq[32 + j] * (g1[r] + bb[32 + j])); }
.Lsl_275:
	v_lshrrev_b32_e32 v2, 23, v195
	v_add_u32_e32 v2, 0xffffff88, v2
	v_cmp_lt_u32_e32 vcc, 63, v2
	s_nop 1
	v_cndmask_b32_e32 v29, 0, v145, vcc
	v_add_u32_e32 v2, v29, v2
	v_cmp_lt_u32_e64 s[2:3], 31, v2
	s_nop 1
	v_cndmask_b32_e64 v29, 0, v146, s[2:3]
	v_add_u32_e32 v2, v29, v2
	v_cmp_lt_u32_e64 s[4:5], 31, v2
	s_nop 1
	v_cndmask_b32_e64 v29, 0, v146, s[4:5]
	v_add_u32_e32 v2, v29, v2
	v_and_b32_e32 v29, 0x7fffff, v195
	v_or_b32_e32 v29, 0x800000, v29
	v_mad_u64_u32 v[192:193], s[6:7], v29, s61, 0
	v_mov_b32_e32 v80, v193
	v_mad_u64_u32 v[196:197], s[6:7], v29, s62, v[80:81]
	v_mov_b32_e32 v80, v197
	v_mad_u64_u32 v[198:199], s[6:7], v29, s63, v[80:81]
	v_mov_b32_e32 v80, v199
	v_mad_u64_u32 v[200:201], s[6:7], v29, s72, v[80:81]
	v_mov_b32_e32 v80, v201
	v_mad_u64_u32 v[202:203], s[6:7], v29, s73, v[80:81]
	v_mov_b32_e32 v80, v203
	v_mad_u64_u32 v[204:205], s[6:7], v29, s74, v[80:81]
	v_mov_b32_e32 v80, v205
	v_mad_u64_u32 v[206:207], s[6:7], v29, s75, v[80:81]
	v_cndmask_b32_e32 v193, v204, v200, vcc
	v_cndmask_b32_e32 v29, v206, v202, vcc
	v_cndmask_b32_e32 v197, v207, v204, vcc
	v_cndmask_b32_e64 v80, v29, v193, s[2:3]
	v_cndmask_b32_e64 v29, v197, v29, s[2:3]
	v_cndmask_b32_e32 v197, v202, v198, vcc
	v_cndmask_b32_e64 v193, v193, v197, s[2:3]
	v_cndmask_b32_e64 v29, v29, v80, s[4:5]
	v_cndmask_b32_e64 v80, v80, v193, s[4:5]
	v_sub_u32_e32 v199, 32, v2
	v_alignbit_b32 v201, v29, v80, v199
	v_cmp_eq_u32_e64 s[6:7], 0, v2
	v_cndmask_b32_e32 v192, v198, v192, vcc
	s_nop 0
	v_cndmask_b32_e64 v2, v201, v29, s[6:7]
	v_cndmask_b32_e32 v29, v200, v196, vcc
	v_cndmask_b32_e64 v196, v197, v29, s[2:3]
	v_cndmask_b32_e64 v193, v193, v196, s[4:5]
	v_alignbit_b32 v197, v80, v193, v199
	v_cndmask_b32_e64 v80, v197, v80, s[6:7]
	v_bfe_u32 v201, v2, 29, 1
	v_cndmask_b32_e64 v29, v29, v192, s[2:3]
	v_alignbit_b32 v197, v2, v80, 30
	v_sub_u32_e32 v202, 0, v201
	v_cndmask_b32_e64 v29, v196, v29, s[4:5]
	v_xor_b32_e32 v197, v197, v202
	v_alignbit_b32 v192, v193, v29, v199
	v_cndmask_b32_e64 v192, v192, v193, s[6:7]
	v_ffbh_u32_e32 v193, v197
	v_alignbit_b32 v80, v80, v192, 30
	v_min_u32_e32 v193, 32, v193
	v_alignbit_b32 v29, v192, v29, 30
	v_xor_b32_e32 v80, v80, v202
	v_sub_u32_e32 v196, 31, v193
	v_xor_b32_e32 v29, v29, v202
	v_alignbit_b32 v197, v197, v80, v196
	v_alignbit_b32 v29, v80, v29, v196
	v_alignbit_b32 v80, v197, v29, 9
	v_ffbh_u32_e32 v192, v80
	v_min_u32_e32 v192, 32, v192
	v_lshrrev_b32_e32 v200, 29, v2
	v_not_b32_e32 v196, v192
	v_alignbit_b32 v29, v80, v29, v196
	v_lshlrev_b32_e32 v80, 31, v200
	v_or_b32_e32 v196, 0x33000000, v80
	v_add_lshl_u32 v192, v192, v193, 23
	v_lshrrev_b32_e32 v29, 9, v29
	v_sub_u32_e32 v192, v196, v192
	v_or_b32_e32 v80, 0.5, v80
	v_lshlrev_b32_e32 v193, 23, v193
	v_or_b32_e32 v29, v192, v29
	v_lshrrev_b32_e32 v192, 9, v197
	v_sub_u32_e32 v80, v80, v193
	v_or_b32_e32 v80, v192, v80
	v_mul_f32_e32 v192, 0x3fc90fda, v80
	v_fma_f32 v193, v80, s0, -v192
	v_fmac_f32_e32 v193, 0x33a22168, v80
	v_fmac_f32_e32 v193, 0x3fc90fda, v29
	v_lshrrev_b32_e32 v2, 30, v2
	v_add_f32_e32 v197, v192, v193
	v_add_u32_e32 v196, v201, v2
	s_branch .LBB0_275
.Lsl_279:
	v_lshrrev_b32_e32 v2, 23, v29
	v_add_u32_e32 v2, 0xffffff88, v2
	v_cmp_lt_u32_e32 vcc, 63, v2
	s_nop 1
	v_cndmask_b32_e32 v80, 0, v145, vcc
	v_add_u32_e32 v2, v80, v2
	v_cmp_lt_u32_e64 s[2:3], 31, v2
	s_nop 1
	v_cndmask_b32_e64 v80, 0, v146, s[2:3]
	v_add_u32_e32 v2, v80, v2
	v_cmp_lt_u32_e64 s[4:5], 31, v2
	s_nop 1
	v_cndmask_b32_e64 v80, 0, v146, s[4:5]
	v_add_u32_e32 v2, v80, v2
	v_and_b32_e32 v80, 0x7fffff, v29
	v_or_b32_e32 v208, 0x800000, v80
	v_mad_u64_u32 v[192:193], s[6:7], v208, s61, 0
	v_mov_b32_e32 v80, v193
	v_mad_u64_u32 v[198:199], s[6:7], v208, s62, v[80:81]
	v_mov_b32_e32 v80, v199
	v_mad_u64_u32 v[200:201], s[6:7], v208, s63, v[80:81]
	v_mov_b32_e32 v80, v201
	v_mad_u64_u32 v[202:203], s[6:7], v208, s72, v[80:81]
	v_mov_b32_e32 v80, v203
	v_mad_u64_u32 v[204:205], s[6:7], v208, s73, v[80:81]
	v_mov_b32_e32 v80, v205
	v_mad_u64_u32 v[206:207], s[6:7], v208, s74, v[80:81]
	v_mov_b32_e32 v80, v207
	v_mad_u64_u32 v[208:209], s[6:7], v208, s75, v[80:81]
	v_cndmask_b32_e32 v193, v206, v202, vcc
	v_cndmask_b32_e32 v80, v208, v204, vcc
	v_cndmask_b32_e32 v201, v209, v206, vcc
	v_cndmask_b32_e64 v199, v80, v193, s[2:3]
	v_cndmask_b32_e64 v80, v201, v80, s[2:3]
	v_cndmask_b32_e32 v201, v204, v200, vcc
	v_cndmask_b32_e64 v193, v193, v201, s[2:3]
	v_cndmask_b32_e64 v80, v80, v199, s[4:5]
	v_cndmask_b32_e64 v199, v199, v193, s[4:5]
	v_sub_u32_e32 v203, 32, v2
	v_alignbit_b32 v204, v80, v199, v203
	v_cmp_eq_u32_e64 s[6:7], 0, v2
	v_cndmask_b32_e32 v192, v200, v192, vcc
	s_nop 0
	v_cndmask_b32_e64 v2, v204, v80, s[6:7]
	v_cndmask_b32_e32 v80, v202, v198, vcc
	v_cndmask_b32_e64 v198, v201, v80, s[2:3]
	v_cndmask_b32_e64 v193, v193, v198, s[4:5]
	v_alignbit_b32 v201, v199, v193, v203
	v_cndmask_b32_e64 v199, v201, v199, s[6:7]
	v_bfe_u32 v204, v2, 29, 1
	v_cndmask_b32_e64 v80, v80, v192, s[2:3]
	v_alignbit_b32 v201, v2, v199, 30
	v_sub_u32_e32 v205, 0, v204
	v_cndmask_b32_e64 v80, v198, v80, s[4:5]
	v_xor_b32_e32 v201, v201, v205
	v_alignbit_b32 v192, v193, v80, v203
	v_cndmask_b32_e64 v192, v192, v193, s[6:7]
	v_ffbh_u32_e32 v198, v201
	v_alignbit_b32 v193, v199, v192, 30
	v_min_u32_e32 v198, 32, v198
	v_alignbit_b32 v80, v192, v80, 30
	v_xor_b32_e32 v193, v193, v205
	v_sub_u32_e32 v199, 31, v198
	v_xor_b32_e32 v80, v80, v205
	v_alignbit_b32 v200, v201, v193, v199
	v_alignbit_b32 v80, v193, v80, v199
	v_alignbit_b32 v192, v200, v80, 9
	v_ffbh_u32_e32 v193, v192
	v_min_u32_e32 v193, 32, v193
	v_lshrrev_b32_e32 v202, 29, v2
	v_not_b32_e32 v199, v193
	v_alignbit_b32 v80, v192, v80, v199
	v_lshlrev_b32_e32 v192, 31, v202
	v_or_b32_e32 v199, 0x33000000, v192
	v_add_lshl_u32 v193, v193, v198, 23
	v_lshrrev_b32_e32 v80, 9, v80
	v_sub_u32_e32 v193, v199, v193
	v_or_b32_e32 v192, 0.5, v192
	v_lshlrev_b32_e32 v198, 23, v198
	v_or_b32_e32 v80, v193, v80
	v_lshrrev_b32_e32 v193, 9, v200
	v_sub_u32_e32 v192, v192, v198
	v_or_b32_e32 v192, v193, v192
	v_mul_f32_e32 v193, 0x3fc90fda, v192
	v_fma_f32 v198, v192, s0, -v193
	v_fmac_f32_e32 v198, 0x33a22168, v192
	v_fmac_f32_e32 v198, 0x3fc90fda, v80
	v_lshrrev_b32_e32 v2, 30, v2
	v_add_f32_e32 v193, v193, v198
	v_add_u32_e32 v192, v204, v2
	s_branch .LBB0_279
; __device__ __forceinline__ int crow16(int r, int hi) { return (r & 3) + 8 * (r >> 2) + 4 * hi; }
; __device__ __forceinline__ void filter_item32(const Args& a, int L, bf16* KR, int t0, int np0, int npn, int lane) {
;     ...
;         for (int r = 0; r < 16; ++r) { const int j = crow16(r, hi); h0[r] = sinf(fq[j] * (h0[r] + b1[j])); h1[r] = sinf(fq[32 + j] * (h1[r] + b1[32 + j])); }
;     ...
;         for (int r = 0; r < 16; ++r) { const int j = crow16(r, hi); h0[r] = sinf(fq[j] * (g0[r] + bb[j])); h1[r] = sinf(fq[32 + j] * (g1[r] + bb[32 + j])); }
.Lsl_283:
	v_lshrrev_b32_e32 v2, 23, v201
	v_add_u32_e32 v2, 0xffffff88, v2
	v_cmp_lt_u32_e32 vcc, 63, v2
	s_nop 1
	v_cndmask_b32_e32 v30, 0, v145, vcc
	v_add_u32_e32 v2, v30, v2
	v_cmp_lt_u32_e64 s[2:3], 31, v2
	s_nop 1
	v_cndmask_b32_e64 v30, 0, v146, s[2:3]
	v_add_u32_e32 v2, v30, v2
	v_cmp_lt_u32_e64 s[4:5], 31, v2
	s_nop 1
	v_cndmask_b32_e64 v30, 0, v146, s[4:5]
	v_add_u32_e32 v2, v30, v2
	v_and_b32_e32 v30, 0x7fffff, v201
	v_or_b32_e32 v30, 0x800000, v30
	v_mad_u64_u32 v[198:199], s[6:7], v30, s61, 0
	v_mov_b32_e32 v80, v199
	v_mad_u64_u32 v[202:203], s[6:7], v30, s62, v[80:81]
	v_mov_b32_e32 v80, v203
	v_mad_u64_u32 v[204:205], s[6:7], v30, s63, v[80:81]
	v_mov_b32_e32 v80, v205
	v_mad_u64_u32 v[206:207], s[6:7], v30, s72, v[80:81]
	v_mov_b32_e32 v80, v207
	v_mad_u64_u32 v[208:209], s[6:7], v30, s73, v[80:81]
	v_mov_b32_e32 v80, v209
	v_mad_u64_u32 v[210:211], s[6:7], v30, s74, v[80:81]
	v_mov_b32_e32 v80, v211
	v_mad_u64_u32 v[212:213], s[6:7], v30, s75, v[80:81]
	v_cndmask_b32_e32 v199, v210, v206, vcc
	v_cndmask_b32_e32 v30, v212, v208, vcc
	v_cndmask_b32_e32 v203, v213, v210, vcc
	v_cndmask_b32_e64 v80, v30, v199, s[2:3]
	v_cndmask_b32_e64 v30, v203, v30, s[2:3]
	v_cndmask_b32_e32 v203, v208, v204, vcc
	v_cndmask_b32_e64 v199, v199, v203, s[2:3]
	v_cndmask_b32_e64 v30, v30, v80, s[4:5]
	v_cndmask_b32_e64 v80, v80, v199, s[4:5]
	v_sub_u32_e32 v205, 32, v2
	v_alignbit_b32 v207, v30, v80, v205
	v_cmp_eq_u32_e64 s[6:7], 0, v2
	v_cndmask_b32_e32 v198, v204, v198, vcc
	s_nop 0
	v_cndmask_b32_e64 v2, v207, v30, s[6:7]
	v_cndmask_b32_e32 v30, v206, v202, vcc
	v_cndmask_b32_e64 v202, v203, v30, s[2:3]
	v_cndmask_b32_e64 v199, v199, v202, s[4:5]
	v_alignbit_b32 v203, v80, v199, v205
	v_cndmask_b32_e64 v80, v203, v80, s[6:7]
	v_bfe_u32 v207, v2, 29, 1
	v_cndmask_b32_e64 v30, v30, v198, s[2:3]
	v_alignbit_b32 v203, v2, v80, 30
	v_sub_u32_e32 v208, 0, v207
	v_cndmask_b32_e64 v30, v202, v30, s[4:5]
	v_xor_b32_e32 v203, v203, v208
	v_alignbit_b32 v198, v199, v30, v205
	v_cndmask_b32_e64 v198, v198, v199, s[6:7]
	v_ffbh_u32_e32 v199, v203
	v_alignbit_b32 v80, v80, v198, 30
	v_min_u32_e32 v199, 32, v199
	v_alignbit_b32 v30, v198, v30, 30
	v_xor_b32_e32 v80, v80, v208
	v_sub_u32_e32 v202, 31, v199
	v_xor_b32_e32 v30, v30, v208
	v_alignbit_b32 v203, v203, v80, v202
	v_alignbit_b32 v30, v80, v30, v202
	v_alignbit_b32 v80, v203, v30, 9
	v_ffbh_u32_e32 v198, v80
	v_min_u32_e32 v198, 32, v198
	v_lshrrev_b32_e32 v206, 29, v2
	v_not_b32_e32 v202, v198
	v_alignbit_b32 v30, v80, v30, v202
	v_lshlrev_b32_e32 v80, 31, v206
	v_or_b32_e32 v202, 0x33000000, v80
	v_add_lshl_u32 v198, v198, v199, 23
	v_lshrrev_b32_e32 v30, 9, v30
	v_sub_u32_e32 v198, v202, v198
	v_or_b32_e32 v80, 0.5, v80
	v_lshlrev_b32_e32 v199, 23, v199
	v_or_b32_e32 v30, v198, v30
	v_lshrrev_b32_e32 v198, 9, v203
	v_sub_u32_e32 v80, v80, v199
	v_or_b32_e32 v80, v198, v80
	v_mul_f32_e32 v198, 0x3fc90fda, v80
	v_fma_f32 v199, v80, s0, -v198
	v_fmac_f32_e32 v199, 0x33a22168, v80
	v_fmac_f32_e32 v199, 0x3fc90fda, v30
	v_lshrrev_b32_e32 v2, 30, v2
	v_add_f32_e32 v203, v198, v199
	v_add_u32_e32 v202, v207, v2
	s_branch .LBB0_283
.Lsl_287:
	v_lshrrev_b32_e32 v2, 23, v30
	v_add_u32_e32 v2, 0xffffff88, v2
	v_cmp_lt_u32_e32 vcc, 63, v2
	s_nop 1
	v_cndmask_b32_e32 v80, 0, v145, vcc
	v_add_u32_e32 v2, v80, v2
	v_cmp_lt_u32_e64 s[2:3], 31, v2
	s_nop 1
	v_cndmask_b32_e64 v80, 0, v146, s[2:3]
	v_add_u32_e32 v2, v80, v2
	v_cmp_lt_u32_e64 s[4:5], 31, v2
	s_nop 1
	v_cndmask_b32_e64 v80, 0, v146, s[4:5]
	v_add_u32_e32 v2, v80, v2
	v_and_b32_e32 v80, 0x7fffff, v30
	v_or_b32_e32 v214, 0x800000, v80
	v_mad_u64_u32 v[198:199], s[6:7], v214, s61, 0
	v_mov_b32_e32 v80, v199
	v_mad_u64_u32 v[204:205], s[6:7], v214, s62, v[80:81]
	v_mov_b32_e32 v80, v205
	v_mad_u64_u32 v[206:207], s[6:7], v214, s63, v[80:81]
	v_mov_b32_e32 v80, v207
	v_mad_u64_u32 v[208:209], s[6:7], v214, s72, v[80:81]
	v_mov_b32_e32 v80, v209
	v_mad_u64_u32 v[210:211], s[6:7], v214, s73, v[80:81]
	v_mov_b32_e32 v80, v211
	v_mad_u64_u32 v[212:213], s[6:7], v214, s74, v[80:81]
	v_mov_b32_e32 v80, v213
	v_mad_u64_u32 v[214:215], s[6:7], v214, s75, v[80:81]
	v_cndmask_b32_e32 v199, v212, v208, vcc
	v_cndmask_b32_e32 v80, v214, v210, vcc
	v_cndmask_b32_e32 v207, v215, v212, vcc
	v_cndmask_b32_e64 v205, v80, v199, s[2:3]
	v_cndmask_b32_e64 v80, v207, v80, s[2:3]
	v_cndmask_b32_e32 v207, v210, v206, vcc
	v_cndmask_b32_e64 v199, v199, v207, s[2:3]
	v_cndmask_b32_e64 v80, v80, v205, s[4:5]
	v_cndmask_b32_e64 v205, v205, v199, s[4:5]
	v_sub_u32_e32 v209, 32, v2
	v_alignbit_b32 v210, v80, v205, v209
	v_cmp_eq_u32_e64 s[6:7], 0, v2
	v_cndmask_b32_e32 v198, v206, v198, vcc
	s_nop 0
	v_cndmask_b32_e64 v2, v210, v80, s[6:7]
	v_cndmask_b32_e32 v80, v208, v204, vcc
	v_cndmask_b32_e64 v204, v207, v80, s[2:3]
	v_cndmask_b32_e64 v199, v199, v204, s[4:5]
	v_alignbit_b32 v207, v205, v199, v209
	v_cndmask_b32_e64 v205, v207, v205, s[6:7]
	v_bfe_u32 v210, v2, 29, 1
	v_cndmask_b32_e64 v80, v80, v198, s[2:3]
	v_alignbit_b32 v207, v2, v205, 30
	v_sub_u32_e32 v211, 0, v210
	v_cndmask_b32_e64 v80, v204, v80, s[4:5]
	v_xor_b32_e32 v207, v207, v211
	v_alignbit_b32 v198, v199, v80, v209
	v_cndmask_b32_e64 v198, v198, v199, s[6:7]
	v_ffbh_u32_e32 v204, v207
	v_alignbit_b32 v199, v205, v198, 30
	v_min_u32_e32 v204, 32, v204
	v_alignbit_b32 v80, v198, v80, 30
	v_xor_b32_e32 v199, v199, v211
	v_sub_u32_e32 v205, 31, v204
	v_xor_b32_e32 v80, v80, v211
	v_alignbit_b32 v206, v207, v199, v205
	v_alignbit_b32 v80, v199, v80, v205
	v_alignbit_b32 v198, v206, v80, 9
	v_ffbh_u32_e32 v199, v198
	v_min_u32_e32 v199, 32, v199
	v_lshrrev_b32_e32 v208, 29, v2
	v_not_b32_e32 v205, v199
	v_alignbit_b32 v80, v198, v80, v205
	v_lshlrev_b32_e32 v198, 31, v208
	v_or_b32_e32 v205, 0x33000000, v198
	v_add_lshl_u32 v199, v199, v204, 23
	v_lshrrev_b32_e32 v80, 9, v80
	v_sub_u32_e32 v199, v205, v199
	v_or_b32_e32 v198, 0.5, v198
	v_lshlrev_b32_e32 v204, 23, v204
	v_or_b32_e32 v80, v199, v80
	v_lshrrev_b32_e32 v199, 9, v206
	v_sub_u32_e32 v198, v198, v204
	v_or_b32_e32 v198, v199, v198
	v_mul_f32_e32 v199, 0x3fc90fda, v198
	v_fma_f32 v204, v198, s0, -v199
	v_fmac_f32_e32 v204, 0x33a22168, v198
	v_fmac_f32_e32 v204, 0x3fc90fda, v80
	v_lshrrev_b32_e32 v2, 30, v2
	v_add_f32_e32 v199, v199, v204
	v_add_u32_e32 v198, v210, v2
	s_branch .LBB0_287
; __device__ __forceinline__ int crow16(int r, int hi) { return (r & 3) + 8 * (r >> 2) + 4 * hi; }
; __device__ __forceinline__ void filter_item32(const Args& a, int L, bf16* KR, int t0, int np0, int npn, int lane) {
;     ...
;         for (int r = 0; r < 16; ++r) { const int j = crow16(r, hi); h0[r] = sinf(fq[j] * (h0[r] + b1[j])); h1[r] = sinf(fq[32 + j] * (h1[r] + b1[32 + j])); }
;     ...
;         for (int r = 0; r < 16; ++r) { const int j = crow16(r, hi); h0[r] = sinf(fq[j] * (g0[r] + bb[j])); h1[r] = sinf(fq[32 + j] * (g1[r] + bb[32 + j])); }
.Lsl_291:
	v_lshrrev_b32_e32 v2, 23, v207
	v_add_u32_e32 v2, 0xffffff88, v2
	v_cmp_lt_u32_e32 vcc, 63, v2
	s_nop 1
	v_cndmask_b32_e32 v31, 0, v145, vcc
	v_add_u32_e32 v2, v31, v2
	v_cmp_lt_u32_e64 s[2:3], 31, v2
	s_nop 1
	v_cndmask_b32_e64 v31, 0, v146, s[2:3]
	v_add_u32_e32 v2, v31, v2
	v_cmp_lt_u32_e64 s[4:5], 31, v2
	s_nop 1
	v_cndmask_b32_e64 v31, 0, v146, s[4:5]
	v_add_u32_e32 v2, v31, v2
	v_and_b32_e32 v31, 0x7fffff, v207
	v_or_b32_e32 v31, 0x800000, v31
	v_mad_u64_u32 v[204:205], s[6:7], v31, s61, 0
	v_mov_b32_e32 v80, v205
	v_mad_u64_u32 v[208:209], s[6:7], v31, s62, v[80:81]
	v_mov_b32_e32 v80, v209
	v_mad_u64_u32 v[210:211], s[6:7], v31, s63, v[80:81]
	v_mov_b32_e32 v80, v211
	v_mad_u64_u32 v[212:213], s[6:7], v31, s72, v[80:81]
	v_mov_b32_e32 v80, v213
	v_mad_u64_u32 v[214:215], s[6:7], v31, s73, v[80:81]
	v_mov_b32_e32 v80, v215
	v_mad_u64_u32 v[216:217], s[6:7], v31, s74, v[80:81]
	v_mov_b32_e32 v80, v217
	v_mad_u64_u32 v[218:219], s[6:7], v31, s75, v[80:81]
	v_cndmask_b32_e32 v205, v216, v212, vcc
	v_cndmask_b32_e32 v31, v218, v214, vcc
	v_cndmask_b32_e32 v209, v219, v216, vcc
	v_cndmask_b32_e64 v80, v31, v205, s[2:3]
	v_cndmask_b32_e64 v31, v209, v31, s[2:3]
	v_cndmask_b32_e32 v209, v214, v210, vcc
	v_cndmask_b32_e64 v205, v205, v209, s[2:3]
	v_cndmask_b32_e64 v31, v31, v80, s[4:5]
	v_cndmask_b32_e64 v80, v80, v205, s[4:5]
	v_sub_u32_e32 v211, 32, v2
	v_alignbit_b32 v213, v31, v80, v211
	v_cmp_eq_u32_e64 s[6:7], 0, v2
	v_cndmask_b32_e32 v204, v210, v204, vcc
	s_nop 0
	v_cndmask_b32_e64 v2, v213, v31, s[6:7]
	v_cndmask_b32_e32 v31, v212, v208, vcc
	v_cndmask_b32_e64 v208, v209, v31, s[2:3]
	v_cndmask_b32_e64 v205, v205, v208, s[4:5]
	v_alignbit_b32 v209, v80, v205, v211
	v_cndmask_b32_e64 v80, v209, v80, s[6:7]
	v_bfe_u32 v213, v2, 29, 1
	v_cndmask_b32_e64 v31, v31, v204, s[2:3]
	v_alignbit_b32 v209, v2, v80, 30
	v_sub_u32_e32 v214, 0, v213
	v_cndmask_b32_e64 v31, v208, v31, s[4:5]
	v_xor_b32_e32 v209, v209, v214
	v_alignbit_b32 v204, v205, v31, v211
	v_cndmask_b32_e64 v204, v204, v205, s[6:7]
	v_ffbh_u32_e32 v205, v209
	v_alignbit_b32 v80, v80, v204, 30
	v_min_u32_e32 v205, 32, v205
	v_alignbit_b32 v31, v204, v31, 30
	v_xor_b32_e32 v80, v80, v214
	v_sub_u32_e32 v208, 31, v205
	v_xor_b32_e32 v31, v31, v214
	v_alignbit_b32 v209, v209, v80, v208
	v_alignbit_b32 v31, v80, v31, v208
	v_alignbit_b32 v80, v209, v31, 9
	v_ffbh_u32_e32 v204, v80
	v_min_u32_e32 v204, 32, v204
	v_lshrrev_b32_e32 v212, 29, v2
	v_not_b32_e32 v208, v204
	v_alignbit_b32 v31, v80, v31, v208
	v_lshlrev_b32_e32 v80, 31, v212
	v_or_b32_e32 v208, 0x33000000, v80
	v_add_lshl_u32 v204, v204, v205, 23
	v_lshrrev_b32_e32 v31, 9, v31
	v_sub_u32_e32 v204, v208, v204
	v_or_b32_e32 v80, 0.5, v80
	v_lshlrev_b32_e32 v205, 23, v205
	v_or_b32_e32 v31, v204, v31
	v_lshrrev_b32_e32 v204, 9, v209
	v_sub_u32_e32 v80, v80, v205
	v_or_b32_e32 v80, v204, v80
	v_mul_f32_e32 v204, 0x3fc90fda, v80
	v_fma_f32 v205, v80, s0, -v204
	v_fmac_f32_e32 v205, 0x33a22168, v80
	v_fmac_f32_e32 v205, 0x3fc90fda, v31
	v_lshrrev_b32_e32 v2, 30, v2
	v_add_f32_e32 v209, v204, v205
	v_add_u32_e32 v208, v213, v2
	s_branch .LBB0_291
.Lsl_295:
	v_lshrrev_b32_e32 v2, 23, v31
	v_add_u32_e32 v2, 0xffffff88, v2
	v_cmp_lt_u32_e32 vcc, 63, v2
	s_nop 1
	v_cndmask_b32_e32 v80, 0, v145, vcc
	v_add_u32_e32 v2, v80, v2
	v_cmp_lt_u32_e64 s[2:3], 31, v2
	s_nop 1
	v_cndmask_b32_e64 v80, 0, v146, s[2:3]
	v_add_u32_e32 v2, v80, v2
	v_cmp_lt_u32_e64 s[4:5], 31, v2
	s_nop 1
	v_cndmask_b32_e64 v80, 0, v146, s[4:5]
	v_add_u32_e32 v2, v80, v2
	v_and_b32_e32 v80, 0x7fffff, v31
	v_or_b32_e32 v220, 0x800000, v80
	v_mad_u64_u32 v[204:205], s[6:7], v220, s61, 0
	v_mov_b32_e32 v80, v205
	v_mad_u64_u32 v[210:211], s[6:7], v220, s62, v[80:81]
	v_mov_b32_e32 v80, v211
	v_mad_u64_u32 v[212:213], s[6:7], v220, s63, v[80:81]
	v_mov_b32_e32 v80, v213
	v_mad_u64_u32 v[214:215], s[6:7], v220, s72, v[80:81]
	v_mov_b32_e32 v80, v215
	v_mad_u64_u32 v[216:217], s[6:7], v220, s73, v[80:81]
	v_mov_b32_e32 v80, v217
	v_mad_u64_u32 v[218:219], s[6:7], v220, s74, v[80:81]
	v_mov_b32_e32 v80, v219
	v_mad_u64_u32 v[220:221], s[6:7], v220, s75, v[80:81]
	v_cndmask_b32_e32 v205, v218, v214, vcc
	v_cndmask_b32_e32 v80, v220, v216, vcc
	v_cndmask_b32_e32 v213, v221, v218, vcc
	v_cndmask_b32_e64 v211, v80, v205, s[2:3]
	v_cndmask_b32_e64 v80, v213, v80, s[2:3]
	v_cndmask_b32_e32 v213, v216, v212, vcc
	v_cndmask_b32_e64 v205, v205, v213, s[2:3]
	v_cndmask_b32_e64 v80, v80, v211, s[4:5]
	v_cndmask_b32_e64 v211, v211, v205, s[4:5]
	v_sub_u32_e32 v215, 32, v2
	v_alignbit_b32 v216, v80, v211, v215
	v_cmp_eq_u32_e64 s[6:7], 0, v2
	v_cndmask_b32_e32 v204, v212, v204, vcc
	s_nop 0
	v_cndmask_b32_e64 v2, v216, v80, s[6:7]
	v_cndmask_b32_e32 v80, v214, v210, vcc
	v_cndmask_b32_e64 v210, v213, v80, s[2:3]
	v_cndmask_b32_e64 v205, v205, v210, s[4:5]
	v_alignbit_b32 v213, v211, v205, v215
	v_cndmask_b32_e64 v211, v213, v211, s[6:7]
	v_bfe_u32 v216, v2, 29, 1
	v_cndmask_b32_e64 v80, v80, v204, s[2:3]
	v_alignbit_b32 v213, v2, v211, 30
	v_sub_u32_e32 v217, 0, v216
	v_cndmask_b32_e64 v80, v210, v80, s[4:5]
	v_xor_b32_e32 v213, v213, v217
	v_alignbit_b32 v204, v205, v80, v215
	v_cndmask_b32_e64 v204, v204, v205, s[6:7]
	v_ffbh_u32_e32 v210, v213
	v_alignbit_b32 v205, v211, v204, 30
	v_min_u32_e32 v210, 32, v210
	v_alignbit_b32 v80, v204, v80, 30
	v_xor_b32_e32 v205, v205, v217
	v_sub_u32_e32 v211, 31, v210
	v_xor_b32_e32 v80, v80, v217
	v_alignbit_b32 v212, v213, v205, v211
	v_alignbit_b32 v80, v205, v80, v211
	v_alignbit_b32 v204, v212, v80, 9
	v_ffbh_u32_e32 v205, v204
	v_min_u32_e32 v205, 32, v205
	v_lshrrev_b32_e32 v214, 29, v2
	v_not_b32_e32 v211, v205
	v_alignbit_b32 v80, v204, v80, v211
	v_lshlrev_b32_e32 v204, 31, v214
	v_or_b32_e32 v211, 0x33000000, v204
	v_add_lshl_u32 v205, v205, v210, 23
	v_lshrrev_b32_e32 v80, 9, v80
	v_sub_u32_e32 v205, v211, v205
	v_or_b32_e32 v204, 0.5, v204
	v_lshlrev_b32_e32 v210, 23, v210
	v_or_b32_e32 v80, v205, v80
	v_lshrrev_b32_e32 v205, 9, v212
	v_sub_u32_e32 v204, v204, v210
	v_or_b32_e32 v204, v205, v204
	v_mul_f32_e32 v205, 0x3fc90fda, v204
	v_fma_f32 v210, v204, s0, -v205
	v_fmac_f32_e32 v210, 0x33a22168, v204
	v_fmac_f32_e32 v210, 0x3fc90fda, v80
	v_lshrrev_b32_e32 v2, 30, v2
	v_add_f32_e32 v205, v205, v210
	v_add_u32_e32 v204, v216, v2
	s_branch .LBB0_295
; __device__ __forceinline__ int crow16(int r, int hi) { return (r & 3) + 8 * (r >> 2) + 4 * hi; }
; __device__ __forceinline__ void filter_item32(const Args& a, int L, bf16* KR, int t0, int np0, int npn, int lane) {
;     ...
;         for (int r = 0; r < 16; ++r) { const int j = crow16(r, hi); h0[r] = sinf(fq[j] * (h0[r] + b1[j])); h1[r] = sinf(fq[32 + j] * (h1[r] + b1[32 + j])); }
;     ...
;         for (int r = 0; r < 16; ++r) { const int j = crow16(r, hi); h0[r] = sinf(fq[j] * (g0[r] + bb[j])); h1[r] = sinf(fq[32 + j] * (g1[r] + bb[32 + j])); }
.Lsl_299:
	v_lshrrev_b32_e32 v2, 23, v213
	v_add_u32_e32 v2, 0xffffff88, v2
	v_cmp_lt_u32_e32 vcc, 63, v2
	s_nop 1
	v_cndmask_b32_e32 v32, 0, v145, vcc
	v_add_u32_e32 v2, v32, v2
	v_cmp_lt_u32_e64 s[2:3], 31, v2
	s_nop 1
	v_cndmask_b32_e64 v32, 0, v146, s[2:3]
	v_add_u32_e32 v2, v32, v2
	v_cmp_lt_u32_e64 s[4:5], 31, v2
	s_nop 1
	v_cndmask_b32_e64 v32, 0, v146, s[4:5]
	v_add_u32_e32 v2, v32, v2
	v_and_b32_e32 v32, 0x7fffff, v213
	v_or_b32_e32 v32, 0x800000, v32
	v_mad_u64_u32 v[210:211], s[6:7], v32, s61, 0
	v_mov_b32_e32 v80, v211
	v_mad_u64_u32 v[214:215], s[6:7], v32, s62, v[80:81]
	v_mov_b32_e32 v80, v215
	v_mad_u64_u32 v[216:217], s[6:7], v32, s63, v[80:81]
	v_mov_b32_e32 v80, v217
	v_mad_u64_u32 v[218:219], s[6:7], v32, s72, v[80:81]
	v_mov_b32_e32 v80, v219
	v_mad_u64_u32 v[220:221], s[6:7], v32, s73, v[80:81]
	v_mov_b32_e32 v80, v221
	v_mad_u64_u32 v[222:223], s[6:7], v32, s74, v[80:81]
	v_mov_b32_e32 v80, v223
	v_mad_u64_u32 v[224:225], s[6:7], v32, s75, v[80:81]
	v_cndmask_b32_e32 v211, v222, v218, vcc
	v_cndmask_b32_e32 v32, v224, v220, vcc
	v_cndmask_b32_e32 v215, v225, v222, vcc
	v_cndmask_b32_e64 v80, v32, v211, s[2:3]
	v_cndmask_b32_e64 v32, v215, v32, s[2:3]
	v_cndmask_b32_e32 v215, v220, v216, vcc
	v_cndmask_b32_e64 v211, v211, v215, s[2:3]
	v_cndmask_b32_e64 v32, v32, v80, s[4:5]
	v_cndmask_b32_e64 v80, v80, v211, s[4:5]
	v_sub_u32_e32 v217, 32, v2
	v_alignbit_b32 v219, v32, v80, v217
	v_cmp_eq_u32_e64 s[6:7], 0, v2
	v_cndmask_b32_e32 v210, v216, v210, vcc
	s_nop 0
	v_cndmask_b32_e64 v2, v219, v32, s[6:7]
	v_cndmask_b32_e32 v32, v218, v214, vcc
	v_cndmask_b32_e64 v214, v215, v32, s[2:3]
	v_cndmask_b32_e64 v211, v211, v214, s[4:5]
	v_alignbit_b32 v215, v80, v211, v217
	v_cndmask_b32_e64 v80, v215, v80, s[6:7]
	v_bfe_u32 v219, v2, 29, 1
	v_cndmask_b32_e64 v32, v32, v210, s[2:3]
	v_alignbit_b32 v215, v2, v80, 30
	v_sub_u32_e32 v220, 0, v219
	v_cndmask_b32_e64 v32, v214, v32, s[4:5]
	v_xor_b32_e32 v215, v215, v220
	v_alignbit_b32 v210, v211, v32, v217
	v_cndmask_b32_e64 v210, v210, v211, s[6:7]
	v_ffbh_u32_e32 v211, v215
	v_alignbit_b32 v80, v80, v210, 30
	v_min_u32_e32 v211, 32, v211
	v_alignbit_b32 v32, v210, v32, 30
	v_xor_b32_e32 v80, v80, v220
	v_sub_u32_e32 v214, 31, v211
	v_xor_b32_e32 v32, v32, v220
	v_alignbit_b32 v215, v215, v80, v214
	v_alignbit_b32 v32, v80, v32, v214
	v_alignbit_b32 v80, v215, v32, 9
	v_ffbh_u32_e32 v210, v80
	v_min_u32_e32 v210, 32, v210
	v_lshrrev_b32_e32 v218, 29, v2
	v_not_b32_e32 v214, v210
	v_alignbit_b32 v32, v80, v32, v214
	v_lshlrev_b32_e32 v80, 31, v218
	v_or_b32_e32 v214, 0x33000000, v80
	v_add_lshl_u32 v210, v210, v211, 23
	v_lshrrev_b32_e32 v32, 9, v32
	v_sub_u32_e32 v210, v214, v210
	v_or_b32_e32 v80, 0.5, v80
	v_lshlrev_b32_e32 v211, 23, v211
	v_or_b32_e32 v32, v210, v32
	v_lshrrev_b32_e32 v210, 9, v215
	v_sub_u32_e32 v80, v80, v211
	v_or_b32_e32 v80, v210, v80
	v_mul_f32_e32 v210, 0x3fc90fda, v80
	v_fma_f32 v211, v80, s0, -v210
	v_fmac_f32_e32 v211, 0x33a22168, v80
	v_fmac_f32_e32 v211, 0x3fc90fda, v32
	v_lshrrev_b32_e32 v2, 30, v2
	v_add_f32_e32 v215, v210, v211
	v_add_u32_e32 v214, v219, v2
	s_branch .LBB0_299
.Lsl_303:
	v_lshrrev_b32_e32 v2, 23, v32
	v_add_u32_e32 v2, 0xffffff88, v2
	v_cmp_lt_u32_e32 vcc, 63, v2
	s_nop 1
	v_cndmask_b32_e32 v80, 0, v145, vcc
	v_add_u32_e32 v2, v80, v2
	v_cmp_lt_u32_e64 s[2:3], 31, v2
	s_nop 1
	v_cndmask_b32_e64 v80, 0, v146, s[2:3]
	v_add_u32_e32 v2, v80, v2
	v_cmp_lt_u32_e64 s[4:5], 31, v2
	s_nop 1
	v_cndmask_b32_e64 v80, 0, v146, s[4:5]
	v_add_u32_e32 v2, v80, v2
	v_and_b32_e32 v80, 0x7fffff, v32
	v_or_b32_e32 v226, 0x800000, v80
	v_mad_u64_u32 v[210:211], s[6:7], v226, s61, 0
	v_mov_b32_e32 v80, v211
	v_mad_u64_u32 v[216:217], s[6:7], v226, s62, v[80:81]
	v_mov_b32_e32 v80, v217
	v_mad_u64_u32 v[218:219], s[6:7], v226, s63, v[80:81]
	v_mov_b32_e32 v80, v219
	v_mad_u64_u32 v[220:221], s[6:7], v226, s72, v[80:81]
	v_mov_b32_e32 v80, v221
	v_mad_u64_u32 v[222:223], s[6:7], v226, s73, v[80:81]
	v_mov_b32_e32 v80, v223
	v_mad_u64_u32 v[224:225], s[6:7], v226, s74, v[80:81]
	v_mov_b32_e32 v80, v225
	v_mad_u64_u32 v[226:227], s[6:7], v226, s75, v[80:81]
	v_cndmask_b32_e32 v211, v224, v220, vcc
	v_cndmask_b32_e32 v80, v226, v222, vcc
	v_cndmask_b32_e32 v219, v227, v224, vcc
	v_cndmask_b32_e64 v217, v80, v211, s[2:3]
	v_cndmask_b32_e64 v80, v219, v80, s[2:3]
	v_cndmask_b32_e32 v219, v222, v218, vcc
	v_cndmask_b32_e64 v211, v211, v219, s[2:3]
	v_cndmask_b32_e64 v80, v80, v217, s[4:5]
	v_cndmask_b32_e64 v217, v217, v211, s[4:5]
	v_sub_u32_e32 v221, 32, v2
	v_alignbit_b32 v222, v80, v217, v221
	v_cmp_eq_u32_e64 s[6:7], 0, v2
	v_cndmask_b32_e32 v210, v218, v210, vcc
	s_nop 0
	v_cndmask_b32_e64 v2, v222, v80, s[6:7]
	v_cndmask_b32_e32 v80, v220, v216, vcc
	v_cndmask_b32_e64 v216, v219, v80, s[2:3]
	v_cndmask_b32_e64 v211, v211, v216, s[4:5]
	v_alignbit_b32 v219, v217, v211, v221
	v_cndmask_b32_e64 v217, v219, v217, s[6:7]
	v_bfe_u32 v222, v2, 29, 1
	v_cndmask_b32_e64 v80, v80, v210, s[2:3]
	v_alignbit_b32 v219, v2, v217, 30
	v_sub_u32_e32 v223, 0, v222
	v_cndmask_b32_e64 v80, v216, v80, s[4:5]
	v_xor_b32_e32 v219, v219, v223
	v_alignbit_b32 v210, v211, v80, v221
	v_cndmask_b32_e64 v210, v210, v211, s[6:7]
	v_ffbh_u32_e32 v216, v219
	v_alignbit_b32 v211, v217, v210, 30
	v_min_u32_e32 v216, 32, v216
	v_alignbit_b32 v80, v210, v80, 30
	v_xor_b32_e32 v211, v211, v223
	v_sub_u32_e32 v217, 31, v216
	v_xor_b32_e32 v80, v80, v223
	v_alignbit_b32 v218, v219, v211, v217
	v_alignbit_b32 v80, v211, v80, v217
	v_alignbit_b32 v210, v218, v80, 9
	v_ffbh_u32_e32 v211, v210
	v_min_u32_e32 v211, 32, v211
	v_lshrrev_b32_e32 v220, 29, v2
	v_not_b32_e32 v217, v211
	v_alignbit_b32 v80, v210, v80, v217
	v_lshlrev_b32_e32 v210, 31, v220
	v_or_b32_e32 v217, 0x33000000, v210
	v_add_lshl_u32 v211, v211, v216, 23
	v_lshrrev_b32_e32 v80, 9, v80
	v_sub_u32_e32 v211, v217, v211
	v_or_b32_e32 v210, 0.5, v210
	v_lshlrev_b32_e32 v216, 23, v216
	v_or_b32_e32 v80, v211, v80
	v_lshrrev_b32_e32 v211, 9, v218
	v_sub_u32_e32 v210, v210, v216
	v_or_b32_e32 v210, v211, v210
	v_mul_f32_e32 v211, 0x3fc90fda, v210
	v_fma_f32 v216, v210, s0, -v211
	v_fmac_f32_e32 v216, 0x33a22168, v210
	v_fmac_f32_e32 v216, 0x3fc90fda, v80
	v_lshrrev_b32_e32 v2, 30, v2
	v_add_f32_e32 v211, v211, v216
	v_add_u32_e32 v210, v222, v2
	s_branch .LBB0_303
; __device__ __forceinline__ int crow16(int r, int hi) { return (r & 3) + 8 * (r >> 2) + 4 * hi; }
; __device__ __forceinline__ void filter_item32(const Args& a, int L, bf16* KR, int t0, int np0, int npn, int lane) {
;     ...
;         for (int r = 0; r < 16; ++r) { const int j = crow16(r, hi); h0[r] = sinf(fq[j] * (g0[r] + bb[j])); h1[r] = sinf(fq[32 + j] * (g1[r] + bb[32 + j])); }
.Lsl_307:
	v_lshrrev_b32_e32 v2, 23, v218
	v_add_u32_e32 v2, 0xffffff88, v2
	v_cmp_lt_u32_e32 vcc, 63, v2
	s_nop 1
	v_cndmask_b32_e32 v33, 0, v145, vcc
	v_add_u32_e32 v2, v33, v2
	v_cmp_lt_u32_e64 s[2:3], 31, v2
	s_nop 1
	v_cndmask_b32_e64 v33, 0, v146, s[2:3]
	v_add_u32_e32 v2, v33, v2
	v_cmp_lt_u32_e64 s[4:5], 31, v2
	s_nop 1
	v_cndmask_b32_e64 v33, 0, v146, s[4:5]
	v_add_u32_e32 v2, v33, v2
	v_and_b32_e32 v33, 0x7fffff, v218
	v_or_b32_e32 v33, 0x800000, v33
	v_mad_u64_u32 v[220:221], s[6:7], v33, s61, 0
	v_mov_b32_e32 v80, v221
	v_mad_u64_u32 v[222:223], s[6:7], v33, s62, v[80:81]
	v_mov_b32_e32 v80, v223
	v_mad_u64_u32 v[224:225], s[6:7], v33, s63, v[80:81]
	v_mov_b32_e32 v80, v225
	v_mad_u64_u32 v[226:227], s[6:7], v33, s72, v[80:81]
	v_mov_b32_e32 v80, v227
	v_mad_u64_u32 v[228:229], s[6:7], v33, s73, v[80:81]
	v_mov_b32_e32 v80, v229
	v_mad_u64_u32 v[230:231], s[6:7], v33, s74, v[80:81]
	v_mov_b32_e32 v80, v231
	v_mad_u64_u32 v[232:233], s[6:7], v33, s75, v[80:81]
	v_cndmask_b32_e32 v216, v230, v226, vcc
	v_cndmask_b32_e32 v33, v232, v228, vcc
	v_cndmask_b32_e32 v219, v233, v230, vcc
	v_cndmask_b32_e64 v80, v33, v216, s[2:3]
	v_cndmask_b32_e64 v33, v219, v33, s[2:3]
	v_cndmask_b32_e32 v219, v228, v224, vcc
	v_cndmask_b32_e64 v216, v216, v219, s[2:3]
	v_cndmask_b32_e64 v33, v33, v80, s[4:5]
	v_cndmask_b32_e64 v80, v80, v216, s[4:5]
	v_sub_u32_e32 v221, 32, v2
	v_alignbit_b32 v223, v33, v80, v221
	v_cmp_eq_u32_e64 s[6:7], 0, v2
	v_cndmask_b32_e32 v220, v224, v220, vcc
	s_nop 0
	v_cndmask_b32_e64 v2, v223, v33, s[6:7]
	v_cndmask_b32_e32 v33, v226, v222, vcc
	v_cndmask_b32_e64 v219, v219, v33, s[2:3]
	v_cndmask_b32_e64 v216, v216, v219, s[4:5]
	v_alignbit_b32 v222, v80, v216, v221
	v_cndmask_b32_e64 v80, v222, v80, s[6:7]
	v_bfe_u32 v225, v2, 29, 1
	v_cndmask_b32_e64 v33, v33, v220, s[2:3]
	v_alignbit_b32 v222, v2, v80, 30
	v_sub_u32_e32 v226, 0, v225
	v_cndmask_b32_e64 v33, v219, v33, s[4:5]
	v_xor_b32_e32 v222, v222, v226
	v_alignbit_b32 v219, v216, v33, v221
	v_cndmask_b32_e64 v216, v219, v216, s[6:7]
	v_ffbh_u32_e32 v219, v222
	v_alignbit_b32 v80, v80, v216, 30
	v_min_u32_e32 v219, 32, v219
	v_alignbit_b32 v33, v216, v33, 30
	v_xor_b32_e32 v80, v80, v226
	v_sub_u32_e32 v220, 31, v219
	v_xor_b32_e32 v33, v33, v226
	v_alignbit_b32 v221, v222, v80, v220
	v_alignbit_b32 v33, v80, v33, v220
	v_alignbit_b32 v80, v221, v33, 9
	v_ffbh_u32_e32 v216, v80
	v_min_u32_e32 v216, 32, v216
	v_lshrrev_b32_e32 v223, 29, v2
	v_not_b32_e32 v220, v216
	v_alignbit_b32 v33, v80, v33, v220
	v_lshlrev_b32_e32 v80, 31, v223
	v_or_b32_e32 v220, 0x33000000, v80
	v_add_lshl_u32 v216, v216, v219, 23
	v_lshrrev_b32_e32 v33, 9, v33
	v_sub_u32_e32 v216, v220, v216
	v_or_b32_e32 v80, 0.5, v80
	v_lshlrev_b32_e32 v219, 23, v219
	v_or_b32_e32 v33, v216, v33
	v_lshrrev_b32_e32 v216, 9, v221
	v_sub_u32_e32 v80, v80, v219
	v_or_b32_e32 v80, v216, v80
	v_mul_f32_e32 v216, 0x3fc90fda, v80
	v_fma_f32 v219, v80, s0, -v216
	v_fmac_f32_e32 v219, 0x33a22168, v80
	v_fmac_f32_e32 v219, 0x3fc90fda, v33
	v_lshrrev_b32_e32 v2, 30, v2
	v_add_f32_e32 v220, v216, v219
	v_add_u32_e32 v219, v225, v2
	s_branch .LBB0_307
.Lsl_311:
	v_lshrrev_b32_e32 v2, 23, v33
	v_add_u32_e32 v2, 0xffffff88, v2
	v_cmp_lt_u32_e32 vcc, 63, v2
	s_nop 1
	v_cndmask_b32_e32 v34, 0, v145, vcc
	v_add_u32_e32 v2, v34, v2
	v_cmp_lt_u32_e64 s[2:3], 31, v2
	s_nop 1
	v_cndmask_b32_e64 v34, 0, v146, s[2:3]
	v_add_u32_e32 v2, v34, v2
	v_cmp_lt_u32_e64 s[4:5], 31, v2
	s_nop 1
	v_cndmask_b32_e64 v34, 0, v146, s[4:5]
	v_add_u32_e32 v2, v34, v2
	v_and_b32_e32 v34, 0x7fffff, v33
	v_or_b32_e32 v216, 0x800000, v34
	v_mad_u64_u32 v[34:35], s[6:7], v216, s61, 0
	v_mov_b32_e32 v80, v35
	v_mad_u64_u32 v[222:223], s[6:7], v216, s62, v[80:81]
	v_mov_b32_e32 v80, v223
	v_mad_u64_u32 v[224:225], s[6:7], v216, s63, v[80:81]
	v_mov_b32_e32 v80, v225
	v_mad_u64_u32 v[226:227], s[6:7], v216, s72, v[80:81]
	v_mov_b32_e32 v80, v227
	v_mad_u64_u32 v[228:229], s[6:7], v216, s73, v[80:81]
	v_mov_b32_e32 v80, v229
	v_mad_u64_u32 v[230:231], s[6:7], v216, s74, v[80:81]
	v_mov_b32_e32 v80, v231
	v_mad_u64_u32 v[232:233], s[6:7], v216, s75, v[80:81]
	v_cndmask_b32_e32 v35, v230, v226, vcc
	v_cndmask_b32_e32 v80, v232, v228, vcc
	v_cndmask_b32_e32 v221, v233, v230, vcc
	v_cndmask_b32_e64 v216, v80, v35, s[2:3]
	v_cndmask_b32_e64 v80, v221, v80, s[2:3]
	v_cndmask_b32_e32 v221, v228, v224, vcc
	v_cndmask_b32_e64 v35, v35, v221, s[2:3]
	v_cndmask_b32_e64 v80, v80, v216, s[4:5]
	v_cndmask_b32_e64 v216, v216, v35, s[4:5]
	v_sub_u32_e32 v223, 32, v2
	v_alignbit_b32 v225, v80, v216, v223
	v_cmp_eq_u32_e64 s[6:7], 0, v2
	v_cndmask_b32_e32 v34, v224, v34, vcc
	s_nop 0
	v_cndmask_b32_e64 v2, v225, v80, s[6:7]
	v_cndmask_b32_e32 v80, v226, v222, vcc
	v_cndmask_b32_e64 v221, v221, v80, s[2:3]
	v_cndmask_b32_e64 v35, v35, v221, s[4:5]
	v_alignbit_b32 v222, v216, v35, v223
	v_cndmask_b32_e64 v34, v80, v34, s[2:3]
	v_cndmask_b32_e64 v216, v222, v216, s[6:7]
	v_bfe_u32 v226, v2, 29, 1
	v_cndmask_b32_e64 v34, v221, v34, s[4:5]
	v_alignbit_b32 v222, v2, v216, 30
	v_sub_u32_e32 v227, 0, v226
	v_alignbit_b32 v80, v35, v34, v223
	v_xor_b32_e32 v222, v222, v227
	v_cndmask_b32_e64 v35, v80, v35, s[6:7]
	v_alignbit_b32 v80, v216, v35, 30
	v_ffbh_u32_e32 v216, v222
	v_min_u32_e32 v216, 32, v216
	v_alignbit_b32 v34, v35, v34, 30
	v_xor_b32_e32 v80, v80, v227
	v_sub_u32_e32 v221, 31, v216
	v_xor_b32_e32 v34, v34, v227
	v_alignbit_b32 v222, v222, v80, v221
	v_alignbit_b32 v34, v80, v34, v221
	v_alignbit_b32 v35, v222, v34, 9
	v_ffbh_u32_e32 v80, v35
	v_min_u32_e32 v80, 32, v80
	v_lshrrev_b32_e32 v225, 29, v2
	v_not_b32_e32 v221, v80
	v_alignbit_b32 v34, v35, v34, v221
	v_lshlrev_b32_e32 v35, 31, v225
	v_or_b32_e32 v221, 0x33000000, v35
	v_add_lshl_u32 v80, v80, v216, 23
	v_lshrrev_b32_e32 v34, 9, v34
	v_sub_u32_e32 v80, v221, v80
	v_or_b32_e32 v35, 0.5, v35
	v_lshlrev_b32_e32 v216, 23, v216
	v_or_b32_e32 v34, v80, v34
	v_lshrrev_b32_e32 v80, 9, v222
	v_sub_u32_e32 v35, v35, v216
	v_or_b32_e32 v35, v80, v35
	v_mul_f32_e32 v80, 0x3fc90fda, v35
	v_fma_f32 v216, v35, s0, -v80
	v_fmac_f32_e32 v216, 0x33a22168, v35
	v_fmac_f32_e32 v216, 0x3fc90fda, v34
	v_lshrrev_b32_e32 v2, 30, v2
	v_add_f32_e32 v216, v80, v216
	v_add_u32_e32 v80, v226, v2
	s_branch .LBB0_311

; __device__ __forceinline__ void filter_item32(const Args& a, int L, bf16* KR, int t0, int np0, int npn, int lane) {
;     ...
;     const float tt = (float)t * (1.0f / (float)(L - 1)), w = 6.283185307179586f * (float)t / (float)L;
;     f32x16 h0 = {}, h1 = {};
;     {
;         float cv[8], sv[8];
; #pragma unroll
;         for (int k = 0; k < 8; ++k) { const float f = 1e-4f + (float)(k + 8 * hi) * ((15.0f - 1e-4f) / 15.0f); float s, c; sincosf(f * w, &s, &c); cv[k] = c; sv[k] = -s; }
; #pragma unroll
;         for (int kk = 0; kk < 17; ++kk) {
;             const int urow = kk < 8 ? 1 + kk : (kk < 16 ? 17 + (kk - 8) : 0);
;             const float zb = kk < 8 ? cv[kk & 7] : (kk < 16 ? sv[kk & 7] : (hi == 0 ? tt : 0.f));
;             const float* ub = w1 + urow * 64; const int lo1 = kk < 16 ? 8 * hi * 64 + n : n;
;             const float a0 = ub[lo1], a1 = ub[lo1 + 32];
;             h0 = __builtin_amdgcn_mfma_f32_32x32x2f32(a0, zb, h0, 0, 0, 0); h1 = __builtin_amdgcn_mfma_f32_32x32x2f32(a1, zb, h1, 0, 0, 0);
.LBB0_380:
	s_and_b64 vcc, exec, s[2:3]
	s_cbranch_vccz .LBB0_21
	v_or_b32_e32 v64, s85, v103
	v_cvt_f32_i32_e32 v1, v64
	v_mul_f32_e32 v2, 0x40c90fdb, v1
	v_mul_f32_e32 v4, 0x38800000, v2
	v_mul_f32_e32 v34, v129, v4
	v_and_b32_e32 v35, 0x7fffffff, v34
	v_cmp_nlt_f32_e64 s[2:3], |v34|, s60
	s_and_saveexec_b64 s[4:5], s[2:3]
	s_xor_b64 s[8:9], exec, s[4:5]
	s_cbranch_execnz .Lsl_383
.LBB0_383:
	s_andn2_saveexec_b64 s[2:3], s[8:9]
	v_mul_f32_e64 v2, |v34|, s1
	v_rndne_f32_e32 v3, v2
	v_cvt_i32_f32_e32 v2, v3
	v_fma_f32 v38, v3, s92, |v34|
	v_fmac_f32_e32 v38, 0xb3a22168, v3
	v_fmac_f32_e32 v38, 0xa7c234c4, v3
	s_or_b64 exec, exec, s[2:3]
	v_mul_f32_e32 v36, v130, v4
	v_and_b32_e32 v37, 0x7fffffff, v36
	v_cmp_nlt_f32_e64 s[2:3], |v36|, s60
	s_and_saveexec_b64 s[4:5], s[2:3]
	s_xor_b64 s[8:9], exec, s[4:5]
	s_cbranch_execnz .Lsl_387
.LBB0_387:
	s_andn2_saveexec_b64 s[2:3], s[8:9]
	v_mul_f32_e64 v3, |v36|, s1
	v_rndne_f32_e32 v5, v3
	v_cvt_i32_f32_e32 v3, v5
	v_fma_f32 v41, v5, s92, |v36|
	v_fmac_f32_e32 v41, 0xb3a22168, v5
	v_fmac_f32_e32 v41, 0xa7c234c4, v5
	s_or_b64 exec, exec, s[2:3]
	v_mul_f32_e32 v39, v131, v4
	v_and_b32_e32 v40, 0x7fffffff, v39
	v_cmp_nlt_f32_e64 s[2:3], |v39|, s60
	s_and_saveexec_b64 s[4:5], s[2:3]
	s_xor_b64 s[8:9], exec, s[4:5]
	s_cbranch_execnz .Lsl_391
.LBB0_391:
	s_andn2_saveexec_b64 s[2:3], s[8:9]
	v_mul_f32_e64 v5, |v39|, s1
	v_rndne_f32_e32 v5, v5
	v_cvt_i32_f32_e32 v58, v5
	v_fma_f32 v42, v5, s92, |v39|
	v_fmac_f32_e32 v42, 0xb3a22168, v5
	v_fmac_f32_e32 v42, 0xa7c234c4, v5
	s_or_b64 exec, exec, s[2:3]
	v_mul_f32_e32 v43, v132, v4
	v_and_b32_e32 v44, 0x7fffffff, v43
	v_cmp_nlt_f32_e64 s[2:3], |v43|, s60
	s_and_saveexec_b64 s[4:5], s[2:3]
	s_xor_b64 s[8:9], exec, s[4:5]
	s_cbranch_execnz .Lsl_395
.LBB0_395:
	s_andn2_saveexec_b64 s[2:3], s[8:9]
	v_mul_f32_e64 v5, |v43|, s1
	v_rndne_f32_e32 v5, v5
	v_cvt_i32_f32_e32 v59, v5
	v_fma_f32 v47, v5, s92, |v43|
	v_fmac_f32_e32 v47, 0xb3a22168, v5
	v_fmac_f32_e32 v47, 0xa7c234c4, v5
	s_or_b64 exec, exec, s[2:3]
	v_mul_f32_e32 v45, v133, v4
	v_and_b32_e32 v46, 0x7fffffff, v45
	v_cmp_nlt_f32_e64 s[2:3], |v45|, s60
	s_and_saveexec_b64 s[4:5], s[2:3]
	s_xor_b64 s[8:9], exec, s[4:5]
	s_cbranch_execnz .Lsl_399
.LBB0_399:
	s_andn2_saveexec_b64 s[2:3], s[8:9]
	v_mul_f32_e64 v5, |v45|, s1
	v_rndne_f32_e32 v5, v5
	v_cvt_i32_f32_e32 v60, v5
	v_fma_f32 v48, v5, s92, |v45|
	v_fmac_f32_e32 v48, 0xb3a22168, v5
	v_fmac_f32_e32 v48, 0xa7c234c4, v5
	s_or_b64 exec, exec, s[2:3]
	v_mul_f32_e32 v49, v134, v4
	v_and_b32_e32 v50, 0x7fffffff, v49
	v_cmp_nlt_f32_e64 s[2:3], |v49|, s60
	s_and_saveexec_b64 s[4:5], s[2:3]
	s_xor_b64 s[8:9], exec, s[4:5]
	s_cbranch_execnz .Lsl_403
.LBB0_403:
	s_andn2_saveexec_b64 s[2:3], s[8:9]
	v_mul_f32_e64 v5, |v49|, s1
	v_rndne_f32_e32 v5, v5
	v_cvt_i32_f32_e32 v61, v5
	v_fma_f32 v51, v5, s92, |v49|
	v_fmac_f32_e32 v51, 0xb3a22168, v5
	v_fmac_f32_e32 v51, 0xa7c234c4, v5
	s_or_b64 exec, exec, s[2:3]
	v_mul_f32_e32 v52, v135, v4
	v_and_b32_e32 v53, 0x7fffffff, v52
	v_cmp_nlt_f32_e64 s[2:3], |v52|, s60
	s_and_saveexec_b64 s[4:5], s[2:3]
	s_xor_b64 s[8:9], exec, s[4:5]
	s_cbranch_execnz .Lsl_407
.LBB0_407:
	s_andn2_saveexec_b64 s[2:3], s[8:9]
	v_mul_f32_e64 v5, |v52|, s1
	v_rndne_f32_e32 v5, v5
	v_cvt_i32_f32_e32 v62, v5
	v_fma_f32 v54, v5, s92, |v52|
	v_fmac_f32_e32 v54, 0xb3a22168, v5
	v_fmac_f32_e32 v54, 0xa7c234c4, v5
	s_or_b64 exec, exec, s[2:3]
	v_mul_f32_e32 v55, v128, v4
	v_and_b32_e32 v56, 0x7fffffff, v55
	v_cmp_nlt_f32_e64 s[2:3], |v55|, s60
	s_and_saveexec_b64 s[4:5], s[2:3]
	s_xor_b64 s[8:9], exec, s[4:5]
	s_cbranch_execnz .Lsl_411
.LBB0_411:
	s_andn2_saveexec_b64 s[2:3], s[8:9]
	v_mul_f32_e64 v4, |v55|, s1
	v_rndne_f32_e32 v4, v4
	v_cvt_i32_f32_e32 v63, v4
	v_fma_f32 v57, v4, s92, |v55|
	v_fmac_f32_e32 v57, 0xb3a22168, v4
	v_fmac_f32_e32 v57, 0xa7c234c4, v4
	s_or_b64 exec, exec, s[2:3]
	global_load_dword v4, v[82:83], off offset:256
	global_load_dword v6, v[82:83], off offset:384
	global_load_dword v65, v[82:83], off offset:512
	global_load_dword v71, v[82:83], off offset:640
	v_mul_f32_e32 v68, v41, v41
	v_and_b32_e32 v69, 1, v3
	v_fmamk_f32 v72, v68, 0xb94c1982, v142
	v_fmamk_f32 v73, v68, 0x37d75334, v143
	v_cmp_eq_u32_e64 s[10:11], 0, v69
	v_fmaak_f32 v69, v68, v72, 0xbe2aaa9d
	v_fmaak_f32 v72, v68, v73, 0x3d2aabf7
	v_mul_f32_e32 v69, v68, v69
	v_fmaak_f32 v72, v68, v72, 0xbf000004
	v_fmac_f32_e32 v41, v41, v69
	v_fma_f32 v69, v68, v72, 1.0
	global_load_dword v72, v[82:83], off offset:768
	v_mul_f32_e32 v5, v38, v38
	v_lshlrev_b32_e32 v67, 30, v2
	v_and_b32_e32 v2, 1, v2
	v_fmamk_f32 v7, v5, 0xb94c1982, v142
	v_fmamk_f32 v8, v5, 0x37d75334, v143
	v_cmp_eq_u32_e64 s[12:13], 0, v2
	v_fmaak_f32 v2, v5, v7, 0xbe2aaa9d
	v_fmaak_f32 v7, v5, v8, 0x3d2aabf7
	v_mul_f32_e32 v2, v5, v2
	v_fmaak_f32 v7, v5, v7, 0xbf000004
	v_fmac_f32_e32 v38, v38, v2
	v_fma_f32 v70, v5, v7, 1.0
	v_xor_b32_e32 v2, 0x80000000, v38
	v_cndmask_b32_e64 v2, v2, v70, s[12:13]
	v_cmp_class_f32_e64 s[6:7], v34, s96
	v_bitop3_b32 v2, v2, v67, s53 bitop3:0x78
	v_xor_b32_e32 v34, v35, v34
	v_cndmask_b32_e64 v2, v147, v2, s[6:7]
	global_load_dword v35, v[84:85], off offset:128
	v_lshlrev_b32_e32 v66, 30, v3
	v_xor_b32_e32 v68, 0x80000000, v41
	v_cndmask_b32_e64 v68, v68, v69, s[10:11]
	v_cmp_class_f32_e64 s[2:3], v36, s96
	v_bitop3_b32 v68, v68, v66, s53 bitop3:0x78
	v_mul_f32_e32 v73, v42, v42
	v_cndmask_b32_e64 v68, v147, v68, s[2:3]
	v_fmamk_f32 v74, v73, 0x37d75334, v143
	v_cmp_class_f32_e64 vcc, v39, s96
	v_cndmask_b32_e64 v38, v70, v38, s[12:13]
	v_xor_b32_e32 v34, v34, v38
	v_cndmask_b32_e64 v38, v69, v41, s[10:11]
	v_xor_b32_e32 v36, v37, v36
	v_xor_b32_e32 v36, v36, v38
	v_cmp_class_f32_e64 s[8:9], v43, s96
	v_cmp_class_f32_e64 s[16:17], v45, s96
	v_cmp_class_f32_e64 s[20:21], v49, s96
	v_cmp_class_f32_e64 s[26:27], v52, s96
	v_cmp_class_f32_e64 s[30:31], v55, s96
	v_and_b32_e32 v67, 0x80000000, v67
	v_xor_b32_e32 v34, v34, v67
	v_cndmask_b32_e64 v34, v148, -v34, s[6:7]
	v_xor_b32_e32 v37, v40, v39
	v_mul_f32_e32 v150, 0x38800200, v1
	s_waitcnt vmcnt(5)
; __device__ __forceinline__ void filter_item32(const Args& a, int L, bf16* KR, int t0, int np0, int npn, int lane) {
;     ...
;         for (int k = 0; k < 8; ++k) { const float f = 1e-4f + (float)(k + 8 * hi) * ((15.0f - 1e-4f) / 15.0f); float s, c; sincosf(f * w, &s, &c); cv[k] = c; sv[k] = -s; }
; #pragma unroll
;         for (int kk = 0; kk < 17; ++kk) {
;             const int urow = kk < 8 ? 1 + kk : (kk < 16 ? 17 + (kk - 8) : 0);
;             const float zb = kk < 8 ? cv[kk & 7] : (kk < 16 ? sv[kk & 7] : (hi == 0 ? tt : 0.f));
;             const float* ub = w1 + urow * 64; const int lo1 = kk < 16 ? 8 * hi * 64 + n : n;
;             const float a0 = ub[lo1], a1 = ub[lo1 + 32];
;             h0 = __builtin_amdgcn_mfma_f32_32x32x2f32(a0, zb, h0, 0, 0, 0); h1 = __builtin_amdgcn_mfma_f32_32x32x2f32(a1, zb, h1, 0, 0, 0);
	v_mfma_f32_32x32x2_f32 v[18:33], v4, v2, 0
	global_load_dword v38, v[100:101], off offset:128
	s_waitcnt vmcnt(5)
	v_mfma_f32_32x32x2_f32 v[2:17], v6, v2, 0
	s_waitcnt vmcnt(4)
	v_mfma_f32_32x32x2_f32 v[18:33], v65, v68, v[18:33]
	v_lshlrev_b32_e32 v65, 30, v58
	v_and_b32_e32 v58, 1, v58
	v_cmp_eq_u32_e64 s[4:5], 0, v58
	s_waitcnt vmcnt(3)
	v_mfma_f32_32x32x2_f32 v[2:17], v71, v68, v[2:17]
	global_load_dword v71, v[82:83], off offset:896
	v_fmamk_f32 v68, v73, 0xb94c1982, v142
	v_fmaak_f32 v58, v73, v68, 0xbe2aaa9d
	v_fmaak_f32 v68, v73, v74, 0x3d2aabf7
	v_mul_f32_e32 v58, v73, v58
	v_fmaak_f32 v68, v73, v68, 0xbf000004
	v_fmac_f32_e32 v42, v42, v58
	v_fma_f32 v68, v73, v68, 1.0
	v_xor_b32_e32 v58, 0x80000000, v42
	v_cndmask_b32_e64 v58, v58, v68, s[4:5]
	v_bitop3_b32 v58, v58, v65, s53 bitop3:0x78
	v_cndmask_b32_e32 v73, v147, v58, vcc
	v_mul_f32_e32 v74, v47, v47
	v_lshlrev_b32_e32 v58, 30, v59
	v_and_b32_e32 v59, 1, v59
	s_waitcnt vmcnt(3)
	v_mfma_f32_32x32x2_f32 v[18:33], v72, v73, v[18:33]
	global_load_dword v72, v[82:83], off offset:1024
	v_fmamk_f32 v75, v74, 0x37d75334, v143
	v_cmp_eq_u32_e64 s[14:15], 0, v59
	s_waitcnt vmcnt(1)
	v_mfma_f32_32x32x2_f32 v[2:17], v71, v73, v[2:17]
	global_load_dword v73, v[82:83], off offset:1152
	v_fmamk_f32 v71, v74, 0xb94c1982, v142
	v_fmaak_f32 v59, v74, v71, 0xbe2aaa9d
	v_fmaak_f32 v71, v74, v75, 0x3d2aabf7
	v_mul_f32_e32 v59, v74, v59
	v_fmaak_f32 v71, v74, v71, 0xbf000004
	v_fmac_f32_e32 v47, v47, v59
	v_fma_f32 v59, v74, v71, 1.0
	v_xor_b32_e32 v71, 0x80000000, v47
	v_cndmask_b32_e64 v71, v71, v59, s[14:15]
	v_bitop3_b32 v71, v71, v58, s53 bitop3:0x78
	v_cndmask_b32_e64 v74, v147, v71, s[8:9]
	v_mul_f32_e32 v75, v48, v48
	v_lshlrev_b32_e32 v71, 30, v60
	v_and_b32_e32 v60, 1, v60
	s_waitcnt vmcnt(1)
	v_mfma_f32_32x32x2_f32 v[18:33], v72, v74, v[18:33]
	global_load_dword v72, v[82:83], off offset:1280
	v_fmamk_f32 v76, v75, 0x37d75334, v143
	v_cmp_eq_u32_e64 s[18:19], 0, v60
	s_waitcnt vmcnt(1)
	v_mfma_f32_32x32x2_f32 v[2:17], v73, v74, v[2:17]
	global_load_dword v73, v[82:83], off offset:1408
	v_fmamk_f32 v74, v75, 0xb94c1982, v142
	v_fmaak_f32 v60, v75, v74, 0xbe2aaa9d
	v_fmaak_f32 v74, v75, v76, 0x3d2aabf7
	v_mul_f32_e32 v60, v75, v60
	v_fmaak_f32 v74, v75, v74, 0xbf000004
	v_fmac_f32_e32 v48, v48, v60
	v_fma_f32 v60, v75, v74, 1.0
	v_xor_b32_e32 v74, 0x80000000, v48
	v_cndmask_b32_e64 v74, v74, v60, s[18:19]
	v_bitop3_b32 v74, v74, v71, s53 bitop3:0x78
	v_cndmask_b32_e64 v74, v147, v74, s[16:17]
	v_mul_f32_e32 v75, v51, v51
	v_fmamk_f32 v76, v75, 0xb94c1982, v142
	v_fmaak_f32 v76, v75, v76, 0xbe2aaa9d
	s_waitcnt vmcnt(1)
	v_mfma_f32_32x32x2_f32 v[18:33], v72, v74, v[18:33]
	global_load_dword v72, v[82:83], off offset:1536
	s_waitcnt vmcnt(1)
	v_mfma_f32_32x32x2_f32 v[2:17], v73, v74, v[2:17]
	global_load_dword v73, v[82:83], off offset:1664
	v_mul_f32_e32 v74, v75, v76
	v_fmac_f32_e32 v51, v51, v74
	v_fmamk_f32 v74, v75, 0x37d75334, v143
	v_fmaak_f32 v74, v75, v74, 0x3d2aabf7
	v_fmaak_f32 v74, v75, v74, 0xbf000004
	v_lshlrev_b32_e32 v76, 30, v61
	v_and_b32_e32 v61, 1, v61
	v_cmp_eq_u32_e64 s[22:23], 0, v61
	v_fma_f32 v61, v75, v74, 1.0
	v_xor_b32_e32 v74, 0x80000000, v51
	v_cndmask_b32_e64 v74, v74, v61, s[22:23]
	v_bitop3_b32 v74, v74, v76, s53 bitop3:0x78
	v_cndmask_b32_e64 v74, v147, v74, s[20:21]
	v_mul_f32_e32 v75, v54, v54
	v_fmamk_f32 v77, v75, 0xb94c1982, v142
	s_waitcnt vmcnt(1)
	v_mfma_f32_32x32x2_f32 v[18:33], v72, v74, v[18:33]
	global_load_dword v72, v[82:83], off offset:1792
	v_fmaak_f32 v77, v75, v77, 0xbe2aaa9d
	s_waitcnt vmcnt(1)
	v_mfma_f32_32x32x2_f32 v[2:17], v73, v74, v[2:17]
	global_load_dword v73, v[82:83], off offset:1920
	v_mul_f32_e32 v74, v75, v77
	v_fmac_f32_e32 v54, v54, v74
	v_fmamk_f32 v74, v75, 0x37d75334, v143
	v_fmaak_f32 v74, v75, v74, 0x3d2aabf7
	v_fmaak_f32 v74, v75, v74, 0xbf000004
	v_fma_f32 v74, v75, v74, 1.0
	v_lshlrev_b32_e32 v75, 30, v62
	v_and_b32_e32 v62, 1, v62
	v_cmp_eq_u32_e64 s[24:25], 0, v62
	v_xor_b32_e32 v62, 0x80000000, v54
	v_mul_f32_e32 v77, v57, v57
	v_cndmask_b32_e64 v62, v62, v74, s[24:25]
	v_bitop3_b32 v62, v62, v75, s53 bitop3:0x78
	v_cndmask_b32_e64 v62, v147, v62, s[26:27]
	v_fmamk_f32 v78, v77, 0xb94c1982, v142
	s_waitcnt vmcnt(1)
	v_mfma_f32_32x32x2_f32 v[18:33], v72, v62, v[18:33]
	global_load_dword v72, v[82:83], off offset:2048
	s_waitcnt vmcnt(1)
	v_mfma_f32_32x32x2_f32 v[2:17], v73, v62, v[2:17]
	v_fmaak_f32 v62, v77, v78, 0xbe2aaa9d
	v_mul_f32_e32 v62, v77, v62
	v_fmac_f32_e32 v57, v57, v62
	v_fmamk_f32 v62, v77, 0x37d75334, v143
	v_fmaak_f32 v62, v77, v62, 0x3d2aabf7
	v_fmaak_f32 v62, v77, v62, 0xbf000004
	v_lshlrev_b32_e32 v73, 30, v63
	v_and_b32_e32 v63, 1, v63
	v_fma_f32 v62, v77, v62, 1.0
	v_cmp_eq_u32_e64 s[28:29], 0, v63
	v_xor_b32_e32 v63, 0x80000000, v57
	s_nop 0
	v_cndmask_b32_e64 v63, v63, v62, s[28:29]
	v_bitop3_b32 v63, v63, v73, s53 bitop3:0x78
	v_cndmask_b32_e64 v63, v147, v63, s[30:31]
	s_waitcnt vmcnt(0)
; __device__ __forceinline__ int crow16(int r, int hi) { return (r & 3) + 8 * (r >> 2) + 4 * hi; }
; __device__ __forceinline__ void filter_item32(const Args& a, int L, bf16* KR, int t0, int np0, int npn, int lane) {
;     ...
;         for (int kk = 0; kk < 17; ++kk) {
;             const int urow = kk < 8 ? 1 + kk : (kk < 16 ? 17 + (kk - 8) : 0);
;             const float zb = kk < 8 ? cv[kk & 7] : (kk < 16 ? sv[kk & 7] : (hi == 0 ? tt : 0.f));
;             const float* ub = w1 + urow * 64; const int lo1 = kk < 16 ? 8 * hi * 64 + n : n;
;             const float a0 = ub[lo1], a1 = ub[lo1 + 32];
;             h0 = __builtin_amdgcn_mfma_f32_32x32x2f32(a0, zb, h0, 0, 0, 0); h1 = __builtin_amdgcn_mfma_f32_32x32x2f32(a1, zb, h1, 0, 0, 0);
;         }
; #pragma unroll
;         for (int r = 0; r < 16; ++r) { const int j = crow16(r, hi); h0[r] = sinf(fq[j] * (h0[r] + b1[j])); h1[r] = sinf(fq[32 + j] * (h1[r] + b1[32 + j])); }
	s_nop 0
	v_mfma_f32_32x32x2_f32 v[18:33], v72, v63, v[18:33]
	global_load_dword v72, v[82:83], off offset:2176
	s_waitcnt vmcnt(0)
	v_mfma_f32_32x32x2_f32 v[2:17], v72, v63, v[2:17]
	global_load_dword v63, v[84:85], off
	v_mfma_f32_32x32x2_f32 v[2:17], v35, v34, v[2:17]
	v_and_b32_e32 v35, 0x80000000, v66
	v_xor_b32_e32 v35, v36, v35
	v_cndmask_b32_e64 v35, v148, -v35, s[2:3]
	v_cndmask_b32_e64 v36, v68, v42, s[4:5]
	v_xor_b32_e32 v36, v37, v36
	v_xor_b32_e32 v37, v44, v43
	s_waitcnt vmcnt(0)
	v_mfma_f32_32x32x2_f32 v[18:33], v63, v34, v[18:33]
	global_load_dword v34, v[86:87], off
	s_waitcnt vmcnt(0)
	v_mfma_f32_32x32x2_f32 v[18:33], v34, v35, v[18:33]
	global_load_dword v34, v[86:87], off offset:128
	s_waitcnt vmcnt(0)
	v_mfma_f32_32x32x2_f32 v[2:17], v34, v35, v[2:17]
	global_load_dword v34, v[88:89], off
	v_and_b32_e32 v35, 0x80000000, v65
	v_xor_b32_e32 v35, v36, v35
	v_cndmask_b32_e64 v35, v148, -v35, vcc
	v_cndmask_b32_e64 v36, v59, v47, s[14:15]
	v_xor_b32_e32 v36, v37, v36
	v_xor_b32_e32 v37, v46, v45
	s_waitcnt vmcnt(0)
	v_mfma_f32_32x32x2_f32 v[18:33], v34, v35, v[18:33]
	global_load_dword v34, v[88:89], off offset:128
	s_waitcnt vmcnt(0)
	v_mfma_f32_32x32x2_f32 v[2:17], v34, v35, v[2:17]
	global_load_dword v34, v[90:91], off
	v_and_b32_e32 v35, 0x80000000, v58
	v_xor_b32_e32 v35, v36, v35
	v_cndmask_b32_e64 v35, v148, -v35, s[8:9]
	v_cndmask_b32_e64 v36, v60, v48, s[18:19]
	v_xor_b32_e32 v36, v37, v36
	v_xor_b32_e32 v37, v50, v49
	s_waitcnt vmcnt(0)
	v_mfma_f32_32x32x2_f32 v[18:33], v34, v35, v[18:33]
	global_load_dword v34, v[90:91], off offset:128
	s_waitcnt vmcnt(0)
	v_mfma_f32_32x32x2_f32 v[2:17], v34, v35, v[2:17]
	global_load_dword v34, v[92:93], off
	v_and_b32_e32 v35, 0x80000000, v71
	v_xor_b32_e32 v35, v36, v35
	v_cndmask_b32_e64 v35, v148, -v35, s[16:17]
	v_cndmask_b32_e64 v36, v61, v51, s[22:23]
	v_xor_b32_e32 v36, v37, v36
	v_xor_b32_e32 v37, v53, v52
	s_waitcnt vmcnt(0)
	v_mfma_f32_32x32x2_f32 v[18:33], v34, v35, v[18:33]
	global_load_dword v34, v[92:93], off offset:128
	s_waitcnt vmcnt(0)
	v_mfma_f32_32x32x2_f32 v[2:17], v34, v35, v[2:17]
	global_load_dword v34, v[94:95], off
	v_and_b32_e32 v35, 0x80000000, v76
	v_xor_b32_e32 v35, v36, v35
	v_cndmask_b32_e64 v35, v148, -v35, s[20:21]
	v_cndmask_b32_e64 v36, v74, v54, s[24:25]
	v_xor_b32_e32 v36, v37, v36
	v_xor_b32_e32 v37, v56, v55
	s_waitcnt vmcnt(0)
	v_mfma_f32_32x32x2_f32 v[18:33], v34, v35, v[18:33]
	global_load_dword v34, v[94:95], off offset:128
	s_waitcnt vmcnt(0)
	v_mfma_f32_32x32x2_f32 v[2:17], v34, v35, v[2:17]
	global_load_dword v34, v[96:97], off
	v_and_b32_e32 v35, 0x80000000, v75
	v_xor_b32_e32 v35, v36, v35
	v_cndmask_b32_e64 v35, v148, -v35, s[26:27]
	v_cndmask_b32_e64 v36, v62, v57, s[28:29]
	v_xor_b32_e32 v36, v37, v36
	v_cndmask_b32_e64 v37, 0, v150, s[54:55]
	s_waitcnt vmcnt(0)
	v_mfma_f32_32x32x2_f32 v[18:33], v34, v35, v[18:33]
	global_load_dword v34, v[96:97], off offset:128
	s_waitcnt vmcnt(0)
	v_mfma_f32_32x32x2_f32 v[2:17], v34, v35, v[2:17]
	global_load_dword v34, v[98:99], off
	v_and_b32_e32 v35, 0x80000000, v73
	v_xor_b32_e32 v35, v36, v35
	v_cndmask_b32_e64 v35, v148, -v35, s[30:31]
	s_waitcnt vmcnt(0)
	s_nop 0
	v_mfma_f32_32x32x2_f32 v[18:33], v34, v35, v[18:33]
	global_load_dword v34, v[98:99], off offset:128
	s_waitcnt vmcnt(0)
	v_mfma_f32_32x32x2_f32 v[2:17], v34, v35, v[2:17]
	global_load_dword v34, v[100:101], off
	global_load_dword v1, v[106:107], off
	global_load_dword v65, v[104:105], off
	v_mfma_f32_32x32x2_f32 v[2:17], v38, v37, v[2:17]
	s_waitcnt vmcnt(2)
	v_mfma_f32_32x32x2_f32 v[18:33], v34, v37, v[18:33]
	s_waitcnt vmcnt(1)
	s_nop 15
	s_nop 0
	v_add_f32_e32 v1, v18, v1
	s_waitcnt vmcnt(0)
	v_mul_f32_e32 v1, v65, v1
	v_and_b32_e32 v34, 0x7fffffff, v1
	v_cmp_nlt_f32_e64 s[2:3], |v1|, s60
	s_and_saveexec_b64 s[4:5], s[2:3]
	s_xor_b64 s[8:9], exec, s[4:5]
	s_cbranch_execnz .Lsl_415
.LBB0_415:
	s_andn2_saveexec_b64 s[2:3], s[8:9]
	v_mul_f32_e64 v18, |v1|, s1
	v_rndne_f32_e32 v18, v18
	v_cvt_i32_f32_e32 v35, v18
	v_fma_f32 v36, v18, s92, |v1|
	v_fmac_f32_e32 v36, 0xb3a22168, v18
	v_fmac_f32_e32 v36, 0xa7c234c4, v18
	s_or_b64 exec, exec, s[2:3]
	global_load_dword v18, v[106:107], off offset:128
	global_load_dword v66, v[104:105], off offset:128
	s_waitcnt vmcnt(1)
	v_add_f32_e32 v2, v2, v18
	s_waitcnt vmcnt(0)
	v_mul_f32_e32 v18, v66, v2
	v_and_b32_e32 v48, 0x7fffffff, v18
	v_cmp_nlt_f32_e64 s[2:3], |v18|, s60
	s_and_saveexec_b64 s[4:5], s[2:3]
	s_xor_b64 s[8:9], exec, s[4:5]
	s_cbranch_execnz .Lsl_419

; __device__ __forceinline__ void filter_item32(const Args& a, int L, bf16* KR, int t0, int np0, int npn, int lane) {
;     ...
;         for (int k = 0; k < 8; ++k) { const float f = 1e-4f + (float)(k + 8 * hi) * ((15.0f - 1e-4f) / 15.0f); float s, c; sincosf(f * w, &s, &c); cv[k] = c; sv[k] = -s; }
.Lsl_383:
	v_lshrrev_b32_e32 v2, 23, v35
	v_add_u32_e32 v2, 0xffffff88, v2
	v_cmp_lt_u32_e32 vcc, 63, v2
	s_nop 1
	v_cndmask_b32_e32 v3, 0, v145, vcc
	v_add_u32_e32 v2, v3, v2
	v_cmp_lt_u32_e64 s[2:3], 31, v2
	s_nop 1
	v_cndmask_b32_e64 v3, 0, v146, s[2:3]
	v_add_u32_e32 v2, v3, v2
	v_cmp_lt_u32_e64 s[4:5], 31, v2
	s_nop 1
	v_cndmask_b32_e64 v3, 0, v146, s[4:5]
	v_add_u32_e32 v5, v3, v2
	v_and_b32_e32 v2, 0x7fffff, v35
	v_or_b32_e32 v16, 0x800000, v2
	v_mad_u64_u32 v[2:3], s[6:7], v16, s61, 0
	v_mov_b32_e32 v80, v3
	v_mad_u64_u32 v[6:7], s[6:7], v16, s62, v[80:81]
	v_mov_b32_e32 v80, v7
	v_mad_u64_u32 v[8:9], s[6:7], v16, s63, v[80:81]
	v_mov_b32_e32 v80, v9
	v_mad_u64_u32 v[10:11], s[6:7], v16, s72, v[80:81]
	v_mov_b32_e32 v80, v11
	v_mad_u64_u32 v[12:13], s[6:7], v16, s73, v[80:81]
	v_mov_b32_e32 v80, v13
	v_mad_u64_u32 v[14:15], s[6:7], v16, s74, v[80:81]
	v_mov_b32_e32 v80, v15
	v_mad_u64_u32 v[16:17], s[6:7], v16, s75, v[80:81]
	v_cndmask_b32_e32 v3, v14, v10, vcc
	v_cndmask_b32_e32 v7, v16, v12, vcc
	v_cndmask_b32_e32 v11, v17, v14, vcc
	v_cndmask_b32_e64 v9, v7, v3, s[2:3]
	v_cndmask_b32_e64 v7, v11, v7, s[2:3]
	v_cndmask_b32_e32 v11, v12, v8, vcc
	v_cndmask_b32_e64 v3, v3, v11, s[2:3]
	v_cndmask_b32_e64 v7, v7, v9, s[4:5]
	v_cndmask_b32_e64 v9, v9, v3, s[4:5]
	v_sub_u32_e32 v12, 32, v5
	v_alignbit_b32 v13, v7, v9, v12
	v_cmp_eq_u32_e64 s[6:7], 0, v5
	v_cndmask_b32_e32 v6, v10, v6, vcc
	v_cndmask_b32_e32 v2, v8, v2, vcc
	v_cndmask_b32_e64 v5, v13, v7, s[6:7]
	v_cndmask_b32_e64 v7, v11, v6, s[2:3]
	v_cndmask_b32_e64 v3, v3, v7, s[4:5]
	v_alignbit_b32 v10, v9, v3, v12
	v_cndmask_b32_e64 v9, v10, v9, s[6:7]
	v_bfe_u32 v13, v5, 29, 1
	v_cndmask_b32_e64 v2, v6, v2, s[2:3]
	v_alignbit_b32 v10, v5, v9, 30
	v_sub_u32_e32 v14, 0, v13
	v_cndmask_b32_e64 v2, v7, v2, s[4:5]
	v_xor_b32_e32 v10, v10, v14
	v_alignbit_b32 v6, v3, v2, v12
	v_cndmask_b32_e64 v3, v6, v3, s[6:7]
	v_ffbh_u32_e32 v7, v10
	v_alignbit_b32 v6, v9, v3, 30
	v_min_u32_e32 v7, 32, v7
	v_alignbit_b32 v2, v3, v2, 30
	v_xor_b32_e32 v6, v6, v14
	v_sub_u32_e32 v8, 31, v7
	v_xor_b32_e32 v2, v2, v14
	v_alignbit_b32 v9, v10, v6, v8
	v_alignbit_b32 v2, v6, v2, v8
	v_alignbit_b32 v3, v9, v2, 9
	v_ffbh_u32_e32 v6, v3
	v_min_u32_e32 v6, 32, v6
	v_lshrrev_b32_e32 v11, 29, v5
	v_not_b32_e32 v8, v6
	v_alignbit_b32 v2, v3, v2, v8
	v_lshlrev_b32_e32 v3, 31, v11
	v_or_b32_e32 v8, 0x33000000, v3
	v_add_lshl_u32 v6, v6, v7, 23
	v_lshrrev_b32_e32 v2, 9, v2
	v_sub_u32_e32 v6, v8, v6
	v_or_b32_e32 v3, 0.5, v3
	v_lshlrev_b32_e32 v7, 23, v7
	v_or_b32_e32 v2, v6, v2
	v_lshrrev_b32_e32 v6, 9, v9
	v_sub_u32_e32 v3, v3, v7
	v_or_b32_e32 v3, v6, v3
	v_mul_f32_e32 v6, 0x3fc90fda, v3
	v_fma_f32 v7, v3, s0, -v6
	v_fmac_f32_e32 v7, 0x33a22168, v3
	v_fmac_f32_e32 v7, 0x3fc90fda, v2
	v_lshrrev_b32_e32 v2, 30, v5
	v_add_f32_e32 v38, v6, v7
	v_add_u32_e32 v2, v13, v2
	s_branch .LBB0_383
.Lsl_387:
	v_lshrrev_b32_e32 v3, 23, v37
	v_add_u32_e32 v3, 0xffffff88, v3
	v_cmp_lt_u32_e32 vcc, 63, v3
	s_nop 1
	v_cndmask_b32_e32 v5, 0, v145, vcc
	v_add_u32_e32 v3, v5, v3
	v_cmp_lt_u32_e64 s[2:3], 31, v3
	s_nop 1
	v_cndmask_b32_e64 v5, 0, v146, s[2:3]
	v_add_u32_e32 v3, v5, v3
	v_cmp_lt_u32_e64 s[4:5], 31, v3
	s_nop 1
	v_cndmask_b32_e64 v5, 0, v146, s[4:5]
	v_add_u32_e32 v3, v5, v3
	v_and_b32_e32 v5, 0x7fffff, v37
	v_or_b32_e32 v5, 0x800000, v5
	v_mad_u64_u32 v[6:7], s[6:7], v5, s61, 0
	v_mov_b32_e32 v80, v7
	v_mad_u64_u32 v[8:9], s[6:7], v5, s62, v[80:81]
	v_mov_b32_e32 v80, v9
	v_mad_u64_u32 v[10:11], s[6:7], v5, s63, v[80:81]
	v_mov_b32_e32 v80, v11
	v_mad_u64_u32 v[12:13], s[6:7], v5, s72, v[80:81]
	v_mov_b32_e32 v80, v13
	v_mad_u64_u32 v[14:15], s[6:7], v5, s73, v[80:81]
	v_mov_b32_e32 v80, v15
	v_mad_u64_u32 v[16:17], s[6:7], v5, s74, v[80:81]
	v_mov_b32_e32 v80, v17
	v_mad_u64_u32 v[18:19], s[6:7], v5, s75, v[80:81]
	v_cndmask_b32_e32 v7, v16, v12, vcc
	v_cndmask_b32_e32 v5, v18, v14, vcc
	v_cndmask_b32_e32 v11, v19, v16, vcc
	v_cndmask_b32_e64 v9, v5, v7, s[2:3]
	v_cndmask_b32_e64 v5, v11, v5, s[2:3]
	v_cndmask_b32_e32 v11, v14, v10, vcc
	v_cndmask_b32_e64 v7, v7, v11, s[2:3]
	v_cndmask_b32_e64 v5, v5, v9, s[4:5]
	v_cndmask_b32_e64 v9, v9, v7, s[4:5]
	v_sub_u32_e32 v13, 32, v3
	v_alignbit_b32 v14, v5, v9, v13
	v_cmp_eq_u32_e64 s[6:7], 0, v3
	v_cndmask_b32_e32 v6, v10, v6, vcc
	s_nop 0
	v_cndmask_b32_e64 v3, v14, v5, s[6:7]
	v_cndmask_b32_e32 v5, v12, v8, vcc
	v_cndmask_b32_e64 v8, v11, v5, s[2:3]
	v_cndmask_b32_e64 v7, v7, v8, s[4:5]
	v_alignbit_b32 v11, v9, v7, v13
	v_cndmask_b32_e64 v9, v11, v9, s[6:7]
	v_bfe_u32 v14, v3, 29, 1
	v_cndmask_b32_e64 v5, v5, v6, s[2:3]
	v_alignbit_b32 v11, v3, v9, 30
	v_sub_u32_e32 v15, 0, v14
	v_cndmask_b32_e64 v5, v8, v5, s[4:5]
	v_xor_b32_e32 v11, v11, v15
	v_alignbit_b32 v6, v7, v5, v13
	v_cndmask_b32_e64 v6, v6, v7, s[6:7]
	v_ffbh_u32_e32 v8, v11
	v_alignbit_b32 v7, v9, v6, 30
	v_min_u32_e32 v8, 32, v8
	v_alignbit_b32 v5, v6, v5, 30
	v_xor_b32_e32 v7, v7, v15
	v_sub_u32_e32 v9, 31, v8
	v_xor_b32_e32 v5, v5, v15
	v_alignbit_b32 v10, v11, v7, v9
	v_alignbit_b32 v5, v7, v5, v9
	v_alignbit_b32 v6, v10, v5, 9
	v_ffbh_u32_e32 v7, v6
	v_min_u32_e32 v7, 32, v7
	v_lshrrev_b32_e32 v12, 29, v3
	v_not_b32_e32 v9, v7
	v_alignbit_b32 v5, v6, v5, v9
	v_lshlrev_b32_e32 v6, 31, v12
	v_or_b32_e32 v9, 0x33000000, v6
	v_add_lshl_u32 v7, v7, v8, 23
	v_lshrrev_b32_e32 v5, 9, v5
	v_sub_u32_e32 v7, v9, v7
	v_or_b32_e32 v6, 0.5, v6
	v_lshlrev_b32_e32 v8, 23, v8
	v_or_b32_e32 v5, v7, v5
	v_lshrrev_b32_e32 v7, 9, v10
	v_sub_u32_e32 v6, v6, v8
	v_or_b32_e32 v6, v7, v6
	v_mul_f32_e32 v7, 0x3fc90fda, v6
	v_fma_f32 v8, v6, s0, -v7
	v_fmac_f32_e32 v8, 0x33a22168, v6
	v_fmac_f32_e32 v8, 0x3fc90fda, v5
	v_lshrrev_b32_e32 v3, 30, v3
	v_add_f32_e32 v41, v7, v8
	v_add_u32_e32 v3, v14, v3
	s_branch .LBB0_387
; __device__ __forceinline__ void filter_item32(const Args& a, int L, bf16* KR, int t0, int np0, int npn, int lane) {
;     ...
;         for (int k = 0; k < 8; ++k) { const float f = 1e-4f + (float)(k + 8 * hi) * ((15.0f - 1e-4f) / 15.0f); float s, c; sincosf(f * w, &s, &c); cv[k] = c; sv[k] = -s; }
.Lsl_391:
	v_lshrrev_b32_e32 v5, 23, v40
	v_add_u32_e32 v5, 0xffffff88, v5
	v_cmp_lt_u32_e32 vcc, 63, v5
	s_nop 1
	v_cndmask_b32_e32 v6, 0, v145, vcc
	v_add_u32_e32 v5, v6, v5
	v_cmp_lt_u32_e64 s[2:3], 31, v5
	s_nop 1
	v_cndmask_b32_e64 v6, 0, v146, s[2:3]
	v_add_u32_e32 v5, v6, v5
	v_cmp_lt_u32_e64 s[4:5], 31, v5
	s_nop 1
	v_cndmask_b32_e64 v6, 0, v146, s[4:5]
	v_add_u32_e32 v5, v6, v5
	v_and_b32_e32 v6, 0x7fffff, v40
	v_or_b32_e32 v18, 0x800000, v6
	v_mad_u64_u32 v[6:7], s[6:7], v18, s61, 0
	v_mov_b32_e32 v80, v7
	v_mad_u64_u32 v[8:9], s[6:7], v18, s62, v[80:81]
	v_mov_b32_e32 v80, v9
	v_mad_u64_u32 v[10:11], s[6:7], v18, s63, v[80:81]
	v_mov_b32_e32 v80, v11
	v_mad_u64_u32 v[12:13], s[6:7], v18, s72, v[80:81]
	v_mov_b32_e32 v80, v13
	v_mad_u64_u32 v[14:15], s[6:7], v18, s73, v[80:81]
	v_mov_b32_e32 v80, v15
	v_mad_u64_u32 v[16:17], s[6:7], v18, s74, v[80:81]
	v_mov_b32_e32 v80, v17
	v_mad_u64_u32 v[18:19], s[6:7], v18, s75, v[80:81]
	v_cndmask_b32_e32 v7, v16, v12, vcc
	v_cndmask_b32_e32 v9, v18, v14, vcc
	v_cndmask_b32_e32 v13, v19, v16, vcc
	v_cndmask_b32_e64 v11, v9, v7, s[2:3]
	v_cndmask_b32_e64 v9, v13, v9, s[2:3]
	v_cndmask_b32_e32 v13, v14, v10, vcc
	v_cndmask_b32_e64 v7, v7, v13, s[2:3]
	v_cndmask_b32_e64 v9, v9, v11, s[4:5]
	v_cndmask_b32_e64 v11, v11, v7, s[4:5]
	v_sub_u32_e32 v14, 32, v5
	v_alignbit_b32 v15, v9, v11, v14
	v_cmp_eq_u32_e64 s[6:7], 0, v5
	v_cndmask_b32_e32 v8, v12, v8, vcc
	v_cndmask_b32_e32 v6, v10, v6, vcc
	v_cndmask_b32_e64 v5, v15, v9, s[6:7]
	v_cndmask_b32_e64 v9, v13, v8, s[2:3]
	v_cndmask_b32_e64 v7, v7, v9, s[4:5]
	v_alignbit_b32 v12, v11, v7, v14
	v_cndmask_b32_e64 v11, v12, v11, s[6:7]
	v_bfe_u32 v15, v5, 29, 1
	v_cndmask_b32_e64 v6, v8, v6, s[2:3]
	v_alignbit_b32 v12, v5, v11, 30
	v_sub_u32_e32 v16, 0, v15
	v_cndmask_b32_e64 v6, v9, v6, s[4:5]
	v_xor_b32_e32 v12, v12, v16
	v_alignbit_b32 v8, v7, v6, v14
	v_cndmask_b32_e64 v7, v8, v7, s[6:7]
	v_ffbh_u32_e32 v9, v12
	v_alignbit_b32 v8, v11, v7, 30
	v_min_u32_e32 v9, 32, v9
	v_alignbit_b32 v6, v7, v6, 30
	v_xor_b32_e32 v8, v8, v16
	v_sub_u32_e32 v10, 31, v9
	v_xor_b32_e32 v6, v6, v16
	v_alignbit_b32 v11, v12, v8, v10
	v_alignbit_b32 v6, v8, v6, v10
	v_alignbit_b32 v7, v11, v6, 9
	v_ffbh_u32_e32 v8, v7
	v_min_u32_e32 v8, 32, v8
	v_lshrrev_b32_e32 v13, 29, v5
	v_not_b32_e32 v10, v8
	v_alignbit_b32 v6, v7, v6, v10
	v_lshlrev_b32_e32 v7, 31, v13
	v_or_b32_e32 v10, 0x33000000, v7
	v_add_lshl_u32 v8, v8, v9, 23
	v_lshrrev_b32_e32 v6, 9, v6
	v_sub_u32_e32 v8, v10, v8
	v_or_b32_e32 v7, 0.5, v7
	v_lshlrev_b32_e32 v9, 23, v9
	v_or_b32_e32 v6, v8, v6
	v_lshrrev_b32_e32 v8, 9, v11
	v_sub_u32_e32 v7, v7, v9
	v_or_b32_e32 v7, v8, v7
	v_mul_f32_e32 v8, 0x3fc90fda, v7
	v_fma_f32 v9, v7, s0, -v8
	v_fmac_f32_e32 v9, 0x33a22168, v7
	v_fmac_f32_e32 v9, 0x3fc90fda, v6
	v_lshrrev_b32_e32 v5, 30, v5
	v_add_f32_e32 v42, v8, v9
	v_add_u32_e32 v58, v15, v5
	s_branch .LBB0_391
.Lsl_395:
	v_lshrrev_b32_e32 v5, 23, v44
	v_add_u32_e32 v5, 0xffffff88, v5
	v_cmp_lt_u32_e32 vcc, 63, v5
	s_nop 1
	v_cndmask_b32_e32 v6, 0, v145, vcc
	v_add_u32_e32 v5, v6, v5
	v_cmp_lt_u32_e64 s[2:3], 31, v5
	s_nop 1
	v_cndmask_b32_e64 v6, 0, v146, s[2:3]
	v_add_u32_e32 v5, v6, v5
	v_cmp_lt_u32_e64 s[4:5], 31, v5
	s_nop 1
	v_cndmask_b32_e64 v6, 0, v146, s[4:5]
	v_add_u32_e32 v5, v6, v5
	v_and_b32_e32 v6, 0x7fffff, v44
	v_or_b32_e32 v18, 0x800000, v6
	v_mad_u64_u32 v[6:7], s[6:7], v18, s61, 0
	v_mov_b32_e32 v80, v7
	v_mad_u64_u32 v[8:9], s[6:7], v18, s62, v[80:81]
	v_mov_b32_e32 v80, v9
	v_mad_u64_u32 v[10:11], s[6:7], v18, s63, v[80:81]
	v_mov_b32_e32 v80, v11
	v_mad_u64_u32 v[12:13], s[6:7], v18, s72, v[80:81]
	v_mov_b32_e32 v80, v13
	v_mad_u64_u32 v[14:15], s[6:7], v18, s73, v[80:81]
	v_mov_b32_e32 v80, v15
	v_mad_u64_u32 v[16:17], s[6:7], v18, s74, v[80:81]
	v_mov_b32_e32 v80, v17
	v_mad_u64_u32 v[18:19], s[6:7], v18, s75, v[80:81]
	v_cndmask_b32_e32 v7, v16, v12, vcc
	v_cndmask_b32_e32 v9, v18, v14, vcc
	v_cndmask_b32_e32 v13, v19, v16, vcc
	v_cndmask_b32_e64 v11, v9, v7, s[2:3]
	v_cndmask_b32_e64 v9, v13, v9, s[2:3]
	v_cndmask_b32_e32 v13, v14, v10, vcc
	v_cndmask_b32_e64 v7, v7, v13, s[2:3]
	v_cndmask_b32_e64 v9, v9, v11, s[4:5]
	v_cndmask_b32_e64 v11, v11, v7, s[4:5]
	v_sub_u32_e32 v14, 32, v5
	v_alignbit_b32 v15, v9, v11, v14
	v_cmp_eq_u32_e64 s[6:7], 0, v5
	v_cndmask_b32_e32 v8, v12, v8, vcc
	v_cndmask_b32_e32 v6, v10, v6, vcc
	v_cndmask_b32_e64 v5, v15, v9, s[6:7]
	v_cndmask_b32_e64 v9, v13, v8, s[2:3]
	v_cndmask_b32_e64 v7, v7, v9, s[4:5]
	v_alignbit_b32 v12, v11, v7, v14
	v_cndmask_b32_e64 v11, v12, v11, s[6:7]
	v_bfe_u32 v15, v5, 29, 1
	v_cndmask_b32_e64 v6, v8, v6, s[2:3]
	v_alignbit_b32 v12, v5, v11, 30
	v_sub_u32_e32 v16, 0, v15
	v_cndmask_b32_e64 v6, v9, v6, s[4:5]
	v_xor_b32_e32 v12, v12, v16
	v_alignbit_b32 v8, v7, v6, v14
	v_cndmask_b32_e64 v7, v8, v7, s[6:7]
	v_ffbh_u32_e32 v9, v12
	v_alignbit_b32 v8, v11, v7, 30
	v_min_u32_e32 v9, 32, v9
	v_alignbit_b32 v6, v7, v6, 30
	v_xor_b32_e32 v8, v8, v16
	v_sub_u32_e32 v10, 31, v9
	v_xor_b32_e32 v6, v6, v16
	v_alignbit_b32 v11, v12, v8, v10
	v_alignbit_b32 v6, v8, v6, v10
	v_alignbit_b32 v7, v11, v6, 9
	v_ffbh_u32_e32 v8, v7
	v_min_u32_e32 v8, 32, v8
	v_lshrrev_b32_e32 v13, 29, v5
	v_not_b32_e32 v10, v8
	v_alignbit_b32 v6, v7, v6, v10
	v_lshlrev_b32_e32 v7, 31, v13
	v_or_b32_e32 v10, 0x33000000, v7
	v_add_lshl_u32 v8, v8, v9, 23
	v_lshrrev_b32_e32 v6, 9, v6
	v_sub_u32_e32 v8, v10, v8
	v_or_b32_e32 v7, 0.5, v7
	v_lshlrev_b32_e32 v9, 23, v9
	v_or_b32_e32 v6, v8, v6
	v_lshrrev_b32_e32 v8, 9, v11
	v_sub_u32_e32 v7, v7, v9
	v_or_b32_e32 v7, v8, v7
	v_mul_f32_e32 v8, 0x3fc90fda, v7
	v_fma_f32 v9, v7, s0, -v8
	v_fmac_f32_e32 v9, 0x33a22168, v7
	v_fmac_f32_e32 v9, 0x3fc90fda, v6
	v_lshrrev_b32_e32 v5, 30, v5
	v_add_f32_e32 v47, v8, v9
	v_add_u32_e32 v59, v15, v5
	s_branch .LBB0_395
; __device__ __forceinline__ void filter_item32(const Args& a, int L, bf16* KR, int t0, int np0, int npn, int lane) {
;     ...
;         for (int k = 0; k < 8; ++k) { const float f = 1e-4f + (float)(k + 8 * hi) * ((15.0f - 1e-4f) / 15.0f); float s, c; sincosf(f * w, &s, &c); cv[k] = c; sv[k] = -s; }
.Lsl_399:
	v_lshrrev_b32_e32 v5, 23, v46
	v_add_u32_e32 v5, 0xffffff88, v5
	v_cmp_lt_u32_e32 vcc, 63, v5
	s_nop 1
	v_cndmask_b32_e32 v6, 0, v145, vcc
	v_add_u32_e32 v5, v6, v5
	v_cmp_lt_u32_e64 s[2:3], 31, v5
	s_nop 1
	v_cndmask_b32_e64 v6, 0, v146, s[2:3]
	v_add_u32_e32 v5, v6, v5
	v_cmp_lt_u32_e64 s[4:5], 31, v5
	s_nop 1
	v_cndmask_b32_e64 v6, 0, v146, s[4:5]
	v_add_u32_e32 v5, v6, v5
	v_and_b32_e32 v6, 0x7fffff, v46
	v_or_b32_e32 v18, 0x800000, v6
	v_mad_u64_u32 v[6:7], s[6:7], v18, s61, 0
	v_mov_b32_e32 v80, v7
	v_mad_u64_u32 v[8:9], s[6:7], v18, s62, v[80:81]
	v_mov_b32_e32 v80, v9
	v_mad_u64_u32 v[10:11], s[6:7], v18, s63, v[80:81]
	v_mov_b32_e32 v80, v11
	v_mad_u64_u32 v[12:13], s[6:7], v18, s72, v[80:81]
	v_mov_b32_e32 v80, v13
	v_mad_u64_u32 v[14:15], s[6:7], v18, s73, v[80:81]
	v_mov_b32_e32 v80, v15
	v_mad_u64_u32 v[16:17], s[6:7], v18, s74, v[80:81]
	v_mov_b32_e32 v80, v17
	v_mad_u64_u32 v[18:19], s[6:7], v18, s75, v[80:81]
	v_cndmask_b32_e32 v7, v16, v12, vcc
	v_cndmask_b32_e32 v9, v18, v14, vcc
	v_cndmask_b32_e32 v13, v19, v16, vcc
	v_cndmask_b32_e64 v11, v9, v7, s[2:3]
	v_cndmask_b32_e64 v9, v13, v9, s[2:3]
	v_cndmask_b32_e32 v13, v14, v10, vcc
	v_cndmask_b32_e64 v7, v7, v13, s[2:3]
	v_cndmask_b32_e64 v9, v9, v11, s[4:5]
	v_cndmask_b32_e64 v11, v11, v7, s[4:5]
	v_sub_u32_e32 v14, 32, v5
	v_alignbit_b32 v15, v9, v11, v14
	v_cmp_eq_u32_e64 s[6:7], 0, v5
	v_cndmask_b32_e32 v8, v12, v8, vcc
	v_cndmask_b32_e32 v6, v10, v6, vcc
	v_cndmask_b32_e64 v5, v15, v9, s[6:7]
	v_cndmask_b32_e64 v9, v13, v8, s[2:3]
	v_cndmask_b32_e64 v7, v7, v9, s[4:5]
	v_alignbit_b32 v12, v11, v7, v14
	v_cndmask_b32_e64 v11, v12, v11, s[6:7]
	v_bfe_u32 v15, v5, 29, 1
	v_cndmask_b32_e64 v6, v8, v6, s[2:3]
	v_alignbit_b32 v12, v5, v11, 30
	v_sub_u32_e32 v16, 0, v15
	v_cndmask_b32_e64 v6, v9, v6, s[4:5]
	v_xor_b32_e32 v12, v12, v16
	v_alignbit_b32 v8, v7, v6, v14
	v_cndmask_b32_e64 v7, v8, v7, s[6:7]
	v_ffbh_u32_e32 v9, v12
	v_alignbit_b32 v8, v11, v7, 30
	v_min_u32_e32 v9, 32, v9
	v_alignbit_b32 v6, v7, v6, 30
	v_xor_b32_e32 v8, v8, v16
	v_sub_u32_e32 v10, 31, v9
	v_xor_b32_e32 v6, v6, v16
	v_alignbit_b32 v11, v12, v8, v10
	v_alignbit_b32 v6, v8, v6, v10
	v_alignbit_b32 v7, v11, v6, 9
	v_ffbh_u32_e32 v8, v7
	v_min_u32_e32 v8, 32, v8
	v_lshrrev_b32_e32 v13, 29, v5
	v_not_b32_e32 v10, v8
	v_alignbit_b32 v6, v7, v6, v10
	v_lshlrev_b32_e32 v7, 31, v13
	v_or_b32_e32 v10, 0x33000000, v7
	v_add_lshl_u32 v8, v8, v9, 23
	v_lshrrev_b32_e32 v6, 9, v6
	v_sub_u32_e32 v8, v10, v8
	v_or_b32_e32 v7, 0.5, v7
	v_lshlrev_b32_e32 v9, 23, v9
	v_or_b32_e32 v6, v8, v6
	v_lshrrev_b32_e32 v8, 9, v11
	v_sub_u32_e32 v7, v7, v9
	v_or_b32_e32 v7, v8, v7
	v_mul_f32_e32 v8, 0x3fc90fda, v7
	v_fma_f32 v9, v7, s0, -v8
	v_fmac_f32_e32 v9, 0x33a22168, v7
	v_fmac_f32_e32 v9, 0x3fc90fda, v6
	v_lshrrev_b32_e32 v5, 30, v5
	v_add_f32_e32 v48, v8, v9
	v_add_u32_e32 v60, v15, v5
	s_branch .LBB0_399
.Lsl_403:
	v_lshrrev_b32_e32 v5, 23, v50
	v_add_u32_e32 v5, 0xffffff88, v5
	v_cmp_lt_u32_e32 vcc, 63, v5
	s_nop 1
	v_cndmask_b32_e32 v6, 0, v145, vcc
	v_add_u32_e32 v5, v6, v5
	v_cmp_lt_u32_e64 s[2:3], 31, v5
	s_nop 1
	v_cndmask_b32_e64 v6, 0, v146, s[2:3]
	v_add_u32_e32 v5, v6, v5
	v_cmp_lt_u32_e64 s[4:5], 31, v5
	s_nop 1
	v_cndmask_b32_e64 v6, 0, v146, s[4:5]
	v_add_u32_e32 v5, v6, v5
	v_and_b32_e32 v6, 0x7fffff, v50
	v_or_b32_e32 v18, 0x800000, v6
	v_mad_u64_u32 v[6:7], s[6:7], v18, s61, 0
	v_mov_b32_e32 v80, v7
	v_mad_u64_u32 v[8:9], s[6:7], v18, s62, v[80:81]
	v_mov_b32_e32 v80, v9
	v_mad_u64_u32 v[10:11], s[6:7], v18, s63, v[80:81]
	v_mov_b32_e32 v80, v11
	v_mad_u64_u32 v[12:13], s[6:7], v18, s72, v[80:81]
	v_mov_b32_e32 v80, v13
	v_mad_u64_u32 v[14:15], s[6:7], v18, s73, v[80:81]
	v_mov_b32_e32 v80, v15
	v_mad_u64_u32 v[16:17], s[6:7], v18, s74, v[80:81]
	v_mov_b32_e32 v80, v17
	v_mad_u64_u32 v[18:19], s[6:7], v18, s75, v[80:81]
	v_cndmask_b32_e32 v7, v16, v12, vcc
	v_cndmask_b32_e32 v9, v18, v14, vcc
	v_cndmask_b32_e32 v13, v19, v16, vcc
	v_cndmask_b32_e64 v11, v9, v7, s[2:3]
	v_cndmask_b32_e64 v9, v13, v9, s[2:3]
	v_cndmask_b32_e32 v13, v14, v10, vcc
	v_cndmask_b32_e64 v7, v7, v13, s[2:3]
	v_cndmask_b32_e64 v9, v9, v11, s[4:5]
	v_cndmask_b32_e64 v11, v11, v7, s[4:5]
	v_sub_u32_e32 v14, 32, v5
	v_alignbit_b32 v15, v9, v11, v14
	v_cmp_eq_u32_e64 s[6:7], 0, v5
	v_cndmask_b32_e32 v8, v12, v8, vcc
	v_cndmask_b32_e32 v6, v10, v6, vcc
	v_cndmask_b32_e64 v5, v15, v9, s[6:7]
	v_cndmask_b32_e64 v9, v13, v8, s[2:3]
	v_cndmask_b32_e64 v7, v7, v9, s[4:5]
	v_alignbit_b32 v12, v11, v7, v14
	v_cndmask_b32_e64 v11, v12, v11, s[6:7]
	v_bfe_u32 v15, v5, 29, 1
	v_cndmask_b32_e64 v6, v8, v6, s[2:3]
	v_alignbit_b32 v12, v5, v11, 30
	v_sub_u32_e32 v16, 0, v15
	v_cndmask_b32_e64 v6, v9, v6, s[4:5]
	v_xor_b32_e32 v12, v12, v16
	v_alignbit_b32 v8, v7, v6, v14
	v_cndmask_b32_e64 v7, v8, v7, s[6:7]
	v_ffbh_u32_e32 v9, v12
	v_alignbit_b32 v8, v11, v7, 30
	v_min_u32_e32 v9, 32, v9
	v_alignbit_b32 v6, v7, v6, 30
	v_xor_b32_e32 v8, v8, v16
	v_sub_u32_e32 v10, 31, v9
	v_xor_b32_e32 v6, v6, v16
	v_alignbit_b32 v11, v12, v8, v10
	v_alignbit_b32 v6, v8, v6, v10
	v_alignbit_b32 v7, v11, v6, 9
	v_ffbh_u32_e32 v8, v7
	v_min_u32_e32 v8, 32, v8
	v_lshrrev_b32_e32 v13, 29, v5
	v_not_b32_e32 v10, v8
	v_alignbit_b32 v6, v7, v6, v10
	v_lshlrev_b32_e32 v7, 31, v13
	v_or_b32_e32 v10, 0x33000000, v7
	v_add_lshl_u32 v8, v8, v9, 23
	v_lshrrev_b32_e32 v6, 9, v6
	v_sub_u32_e32 v8, v10, v8
	v_or_b32_e32 v7, 0.5, v7
	v_lshlrev_b32_e32 v9, 23, v9
	v_or_b32_e32 v6, v8, v6
	v_lshrrev_b32_e32 v8, 9, v11
	v_sub_u32_e32 v7, v7, v9
	v_or_b32_e32 v7, v8, v7
	v_mul_f32_e32 v8, 0x3fc90fda, v7
	v_fma_f32 v9, v7, s0, -v8
	v_fmac_f32_e32 v9, 0x33a22168, v7
	v_fmac_f32_e32 v9, 0x3fc90fda, v6
	v_lshrrev_b32_e32 v5, 30, v5
	v_add_f32_e32 v51, v8, v9
	v_add_u32_e32 v61, v15, v5
	s_branch .LBB0_403
; __device__ __forceinline__ void filter_item32(const Args& a, int L, bf16* KR, int t0, int np0, int npn, int lane) {
;     ...
;         for (int k = 0; k < 8; ++k) { const float f = 1e-4f + (float)(k + 8 * hi) * ((15.0f - 1e-4f) / 15.0f); float s, c; sincosf(f * w, &s, &c); cv[k] = c; sv[k] = -s; }
.Lsl_407:
	v_lshrrev_b32_e32 v5, 23, v53
	v_add_u32_e32 v5, 0xffffff88, v5
	v_cmp_lt_u32_e32 vcc, 63, v5
	s_nop 1
	v_cndmask_b32_e32 v6, 0, v145, vcc
	v_add_u32_e32 v5, v6, v5
	v_cmp_lt_u32_e64 s[2:3], 31, v5
	s_nop 1
	v_cndmask_b32_e64 v6, 0, v146, s[2:3]
	v_add_u32_e32 v5, v6, v5
	v_cmp_lt_u32_e64 s[4:5], 31, v5
	s_nop 1
	v_cndmask_b32_e64 v6, 0, v146, s[4:5]
	v_add_u32_e32 v5, v6, v5
	v_and_b32_e32 v6, 0x7fffff, v53
	v_or_b32_e32 v18, 0x800000, v6
	v_mad_u64_u32 v[6:7], s[6:7], v18, s61, 0
	v_mov_b32_e32 v80, v7
	v_mad_u64_u32 v[8:9], s[6:7], v18, s62, v[80:81]
	v_mov_b32_e32 v80, v9
	v_mad_u64_u32 v[10:11], s[6:7], v18, s63, v[80:81]
	v_mov_b32_e32 v80, v11
	v_mad_u64_u32 v[12:13], s[6:7], v18, s72, v[80:81]
	v_mov_b32_e32 v80, v13
	v_mad_u64_u32 v[14:15], s[6:7], v18, s73, v[80:81]
	v_mov_b32_e32 v80, v15
	v_mad_u64_u32 v[16:17], s[6:7], v18, s74, v[80:81]
	v_mov_b32_e32 v80, v17
	v_mad_u64_u32 v[18:19], s[6:7], v18, s75, v[80:81]
	v_cndmask_b32_e32 v7, v16, v12, vcc
	v_cndmask_b32_e32 v9, v18, v14, vcc
	v_cndmask_b32_e32 v13, v19, v16, vcc
	v_cndmask_b32_e64 v11, v9, v7, s[2:3]
	v_cndmask_b32_e64 v9, v13, v9, s[2:3]
	v_cndmask_b32_e32 v13, v14, v10, vcc
	v_cndmask_b32_e64 v7, v7, v13, s[2:3]
	v_cndmask_b32_e64 v9, v9, v11, s[4:5]
	v_cndmask_b32_e64 v11, v11, v7, s[4:5]
	v_sub_u32_e32 v14, 32, v5
	v_alignbit_b32 v15, v9, v11, v14
	v_cmp_eq_u32_e64 s[6:7], 0, v5
	v_cndmask_b32_e32 v8, v12, v8, vcc
	v_cndmask_b32_e32 v6, v10, v6, vcc
	v_cndmask_b32_e64 v5, v15, v9, s[6:7]
	v_cndmask_b32_e64 v9, v13, v8, s[2:3]
	v_cndmask_b32_e64 v7, v7, v9, s[4:5]
	v_alignbit_b32 v12, v11, v7, v14
	v_cndmask_b32_e64 v11, v12, v11, s[6:7]
	v_bfe_u32 v15, v5, 29, 1
	v_cndmask_b32_e64 v6, v8, v6, s[2:3]
	v_alignbit_b32 v12, v5, v11, 30
	v_sub_u32_e32 v16, 0, v15
	v_cndmask_b32_e64 v6, v9, v6, s[4:5]
	v_xor_b32_e32 v12, v12, v16
	v_alignbit_b32 v8, v7, v6, v14
	v_cndmask_b32_e64 v7, v8, v7, s[6:7]
	v_ffbh_u32_e32 v9, v12
	v_alignbit_b32 v8, v11, v7, 30
	v_min_u32_e32 v9, 32, v9
	v_alignbit_b32 v6, v7, v6, 30
	v_xor_b32_e32 v8, v8, v16
	v_sub_u32_e32 v10, 31, v9
	v_xor_b32_e32 v6, v6, v16
	v_alignbit_b32 v11, v12, v8, v10
	v_alignbit_b32 v6, v8, v6, v10
	v_alignbit_b32 v7, v11, v6, 9
	v_ffbh_u32_e32 v8, v7
	v_min_u32_e32 v8, 32, v8
	v_lshrrev_b32_e32 v13, 29, v5
	v_not_b32_e32 v10, v8
	v_alignbit_b32 v6, v7, v6, v10
	v_lshlrev_b32_e32 v7, 31, v13
	v_or_b32_e32 v10, 0x33000000, v7
	v_add_lshl_u32 v8, v8, v9, 23
	v_lshrrev_b32_e32 v6, 9, v6
	v_sub_u32_e32 v8, v10, v8
	v_or_b32_e32 v7, 0.5, v7
	v_lshlrev_b32_e32 v9, 23, v9
	v_or_b32_e32 v6, v8, v6
	v_lshrrev_b32_e32 v8, 9, v11
	v_sub_u32_e32 v7, v7, v9
	v_or_b32_e32 v7, v8, v7
	v_mul_f32_e32 v8, 0x3fc90fda, v7
	v_fma_f32 v9, v7, s0, -v8
	v_fmac_f32_e32 v9, 0x33a22168, v7
	v_fmac_f32_e32 v9, 0x3fc90fda, v6
	v_lshrrev_b32_e32 v5, 30, v5
	v_add_f32_e32 v54, v8, v9
	v_add_u32_e32 v62, v15, v5
	s_branch .LBB0_407
.Lsl_411:
	v_lshrrev_b32_e32 v4, 23, v56
	v_add_u32_e32 v4, 0xffffff88, v4
	v_cmp_lt_u32_e32 vcc, 63, v4
	s_nop 1
	v_cndmask_b32_e32 v5, 0, v145, vcc
	v_add_u32_e32 v4, v5, v4
	v_cmp_lt_u32_e64 s[2:3], 31, v4
	s_nop 1
	v_cndmask_b32_e64 v5, 0, v146, s[2:3]
	v_add_u32_e32 v4, v5, v4
	v_cmp_lt_u32_e64 s[4:5], 31, v4
	s_nop 1
	v_cndmask_b32_e64 v5, 0, v146, s[4:5]
	v_add_u32_e32 v18, v5, v4
	v_and_b32_e32 v4, 0x7fffff, v56
	v_or_b32_e32 v16, 0x800000, v4
	v_mad_u64_u32 v[4:5], s[6:7], v16, s61, 0
	v_mov_b32_e32 v80, v5
	v_mad_u64_u32 v[6:7], s[6:7], v16, s62, v[80:81]
	v_mov_b32_e32 v80, v7
	v_mad_u64_u32 v[8:9], s[6:7], v16, s63, v[80:81]
	v_mov_b32_e32 v80, v9
	v_mad_u64_u32 v[10:11], s[6:7], v16, s72, v[80:81]
	v_mov_b32_e32 v80, v11
	v_mad_u64_u32 v[12:13], s[6:7], v16, s73, v[80:81]
	v_mov_b32_e32 v80, v13
	v_mad_u64_u32 v[14:15], s[6:7], v16, s74, v[80:81]
	v_mov_b32_e32 v80, v15
	v_mad_u64_u32 v[16:17], s[6:7], v16, s75, v[80:81]
	v_cndmask_b32_e32 v5, v14, v10, vcc
	v_cndmask_b32_e32 v7, v16, v12, vcc
	v_cndmask_b32_e32 v11, v17, v14, vcc
	v_cndmask_b32_e64 v9, v7, v5, s[2:3]
	v_cndmask_b32_e64 v7, v11, v7, s[2:3]
	v_cndmask_b32_e32 v11, v12, v8, vcc
	v_cndmask_b32_e64 v5, v5, v11, s[2:3]
	v_cndmask_b32_e32 v6, v10, v6, vcc
	v_cndmask_b32_e64 v7, v7, v9, s[4:5]
	v_cndmask_b32_e64 v9, v9, v5, s[4:5]
	v_sub_u32_e32 v12, 32, v18
	v_cndmask_b32_e64 v10, v11, v6, s[2:3]
	v_alignbit_b32 v13, v7, v9, v12
	v_cmp_eq_u32_e64 s[6:7], 0, v18
	v_cndmask_b32_e64 v5, v5, v10, s[4:5]
	v_alignbit_b32 v11, v9, v5, v12
	v_cndmask_b32_e64 v7, v13, v7, s[6:7]
	v_cndmask_b32_e32 v4, v8, v4, vcc
	v_cndmask_b32_e64 v9, v11, v9, s[6:7]
	v_bfe_u32 v14, v7, 29, 1
	v_cndmask_b32_e64 v4, v6, v4, s[2:3]
	v_alignbit_b32 v11, v7, v9, 30
	v_sub_u32_e32 v15, 0, v14
	v_cndmask_b32_e64 v4, v10, v4, s[4:5]
	v_xor_b32_e32 v11, v11, v15
	v_alignbit_b32 v6, v5, v4, v12
	v_cndmask_b32_e64 v5, v6, v5, s[6:7]
	v_ffbh_u32_e32 v8, v11
	v_alignbit_b32 v6, v9, v5, 30
	v_min_u32_e32 v8, 32, v8
	v_alignbit_b32 v4, v5, v4, 30
	v_xor_b32_e32 v6, v6, v15
	v_sub_u32_e32 v9, 31, v8
	v_xor_b32_e32 v4, v4, v15
	v_alignbit_b32 v10, v11, v6, v9
	v_alignbit_b32 v4, v6, v4, v9
	v_alignbit_b32 v5, v10, v4, 9
	v_ffbh_u32_e32 v6, v5
	v_min_u32_e32 v6, 32, v6
	v_lshrrev_b32_e32 v13, 29, v7
	v_not_b32_e32 v9, v6
	v_alignbit_b32 v4, v5, v4, v9
	v_lshlrev_b32_e32 v5, 31, v13
	v_or_b32_e32 v9, 0x33000000, v5
	v_add_lshl_u32 v6, v6, v8, 23
	v_lshrrev_b32_e32 v4, 9, v4
	v_sub_u32_e32 v6, v9, v6
	v_or_b32_e32 v5, 0.5, v5
	v_lshlrev_b32_e32 v8, 23, v8
	v_or_b32_e32 v4, v6, v4
	v_lshrrev_b32_e32 v6, 9, v10
	v_sub_u32_e32 v5, v5, v8
	v_or_b32_e32 v5, v6, v5
	v_mul_f32_e32 v6, 0x3fc90fda, v5
	v_fma_f32 v8, v5, s0, -v6
	v_fmac_f32_e32 v8, 0x33a22168, v5
	v_fmac_f32_e32 v8, 0x3fc90fda, v4
	v_lshrrev_b32_e32 v4, 30, v7
	v_add_f32_e32 v57, v6, v8
	v_add_u32_e32 v63, v14, v4
	s_branch .LBB0_411

.LBB0_1015:
	v_max_f32_e32 v128, v80, v64
	ds_read_b128 v[136:139], v179 offset:53248
	ds_read_b128 v[196:199], v179 offset:53280
	ds_read_b128 v[200:203], v179 offset:53312
	ds_read_b128 v[204:207], v179 offset:53344
	v_max3_f32 v128, v128, v81, v65
	v_max3_f32 v128, v128, v82, v66
	v_max3_f32 v128, v128, v83, v67
	v_max3_f32 v128, v128, v84, v68
	v_max3_f32 v128, v128, v85, v69
	v_max3_f32 v128, v128, v86, v70
	v_max3_f32 v140, v128, v87, v71
	s_add_i32 s8, s7, 1
	s_min_u32 s8, s8, s6
	s_lshl_b32 s8, s8, 17
	buffer_load_dwordx4 v[128:131], v191, s[0:3], s8 offen
	buffer_load_dwordx4 v[132:135], v192, s[0:3], s8 offen
	v_max3_f32 v141, v88, v72, v89
	v_max3_f32 v141, v141, v73, v90
	v_max3_f32 v141, v141, v74, v91
	v_max3_f32 v141, v141, v75, v92
	v_max3_f32 v141, v141, v76, v93
	v_max3_f32 v141, v141, v77, v94
	v_max3_f32 v141, v141, v78, v95
	v_max3_f32 v140, v141, v79, v140
	s_waitcnt lgkmcnt(3)
	v_mfma_f32_32x32x16_bf16 v[48:63], v[136:139], v[156:159], v[48:63]
	v_mov_b32_e32 v141, v140
	ds_read_b128 v[208:211], v179 offset:57856
	s_add_i32 s8, s7, -1
	s_nop 1
	v_permlane32_swap_b32_e32 v141, v140
	v_max_f32_e32 v194, v140, v141
	s_min_u32 s8, s8, s6
	s_lshl_b32 s8, s8, 7
	buffer_load_dwordx4 v[140:143], v177, s[24:27], s8 offen
	buffer_load_dwordx4 v[136:139], v178, s[24:27], s8 offen
	v_sub_f32_e32 v216, v194, v193
	s_waitcnt lgkmcnt(3)
	v_mfma_f32_32x32x16_bf16 v[48:63], v[196:199], v[152:155], v[48:63]
	v_mul_f32_e32 v196, 0x3e38aa3b, v216
	v_cmp_ge_f32_e32 vcc, s72, v196
	ds_read_b128 v[212:215], v179 offset:57888
	s_cmp_eq_u64 vcc, exec
	v_max_f32_e32 v222, v193, v194
	s_cselect_b64 vcc, -1, 0
	v_cndmask_b32_e32 v194, v222, v193, vcc
	v_mul_f32_e32 v228, 0xbe38aa3b, v194
	v_fmamk_f32 v80, v80, 0x3e38aa3b, v228
	v_fmamk_f32 v81, v81, 0x3e38aa3b, v228
	s_waitcnt lgkmcnt(3)
	v_mfma_f32_32x32x16_bf16 v[48:63], v[200:203], v[148:151], v[48:63]
	ds_read_b128 v[216:219], v179 offset:57920
	v_exp_f32_e32 v196, v80
	v_exp_f32_e32 v197, v81
	v_fmamk_f32 v198, v82, 0x3e38aa3b, v228
	v_fmamk_f32 v199, v83, 0x3e38aa3b, v228
	s_waitcnt lgkmcnt(3)
	v_mfma_f32_32x32x16_bf16 v[48:63], v[204:207], v[144:147], v[48:63]
	ds_read_b128 v[80:83], v179 offset:57952
	v_exp_f32_e32 v198, v198
	v_exp_f32_e32 v199, v199
	v_add_f32_e32 v202, 0, v196
	v_add_f32_e32 v203, 0, v197
	v_fmamk_f32 v84, v84, 0x3e38aa3b, v228
	v_fmamk_f32 v85, v85, 0x3e38aa3b, v228
	s_waitcnt lgkmcnt(3)
	v_mfma_f32_32x32x16_bf16 v[32:47], v[208:211], v[156:159], v[32:47]
	ds_read_b128 v[224:227], v179 offset:62464
	v_exp_f32_e32 v200, v84
	v_exp_f32_e32 v201, v85
	v_add_f32_e32 v204, v198, v202
	v_add_f32_e32 v205, v199, v203
	v_fmamk_f32 v202, v86, 0x3e38aa3b, v228
	v_fmamk_f32 v203, v87, 0x3e38aa3b, v228
	s_waitcnt lgkmcnt(3)
	v_mfma_f32_32x32x16_bf16 v[32:47], v[212:215], v[152:155], v[32:47]
	ds_read_b128 v[84:87], v179 offset:62496
	v_exp_f32_e32 v202, v202
	v_exp_f32_e32 v203, v203
	v_add_f32_e32 v206, v200, v204
	v_add_f32_e32 v207, v201, v205
	v_fmamk_f32 v88, v88, 0x3e38aa3b, v228
	v_fmamk_f32 v89, v89, 0x3e38aa3b, v228
	s_waitcnt lgkmcnt(3)
	v_mfma_f32_32x32x16_bf16 v[32:47], v[216:219], v[148:151], v[32:47]
	ds_read_b128 v[234:237], v179 offset:62528
	v_exp_f32_e32 v204, v88
	v_exp_f32_e32 v205, v89
	v_add_f32_e32 v208, v202, v206
	v_add_f32_e32 v209, v203, v207
	v_fmamk_f32 v206, v90, 0x3e38aa3b, v228
	v_fmamk_f32 v207, v91, 0x3e38aa3b, v228
	s_waitcnt lgkmcnt(3)
	v_mfma_f32_32x32x16_bf16 v[32:47], v[80:83], v[144:147], v[32:47]
	ds_read_b128 v[88:91], v179 offset:62560
	v_exp_f32_e32 v206, v206
	v_exp_f32_e32 v207, v207
	v_add_f32_e32 v210, v204, v208
	v_add_f32_e32 v211, v205, v209
	v_fmamk_f32 v92, v92, 0x3e38aa3b, v228
	v_fmamk_f32 v93, v93, 0x3e38aa3b, v228
	s_waitcnt lgkmcnt(3)
	v_mfma_f32_32x32x16_bf16 v[16:31], v[224:227], v[156:159], v[16:31]
	ds_read_b128 v[80:83], v180 offset:32256
	v_exp_f32_e32 v208, v92
	v_exp_f32_e32 v209, v93
	v_add_f32_e32 v212, v206, v210
	v_add_f32_e32 v213, v207, v211
	v_fmamk_f32 v210, v94, 0x3e38aa3b, v228
	v_fmamk_f32 v211, v95, 0x3e38aa3b, v228
	s_waitcnt lgkmcnt(3)
	v_mfma_f32_32x32x16_bf16 v[16:31], v[84:87], v[152:155], v[16:31]
	ds_read_b128 v[92:95], v180 offset:32288
	v_exp_f32_e32 v210, v210
	v_exp_f32_e32 v211, v211
	v_add_f32_e32 v214, v208, v212
	v_add_f32_e32 v215, v209, v213
	v_fmamk_f32 v64, v64, 0x3e38aa3b, v228
	v_fmamk_f32 v65, v65, 0x3e38aa3b, v228
	s_waitcnt lgkmcnt(3)
	v_mfma_f32_32x32x16_bf16 v[16:31], v[234:237], v[148:151], v[16:31]
	ds_read_b128 v[84:87], v180 offset:32320
	v_exp_f32_e32 v212, v64
	v_exp_f32_e32 v213, v65
	v_add_f32_e32 v216, v210, v214
	v_add_f32_e32 v217, v211, v215
	v_fmamk_f32 v214, v66, 0x3e38aa3b, v228
	v_fmamk_f32 v215, v67, 0x3e38aa3b, v228
	s_waitcnt lgkmcnt(3)
	v_mfma_f32_32x32x16_bf16 v[16:31], v[88:91], v[144:147], v[16:31]
	ds_read_b128 v[64:67], v180 offset:32352
	v_exp_f32_e32 v214, v214
	v_exp_f32_e32 v215, v215
	v_add_f32_e32 v218, v212, v216
	v_add_f32_e32 v219, v213, v217
	v_fmamk_f32 v68, v68, 0x3e38aa3b, v228
	v_fmamk_f32 v69, v69, 0x3e38aa3b, v228
	s_waitcnt lgkmcnt(3)
	v_mfma_f32_32x32x16_bf16 v[0:15], v[80:83], v[156:159], v[0:15]
	ds_read_b128 v[88:91], v187 offset:17408
	v_exp_f32_e32 v216, v68
	v_exp_f32_e32 v217, v69
	v_add_f32_e32 v220, v214, v218
	v_add_f32_e32 v221, v215, v219
	v_fmamk_f32 v80, v70, 0x3e38aa3b, v228
	v_fmamk_f32 v81, v71, 0x3e38aa3b, v228
	s_waitcnt lgkmcnt(3)
	v_mfma_f32_32x32x16_bf16 v[0:15], v[92:95], v[152:155], v[0:15]
	ds_read_b128 v[68:71], v187 offset:26112
	v_exp_f32_e32 v218, v80
	v_exp_f32_e32 v219, v81
	v_add_f32_e32 v80, v216, v220
	v_add_f32_e32 v81, v217, v221
	v_fmamk_f32 v72, v72, 0x3e38aa3b, v228
	v_fmamk_f32 v73, v73, 0x3e38aa3b, v228
	s_waitcnt lgkmcnt(3)
	v_mfma_f32_32x32x16_bf16 v[0:15], v[84:87], v[148:151], v[0:15]
	ds_read_b128 v[244:247], v187 offset:17440
	v_exp_f32_e32 v220, v72
	v_exp_f32_e32 v221, v73
	v_add_f32_e32 v72, v218, v80
	v_add_f32_e32 v73, v219, v81
	v_fmamk_f32 v74, v74, 0x3e38aa3b, v228
	v_fmamk_f32 v75, v75, 0x3e38aa3b, v228
	s_waitcnt lgkmcnt(3)
	v_mfma_f32_32x32x16_bf16 v[0:15], v[64:67], v[144:147], v[0:15]
	ds_read_b128 v[248:251], v187 offset:26144
	v_exp_f32_e32 v223, v74
	v_exp_f32_e32 v224, v75
	v_add_f32_e32 v72, v220, v72
	v_add_f32_e32 v73, v221, v73
	v_fmamk_f32 v64, v76, 0x3e38aa3b, v228
	v_fmamk_f32 v65, v77, 0x3e38aa3b, v228
	s_waitcnt lgkmcnt(3)
	v_mfma_f32_32x32x16_bf16 v[80:95], v[88:91], v[96:99], 0
	ds_read_b128 v[252:255], v187 offset:17472
	v_exp_f32_e32 v146, v64
	v_exp_f32_e32 v147, v65
	v_add_f32_e32 v64, v223, v72
	v_add_f32_e32 v65, v224, v73
	v_fmamk_f32 v66, v78, 0x3e38aa3b, v228
	v_fmac_f32_e32 v228, 0x3e38aa3b, v79
	s_nop 0
	v_exp_f32_e32 v225, v66
	v_add_f32_e32 v227, v146, v64
	v_add_f32_e32 v229, v147, v65
	s_waitcnt lgkmcnt(3)
	v_mfma_f32_32x32x16_bf16 v[64:79], v[68:71], v[96:99], 0
	ds_read_b128 v[234:237], v187 offset:26176
	v_exp_f32_e32 v226, v228
	s_waitcnt lgkmcnt(3)
	v_mfma_f32_32x32x16_bf16 v[80:95], v[244:247], v[100:103], v[80:95]
	ds_read_b128 v[238:241], v187 offset:17504
	v_cvt_pk_bf16_f32 v156, v196, v197
	v_cvt_pk_bf16_f32 v157, v198, v199
	v_add_f32_e32 v227, v225, v227
	v_add_f32_e32 v228, v226, v229
	s_waitcnt lgkmcnt(3)
	v_mfma_f32_32x32x16_bf16 v[64:79], v[248:251], v[100:103], v[64:79]
	ds_read_b128 v[244:247], v187 offset:26208
	v_cvt_pk_bf16_f32 v158, v200, v201
	v_cvt_pk_bf16_f32 v159, v202, v203
	s_waitcnt lgkmcnt(3)
	v_mfma_f32_32x32x16_bf16 v[80:95], v[252:255], v[104:107], v[80:95]
	v_cvt_pk_bf16_f32 v152, v204, v205
	v_cvt_pk_bf16_f32 v153, v206, v207
	s_waitcnt vmcnt(7)
	ds_write_b128 v186, v[112:115]
	s_waitcnt vmcnt(6)
	ds_write_b128 v186, v[116:119] offset:8704
	v_add_u32_e32 v112, 0x8800, v188
	s_waitcnt vmcnt(5)
	ds_write2_b64 v112, v[124:125], v[126:127] offset1:2
	v_add_u32_e32 v112, 0xa800, v188
	s_waitcnt vmcnt(4)
	ds_write2_b64 v112, v[120:121], v[122:123] offset0:128 offset1:130
	s_waitcnt lgkmcnt(6)
	v_mfma_f32_32x32x16_bf16 v[64:79], v[234:237], v[104:107], v[64:79]
	v_cvt_pk_bf16_f32 v154, v208, v209
	v_cvt_pk_bf16_f32 v155, v210, v211
	s_waitcnt lgkmcnt(5)
	v_mfma_f32_32x32x16_bf16 v[80:95], v[238:241], v[108:111], v[80:95]
	v_cvt_pk_bf16_f32 v148, v212, v213
	v_cvt_pk_bf16_f32 v149, v214, v215
	s_waitcnt lgkmcnt(4)
	v_mfma_f32_32x32x16_bf16 v[64:79], v[244:247], v[108:111], v[64:79]
	v_cvt_pk_bf16_f32 v150, v216, v217
	v_cvt_pk_bf16_f32 v151, v218, v219
	v_cvt_pk_bf16_f32 v144, v220, v221
	v_cvt_pk_bf16_f32 v145, v223, v224
	v_cvt_pk_bf16_f32 v146, v146, v147
	v_cvt_pk_bf16_f32 v147, v225, v226
	s_cbranch_vccnz .LBB0_1017
	v_sub_f32_e32 v112, v193, v222
	v_mul_f32_e32 v112, 0x3e38aa3b, v112
	v_exp_f32_e32 v112, v112
	s_nop 0
	v_pk_mul_f32 v[62:63], v[112:113], v[62:63] op_sel_hi:[0,1]
	v_pk_mul_f32 v[60:61], v[112:113], v[60:61] op_sel_hi:[0,1]
	v_pk_mul_f32 v[58:59], v[112:113], v[58:59] op_sel_hi:[0,1]
	v_pk_mul_f32 v[56:57], v[112:113], v[56:57] op_sel_hi:[0,1]
	v_pk_mul_f32 v[54:55], v[112:113], v[54:55] op_sel_hi:[0,1]
	v_pk_mul_f32 v[52:53], v[112:113], v[52:53] op_sel_hi:[0,1]
	v_pk_mul_f32 v[50:51], v[112:113], v[50:51] op_sel_hi:[0,1]
	v_pk_mul_f32 v[48:49], v[112:113], v[48:49] op_sel_hi:[0,1]
	v_pk_mul_f32 v[46:47], v[112:113], v[46:47] op_sel_hi:[0,1]
	v_pk_mul_f32 v[44:45], v[112:113], v[44:45] op_sel_hi:[0,1]
	v_pk_mul_f32 v[42:43], v[112:113], v[42:43] op_sel_hi:[0,1]
	v_pk_mul_f32 v[40:41], v[112:113], v[40:41] op_sel_hi:[0,1]
	v_pk_mul_f32 v[38:39], v[112:113], v[38:39] op_sel_hi:[0,1]
	v_pk_mul_f32 v[36:37], v[112:113], v[36:37] op_sel_hi:[0,1]
	v_pk_mul_f32 v[34:35], v[112:113], v[34:35] op_sel_hi:[0,1]
	v_pk_mul_f32 v[32:33], v[112:113], v[32:33] op_sel_hi:[0,1]
	v_pk_mul_f32 v[30:31], v[112:113], v[30:31] op_sel_hi:[0,1]
	v_pk_mul_f32 v[28:29], v[112:113], v[28:29] op_sel_hi:[0,1]
	v_pk_mul_f32 v[26:27], v[112:113], v[26:27] op_sel_hi:[0,1]
	v_pk_mul_f32 v[24:25], v[112:113], v[24:25] op_sel_hi:[0,1]
	v_pk_mul_f32 v[22:23], v[112:113], v[22:23] op_sel_hi:[0,1]
	v_pk_mul_f32 v[20:21], v[112:113], v[20:21] op_sel_hi:[0,1]
	v_pk_mul_f32 v[18:19], v[112:113], v[18:19] op_sel_hi:[0,1]
	v_pk_mul_f32 v[16:17], v[112:113], v[16:17] op_sel_hi:[0,1]
	v_pk_mul_f32 v[14:15], v[112:113], v[14:15] op_sel_hi:[0,1]
	v_pk_mul_f32 v[12:13], v[112:113], v[12:13] op_sel_hi:[0,1]
	v_pk_mul_f32 v[10:11], v[112:113], v[10:11] op_sel_hi:[0,1]
	v_pk_mul_f32 v[8:9], v[112:113], v[8:9] op_sel_hi:[0,1]
	v_pk_mul_f32 v[6:7], v[112:113], v[6:7] op_sel_hi:[0,1]
	v_pk_mul_f32 v[4:5], v[112:113], v[4:5] op_sel_hi:[0,1]
	v_pk_mul_f32 v[2:3], v[112:113], v[2:3] op_sel_hi:[0,1]
	v_pk_mul_f32 v[0:1], v[112:113], v[0:1] op_sel_hi:[0,1]
	v_mul_f32_e32 v195, v195, v112
.LBB0_1017:
	s_waitcnt lgkmcnt(0)
	s_barrier
	ds_read_b128 v[120:123], v179 offset:34816
	ds_read_b128 v[196:199], v179 offset:34848
	ds_read_b128 v[200:203], v179 offset:34880
	ds_read_b128 v[204:207], v179 offset:34912
	v_add_f32_e32 v112, v227, v228
	v_max_f32_e32 v124, v80, v64
	v_add_f32_e32 v195, v112, v195
	s_add_i32 s8, s7, 2
	s_min_u32 s9, s8, s6
	s_lshl_b32 s9, s9, 17
	buffer_load_dwordx4 v[112:115], v191, s[0:3], s9 offen
	buffer_load_dwordx4 v[116:119], v192, s[0:3], s9 offen
	v_max3_f32 v125, v88, v72, v89
	v_max3_f32 v124, v124, v81, v65
	v_max3_f32 v125, v125, v73, v90
	v_max3_f32 v124, v124, v82, v66
	v_max3_f32 v125, v125, v74, v91
	v_max3_f32 v124, v124, v83, v67
	v_max3_f32 v125, v125, v75, v92
	v_max3_f32 v124, v124, v84, v68
	v_max3_f32 v125, v125, v76, v93
	v_max3_f32 v124, v124, v85, v69
	v_max3_f32 v125, v125, v77, v94
	v_max3_f32 v124, v124, v86, v70
	v_max3_f32 v125, v125, v78, v95
	v_max3_f32 v124, v124, v87, v71
	v_max3_f32 v124, v125, v79, v124
	s_waitcnt lgkmcnt(3)
	v_mfma_f32_32x32x16_bf16 v[48:63], v[120:123], v[156:159], v[48:63]
	v_mov_b32_e32 v125, v124
	ds_read_b128 v[208:211], v179 offset:39424
	s_nop 1
	v_permlane32_swap_b32_e32 v125, v124
	v_max_f32_e32 v193, v124, v125
	s_min_u32 s9, s7, s6
	s_lshl_b32 s9, s9, 7
	buffer_load_dwordx4 v[124:127], v177, s[24:27], s9 offen
	buffer_load_dwordx4 v[120:123], v178, s[24:27], s9 offen
	v_sub_f32_e32 v216, v193, v194
	s_waitcnt lgkmcnt(3)
	v_mfma_f32_32x32x16_bf16 v[48:63], v[196:199], v[152:155], v[48:63]
	v_mul_f32_e32 v196, 0x3e38aa3b, v216
	v_cmp_ge_f32_e32 vcc, s72, v196
	ds_read_b128 v[212:215], v179 offset:39456
	s_cmp_eq_u64 vcc, exec
	v_max_f32_e32 v220, v194, v193
	s_cselect_b64 vcc, -1, 0
	v_cndmask_b32_e32 v193, v220, v194, vcc
	v_mul_f32_e32 v238, 0xbe38aa3b, v193
	v_fmamk_f32 v80, v80, 0x3e38aa3b, v238
	v_fmamk_f32 v81, v81, 0x3e38aa3b, v238
	s_waitcnt lgkmcnt(3)
	v_mfma_f32_32x32x16_bf16 v[48:63], v[200:203], v[148:151], v[48:63]
	ds_read_b128 v[216:219], v179 offset:39488
	v_exp_f32_e32 v196, v80
	v_exp_f32_e32 v197, v81
	v_fmamk_f32 v198, v82, 0x3e38aa3b, v238
	v_fmamk_f32 v199, v83, 0x3e38aa3b, v238
	s_waitcnt lgkmcnt(3)
	v_mfma_f32_32x32x16_bf16 v[48:63], v[204:207], v[144:147], v[48:63]
	ds_read_b128 v[80:83], v179 offset:39520
	v_exp_f32_e32 v198, v198
	v_exp_f32_e32 v199, v199
	v_add_f32_e32 v202, 0, v196
	v_add_f32_e32 v203, 0, v197
	v_fmamk_f32 v84, v84, 0x3e38aa3b, v238
	v_fmamk_f32 v85, v85, 0x3e38aa3b, v238
	s_waitcnt lgkmcnt(3)
	v_mfma_f32_32x32x16_bf16 v[32:47], v[208:211], v[156:159], v[32:47]
	ds_read_b128 v[222:225], v179 offset:44032
	v_exp_f32_e32 v200, v84
	v_exp_f32_e32 v201, v85
	v_add_f32_e32 v204, v198, v202
	v_add_f32_e32 v205, v199, v203
	v_fmamk_f32 v202, v86, 0x3e38aa3b, v238
	v_fmamk_f32 v203, v87, 0x3e38aa3b, v238
	s_waitcnt lgkmcnt(3)
	v_mfma_f32_32x32x16_bf16 v[32:47], v[212:215], v[152:155], v[32:47]
	ds_read_b128 v[84:87], v179 offset:44064
	v_exp_f32_e32 v202, v202
	v_exp_f32_e32 v203, v203
	v_add_f32_e32 v206, v200, v204
	v_add_f32_e32 v207, v201, v205
	v_fmamk_f32 v88, v88, 0x3e38aa3b, v238
	v_fmamk_f32 v89, v89, 0x3e38aa3b, v238
	s_waitcnt lgkmcnt(3)
	v_mfma_f32_32x32x16_bf16 v[32:47], v[216:219], v[148:151], v[32:47]
	ds_read_b128 v[226:229], v179 offset:44096
	v_exp_f32_e32 v204, v88
	v_exp_f32_e32 v205, v89
	v_add_f32_e32 v208, v202, v206
	v_add_f32_e32 v209, v203, v207
	v_fmamk_f32 v206, v90, 0x3e38aa3b, v238
	v_fmamk_f32 v207, v91, 0x3e38aa3b, v238
	s_waitcnt lgkmcnt(3)
	v_mfma_f32_32x32x16_bf16 v[32:47], v[80:83], v[144:147], v[32:47]
	ds_read_b128 v[88:91], v179 offset:44128
	v_exp_f32_e32 v206, v206
	v_exp_f32_e32 v207, v207
	v_add_f32_e32 v210, v204, v208
	v_add_f32_e32 v211, v205, v209
	v_fmamk_f32 v92, v92, 0x3e38aa3b, v238
	v_fmamk_f32 v93, v93, 0x3e38aa3b, v238
	s_waitcnt lgkmcnt(3)
	v_mfma_f32_32x32x16_bf16 v[16:31], v[222:225], v[156:159], v[16:31]
	ds_read_b128 v[80:83], v179 offset:48640
	v_exp_f32_e32 v208, v92
	v_exp_f32_e32 v209, v93
	v_add_f32_e32 v212, v206, v210
	v_add_f32_e32 v213, v207, v211
	v_fmamk_f32 v210, v94, 0x3e38aa3b, v238
	v_fmamk_f32 v211, v95, 0x3e38aa3b, v238
	s_waitcnt lgkmcnt(3)
	v_mfma_f32_32x32x16_bf16 v[16:31], v[84:87], v[152:155], v[16:31]
	ds_read_b128 v[92:95], v179 offset:48672
	v_exp_f32_e32 v210, v210
	v_exp_f32_e32 v211, v211
	v_add_f32_e32 v214, v208, v212
	v_add_f32_e32 v215, v209, v213
	v_fmamk_f32 v64, v64, 0x3e38aa3b, v238
	v_fmamk_f32 v65, v65, 0x3e38aa3b, v238
	s_waitcnt lgkmcnt(3)
	v_mfma_f32_32x32x16_bf16 v[16:31], v[226:229], v[148:151], v[16:31]
	ds_read_b128 v[84:87], v179 offset:48704
	v_exp_f32_e32 v212, v64
	v_exp_f32_e32 v213, v65
	v_add_f32_e32 v216, v210, v214
	v_add_f32_e32 v217, v211, v215
	v_fmamk_f32 v214, v66, 0x3e38aa3b, v238
	v_fmamk_f32 v215, v67, 0x3e38aa3b, v238
	s_waitcnt lgkmcnt(3)
	v_mfma_f32_32x32x16_bf16 v[16:31], v[88:91], v[144:147], v[16:31]
	ds_read_b128 v[64:67], v179 offset:48736
	v_exp_f32_e32 v214, v214
	v_exp_f32_e32 v215, v215
	v_add_f32_e32 v218, v212, v216
	v_add_f32_e32 v219, v213, v217
	v_fmamk_f32 v68, v68, 0x3e38aa3b, v238
	v_fmamk_f32 v69, v69, 0x3e38aa3b, v238
	s_waitcnt lgkmcnt(3)
	v_mfma_f32_32x32x16_bf16 v[0:15], v[80:83], v[156:159], v[0:15]
	ds_read_b128 v[88:91], v187
	v_exp_f32_e32 v216, v68
	v_exp_f32_e32 v217, v69
	v_add_f32_e32 v221, v214, v218
	v_add_f32_e32 v222, v215, v219
	v_fmamk_f32 v80, v70, 0x3e38aa3b, v238
	v_fmamk_f32 v81, v71, 0x3e38aa3b, v238
	s_waitcnt lgkmcnt(3)
	v_mfma_f32_32x32x16_bf16 v[0:15], v[92:95], v[152:155], v[0:15]
	ds_read_b128 v[68:71], v187 offset:8704
	v_exp_f32_e32 v218, v80
	v_exp_f32_e32 v219, v81
	v_add_f32_e32 v80, v216, v221
	v_add_f32_e32 v81, v217, v222
	v_fmamk_f32 v72, v72, 0x3e38aa3b, v238
	v_fmamk_f32 v73, v73, 0x3e38aa3b, v238
	s_waitcnt lgkmcnt(3)
	v_mfma_f32_32x32x16_bf16 v[0:15], v[84:87], v[148:151], v[0:15]
	ds_read_b128 v[244:247], v187 offset:32
	v_exp_f32_e32 v221, v72
	v_exp_f32_e32 v222, v73
	v_add_f32_e32 v72, v218, v80
	v_add_f32_e32 v73, v219, v81
	v_fmamk_f32 v74, v74, 0x3e38aa3b, v238
	v_fmamk_f32 v75, v75, 0x3e38aa3b, v238
	s_waitcnt lgkmcnt(3)
	v_mfma_f32_32x32x16_bf16 v[0:15], v[64:67], v[144:147], v[0:15]
	ds_read_b128 v[248:251], v187 offset:8736
	v_exp_f32_e32 v223, v74
	v_exp_f32_e32 v224, v75
	v_add_f32_e32 v72, v221, v72
	v_add_f32_e32 v73, v222, v73
	v_fmamk_f32 v64, v76, 0x3e38aa3b, v238
	v_fmamk_f32 v65, v77, 0x3e38aa3b, v238
	s_waitcnt lgkmcnt(3)
	v_mfma_f32_32x32x16_bf16 v[80:95], v[88:91], v[96:99], 0
	ds_read_b128 v[252:255], v187 offset:64
	v_exp_f32_e32 v146, v64
	v_exp_f32_e32 v147, v65
	v_add_f32_e32 v64, v223, v72
	v_add_f32_e32 v65, v224, v73
	v_fmamk_f32 v66, v78, 0x3e38aa3b, v238
	v_fmac_f32_e32 v238, 0x3e38aa3b, v79
	v_exp_f32_e32 v225, v66
	v_add_f32_e32 v227, v146, v64
	v_add_f32_e32 v229, v147, v65
	s_waitcnt lgkmcnt(3)
	v_mfma_f32_32x32x16_bf16 v[64:79], v[68:71], v[96:99], 0
	ds_read_b128 v[234:237], v187 offset:8768
	v_exp_f32_e32 v226, v238
	s_waitcnt lgkmcnt(3)
	v_mfma_f32_32x32x16_bf16 v[80:95], v[244:247], v[100:103], v[80:95]
	ds_read_b128 v[238:241], v187 offset:96
	v_cvt_pk_bf16_f32 v156, v196, v197
	v_cvt_pk_bf16_f32 v157, v198, v199
	v_add_f32_e32 v227, v225, v227
	v_add_f32_e32 v228, v226, v229
	s_waitcnt lgkmcnt(3)
	v_mfma_f32_32x32x16_bf16 v[64:79], v[248:251], v[100:103], v[64:79]
	ds_read_b128 v[244:247], v187 offset:8800
	v_cvt_pk_bf16_f32 v158, v200, v201
	v_cvt_pk_bf16_f32 v159, v202, v203
	s_waitcnt lgkmcnt(3)
	v_mfma_f32_32x32x16_bf16 v[80:95], v[252:255], v[104:107], v[80:95]
	v_cvt_pk_bf16_f32 v152, v204, v205
	v_cvt_pk_bf16_f32 v153, v206, v207
	s_waitcnt vmcnt(7)
	ds_write_b128 v186, v[128:131] offset:17408
	s_waitcnt vmcnt(6)
	ds_write_b128 v186, v[132:135] offset:26112
	v_add_u32_e32 v128, 0xd000, v188
	s_waitcnt vmcnt(5)
	ds_write2_b64 v128, v[140:141], v[142:143] offset1:2
	v_add_u32_e32 v128, 0xf000, v188
	s_waitcnt vmcnt(4)
	ds_write2_b64 v128, v[136:137], v[138:139] offset0:128 offset1:130
	s_waitcnt lgkmcnt(6)
	v_mfma_f32_32x32x16_bf16 v[64:79], v[234:237], v[104:107], v[64:79]
	v_cvt_pk_bf16_f32 v154, v208, v209
	v_cvt_pk_bf16_f32 v155, v210, v211
	s_waitcnt lgkmcnt(5)
	v_mfma_f32_32x32x16_bf16 v[80:95], v[238:241], v[108:111], v[80:95]
	v_cvt_pk_bf16_f32 v148, v212, v213
	v_cvt_pk_bf16_f32 v149, v214, v215
	s_waitcnt lgkmcnt(4)
	v_mfma_f32_32x32x16_bf16 v[64:79], v[244:247], v[108:111], v[64:79]
	v_cvt_pk_bf16_f32 v150, v216, v217
	v_cvt_pk_bf16_f32 v151, v218, v219
	v_cvt_pk_bf16_f32 v144, v221, v222
	v_cvt_pk_bf16_f32 v145, v223, v224
	v_cvt_pk_bf16_f32 v146, v146, v147
	v_cvt_pk_bf16_f32 v147, v225, v226
	s_cbranch_vccnz .LBB0_1019
	v_sub_f32_e32 v128, v194, v220
	v_mul_f32_e32 v128, 0x3e38aa3b, v128
	v_exp_f32_e32 v128, v128
	s_nop 0
	v_pk_mul_f32 v[62:63], v[128:129], v[62:63] op_sel_hi:[0,1]
	v_pk_mul_f32 v[60:61], v[128:129], v[60:61] op_sel_hi:[0,1]
	v_pk_mul_f32 v[58:59], v[128:129], v[58:59] op_sel_hi:[0,1]
	v_pk_mul_f32 v[56:57], v[128:129], v[56:57] op_sel_hi:[0,1]
	v_pk_mul_f32 v[54:55], v[128:129], v[54:55] op_sel_hi:[0,1]
	v_pk_mul_f32 v[52:53], v[128:129], v[52:53] op_sel_hi:[0,1]
	v_pk_mul_f32 v[50:51], v[128:129], v[50:51] op_sel_hi:[0,1]
	v_pk_mul_f32 v[48:49], v[128:129], v[48:49] op_sel_hi:[0,1]
	v_pk_mul_f32 v[46:47], v[128:129], v[46:47] op_sel_hi:[0,1]
	v_pk_mul_f32 v[44:45], v[128:129], v[44:45] op_sel_hi:[0,1]
	v_pk_mul_f32 v[42:43], v[128:129], v[42:43] op_sel_hi:[0,1]
	v_pk_mul_f32 v[40:41], v[128:129], v[40:41] op_sel_hi:[0,1]
	v_pk_mul_f32 v[38:39], v[128:129], v[38:39] op_sel_hi:[0,1]
	v_pk_mul_f32 v[36:37], v[128:129], v[36:37] op_sel_hi:[0,1]
	v_pk_mul_f32 v[34:35], v[128:129], v[34:35] op_sel_hi:[0,1]
	v_pk_mul_f32 v[32:33], v[128:129], v[32:33] op_sel_hi:[0,1]
	v_pk_mul_f32 v[30:31], v[128:129], v[30:31] op_sel_hi:[0,1]
	v_pk_mul_f32 v[28:29], v[128:129], v[28:29] op_sel_hi:[0,1]
	v_pk_mul_f32 v[26:27], v[128:129], v[26:27] op_sel_hi:[0,1]
	v_pk_mul_f32 v[24:25], v[128:129], v[24:25] op_sel_hi:[0,1]
	v_pk_mul_f32 v[22:23], v[128:129], v[22:23] op_sel_hi:[0,1]
	v_pk_mul_f32 v[20:21], v[128:129], v[20:21] op_sel_hi:[0,1]
	v_pk_mul_f32 v[18:19], v[128:129], v[18:19] op_sel_hi:[0,1]
	v_pk_mul_f32 v[16:17], v[128:129], v[16:17] op_sel_hi:[0,1]
	v_pk_mul_f32 v[14:15], v[128:129], v[14:15] op_sel_hi:[0,1]
	v_pk_mul_f32 v[12:13], v[128:129], v[12:13] op_sel_hi:[0,1]
	v_pk_mul_f32 v[10:11], v[128:129], v[10:11] op_sel_hi:[0,1]
	v_pk_mul_f32 v[8:9], v[128:129], v[8:9] op_sel_hi:[0,1]
	v_pk_mul_f32 v[6:7], v[128:129], v[6:7] op_sel_hi:[0,1]
	v_pk_mul_f32 v[4:5], v[128:129], v[4:5] op_sel_hi:[0,1]
	v_pk_mul_f32 v[2:3], v[128:129], v[2:3] op_sel_hi:[0,1]
	v_pk_mul_f32 v[0:1], v[128:129], v[0:1] op_sel_hi:[0,1]
	v_mul_f32_e32 v195, v195, v128

;     __device__ __forceinline__ void operator()(const f32x4 (&acc)[2][2][4][2], const Unit& u, int wr, int wc, int fr, int fq) const {
;     ...
;             for (int m = 0; m < 4; ++m) { const int row = grow0 + ai * HALF + wr * 64 + m * 16 + fr;
;                 const float* bp = (xp ? (row < 32768 ? xp + (size_t)row * 1024 : xs + (size_t)(row - 32768) * 1024) : out + (size_t)row * 1024) + col0;
;                 float* op = out + (size_t)row * 1024 + col0;
; #pragma unroll
;                 for (int bj = 0; bj < 2; ++bj)
; #pragma unroll
;                     for (int n = 0; n < 2; ++n) { const f32x4 b = *(const f32x4*)(bp + bj * HALF + n * 16); *(f32x4*)(op + bj * HALF + n * 16) = b + gv[bj][n] * acc[ai][bj][m][n]; }
;                 if (m & 1) asm volatile("" ::: "memory"); }
.LBB0_1079:
	v_lshlrev_b64 v[170:171], 2, v[170:171]
	v_lshl_add_u64 v[174:175], v[174:175], 0, v[170:171]
	global_load_dwordx4 v[180:183], v[174:175], off
	global_load_dwordx4 v[244:247], v[174:175], off offset:64
	global_load_dwordx4 v[248:251], v[174:175], off offset:512
	global_load_dwordx4 v[252:255], v[174:175], off offset:576
	v_lshl_add_u64 v[172:173], s[48:49], 0, v[172:173]
	v_lshl_add_u64 v[172:173], v[172:173], 0, v[170:171]
	s_and_b64 vcc, exec, s[2:3]
	s_waitcnt vmcnt(3)
	v_pk_fma_f32 v[142:143], v[142:143], v[94:95], v[182:183]
	v_pk_fma_f32 v[140:141], v[140:141], v[92:93], v[180:181]
	global_store_dwordx4 v[172:173], v[140:143], off
	s_waitcnt vmcnt(3)
	v_pk_fma_f32 v[138:139], v[138:139], v[90:91], v[246:247]
	v_pk_fma_f32 v[136:137], v[136:137], v[88:89], v[244:245]
	global_store_dwordx4 v[172:173], v[136:139], off offset:64
	s_waitcnt vmcnt(3)
	v_pk_fma_f32 v[134:135], v[134:135], v[86:87], v[250:251]
	v_pk_fma_f32 v[132:133], v[132:133], v[84:85], v[248:249]
	global_store_dwordx4 v[172:173], v[132:135], off offset:512
	s_waitcnt vmcnt(3)
	v_pk_fma_f32 v[130:131], v[130:131], v[78:79], v[254:255]
	v_pk_fma_f32 v[128:129], v[128:129], v[76:77], v[252:253]
	global_store_dwordx4 v[172:173], v[128:131], off offset:576
	s_nop 1
	v_or_b32_e32 v128, 16, v158
	s_cbranch_vccnz .LBB0_1132
	v_cmp_lt_i32_e32 vcc, s69, v128
	s_and_saveexec_b64 s[22:23], vcc
	s_xor_b64 s[22:23], exec, s[22:23]
	s_cbranch_execz .LBB0_1082
	v_add_u32_e32 v148, 0xffff8010, v158
	v_readlane_b32 s72, v242, 0
	v_lshlrev_b64 v[130:131], 12, v[148:149]
	v_readlane_b32 s74, v242, 2
	v_readlane_b32 s75, v242, 3
	v_mov_b32_e32 v129, v149
	v_readlane_b32 s73, v242, 1
	v_lshl_add_u64 v[132:133], s[74:75], 0, v[130:131]
	v_lshlrev_b64 v[130:131], 12, v[128:129]
	v_readlane_b32 s76, v242, 4
	v_readlane_b32 s77, v242, 5
	v_readlane_b32 s78, v242, 6
	v_readlane_b32 s79, v242, 7
	v_readlane_b32 s80, v242, 8
	v_readlane_b32 s81, v242, 9
	v_readlane_b32 s82, v242, 10
	v_readlane_b32 s83, v242, 11
	v_readlane_b32 s84, v242, 12
	v_readlane_b32 s85, v242, 13
	v_readlane_b32 s86, v242, 14
	v_readlane_b32 s87, v242, 15

;     __device__ __forceinline__ void operator()(const f32x4 (&acc)[2][2][4][2], const Unit& u, int wr, int wc, int fr, int fq) const {
;     ...
;             for (int m = 0; m < 4; ++m) { const int row = grow0 + ai * HALF + wr * 64 + m * 16 + fr;
;                 const float* bp = (xp ? (row < 32768 ? xp + (size_t)row * 1024 : xs + (size_t)(row - 32768) * 1024) : out + (size_t)row * 1024) + col0;
;                 float* op = out + (size_t)row * 1024 + col0;
; #pragma unroll
;                 for (int bj = 0; bj < 2; ++bj)
; #pragma unroll
;                     for (int n = 0; n < 2; ++n) { const f32x4 b = *(const f32x4*)(bp + bj * HALF + n * 16); *(f32x4*)(op + bj * HALF + n * 16) = b + gv[bj][n] * acc[ai][bj][m][n]; }
;                 if (m & 1) asm volatile("" ::: "memory"); }
.LBB0_1086:
	v_lshl_add_u64 v[128:129], v[132:133], 0, v[170:171]
	global_load_dwordx4 v[132:135], v[128:129], off
	global_load_dwordx4 v[244:247], v[128:129], off offset:64
	global_load_dwordx4 v[248:251], v[128:129], off offset:512
	global_load_dwordx4 v[252:255], v[128:129], off offset:576
	v_lshl_add_u64 v[130:131], s[48:49], 0, v[130:131]
	v_lshl_add_u64 v[130:131], v[130:131], 0, v[170:171]
	s_and_b64 vcc, exec, s[2:3]
	s_waitcnt vmcnt(3)
	v_pk_fma_f32 v[126:127], v[126:127], v[94:95], v[134:135]
	v_pk_fma_f32 v[124:125], v[124:125], v[92:93], v[132:133]
	global_store_dwordx4 v[130:131], v[124:127], off
	s_waitcnt vmcnt(3)
	v_pk_fma_f32 v[122:123], v[122:123], v[90:91], v[246:247]
	v_pk_fma_f32 v[120:121], v[120:121], v[88:89], v[244:245]
	global_store_dwordx4 v[130:131], v[120:123], off offset:64
	s_waitcnt vmcnt(3)
	v_pk_fma_f32 v[118:119], v[118:119], v[86:87], v[250:251]
	v_pk_fma_f32 v[116:117], v[116:117], v[84:85], v[248:249]
	global_store_dwordx4 v[130:131], v[116:119], off offset:512
	s_waitcnt vmcnt(3)
	v_pk_fma_f32 v[114:115], v[114:115], v[78:79], v[254:255]
	v_pk_fma_f32 v[112:113], v[112:113], v[76:77], v[252:253]
	global_store_dwordx4 v[130:131], v[112:115], off offset:576
	s_nop 1
	v_or_b32_e32 v112, 32, v158
	s_cbranch_vccnz .LBB0_1133
	v_cmp_lt_i32_e32 vcc, s69, v112
	s_and_saveexec_b64 s[22:23], vcc
	s_xor_b64 s[22:23], exec, s[22:23]
	s_cbranch_execz .LBB0_1089
	v_add_u32_e32 v148, 0xffff8020, v158
	v_readlane_b32 s72, v242, 0
	v_lshlrev_b64 v[114:115], 12, v[148:149]
	v_readlane_b32 s74, v242, 2
	v_readlane_b32 s75, v242, 3
	v_mov_b32_e32 v113, v149
	v_readlane_b32 s73, v242, 1
	v_lshl_add_u64 v[116:117], s[74:75], 0, v[114:115]
	v_lshlrev_b64 v[114:115], 12, v[112:113]
	v_readlane_b32 s76, v242, 4
	v_readlane_b32 s77, v242, 5
	v_readlane_b32 s78, v242, 6
	v_readlane_b32 s79, v242, 7
	v_readlane_b32 s80, v242, 8
	v_readlane_b32 s81, v242, 9
	v_readlane_b32 s82, v242, 10
	v_readlane_b32 s83, v242, 11
	v_readlane_b32 s84, v242, 12
	v_readlane_b32 s85, v242, 13
	v_readlane_b32 s86, v242, 14
	v_readlane_b32 s87, v242, 15

;     __device__ __forceinline__ void operator()(const f32x4 (&acc)[2][2][4][2], const Unit& u, int wr, int wc, int fr, int fq) const {
;     ...
;             for (int m = 0; m < 4; ++m) { const int row = grow0 + ai * HALF + wr * 64 + m * 16 + fr;
;                 const float* bp = (xp ? (row < 32768 ? xp + (size_t)row * 1024 : xs + (size_t)(row - 32768) * 1024) : out + (size_t)row * 1024) + col0;
;                 float* op = out + (size_t)row * 1024 + col0;
; #pragma unroll
;                 for (int bj = 0; bj < 2; ++bj)
; #pragma unroll
;                     for (int n = 0; n < 2; ++n) { const f32x4 b = *(const f32x4*)(bp + bj * HALF + n * 16); *(f32x4*)(op + bj * HALF + n * 16) = b + gv[bj][n] * acc[ai][bj][m][n]; }
;                 if (m & 1) asm volatile("" ::: "memory"); }
.LBB0_1093:
	v_lshl_add_u64 v[112:113], v[116:117], 0, v[170:171]
	global_load_dwordx4 v[116:119], v[112:113], off
	global_load_dwordx4 v[244:247], v[112:113], off offset:64
	global_load_dwordx4 v[248:251], v[112:113], off offset:512
	global_load_dwordx4 v[252:255], v[112:113], off offset:576
	v_lshl_add_u64 v[114:115], s[48:49], 0, v[114:115]
	v_lshl_add_u64 v[114:115], v[114:115], 0, v[170:171]
	s_and_b64 vcc, exec, s[2:3]
	s_waitcnt vmcnt(3)
	v_pk_fma_f32 v[110:111], v[110:111], v[94:95], v[118:119]
	v_pk_fma_f32 v[108:109], v[108:109], v[92:93], v[116:117]
	global_store_dwordx4 v[114:115], v[108:111], off
	s_waitcnt vmcnt(3)
	v_pk_fma_f32 v[106:107], v[106:107], v[90:91], v[246:247]
	v_pk_fma_f32 v[104:105], v[104:105], v[88:89], v[244:245]
	global_store_dwordx4 v[114:115], v[104:107], off offset:64
	s_waitcnt vmcnt(3)
	v_pk_fma_f32 v[102:103], v[102:103], v[86:87], v[250:251]
	v_pk_fma_f32 v[100:101], v[100:101], v[84:85], v[248:249]
	global_store_dwordx4 v[114:115], v[100:103], off offset:512
	s_waitcnt vmcnt(3)
	v_pk_fma_f32 v[98:99], v[98:99], v[78:79], v[254:255]
	v_pk_fma_f32 v[96:97], v[96:97], v[76:77], v[252:253]
	global_store_dwordx4 v[114:115], v[96:99], off offset:576
	s_nop 1
	v_or_b32_e32 v96, 48, v158
	s_cbranch_vccnz .LBB0_1134
	v_cmp_lt_i32_e32 vcc, s69, v96
	s_and_saveexec_b64 s[22:23], vcc
	s_xor_b64 s[22:23], exec, s[22:23]
	s_cbranch_execz .LBB0_1096
	v_add_u32_e32 v148, 0xffff8030, v158
	v_readlane_b32 s72, v242, 0
	v_lshlrev_b64 v[98:99], 12, v[148:149]
	v_readlane_b32 s74, v242, 2
	v_readlane_b32 s75, v242, 3
	v_mov_b32_e32 v97, v149
	v_readlane_b32 s73, v242, 1
	v_lshl_add_u64 v[100:101], s[74:75], 0, v[98:99]
	v_lshlrev_b64 v[98:99], 12, v[96:97]
	v_readlane_b32 s76, v242, 4
	v_readlane_b32 s77, v242, 5
	v_readlane_b32 s78, v242, 6
	v_readlane_b32 s79, v242, 7
	v_readlane_b32 s80, v242, 8
	v_readlane_b32 s81, v242, 9
	v_readlane_b32 s82, v242, 10
	v_readlane_b32 s83, v242, 11
	v_readlane_b32 s84, v242, 12
	v_readlane_b32 s85, v242, 13
	v_readlane_b32 s86, v242, 14
	v_readlane_b32 s87, v242, 15

;     __device__ __forceinline__ void operator()(const f32x4 (&acc)[2][2][4][2], const Unit& u, int wr, int wc, int fr, int fq) const {
;     ...
;             for (int m = 0; m < 4; ++m) { const int row = grow0 + ai * HALF + wr * 64 + m * 16 + fr;
;                 const float* bp = (xp ? (row < 32768 ? xp + (size_t)row * 1024 : xs + (size_t)(row - 32768) * 1024) : out + (size_t)row * 1024) + col0;
;                 float* op = out + (size_t)row * 1024 + col0;
; #pragma unroll
;                 for (int bj = 0; bj < 2; ++bj)
; #pragma unroll
;                     for (int n = 0; n < 2; ++n) { const f32x4 b = *(const f32x4*)(bp + bj * HALF + n * 16); *(f32x4*)(op + bj * HALF + n * 16) = b + gv[bj][n] * acc[ai][bj][m][n]; }
;                 if (m & 1) asm volatile("" ::: "memory"); }
.LBB0_1100:
	v_lshl_add_u64 v[96:97], v[100:101], 0, v[170:171]
	global_load_dwordx4 v[100:103], v[96:97], off
	global_load_dwordx4 v[244:247], v[96:97], off offset:64
	global_load_dwordx4 v[248:251], v[96:97], off offset:512
	global_load_dwordx4 v[252:255], v[96:97], off offset:576
	v_lshl_add_u64 v[98:99], s[48:49], 0, v[98:99]
	v_lshl_add_u64 v[98:99], v[98:99], 0, v[170:171]
	s_and_b64 vcc, exec, s[2:3]
	s_waitcnt vmcnt(3)
	v_pk_fma_f32 v[82:83], v[82:83], v[94:95], v[102:103]
	v_pk_fma_f32 v[80:81], v[80:81], v[92:93], v[100:101]
	global_store_dwordx4 v[98:99], v[80:83], off
	s_waitcnt vmcnt(3)
	v_pk_fma_f32 v[74:75], v[74:75], v[90:91], v[246:247]
	v_pk_fma_f32 v[72:73], v[72:73], v[88:89], v[244:245]
	global_store_dwordx4 v[98:99], v[72:75], off offset:64
	s_waitcnt vmcnt(3)
	v_pk_fma_f32 v[70:71], v[70:71], v[86:87], v[250:251]
	v_pk_fma_f32 v[68:69], v[68:69], v[84:85], v[248:249]
	global_store_dwordx4 v[98:99], v[68:71], off offset:512
	s_waitcnt vmcnt(3)
	v_pk_fma_f32 v[66:67], v[66:67], v[78:79], v[254:255]
	v_pk_fma_f32 v[64:65], v[64:65], v[76:77], v[252:253]
	global_store_dwordx4 v[98:99], v[64:67], off offset:576
	s_nop 1
	v_add_u32_e32 v64, 0x80, v158
	s_cbranch_vccnz .LBB0_1135
	v_cmp_lt_i32_e32 vcc, s69, v64
	s_and_saveexec_b64 s[22:23], vcc
	s_xor_b64 s[22:23], exec, s[22:23]
	s_cbranch_execz .LBB0_1103
	v_add_u32_e32 v148, 0xffff8080, v158
	v_readlane_b32 s72, v242, 0
	v_lshlrev_b64 v[66:67], 12, v[148:149]
	v_readlane_b32 s74, v242, 2
	v_readlane_b32 s75, v242, 3
	v_mov_b32_e32 v65, v149
	v_readlane_b32 s73, v242, 1
	v_lshl_add_u64 v[68:69], s[74:75], 0, v[66:67]
	v_lshlrev_b64 v[66:67], 12, v[64:65]
	v_readlane_b32 s76, v242, 4
	v_readlane_b32 s77, v242, 5
	v_readlane_b32 s78, v242, 6
	v_readlane_b32 s79, v242, 7
	v_readlane_b32 s80, v242, 8
	v_readlane_b32 s81, v242, 9
	v_readlane_b32 s82, v242, 10
	v_readlane_b32 s83, v242, 11
	v_readlane_b32 s84, v242, 12
	v_readlane_b32 s85, v242, 13
	v_readlane_b32 s86, v242, 14
	v_readlane_b32 s87, v242, 15

;     __device__ __forceinline__ void operator()(const f32x4 (&acc)[2][2][4][2], const Unit& u, int wr, int wc, int fr, int fq) const {
;     ...
;             for (int m = 0; m < 4; ++m) { const int row = grow0 + ai * HALF + wr * 64 + m * 16 + fr;
;                 const float* bp = (xp ? (row < 32768 ? xp + (size_t)row * 1024 : xs + (size_t)(row - 32768) * 1024) : out + (size_t)row * 1024) + col0;
;                 float* op = out + (size_t)row * 1024 + col0;
; #pragma unroll
;                 for (int bj = 0; bj < 2; ++bj)
; #pragma unroll
;                     for (int n = 0; n < 2; ++n) { const f32x4 b = *(const f32x4*)(bp + bj * HALF + n * 16); *(f32x4*)(op + bj * HALF + n * 16) = b + gv[bj][n] * acc[ai][bj][m][n]; }
;                 if (m & 1) asm volatile("" ::: "memory"); }
.LBB0_1107:
	v_lshl_add_u64 v[64:65], v[68:69], 0, v[170:171]
	global_load_dwordx4 v[68:71], v[64:65], off
	global_load_dwordx4 v[244:247], v[64:65], off offset:64
	global_load_dwordx4 v[248:251], v[64:65], off offset:512
	global_load_dwordx4 v[252:255], v[64:65], off offset:576
	v_lshl_add_u64 v[66:67], s[48:49], 0, v[66:67]
	v_lshl_add_u64 v[66:67], v[66:67], 0, v[170:171]
	s_and_b64 vcc, exec, s[2:3]
	s_waitcnt vmcnt(3)
	v_pk_fma_f32 v[62:63], v[62:63], v[94:95], v[70:71]
	v_pk_fma_f32 v[60:61], v[60:61], v[92:93], v[68:69]
	global_store_dwordx4 v[66:67], v[60:63], off
	s_waitcnt vmcnt(3)
	v_pk_fma_f32 v[58:59], v[58:59], v[90:91], v[246:247]
	v_pk_fma_f32 v[56:57], v[56:57], v[88:89], v[244:245]
	global_store_dwordx4 v[66:67], v[56:59], off offset:64
	s_waitcnt vmcnt(3)
	v_pk_fma_f32 v[54:55], v[54:55], v[86:87], v[250:251]
	v_pk_fma_f32 v[52:53], v[52:53], v[84:85], v[248:249]
	global_store_dwordx4 v[66:67], v[52:55], off offset:512
	s_waitcnt vmcnt(3)
	v_pk_fma_f32 v[50:51], v[50:51], v[78:79], v[254:255]
	v_pk_fma_f32 v[48:49], v[48:49], v[76:77], v[252:253]
	global_store_dwordx4 v[66:67], v[48:51], off offset:576
	s_nop 1
	v_add_u32_e32 v48, 0x90, v158
	s_cbranch_vccnz .LBB0_1136
	v_cmp_lt_i32_e32 vcc, s69, v48
	s_and_saveexec_b64 s[22:23], vcc
	s_xor_b64 s[22:23], exec, s[22:23]
	s_cbranch_execz .LBB0_1110
	v_add_u32_e32 v148, 0xffff8090, v158
	v_readlane_b32 s72, v242, 0
	v_lshlrev_b64 v[50:51], 12, v[148:149]
	v_readlane_b32 s74, v242, 2
	v_readlane_b32 s75, v242, 3
	v_mov_b32_e32 v49, v149
	v_readlane_b32 s73, v242, 1
	v_lshl_add_u64 v[52:53], s[74:75], 0, v[50:51]
	v_lshlrev_b64 v[50:51], 12, v[48:49]
	v_readlane_b32 s76, v242, 4
	v_readlane_b32 s77, v242, 5
	v_readlane_b32 s78, v242, 6
	v_readlane_b32 s79, v242, 7
	v_readlane_b32 s80, v242, 8
	v_readlane_b32 s81, v242, 9
	v_readlane_b32 s82, v242, 10
	v_readlane_b32 s83, v242, 11
	v_readlane_b32 s84, v242, 12
	v_readlane_b32 s85, v242, 13
	v_readlane_b32 s86, v242, 14
	v_readlane_b32 s87, v242, 15

;     __device__ __forceinline__ void operator()(const f32x4 (&acc)[2][2][4][2], const Unit& u, int wr, int wc, int fr, int fq) const {
;     ...
;             for (int m = 0; m < 4; ++m) { const int row = grow0 + ai * HALF + wr * 64 + m * 16 + fr;
;                 const float* bp = (xp ? (row < 32768 ? xp + (size_t)row * 1024 : xs + (size_t)(row - 32768) * 1024) : out + (size_t)row * 1024) + col0;
;                 float* op = out + (size_t)row * 1024 + col0;
; #pragma unroll
;                 for (int bj = 0; bj < 2; ++bj)
; #pragma unroll
;                     for (int n = 0; n < 2; ++n) { const f32x4 b = *(const f32x4*)(bp + bj * HALF + n * 16); *(f32x4*)(op + bj * HALF + n * 16) = b + gv[bj][n] * acc[ai][bj][m][n]; }
;                 if (m & 1) asm volatile("" ::: "memory"); }
.LBB0_1114:
	v_lshl_add_u64 v[48:49], v[52:53], 0, v[170:171]
	global_load_dwordx4 v[52:55], v[48:49], off
	global_load_dwordx4 v[244:247], v[48:49], off offset:64
	global_load_dwordx4 v[248:251], v[48:49], off offset:512
	global_load_dwordx4 v[252:255], v[48:49], off offset:576
	v_lshl_add_u64 v[50:51], s[48:49], 0, v[50:51]
	v_lshl_add_u64 v[50:51], v[50:51], 0, v[170:171]
	s_and_b64 vcc, exec, s[2:3]
	s_waitcnt vmcnt(3)
	v_pk_fma_f32 v[46:47], v[46:47], v[94:95], v[54:55]
	v_pk_fma_f32 v[44:45], v[44:45], v[92:93], v[52:53]
	global_store_dwordx4 v[50:51], v[44:47], off
	s_waitcnt vmcnt(3)
	v_pk_fma_f32 v[42:43], v[42:43], v[90:91], v[246:247]
	v_pk_fma_f32 v[40:41], v[40:41], v[88:89], v[244:245]
	global_store_dwordx4 v[50:51], v[40:43], off offset:64
	s_waitcnt vmcnt(3)
	v_pk_fma_f32 v[38:39], v[38:39], v[86:87], v[250:251]
	v_pk_fma_f32 v[36:37], v[36:37], v[84:85], v[248:249]
	global_store_dwordx4 v[50:51], v[36:39], off offset:512
	s_waitcnt vmcnt(3)
	v_pk_fma_f32 v[34:35], v[34:35], v[78:79], v[254:255]
	v_pk_fma_f32 v[32:33], v[32:33], v[76:77], v[252:253]
	global_store_dwordx4 v[50:51], v[32:35], off offset:576
	s_nop 1
	v_add_u32_e32 v32, 0xa0, v158
	s_cbranch_vccnz .LBB0_1137
	v_cmp_lt_i32_e32 vcc, s69, v32
	s_and_saveexec_b64 s[22:23], vcc
	s_xor_b64 s[22:23], exec, s[22:23]
	s_cbranch_execz .LBB0_1117
	v_add_u32_e32 v148, 0xffff80a0, v158
	v_readlane_b32 s72, v242, 0
	v_lshlrev_b64 v[34:35], 12, v[148:149]
	v_readlane_b32 s74, v242, 2
	v_readlane_b32 s75, v242, 3
	v_mov_b32_e32 v33, v149
	v_readlane_b32 s73, v242, 1
	v_lshl_add_u64 v[36:37], s[74:75], 0, v[34:35]
	v_lshlrev_b64 v[34:35], 12, v[32:33]
	v_readlane_b32 s76, v242, 4
	v_readlane_b32 s77, v242, 5
	v_readlane_b32 s78, v242, 6
	v_readlane_b32 s79, v242, 7
	v_readlane_b32 s80, v242, 8
	v_readlane_b32 s81, v242, 9
	v_readlane_b32 s82, v242, 10
	v_readlane_b32 s83, v242, 11
	v_readlane_b32 s84, v242, 12
	v_readlane_b32 s85, v242, 13
	v_readlane_b32 s86, v242, 14
	v_readlane_b32 s87, v242, 15

;     __device__ __forceinline__ void operator()(const f32x4 (&acc)[2][2][4][2], const Unit& u, int wr, int wc, int fr, int fq) const {
;     ...
;             for (int m = 0; m < 4; ++m) { const int row = grow0 + ai * HALF + wr * 64 + m * 16 + fr;
;                 const float* bp = (xp ? (row < 32768 ? xp + (size_t)row * 1024 : xs + (size_t)(row - 32768) * 1024) : out + (size_t)row * 1024) + col0;
;                 float* op = out + (size_t)row * 1024 + col0;
; #pragma unroll
;                 for (int bj = 0; bj < 2; ++bj)
; #pragma unroll
;                     for (int n = 0; n < 2; ++n) { const f32x4 b = *(const f32x4*)(bp + bj * HALF + n * 16); *(f32x4*)(op + bj * HALF + n * 16) = b + gv[bj][n] * acc[ai][bj][m][n]; }
;                 if (m & 1) asm volatile("" ::: "memory"); }
.LBB0_1121:
	v_lshl_add_u64 v[32:33], v[36:37], 0, v[170:171]
	global_load_dwordx4 v[36:39], v[32:33], off
	global_load_dwordx4 v[244:247], v[32:33], off offset:64
	global_load_dwordx4 v[248:251], v[32:33], off offset:512
	global_load_dwordx4 v[252:255], v[32:33], off offset:576
	v_lshl_add_u64 v[34:35], s[48:49], 0, v[34:35]
	v_lshl_add_u64 v[34:35], v[34:35], 0, v[170:171]
	s_and_b64 vcc, exec, s[2:3]
	s_waitcnt vmcnt(3)
	v_pk_fma_f32 v[30:31], v[30:31], v[94:95], v[38:39]
	v_pk_fma_f32 v[28:29], v[28:29], v[92:93], v[36:37]
	global_store_dwordx4 v[34:35], v[28:31], off
	s_waitcnt vmcnt(3)
	v_pk_fma_f32 v[26:27], v[26:27], v[90:91], v[246:247]
	v_pk_fma_f32 v[24:25], v[24:25], v[88:89], v[244:245]
	global_store_dwordx4 v[34:35], v[24:27], off offset:64
	s_waitcnt vmcnt(3)
	v_pk_fma_f32 v[22:23], v[22:23], v[86:87], v[250:251]
	v_pk_fma_f32 v[20:21], v[20:21], v[84:85], v[248:249]
	global_store_dwordx4 v[34:35], v[20:23], off offset:512
	s_waitcnt vmcnt(3)
	v_pk_fma_f32 v[18:19], v[18:19], v[78:79], v[254:255]
	v_pk_fma_f32 v[16:17], v[16:17], v[76:77], v[252:253]
	global_store_dwordx4 v[34:35], v[16:19], off offset:576
	s_nop 1
	v_add_u32_e32 v16, 0xb0, v158
	s_cbranch_vccnz .LBB0_1138
	v_cmp_lt_i32_e32 vcc, s69, v16
	s_and_saveexec_b64 s[2:3], vcc
	s_xor_b64 s[2:3], exec, s[2:3]
	s_cbranch_execz .LBB0_1124
	v_add_u32_e32 v148, 0xffff80b0, v158
	v_readlane_b32 s72, v242, 0
	v_lshlrev_b64 v[18:19], 12, v[148:149]
	v_readlane_b32 s74, v242, 2
	v_readlane_b32 s75, v242, 3
	v_mov_b32_e32 v17, v149
	v_readlane_b32 s73, v242, 1
	v_lshl_add_u64 v[20:21], s[74:75], 0, v[18:19]
	v_lshlrev_b64 v[18:19], 12, v[16:17]
	v_readlane_b32 s76, v242, 4
	v_readlane_b32 s77, v242, 5
	v_readlane_b32 s78, v242, 6
	v_readlane_b32 s79, v242, 7
	v_readlane_b32 s80, v242, 8
	v_readlane_b32 s81, v242, 9
	v_readlane_b32 s82, v242, 10
	v_readlane_b32 s83, v242, 11
	v_readlane_b32 s84, v242, 12
	v_readlane_b32 s85, v242, 13
	v_readlane_b32 s86, v242, 14
	v_readlane_b32 s87, v242, 15

;     __device__ __forceinline__ void operator()(const f32x4 (&acc)[2][2][4][2], const Unit& u, int wr, int wc, int fr, int fq) const {
;     ...
;             for (int m = 0; m < 4; ++m) { const int row = grow0 + ai * HALF + wr * 64 + m * 16 + fr;
;                 const float* bp = (xp ? (row < 32768 ? xp + (size_t)row * 1024 : xs + (size_t)(row - 32768) * 1024) : out + (size_t)row * 1024) + col0;
;                 float* op = out + (size_t)row * 1024 + col0;
; #pragma unroll
;                 for (int bj = 0; bj < 2; ++bj)
; #pragma unroll
;                     for (int n = 0; n < 2; ++n) { const f32x4 b = *(const f32x4*)(bp + bj * HALF + n * 16); *(f32x4*)(op + bj * HALF + n * 16) = b + gv[bj][n] * acc[ai][bj][m][n]; }
;                 if (m & 1) asm volatile("" ::: "memory"); }
.LBB0_1128:
	v_lshl_add_u64 v[16:17], v[20:21], 0, v[170:171]
	global_load_dwordx4 v[20:23], v[16:17], off
	global_load_dwordx4 v[244:247], v[16:17], off offset:64
	global_load_dwordx4 v[248:251], v[16:17], off offset:512
	global_load_dwordx4 v[252:255], v[16:17], off offset:576
	v_lshl_add_u64 v[18:19], s[48:49], 0, v[18:19]
	v_lshl_add_u64 v[18:19], v[18:19], 0, v[170:171]
	s_andn2_b64 vcc, exec, s[0:1]
	s_mov_b64 s[0:1], -1
	s_waitcnt vmcnt(3)
	v_pk_fma_f32 v[14:15], v[14:15], v[94:95], v[22:23]
	v_pk_fma_f32 v[12:13], v[12:13], v[92:93], v[20:21]
	global_store_dwordx4 v[18:19], v[12:15], off
	s_waitcnt vmcnt(3)
	v_pk_fma_f32 v[10:11], v[10:11], v[90:91], v[246:247]
	v_pk_fma_f32 v[8:9], v[8:9], v[88:89], v[244:245]
	global_store_dwordx4 v[18:19], v[8:11], off offset:64
	s_waitcnt vmcnt(3)
	v_pk_fma_f32 v[6:7], v[6:7], v[86:87], v[250:251]
	v_pk_fma_f32 v[4:5], v[4:5], v[84:85], v[248:249]
	global_store_dwordx4 v[18:19], v[4:7], off offset:512
	s_waitcnt vmcnt(3)
	v_pk_fma_f32 v[2:3], v[2:3], v[78:79], v[254:255]
	v_pk_fma_f32 v[0:1], v[0:1], v[76:77], v[252:253]
	global_store_dwordx4 v[18:19], v[0:3], off offset:576
	s_cbranch_vccnz .LBB0_1065
	s_andn2_b64 vcc, exec, s[6:7]
	s_cbranch_vccnz .LBB0_1064
	s_barrier
	s_branch .LBB0_1064
